# sc1 write-through on all bulk stores inside the layer loop (GEMM epilogues, attention, pool/conv outputs)
# baseline (speedup 1.0000x reference)
.LBB0_293:
	s_lshl_b32 s37, s1, 8
	v_readlane_b32 s0, v255, 33
	s_add_i32 s46, s0, s37
	s_lshl_b64 vcc, s[46:47], 1
	s_add_u32 s37, s21, vcc_lo
	s_addc_u32 s46, s20, vcc_hi
	s_add_u32 vcc_lo, s37, 0x9800000
	s_addc_u32 s46, s46, 0
	s_lshl_b32 s37, s38, 1
	s_add_u32 s37, s21, s37
	s_addc_u32 vcc_hi, s20, 0
	s_add_u32 s0, s37, 0xb000000
	v_mov_b32_e32 v173, 0x3e38aa3b
	s_addc_u32 vcc_hi, vcc_hi, 0
	v_cndmask_b32_e64 v190, v173, 1.0, s[84:85]
	s_and_b64 s[84:85], s[84:85], exec
	v_ashrrev_i32_e32 v187, 31, v186
	s_cselect_b32 s37, 8, 10
	s_cselect_b32 s85, vcc_hi, s46
	s_cselect_b32 s84, s0, vcc_lo
	v_lshlrev_b32_e32 v192, 1, v178
	v_mov_b32_e32 v193, v0
	v_lshl_add_u64 v[192:193], s[84:85], 0, v[192:193]
	v_lshlrev_b64 v[198:199], s37, v[186:187]
	v_pk_mul_f32 v[148:149], v[190:191], v[148:149] op_sel_hi:[0,1]
	v_pk_mul_f32 v[146:147], v[190:191], v[146:147] op_sel_hi:[0,1]
	v_lshl_add_u64 v[198:199], v[192:193], 0, v[198:199]
	v_pk_mul_f32 v[152:153], v[190:191], v[152:153] op_sel_hi:[0,1]
	v_pk_mul_f32 v[150:151], v[190:191], v[150:151] op_sel_hi:[0,1]
	v_cvt_pk_bf16_f32 v146, v146, v147
	v_cvt_pk_bf16_f32 v147, v148, v149
	v_cvt_pk_bf16_f32 v150, v150, v151
	v_cvt_pk_bf16_f32 v151, v152, v153
	global_store_dwordx2 v[198:199], v[146:147], off offset:96 sc1
	v_pk_mul_f32 v[146:147], v[32:33], v[32:33]
	v_pk_mul_f32 v[148:149], v[30:31], v[30:31]
	global_store_dwordx2 v[198:199], v[150:151], off offset:64 sc1
	v_pk_mov_b32 v[150:151], v[148:149], v[146:147] op_sel:[1,0]
	v_mov_b32_e32 v149, v147
	v_pk_add_f32 v[146:147], v[150:151], v[148:149]
	v_pk_mul_f32 v[148:149], v[28:29], v[28:29]
	v_pk_add_f32 v[146:147], v[146:147], v[146:147] op_sel_hi:[0,1]
	v_pk_mul_f32 v[150:151], v[26:27], v[26:27]
	v_mul_f32_e32 v146, v22, v22
	v_pk_mov_b32 v[152:153], v[150:151], v[148:149] op_sel:[1,0]
	v_mov_b32_e32 v151, v149
	v_pk_add_f32 v[148:149], v[152:153], v[150:151]
	v_pk_fma_f32 v[150:151], v[22:23], v[22:23], v[146:147] op_sel_hi:[1,1,0]
	v_mul_f32_e32 v146, v24, v24
	v_pk_add_f32 v[148:149], v[148:149], v[148:149] op_sel_hi:[0,1]
	v_pk_fma_f32 v[152:153], v[24:25], v[24:25], v[146:147] op_sel_hi:[1,1,0]
	v_mul_f32_e32 v150, v18, v18
	v_mul_f32_e32 v152, v19, v19
	v_mul_f32_e32 v146, v20, v20
	v_mul_f32_e32 v148, v21, v21
	v_pk_add_f32 v[150:151], v[150:151], v[152:153]
	v_pk_add_f32 v[146:147], v[146:147], v[148:149]
	v_pk_mul_f32 v[160:161], v[190:191], v[160:161] op_sel_hi:[0,1]
	v_pk_add_f32 v[146:147], v[150:151], v[146:147]
	v_pk_mul_f32 v[158:159], v[190:191], v[158:159] op_sel_hi:[0,1]
	v_add_f32_e32 v146, v146, v147
	ds_bpermute_b32 v147, v169, v146
	v_cvt_pk_bf16_f32 v158, v158, v159
	v_cvt_pk_bf16_f32 v159, v160, v161
	global_store_dwordx2 v[198:199], v[158:159], off sc1
	v_pk_mul_f32 v[156:157], v[190:191], v[156:157] op_sel_hi:[0,1]
	s_waitcnt lgkmcnt(0)
	v_add_f32_e32 v146, v146, v147
	ds_bpermute_b32 v147, v167, v146
	v_pk_mul_f32 v[154:155], v[190:191], v[154:155] op_sel_hi:[0,1]
	v_cvt_pk_bf16_f32 v154, v154, v155
	v_cvt_pk_bf16_f32 v155, v156, v157
	global_store_dwordx2 v[198:199], v[154:155], off offset:32 sc1
	s_waitcnt lgkmcnt(0)
	v_add_f32_e32 v146, v146, v147
	v_fmamk_f32 v146, v146, 0x3c800000, v229
	v_cmp_gt_f32_e32 vcc, s92, v146
	v_mul_f32_e32 v147, 0x4b800000, v146
	s_nop 0
	v_cndmask_b32_e32 v146, v146, v147, vcc
	v_rsq_f32_e32 v146, v146
	s_nop 0
	v_mul_f32_e32 v147, 0x45800000, v146
	v_cndmask_b32_e32 v158, v146, v147, vcc
	v_pk_mul_f32 v[146:147], v[30:31], v[158:159] op_sel_hi:[1,0]
	v_pk_mul_f32 v[148:149], v[32:33], v[158:159] op_sel_hi:[1,0]
	v_pk_mul_f32 v[150:151], v[142:143], v[146:147]
	v_pk_mul_f32 v[152:153], v[144:145], v[148:149]
	v_pk_mul_f32 v[146:147], v[26:27], v[158:159] op_sel_hi:[1,0]
	v_pk_mul_f32 v[148:149], v[28:29], v[158:159] op_sel_hi:[1,0]
	v_pk_mul_f32 v[154:155], v[22:23], v[158:159] op_sel_hi:[1,0]
	v_pk_mul_f32 v[156:157], v[24:25], v[158:159] op_sel_hi:[1,0]
	v_pk_mul_f32 v[198:199], v[18:19], v[158:159] op_sel_hi:[1,0]
	v_pk_mul_f32 v[158:159], v[20:21], v[158:159] op_sel_hi:[1,0]
	v_pk_mul_f32 v[148:149], v[140:141], v[148:149]
	v_pk_mul_f32 v[146:147], v[138:139], v[146:147]
	v_pk_mul_f32 v[156:157], v[136:137], v[156:157]
	v_pk_mul_f32 v[154:155], v[134:135], v[154:155]
	v_pk_mul_f32 v[160:161], v[132:133], v[158:159]
	v_pk_mul_f32 v[158:159], v[130:131], v[198:199]
	v_or_b32_e32 v198, 16, v186
	s_and_b64 vcc, exec, s[4:5]
	s_cbranch_vccnz .LBB0_295
	v_lshlrev_b32_e32 v173, 9, v198
	v_and_b32_e32 v200, 0x1be00, v173
	v_mov_b32_e32 v201, v0
	v_lshl_add_u64 v[200:201], v[196:197], 0, v[200:201]
	global_store_dwordx4 v[200:201], v[150:153], off nt
	global_store_dwordx4 v[200:201], v[146:149], off offset:64 nt
	global_store_dwordx4 v[200:201], v[154:157], off offset:128 nt
	global_store_dwordx4 v[200:201], v[158:161], off offset:192 nt

.LBB0_297:
	v_mov_b32_e32 v191, v190
	v_ashrrev_i32_e32 v199, 31, v198
	v_mov_b32_e32 v200, v190
	v_mov_b32_e32 v201, v190
	v_lshlrev_b64 v[198:199], s37, v[198:199]
	v_pk_mul_f32 v[148:149], v[200:201], v[148:149]
	v_pk_mul_f32 v[146:147], v[190:191], v[146:147]
	v_lshl_add_u64 v[198:199], v[192:193], 0, v[198:199]
	v_cvt_pk_bf16_f32 v146, v146, v147
	v_cvt_pk_bf16_f32 v147, v148, v149
	global_store_dwordx2 v[198:199], v[146:147], off offset:32 sc1
	v_pk_mul_f32 v[146:147], v[200:201], v[156:157]
	v_pk_mul_f32 v[148:149], v[190:191], v[154:155]
	v_pk_mul_f32 v[152:153], v[200:201], v[152:153]
	v_cvt_pk_bf16_f32 v148, v148, v149
	v_cvt_pk_bf16_f32 v149, v146, v147
	global_store_dwordx2 v[198:199], v[148:149], off offset:64 sc1
	v_pk_mul_f32 v[146:147], v[200:201], v[160:161]
	v_pk_mul_f32 v[148:149], v[190:191], v[158:159]
	v_pk_mul_f32 v[150:151], v[190:191], v[150:151]
	v_cvt_pk_bf16_f32 v148, v148, v149
	v_cvt_pk_bf16_f32 v149, v146, v147
	v_cvt_pk_bf16_f32 v150, v150, v151
	v_cvt_pk_bf16_f32 v151, v152, v153
	global_store_dwordx2 v[198:199], v[148:149], off offset:96 sc1
	v_pk_mul_f32 v[146:147], v[36:37], v[36:37]
	v_pk_mul_f32 v[148:149], v[34:35], v[34:35]
	global_store_dwordx2 v[198:199], v[150:151], off sc1
	v_pk_mov_b32 v[150:151], v[148:149], v[146:147] op_sel:[1,0]
	v_mov_b32_e32 v149, v147
	v_pk_add_f32 v[146:147], v[150:151], v[148:149]
	v_pk_mul_f32 v[148:149], v[44:45], v[44:45]
	v_pk_add_f32 v[146:147], v[146:147], v[146:147] op_sel_hi:[0,1]
	v_pk_mul_f32 v[150:151], v[42:43], v[42:43]
	v_mul_f32_e32 v146, v46, v46
	v_pk_mov_b32 v[152:153], v[150:151], v[148:149] op_sel:[1,0]
	v_mov_b32_e32 v151, v149
	v_pk_add_f32 v[148:149], v[152:153], v[150:151]
	v_pk_fma_f32 v[150:151], v[46:47], v[46:47], v[146:147] op_sel_hi:[1,1,0]
	v_mul_f32_e32 v146, v48, v48
	v_pk_add_f32 v[148:149], v[148:149], v[148:149] op_sel_hi:[0,1]
	v_pk_fma_f32 v[152:153], v[48:49], v[48:49], v[146:147] op_sel_hi:[1,1,0]
	v_mul_f32_e32 v150, v38, v38
	v_mul_f32_e32 v152, v39, v39
	v_mul_f32_e32 v146, v40, v40
	v_mul_f32_e32 v148, v41, v41
	v_pk_add_f32 v[150:151], v[150:151], v[152:153]
	v_pk_add_f32 v[146:147], v[146:147], v[148:149]
	s_nop 0
	v_pk_add_f32 v[146:147], v[150:151], v[146:147]
	s_nop 0
	v_add_f32_e32 v146, v146, v147
	ds_bpermute_b32 v147, v169, v146
	s_waitcnt lgkmcnt(0)
	v_add_f32_e32 v146, v146, v147
	ds_bpermute_b32 v147, v167, v146
	s_waitcnt lgkmcnt(0)
	v_add_f32_e32 v146, v146, v147
	v_fmamk_f32 v146, v146, 0x3c800000, v229
	v_cmp_gt_f32_e32 vcc, s92, v146
	v_mul_f32_e32 v147, 0x4b800000, v146
	s_nop 0
	v_cndmask_b32_e32 v146, v146, v147, vcc
	v_rsq_f32_e32 v146, v146
	s_nop 0
	v_mul_f32_e32 v147, 0x45800000, v146
	v_cndmask_b32_e32 v158, v146, v147, vcc
	v_pk_mul_f32 v[146:147], v[34:35], v[158:159] op_sel_hi:[1,0]
	v_pk_mul_f32 v[148:149], v[36:37], v[158:159] op_sel_hi:[1,0]
	v_pk_mul_f32 v[150:151], v[142:143], v[146:147]
	v_pk_mul_f32 v[152:153], v[144:145], v[148:149]
	v_pk_mul_f32 v[146:147], v[42:43], v[158:159] op_sel_hi:[1,0]
	v_pk_mul_f32 v[148:149], v[44:45], v[158:159] op_sel_hi:[1,0]
	v_pk_mul_f32 v[154:155], v[46:47], v[158:159] op_sel_hi:[1,0]
	v_pk_mul_f32 v[156:157], v[48:49], v[158:159] op_sel_hi:[1,0]
	v_pk_mul_f32 v[198:199], v[38:39], v[158:159] op_sel_hi:[1,0]
	v_pk_mul_f32 v[158:159], v[40:41], v[158:159] op_sel_hi:[1,0]
	v_pk_mul_f32 v[148:149], v[140:141], v[148:149]
	v_pk_mul_f32 v[146:147], v[138:139], v[146:147]
	v_pk_mul_f32 v[156:157], v[136:137], v[156:157]
	v_pk_mul_f32 v[154:155], v[134:135], v[154:155]
	v_pk_mul_f32 v[160:161], v[132:133], v[158:159]
	v_pk_mul_f32 v[158:159], v[130:131], v[198:199]
	v_or_b32_e32 v198, 32, v186
	s_and_b64 vcc, exec, s[4:5]
	s_cbranch_vccnz .LBB0_299
	v_lshlrev_b32_e32 v173, 9, v198
	v_and_b32_e32 v200, 0x1de00, v173
	v_mov_b32_e32 v201, v0
	v_lshl_add_u64 v[200:201], v[196:197], 0, v[200:201]
	global_store_dwordx4 v[200:201], v[150:153], off nt
	global_store_dwordx4 v[200:201], v[146:149], off offset:64 nt
	global_store_dwordx4 v[200:201], v[154:157], off offset:128 nt
	global_store_dwordx4 v[200:201], v[158:161], off offset:192 nt

.LBB0_301:
	v_ashrrev_i32_e32 v199, 31, v198
	v_mov_b32_e32 v200, v190
	v_mov_b32_e32 v201, v190
	v_lshlrev_b64 v[198:199], s37, v[198:199]
	v_pk_mul_f32 v[148:149], v[200:201], v[148:149]
	v_pk_mul_f32 v[146:147], v[190:191], v[146:147]
	v_lshl_add_u64 v[198:199], v[192:193], 0, v[198:199]
	v_cvt_pk_bf16_f32 v146, v146, v147
	v_cvt_pk_bf16_f32 v147, v148, v149
	global_store_dwordx2 v[198:199], v[146:147], off offset:32 sc1
	v_pk_mul_f32 v[146:147], v[200:201], v[156:157]
	v_pk_mul_f32 v[148:149], v[190:191], v[154:155]
	v_pk_mul_f32 v[152:153], v[200:201], v[152:153]
	v_cvt_pk_bf16_f32 v148, v148, v149
	v_cvt_pk_bf16_f32 v149, v146, v147
	global_store_dwordx2 v[198:199], v[148:149], off offset:64 sc1
	v_pk_mul_f32 v[146:147], v[200:201], v[160:161]
	v_pk_mul_f32 v[148:149], v[190:191], v[158:159]
	v_pk_mul_f32 v[150:151], v[190:191], v[150:151]
	v_cvt_pk_bf16_f32 v148, v148, v149
	v_cvt_pk_bf16_f32 v149, v146, v147
	v_cvt_pk_bf16_f32 v150, v150, v151
	v_cvt_pk_bf16_f32 v151, v152, v153
	global_store_dwordx2 v[198:199], v[148:149], off offset:96 sc1
	v_pk_mul_f32 v[146:147], v[64:65], v[64:65]
	v_pk_mul_f32 v[148:149], v[62:63], v[62:63]
	global_store_dwordx2 v[198:199], v[150:151], off sc1
	v_pk_mov_b32 v[150:151], v[148:149], v[146:147] op_sel:[1,0]
	v_mov_b32_e32 v149, v147
	v_pk_add_f32 v[146:147], v[150:151], v[148:149]
	v_pk_mul_f32 v[148:149], v[60:61], v[60:61]
	v_pk_add_f32 v[146:147], v[146:147], v[146:147] op_sel_hi:[0,1]
	v_pk_mul_f32 v[150:151], v[58:59], v[58:59]
	v_mul_f32_e32 v146, v54, v54
	v_pk_mov_b32 v[152:153], v[150:151], v[148:149] op_sel:[1,0]
	v_mov_b32_e32 v151, v149
	v_pk_add_f32 v[148:149], v[152:153], v[150:151]
	v_pk_fma_f32 v[150:151], v[54:55], v[54:55], v[146:147] op_sel_hi:[1,1,0]
	v_mul_f32_e32 v146, v56, v56
	v_pk_add_f32 v[148:149], v[148:149], v[148:149] op_sel_hi:[0,1]
	v_pk_fma_f32 v[152:153], v[56:57], v[56:57], v[146:147] op_sel_hi:[1,1,0]
	v_mul_f32_e32 v150, v50, v50
	v_mul_f32_e32 v152, v51, v51
	v_mul_f32_e32 v146, v52, v52
	v_mul_f32_e32 v148, v53, v53
	v_pk_add_f32 v[150:151], v[150:151], v[152:153]
	v_pk_add_f32 v[146:147], v[146:147], v[148:149]
	s_nop 0
	v_pk_add_f32 v[146:147], v[150:151], v[146:147]
	s_nop 0
	v_add_f32_e32 v146, v146, v147
	ds_bpermute_b32 v147, v169, v146
	s_waitcnt lgkmcnt(0)
	v_add_f32_e32 v146, v146, v147
	ds_bpermute_b32 v147, v167, v146
	s_waitcnt lgkmcnt(0)
	v_add_f32_e32 v146, v146, v147
	v_fmamk_f32 v146, v146, 0x3c800000, v229
	v_cmp_gt_f32_e32 vcc, s92, v146
	v_mul_f32_e32 v147, 0x4b800000, v146
	s_nop 0
	v_cndmask_b32_e32 v146, v146, v147, vcc
	v_rsq_f32_e32 v146, v146
	s_nop 0
	v_mul_f32_e32 v147, 0x45800000, v146
	v_cndmask_b32_e32 v146, v146, v147, vcc
	v_pk_mul_f32 v[148:149], v[62:63], v[146:147] op_sel_hi:[1,0]
	v_pk_mul_f32 v[150:151], v[64:65], v[146:147] op_sel_hi:[1,0]
	v_pk_mul_f32 v[158:159], v[142:143], v[148:149]
	v_pk_mul_f32 v[160:161], v[144:145], v[150:151]
	v_pk_mul_f32 v[148:149], v[58:59], v[146:147] op_sel_hi:[1,0]
	v_pk_mul_f32 v[150:151], v[60:61], v[146:147] op_sel_hi:[1,0]
	v_pk_mul_f32 v[154:155], v[138:139], v[148:149]
	v_pk_mul_f32 v[156:157], v[140:141], v[150:151]
	v_pk_mul_f32 v[148:149], v[54:55], v[146:147] op_sel_hi:[1,0]
	v_pk_mul_f32 v[150:151], v[56:57], v[146:147] op_sel_hi:[1,0]
	v_pk_mul_f32 v[198:199], v[50:51], v[146:147] op_sel_hi:[1,0]
	v_pk_mul_f32 v[146:147], v[52:53], v[146:147] op_sel_hi:[1,0]
	v_pk_mul_f32 v[152:153], v[136:137], v[150:151]
	v_pk_mul_f32 v[150:151], v[134:135], v[148:149]
	v_pk_mul_f32 v[148:149], v[132:133], v[146:147]
	v_pk_mul_f32 v[146:147], v[130:131], v[198:199]
	v_or_b32_e32 v198, 48, v186
	s_and_b64 vcc, exec, s[4:5]
	s_cbranch_vccnz .LBB0_303
	v_lshlrev_b32_e32 v173, 9, v198
	v_and_b32_e32 v200, 0x1fe00, v173
	v_mov_b32_e32 v201, v0
	v_lshl_add_u64 v[196:197], v[196:197], 0, v[200:201]
	global_store_dwordx4 v[196:197], v[158:161], off nt
	global_store_dwordx4 v[196:197], v[154:157], off offset:64 nt
	global_store_dwordx4 v[196:197], v[150:153], off offset:128 nt
	global_store_dwordx4 v[196:197], v[146:149], off offset:192 nt

.LBB0_305:
	v_ashrrev_i32_e32 v199, 31, v198
	v_lshlrev_b64 v[196:197], s37, v[198:199]
	v_mov_b32_e32 v198, v190
	v_mov_b32_e32 v199, v190
	v_pk_mul_f32 v[152:153], v[198:199], v[152:153]
	v_pk_mul_f32 v[150:151], v[190:191], v[150:151]
	v_lshl_add_u64 v[196:197], v[192:193], 0, v[196:197]
	v_pk_mul_f32 v[156:157], v[198:199], v[156:157]
	v_pk_mul_f32 v[154:155], v[190:191], v[154:155]
	v_cvt_pk_bf16_f32 v150, v150, v151
	v_cvt_pk_bf16_f32 v151, v152, v153
	v_cvt_pk_bf16_f32 v154, v154, v155
	v_cvt_pk_bf16_f32 v155, v156, v157
	global_store_dwordx2 v[196:197], v[150:151], off offset:64 sc1
	v_pk_mul_f32 v[150:151], v[76:77], v[76:77]
	v_pk_mul_f32 v[152:153], v[74:75], v[74:75]
	global_store_dwordx2 v[196:197], v[154:155], off offset:32 sc1
	v_pk_mov_b32 v[154:155], v[152:153], v[150:151] op_sel:[1,0]
	v_mov_b32_e32 v153, v151
	v_pk_add_f32 v[150:151], v[154:155], v[152:153]
	v_pk_mul_f32 v[152:153], v[72:73], v[72:73]
	v_pk_add_f32 v[150:151], v[150:151], v[150:151] op_sel_hi:[0,1]
	v_pk_mul_f32 v[154:155], v[70:71], v[70:71]
	v_mul_f32_e32 v150, v78, v78
	v_pk_mov_b32 v[156:157], v[154:155], v[152:153] op_sel:[1,0]
	v_mov_b32_e32 v155, v153
	v_pk_add_f32 v[152:153], v[156:157], v[154:155]
	v_pk_fma_f32 v[154:155], v[78:79], v[78:79], v[150:151] op_sel_hi:[1,1,0]
	v_mul_f32_e32 v150, v80, v80
	v_pk_add_f32 v[152:153], v[152:153], v[152:153] op_sel_hi:[0,1]
	v_pk_fma_f32 v[156:157], v[80:81], v[80:81], v[150:151] op_sel_hi:[1,1,0]
	v_mul_f32_e32 v154, v66, v66
	v_mul_f32_e32 v156, v67, v67
	v_mul_f32_e32 v150, v68, v68
	v_mul_f32_e32 v152, v69, v69
	v_pk_add_f32 v[154:155], v[154:155], v[156:157]
	v_pk_add_f32 v[150:151], v[150:151], v[152:153]
	v_pk_mul_f32 v[148:149], v[198:199], v[148:149]
	v_pk_add_f32 v[150:151], v[154:155], v[150:151]
	v_pk_mul_f32 v[146:147], v[190:191], v[146:147]
	v_add_f32_e32 v150, v150, v151
	ds_bpermute_b32 v151, v169, v150
	v_cvt_pk_bf16_f32 v146, v146, v147
	v_cvt_pk_bf16_f32 v147, v148, v149
	global_store_dwordx2 v[196:197], v[146:147], off offset:96 sc1
	v_pk_mul_f32 v[160:161], v[198:199], v[160:161]
	s_waitcnt lgkmcnt(0)
	v_add_f32_e32 v148, v150, v151
	ds_bpermute_b32 v149, v167, v148
	v_pk_mul_f32 v[158:159], v[190:191], v[158:159]
	s_waitcnt lgkmcnt(0)
	v_add_f32_e32 v147, v148, v149
	v_fmamk_f32 v147, v147, 0x3c800000, v229
	v_cvt_pk_bf16_f32 v158, v158, v159
	v_cvt_pk_bf16_f32 v159, v160, v161
	v_mul_f32_e32 v148, 0x4b800000, v147
	v_cmp_gt_f32_e32 vcc, s92, v147
	global_store_dwordx2 v[196:197], v[158:159], off sc1
	v_add_u32_e32 v196, 0x80, v186
	v_cndmask_b32_e32 v147, v147, v148, vcc
	v_ashrrev_i32_e32 v146, 7, v196
	v_rsq_f32_e32 v148, v147
	v_and_or_b32 v146, v146, -2, v179
	v_ashrrev_i32_e32 v147, 31, v146
	v_lshlrev_b64 v[146:147], 17, v[146:147]
	v_lshl_add_u64 v[194:195], v[194:195], 0, v[146:147]
	v_mul_f32_e32 v146, 0x45800000, v148
	v_cndmask_b32_e32 v158, v148, v146, vcc
	v_pk_mul_f32 v[146:147], v[74:75], v[158:159] op_sel_hi:[1,0]
	v_pk_mul_f32 v[148:149], v[76:77], v[158:159] op_sel_hi:[1,0]
	v_pk_mul_f32 v[150:151], v[142:143], v[146:147]
	v_pk_mul_f32 v[152:153], v[144:145], v[148:149]
	v_pk_mul_f32 v[146:147], v[70:71], v[158:159] op_sel_hi:[1,0]
	v_pk_mul_f32 v[148:149], v[72:73], v[158:159] op_sel_hi:[1,0]
	v_pk_mul_f32 v[154:155], v[78:79], v[158:159] op_sel_hi:[1,0]
	v_pk_mul_f32 v[156:157], v[80:81], v[158:159] op_sel_hi:[1,0]
	v_pk_mul_f32 v[198:199], v[66:67], v[158:159] op_sel_hi:[1,0]
	v_pk_mul_f32 v[158:159], v[68:69], v[158:159] op_sel_hi:[1,0]
	v_pk_mul_f32 v[148:149], v[140:141], v[148:149]
	v_pk_mul_f32 v[146:147], v[138:139], v[146:147]
	v_pk_mul_f32 v[156:157], v[136:137], v[156:157]
	v_pk_mul_f32 v[154:155], v[134:135], v[154:155]
	v_pk_mul_f32 v[160:161], v[132:133], v[158:159]
	s_and_b64 vcc, exec, s[4:5]
	v_pk_mul_f32 v[158:159], v[130:131], v[198:199]
	s_cbranch_vccnz .LBB0_307
	v_lshlrev_b32_e32 v173, 9, v196
	v_and_b32_e32 v198, 0x19e00, v173
	v_mov_b32_e32 v199, v0
	v_lshl_add_u64 v[198:199], v[194:195], 0, v[198:199]
	global_store_dwordx4 v[198:199], v[150:153], off nt
	global_store_dwordx4 v[198:199], v[146:149], off offset:64 nt
	global_store_dwordx4 v[198:199], v[154:157], off offset:128 nt
	global_store_dwordx4 v[198:199], v[158:161], off offset:192 nt

.LBB0_309:
	v_ashrrev_i32_e32 v197, 31, v196
	v_mov_b32_e32 v198, v190
	v_mov_b32_e32 v199, v190
	v_lshlrev_b64 v[196:197], s37, v[196:197]
	v_pk_mul_f32 v[148:149], v[198:199], v[148:149]
	v_pk_mul_f32 v[146:147], v[190:191], v[146:147]
	v_lshl_add_u64 v[196:197], v[192:193], 0, v[196:197]
	v_cvt_pk_bf16_f32 v146, v146, v147
	v_cvt_pk_bf16_f32 v147, v148, v149
	global_store_dwordx2 v[196:197], v[146:147], off offset:32 sc1
	v_pk_mul_f32 v[146:147], v[198:199], v[156:157]
	v_pk_mul_f32 v[148:149], v[190:191], v[154:155]
	v_pk_mul_f32 v[152:153], v[198:199], v[152:153]
	v_cvt_pk_bf16_f32 v148, v148, v149
	v_cvt_pk_bf16_f32 v149, v146, v147
	global_store_dwordx2 v[196:197], v[148:149], off offset:64 sc1
	v_pk_mul_f32 v[146:147], v[198:199], v[160:161]
	v_pk_mul_f32 v[148:149], v[190:191], v[158:159]
	v_pk_mul_f32 v[150:151], v[190:191], v[150:151]
	v_cvt_pk_bf16_f32 v148, v148, v149
	v_cvt_pk_bf16_f32 v149, v146, v147
	v_cvt_pk_bf16_f32 v150, v150, v151
	v_cvt_pk_bf16_f32 v151, v152, v153
	global_store_dwordx2 v[196:197], v[148:149], off offset:96 sc1
	v_pk_mul_f32 v[146:147], v[96:97], v[96:97]
	v_pk_mul_f32 v[148:149], v[94:95], v[94:95]
	global_store_dwordx2 v[196:197], v[150:151], off sc1
	v_pk_mov_b32 v[150:151], v[148:149], v[146:147] op_sel:[1,0]
	v_mov_b32_e32 v149, v147
	v_pk_add_f32 v[146:147], v[150:151], v[148:149]
	v_pk_mul_f32 v[148:149], v[92:93], v[92:93]
	v_pk_add_f32 v[146:147], v[146:147], v[146:147] op_sel_hi:[0,1]
	v_pk_mul_f32 v[150:151], v[90:91], v[90:91]
	v_mul_f32_e32 v146, v86, v86
	v_pk_mov_b32 v[152:153], v[150:151], v[148:149] op_sel:[1,0]
	v_mov_b32_e32 v151, v149
	v_pk_add_f32 v[148:149], v[152:153], v[150:151]
	v_pk_fma_f32 v[150:151], v[86:87], v[86:87], v[146:147] op_sel_hi:[1,1,0]
	v_mul_f32_e32 v146, v88, v88
	v_pk_add_f32 v[148:149], v[148:149], v[148:149] op_sel_hi:[0,1]
	v_pk_fma_f32 v[152:153], v[88:89], v[88:89], v[146:147] op_sel_hi:[1,1,0]
	v_mul_f32_e32 v150, v82, v82
	v_mul_f32_e32 v152, v83, v83
	v_mul_f32_e32 v146, v84, v84
	v_mul_f32_e32 v148, v85, v85
	v_pk_add_f32 v[150:151], v[150:151], v[152:153]
	v_pk_add_f32 v[146:147], v[146:147], v[148:149]
	s_nop 0
	v_pk_add_f32 v[146:147], v[150:151], v[146:147]
	s_nop 0
	v_add_f32_e32 v146, v146, v147
	ds_bpermute_b32 v147, v169, v146
	s_waitcnt lgkmcnt(0)
	v_add_f32_e32 v146, v146, v147
	ds_bpermute_b32 v147, v167, v146
	s_waitcnt lgkmcnt(0)
	v_add_f32_e32 v146, v146, v147
	v_fmamk_f32 v146, v146, 0x3c800000, v229
	v_cmp_gt_f32_e32 vcc, s92, v146
	v_mul_f32_e32 v147, 0x4b800000, v146
	s_nop 0
	v_cndmask_b32_e32 v146, v146, v147, vcc
	v_rsq_f32_e32 v146, v146
	s_nop 0
	v_mul_f32_e32 v147, 0x45800000, v146
	v_cndmask_b32_e32 v158, v146, v147, vcc
	v_pk_mul_f32 v[146:147], v[94:95], v[158:159] op_sel_hi:[1,0]
	v_pk_mul_f32 v[148:149], v[96:97], v[158:159] op_sel_hi:[1,0]
	v_pk_mul_f32 v[150:151], v[142:143], v[146:147]
	v_pk_mul_f32 v[152:153], v[144:145], v[148:149]
	v_pk_mul_f32 v[146:147], v[90:91], v[158:159] op_sel_hi:[1,0]
	v_pk_mul_f32 v[148:149], v[92:93], v[158:159] op_sel_hi:[1,0]
	v_pk_mul_f32 v[154:155], v[86:87], v[158:159] op_sel_hi:[1,0]
	v_pk_mul_f32 v[156:157], v[88:89], v[158:159] op_sel_hi:[1,0]
	v_pk_mul_f32 v[196:197], v[82:83], v[158:159] op_sel_hi:[1,0]
	v_pk_mul_f32 v[158:159], v[84:85], v[158:159] op_sel_hi:[1,0]
	v_pk_mul_f32 v[148:149], v[140:141], v[148:149]
	v_pk_mul_f32 v[146:147], v[138:139], v[146:147]
	v_pk_mul_f32 v[156:157], v[136:137], v[156:157]
	v_pk_mul_f32 v[154:155], v[134:135], v[154:155]
	v_pk_mul_f32 v[160:161], v[132:133], v[158:159]
	v_pk_mul_f32 v[158:159], v[130:131], v[196:197]
	v_add_u32_e32 v196, 0x90, v186
	s_and_b64 vcc, exec, s[4:5]
	s_cbranch_vccnz .LBB0_311
	v_lshlrev_b32_e32 v171, 9, v196
	v_and_b32_e32 v198, 0x1be00, v171
	v_mov_b32_e32 v199, v0
	v_lshl_add_u64 v[198:199], v[194:195], 0, v[198:199]
	global_store_dwordx4 v[198:199], v[150:153], off nt
	global_store_dwordx4 v[198:199], v[146:149], off offset:64 nt
	global_store_dwordx4 v[198:199], v[154:157], off offset:128 nt
	global_store_dwordx4 v[198:199], v[158:161], off offset:192 nt

.LBB0_313:
	v_ashrrev_i32_e32 v197, 31, v196
	v_mov_b32_e32 v198, v190
	v_mov_b32_e32 v199, v190
	v_lshlrev_b64 v[196:197], s37, v[196:197]
	v_pk_mul_f32 v[148:149], v[198:199], v[148:149]
	v_pk_mul_f32 v[146:147], v[190:191], v[146:147]
	v_lshl_add_u64 v[196:197], v[192:193], 0, v[196:197]
	v_cvt_pk_bf16_f32 v146, v146, v147
	v_cvt_pk_bf16_f32 v147, v148, v149
	global_store_dwordx2 v[196:197], v[146:147], off offset:32 sc1
	v_pk_mul_f32 v[146:147], v[198:199], v[156:157]
	v_pk_mul_f32 v[148:149], v[190:191], v[154:155]
	v_pk_mul_f32 v[152:153], v[198:199], v[152:153]
	v_cvt_pk_bf16_f32 v148, v148, v149
	v_cvt_pk_bf16_f32 v149, v146, v147
	global_store_dwordx2 v[196:197], v[148:149], off offset:64 sc1
	v_pk_mul_f32 v[146:147], v[198:199], v[160:161]
	v_pk_mul_f32 v[148:149], v[190:191], v[158:159]
	v_pk_mul_f32 v[150:151], v[190:191], v[150:151]
	v_cvt_pk_bf16_f32 v148, v148, v149
	v_cvt_pk_bf16_f32 v149, v146, v147
	v_cvt_pk_bf16_f32 v150, v150, v151
	v_cvt_pk_bf16_f32 v151, v152, v153
	global_store_dwordx2 v[196:197], v[148:149], off offset:96 sc1
	v_pk_mul_f32 v[146:147], v[108:109], v[108:109]
	v_pk_mul_f32 v[148:149], v[106:107], v[106:107]
	global_store_dwordx2 v[196:197], v[150:151], off sc1
	v_pk_mov_b32 v[150:151], v[148:149], v[146:147] op_sel:[1,0]
	v_mov_b32_e32 v149, v147
	v_pk_add_f32 v[146:147], v[150:151], v[148:149]
	v_pk_mul_f32 v[148:149], v[104:105], v[104:105]
	v_pk_add_f32 v[146:147], v[146:147], v[146:147] op_sel_hi:[0,1]
	v_pk_mul_f32 v[150:151], v[102:103], v[102:103]
	v_mul_f32_e32 v146, v110, v110
	v_pk_mov_b32 v[152:153], v[150:151], v[148:149] op_sel:[1,0]
	v_mov_b32_e32 v151, v149
	v_pk_add_f32 v[148:149], v[152:153], v[150:151]
	v_pk_fma_f32 v[150:151], v[110:111], v[110:111], v[146:147] op_sel_hi:[1,1,0]
	v_mul_f32_e32 v146, v112, v112
	v_pk_add_f32 v[148:149], v[148:149], v[148:149] op_sel_hi:[0,1]
	v_pk_fma_f32 v[152:153], v[112:113], v[112:113], v[146:147] op_sel_hi:[1,1,0]
	v_mul_f32_e32 v150, v98, v98
	v_mul_f32_e32 v152, v99, v99
	v_mul_f32_e32 v146, v100, v100
	v_mul_f32_e32 v148, v101, v101
	v_pk_add_f32 v[150:151], v[150:151], v[152:153]
	v_pk_add_f32 v[146:147], v[146:147], v[148:149]
	s_nop 0
	v_pk_add_f32 v[146:147], v[150:151], v[146:147]
	s_nop 0
	v_add_f32_e32 v146, v146, v147
	ds_bpermute_b32 v147, v169, v146
	s_waitcnt lgkmcnt(0)
	v_add_f32_e32 v146, v146, v147
	ds_bpermute_b32 v147, v167, v146
	s_waitcnt lgkmcnt(0)
	v_add_f32_e32 v146, v146, v147
	v_fmamk_f32 v146, v146, 0x3c800000, v229
	v_cmp_gt_f32_e32 vcc, s92, v146
	v_mul_f32_e32 v147, 0x4b800000, v146
	s_nop 0
	v_cndmask_b32_e32 v146, v146, v147, vcc
	v_rsq_f32_e32 v146, v146
	s_nop 0
	v_mul_f32_e32 v147, 0x45800000, v146
	v_cndmask_b32_e32 v158, v146, v147, vcc
	v_pk_mul_f32 v[146:147], v[106:107], v[158:159] op_sel_hi:[1,0]
	v_pk_mul_f32 v[148:149], v[108:109], v[158:159] op_sel_hi:[1,0]
	v_pk_mul_f32 v[150:151], v[142:143], v[146:147]
	v_pk_mul_f32 v[152:153], v[144:145], v[148:149]
	v_pk_mul_f32 v[146:147], v[102:103], v[158:159] op_sel_hi:[1,0]
	v_pk_mul_f32 v[148:149], v[104:105], v[158:159] op_sel_hi:[1,0]
	v_pk_mul_f32 v[154:155], v[110:111], v[158:159] op_sel_hi:[1,0]
	v_pk_mul_f32 v[156:157], v[112:113], v[158:159] op_sel_hi:[1,0]
	v_pk_mul_f32 v[196:197], v[98:99], v[158:159] op_sel_hi:[1,0]
	v_pk_mul_f32 v[158:159], v[100:101], v[158:159] op_sel_hi:[1,0]
	v_pk_mul_f32 v[148:149], v[140:141], v[148:149]
	v_pk_mul_f32 v[146:147], v[138:139], v[146:147]
	v_pk_mul_f32 v[156:157], v[136:137], v[156:157]
	v_pk_mul_f32 v[154:155], v[134:135], v[154:155]
	v_pk_mul_f32 v[160:161], v[132:133], v[158:159]
	v_pk_mul_f32 v[158:159], v[130:131], v[196:197]
	v_add_u32_e32 v196, 0xa0, v186
	s_and_b64 vcc, exec, s[4:5]
	s_cbranch_vccnz .LBB0_315
	v_lshlrev_b32_e32 v171, 9, v196
	v_and_b32_e32 v198, 0x1de00, v171
	v_mov_b32_e32 v199, v0
	v_lshl_add_u64 v[198:199], v[194:195], 0, v[198:199]
	global_store_dwordx4 v[198:199], v[150:153], off nt
	global_store_dwordx4 v[198:199], v[146:149], off offset:64 nt
	global_store_dwordx4 v[198:199], v[154:157], off offset:128 nt
	global_store_dwordx4 v[198:199], v[158:161], off offset:192 nt

.LBB0_317:
	v_ashrrev_i32_e32 v197, 31, v196
	v_mov_b32_e32 v198, v190
	v_mov_b32_e32 v199, v190
	v_lshlrev_b64 v[196:197], s37, v[196:197]
	v_pk_mul_f32 v[148:149], v[198:199], v[148:149]
	v_pk_mul_f32 v[146:147], v[190:191], v[146:147]
	v_lshl_add_u64 v[196:197], v[192:193], 0, v[196:197]
	v_cvt_pk_bf16_f32 v146, v146, v147
	v_cvt_pk_bf16_f32 v147, v148, v149
	global_store_dwordx2 v[196:197], v[146:147], off offset:32 sc1
	v_pk_mul_f32 v[146:147], v[198:199], v[156:157]
	v_pk_mul_f32 v[148:149], v[190:191], v[154:155]
	v_pk_mul_f32 v[152:153], v[198:199], v[152:153]
	v_cvt_pk_bf16_f32 v148, v148, v149
	v_cvt_pk_bf16_f32 v149, v146, v147
	global_store_dwordx2 v[196:197], v[148:149], off offset:64 sc1
	v_pk_mul_f32 v[146:147], v[198:199], v[160:161]
	v_pk_mul_f32 v[148:149], v[190:191], v[158:159]
	v_pk_mul_f32 v[150:151], v[190:191], v[150:151]
	v_cvt_pk_bf16_f32 v148, v148, v149
	v_cvt_pk_bf16_f32 v149, v146, v147
	v_cvt_pk_bf16_f32 v150, v150, v151
	v_cvt_pk_bf16_f32 v151, v152, v153
	global_store_dwordx2 v[196:197], v[148:149], off offset:96 sc1
	v_pk_mul_f32 v[146:147], v[120:121], v[120:121]
	v_pk_mul_f32 v[148:149], v[118:119], v[118:119]
	global_store_dwordx2 v[196:197], v[150:151], off sc1
	v_pk_mov_b32 v[150:151], v[148:149], v[146:147] op_sel:[1,0]
	v_mov_b32_e32 v149, v147
	v_pk_add_f32 v[146:147], v[150:151], v[148:149]
	v_pk_mul_f32 v[148:149], v[116:117], v[116:117]
	v_pk_add_f32 v[146:147], v[146:147], v[146:147] op_sel_hi:[0,1]
	v_pk_mul_f32 v[150:151], v[114:115], v[114:115]
	v_mul_f32_e32 v146, v122, v122
	v_pk_mov_b32 v[152:153], v[150:151], v[148:149] op_sel:[1,0]
	v_mov_b32_e32 v151, v149
	v_pk_add_f32 v[148:149], v[152:153], v[150:151]
	v_pk_fma_f32 v[150:151], v[122:123], v[122:123], v[146:147] op_sel_hi:[1,1,0]
	v_mul_f32_e32 v146, v124, v124
	v_pk_add_f32 v[148:149], v[148:149], v[148:149] op_sel_hi:[0,1]
	v_pk_fma_f32 v[152:153], v[124:125], v[124:125], v[146:147] op_sel_hi:[1,1,0]
	v_mul_f32_e32 v150, v126, v126
	v_mul_f32_e32 v152, v127, v127
	v_mul_f32_e32 v146, v128, v128
	v_mul_f32_e32 v148, v129, v129
	v_pk_add_f32 v[150:151], v[150:151], v[152:153]
	v_pk_add_f32 v[146:147], v[146:147], v[148:149]
	s_nop 0
	v_pk_add_f32 v[146:147], v[150:151], v[146:147]
	s_nop 0
	v_add_f32_e32 v146, v146, v147
	ds_bpermute_b32 v147, v169, v146
	s_waitcnt lgkmcnt(0)
	v_add_f32_e32 v146, v146, v147
	ds_bpermute_b32 v147, v167, v146
	s_waitcnt lgkmcnt(0)
	v_add_f32_e32 v146, v146, v147
	v_fmamk_f32 v146, v146, 0x3c800000, v229
	v_cmp_gt_f32_e32 vcc, s92, v146
	v_mul_f32_e32 v147, 0x4b800000, v146
	s_nop 0
	v_cndmask_b32_e32 v146, v146, v147, vcc
	v_rsq_f32_e32 v146, v146
	s_nop 0
	v_mul_f32_e32 v147, 0x45800000, v146
	v_cndmask_b32_e32 v146, v146, v147, vcc
	v_pk_mul_f32 v[148:149], v[118:119], v[146:147] op_sel_hi:[1,0]
	v_pk_mul_f32 v[150:151], v[120:121], v[146:147] op_sel_hi:[1,0]
	v_pk_mul_f32 v[142:143], v[142:143], v[148:149]
	v_pk_mul_f32 v[148:149], v[114:115], v[146:147] op_sel_hi:[1,0]
	v_pk_mul_f32 v[144:145], v[144:145], v[150:151]
	v_pk_mul_f32 v[150:151], v[116:117], v[146:147] op_sel_hi:[1,0]
	v_pk_mul_f32 v[138:139], v[138:139], v[148:149]
	v_pk_mul_f32 v[148:149], v[122:123], v[146:147] op_sel_hi:[1,0]
	v_pk_mul_f32 v[140:141], v[140:141], v[150:151]
	v_pk_mul_f32 v[150:151], v[124:125], v[146:147] op_sel_hi:[1,0]
	v_pk_mul_f32 v[134:135], v[134:135], v[148:149]
	v_pk_mul_f32 v[148:149], v[126:127], v[146:147] op_sel_hi:[1,0]
	v_pk_mul_f32 v[146:147], v[128:129], v[146:147] op_sel_hi:[1,0]
	v_pk_mul_f32 v[136:137], v[136:137], v[150:151]
	v_pk_mul_f32 v[132:133], v[132:133], v[146:147]
	v_pk_mul_f32 v[130:131], v[130:131], v[148:149]
	v_add_u32_e32 v146, 0xb0, v186
	s_and_b64 vcc, exec, s[4:5]
	s_cbranch_vccnz .LBB0_319
	v_lshlrev_b32_e32 v147, 9, v146
	v_and_b32_e32 v148, 0x1fe00, v147
	v_mov_b32_e32 v149, v0
	v_lshl_add_u64 v[148:149], v[194:195], 0, v[148:149]
	global_store_dwordx4 v[148:149], v[142:145], off nt
	global_store_dwordx4 v[148:149], v[138:141], off offset:64 nt
	global_store_dwordx4 v[148:149], v[134:137], off offset:128 nt
	global_store_dwordx4 v[148:149], v[130:133], off offset:192 nt

.LBB0_321:
	v_ashrrev_i32_e32 v147, 31, v146
	v_mov_b32_e32 v148, v190
	v_mov_b32_e32 v149, v190
	v_lshlrev_b64 v[146:147], s37, v[146:147]
	v_pk_mul_f32 v[144:145], v[148:149], v[144:145]
	v_pk_mul_f32 v[142:143], v[190:191], v[142:143]
	v_pk_mul_f32 v[140:141], v[148:149], v[140:141]
	v_pk_mul_f32 v[138:139], v[190:191], v[138:139]
	v_pk_mul_f32 v[136:137], v[148:149], v[136:137]
	v_pk_mul_f32 v[134:135], v[190:191], v[134:135]
	v_pk_mul_f32 v[132:133], v[148:149], v[132:133]
	v_pk_mul_f32 v[130:131], v[190:191], v[130:131]
	v_lshl_add_u64 v[146:147], v[192:193], 0, v[146:147]
	v_cvt_pk_bf16_f32 v142, v142, v143
	v_cvt_pk_bf16_f32 v143, v144, v145
	v_cvt_pk_bf16_f32 v138, v138, v139
	v_cvt_pk_bf16_f32 v139, v140, v141
	v_cvt_pk_bf16_f32 v134, v134, v135
	v_cvt_pk_bf16_f32 v135, v136, v137
	v_cvt_pk_bf16_f32 v130, v130, v131
	v_cvt_pk_bf16_f32 v131, v132, v133
	global_store_dwordx2 v[146:147], v[142:143], off sc1
	global_store_dwordx2 v[146:147], v[138:139], off offset:32 sc1
	global_store_dwordx2 v[146:147], v[134:135], off offset:64 sc1
	global_store_dwordx2 v[146:147], v[130:131], off offset:96 sc1
	s_mov_b64 s[6:7], 0
.LBB0_322:
	s_and_b64 vcc, exec, s[6:7]
	s_cbranch_vccz .LBB0_387
	s_lshl_b64 s[4:5], s[52:53], 1
	s_add_u32 s4, s21, s4
	s_addc_u32 s5, s20, s5
	v_lshlrev_b32_e32 v130, 1, v178
	v_mov_b32_e32 v131, v0
	v_lshl_add_u64 v[130:131], s[4:5], 0, v[130:131]
	s_mov_b64 s[4:5], 0xb600000
	v_lshl_add_u64 v[130:131], v[130:131], 0, s[4:5]
	s_lshl_b64 s[4:5], s[52:53], 2
	v_ashrrev_i32_e32 v187, 31, v186
	s_add_u32 s6, s36, s4
	v_lshlrev_b64 v[132:133], 8, v[186:187]
	s_addc_u32 s7, s59, s5
	v_lshl_add_u64 v[136:137], v[130:131], 0, v[132:133]
	v_cvt_pk_bf16_f32 v132, v2, v3
	v_cvt_pk_bf16_f32 v133, v4, v5
	s_mov_b64 s[4:5], -1
	s_and_b64 vcc, exec, s[68:69]
	global_store_dwordx2 v[136:137], v[132:133], off sc1
	s_cbranch_vccz .LBB0_325
	v_cvt_pk_bf16_f32 v132, v6, v7
	v_cvt_pk_bf16_f32 v133, v8, v9
	global_store_dwordx2 v[136:137], v[132:133], off offset:32 sc1
	s_mov_b64 s[4:5], 0
.LBB0_325:
	s_ashr_i32 s3, s57, 7
	s_and_b32 s3, s3, -2
	v_mov_b32_e32 v189, v0
	v_or_b32_e32 v134, s3, v179
	v_lshl_add_u64 v[132:133], s[6:7], 0, v[188:189]
	s_mov_b64 s[6:7], 0x6800000
	v_ashrrev_i32_e32 v135, 31, v134
	v_lshl_add_u64 v[132:133], v[132:133], 0, s[6:7]
	v_lshlrev_b64 v[134:135], 17, v[134:135]
	v_lshlrev_b32_e32 v138, 9, v186
	v_lshl_add_u64 v[134:135], v[132:133], 0, v[134:135]
	v_and_b32_e32 v138, 0x19e00, v138
	v_mov_b32_e32 v139, v0
	s_andn2_b64 vcc, exec, s[4:5]
	v_lshl_add_u64 v[138:139], v[134:135], 0, v[138:139]
	s_cbranch_vccnz .LBB0_327
	v_cvt_pk_bf16_f32 v140, v6, v7
	v_cvt_pk_bf16_f32 v141, v8, v9
	global_store_dwordx4 v[138:139], v[2:5], off nt
	global_store_dwordx2 v[136:137], v[140:141], off offset:32 sc1
	global_store_dwordx4 v[138:139], v[6:9], off offset:64 nt
.LBB0_327:
	v_cvt_pk_bf16_f32 v140, v14, v15
	v_cvt_pk_bf16_f32 v141, v16, v17
	s_mov_b64 s[4:5], -1
	s_and_b64 vcc, exec, s[68:69]
	global_store_dwordx2 v[136:137], v[140:141], off offset:64 sc1
	s_cbranch_vccz .LBB0_329
	v_cvt_pk_bf16_f32 v140, v10, v11
	v_cvt_pk_bf16_f32 v141, v12, v13
	global_store_dwordx2 v[136:137], v[140:141], off offset:96 sc1
	s_mov_b64 s[4:5], 0
.LBB0_329:
	s_andn2_b64 vcc, exec, s[4:5]
	s_cbranch_vccnz .LBB0_331
	v_cvt_pk_bf16_f32 v140, v10, v11
	v_cvt_pk_bf16_f32 v141, v12, v13
	global_store_dwordx4 v[138:139], v[14:17], off offset:128 nt
	global_store_dwordx2 v[136:137], v[140:141], off offset:96 sc1
	global_store_dwordx4 v[138:139], v[10:13], off offset:192 nt
.LBB0_331:
	v_or_b32_e32 v138, 16, v186
	v_ashrrev_i32_e32 v139, 31, v138
	v_lshlrev_b64 v[136:137], 8, v[138:139]
	v_lshl_add_u64 v[136:137], v[130:131], 0, v[136:137]
	v_cvt_pk_bf16_f32 v140, v30, v31
	v_cvt_pk_bf16_f32 v141, v32, v33
	s_mov_b64 s[4:5], -1
	s_and_b64 vcc, exec, s[68:69]
	global_store_dwordx2 v[136:137], v[140:141], off sc1
	s_cbranch_vccz .LBB0_333
	v_cvt_pk_bf16_f32 v140, v26, v27
	v_cvt_pk_bf16_f32 v141, v28, v29
	global_store_dwordx2 v[136:137], v[140:141], off offset:32 sc1
	s_mov_b64 s[4:5], 0
.LBB0_333:
	v_lshlrev_b32_e32 v138, 9, v138
	v_and_b32_e32 v138, 0x1be00, v138
	v_mov_b32_e32 v139, v0
	s_andn2_b64 vcc, exec, s[4:5]
	v_lshl_add_u64 v[138:139], v[134:135], 0, v[138:139]
	s_cbranch_vccnz .LBB0_335
	v_cvt_pk_bf16_f32 v140, v26, v27
	v_cvt_pk_bf16_f32 v141, v28, v29
	global_store_dwordx4 v[138:139], v[30:33], off nt
	global_store_dwordx2 v[136:137], v[140:141], off offset:32 sc1
	global_store_dwordx4 v[138:139], v[26:29], off offset:64 nt
.LBB0_335:
	v_cvt_pk_bf16_f32 v140, v22, v23
	v_cvt_pk_bf16_f32 v141, v24, v25
	s_mov_b64 s[4:5], -1
	s_and_b64 vcc, exec, s[68:69]
	global_store_dwordx2 v[136:137], v[140:141], off offset:64 sc1
	s_cbranch_vccz .LBB0_337
	v_cvt_pk_bf16_f32 v140, v18, v19
	v_cvt_pk_bf16_f32 v141, v20, v21
	global_store_dwordx2 v[136:137], v[140:141], off offset:96 sc1
	s_mov_b64 s[4:5], 0
.LBB0_337:
	s_andn2_b64 vcc, exec, s[4:5]
	s_cbranch_vccnz .LBB0_339
	v_cvt_pk_bf16_f32 v140, v18, v19
	v_cvt_pk_bf16_f32 v141, v20, v21
	global_store_dwordx4 v[138:139], v[22:25], off offset:128 nt
	global_store_dwordx2 v[136:137], v[140:141], off offset:96 sc1
	global_store_dwordx4 v[138:139], v[18:21], off offset:192 nt
.LBB0_339:
	v_or_b32_e32 v138, 32, v186
	v_ashrrev_i32_e32 v139, 31, v138
	v_lshlrev_b64 v[136:137], 8, v[138:139]
	v_lshl_add_u64 v[136:137], v[130:131], 0, v[136:137]
	v_cvt_pk_bf16_f32 v140, v34, v35
	v_cvt_pk_bf16_f32 v141, v36, v37
	s_mov_b64 s[4:5], -1
	s_and_b64 vcc, exec, s[68:69]
	global_store_dwordx2 v[136:137], v[140:141], off sc1
	s_cbranch_vccz .LBB0_341
	v_cvt_pk_bf16_f32 v140, v42, v43
	v_cvt_pk_bf16_f32 v141, v44, v45
	global_store_dwordx2 v[136:137], v[140:141], off offset:32 sc1
	s_mov_b64 s[4:5], 0
.LBB0_341:
	v_lshlrev_b32_e32 v138, 9, v138
	v_and_b32_e32 v138, 0x1de00, v138
	v_mov_b32_e32 v139, v0
	s_andn2_b64 vcc, exec, s[4:5]
	v_lshl_add_u64 v[138:139], v[134:135], 0, v[138:139]
	s_cbranch_vccnz .LBB0_343
	v_cvt_pk_bf16_f32 v140, v42, v43
	v_cvt_pk_bf16_f32 v141, v44, v45
	global_store_dwordx4 v[138:139], v[34:37], off nt
	global_store_dwordx2 v[136:137], v[140:141], off offset:32 sc1
	global_store_dwordx4 v[138:139], v[42:45], off offset:64 nt
.LBB0_343:
	v_cvt_pk_bf16_f32 v140, v46, v47
	v_cvt_pk_bf16_f32 v141, v48, v49
	s_mov_b64 s[4:5], -1
	s_and_b64 vcc, exec, s[68:69]
	global_store_dwordx2 v[136:137], v[140:141], off offset:64 sc1
	s_cbranch_vccz .LBB0_345
	v_cvt_pk_bf16_f32 v140, v38, v39
	v_cvt_pk_bf16_f32 v141, v40, v41
	global_store_dwordx2 v[136:137], v[140:141], off offset:96 sc1
	s_mov_b64 s[4:5], 0
.LBB0_345:
	s_andn2_b64 vcc, exec, s[4:5]
	s_cbranch_vccnz .LBB0_347
	v_cvt_pk_bf16_f32 v140, v38, v39
	v_cvt_pk_bf16_f32 v141, v40, v41
	global_store_dwordx4 v[138:139], v[46:49], off offset:128 nt
	global_store_dwordx2 v[136:137], v[140:141], off offset:96 sc1
	global_store_dwordx4 v[138:139], v[38:41], off offset:192 nt
.LBB0_347:
	v_or_b32_e32 v138, 48, v186
	v_ashrrev_i32_e32 v139, 31, v138
	v_lshlrev_b64 v[136:137], 8, v[138:139]
	v_lshl_add_u64 v[136:137], v[130:131], 0, v[136:137]
	v_cvt_pk_bf16_f32 v140, v62, v63
	v_cvt_pk_bf16_f32 v141, v64, v65
	s_mov_b64 s[4:5], -1
	s_and_b64 vcc, exec, s[68:69]
	global_store_dwordx2 v[136:137], v[140:141], off sc1
	s_cbranch_vccz .LBB0_349
	v_cvt_pk_bf16_f32 v140, v58, v59
	v_cvt_pk_bf16_f32 v141, v60, v61
	global_store_dwordx2 v[136:137], v[140:141], off offset:32 sc1
	s_mov_b64 s[4:5], 0
.LBB0_349:
	v_lshlrev_b32_e32 v138, 9, v138
	v_and_b32_e32 v138, 0x1fe00, v138
	v_mov_b32_e32 v139, v0
	s_andn2_b64 vcc, exec, s[4:5]
	v_lshl_add_u64 v[134:135], v[134:135], 0, v[138:139]
	s_cbranch_vccnz .LBB0_351
	v_cvt_pk_bf16_f32 v138, v58, v59
	v_cvt_pk_bf16_f32 v139, v60, v61
	global_store_dwordx4 v[134:135], v[62:65], off nt
	global_store_dwordx2 v[136:137], v[138:139], off offset:32 sc1
	global_store_dwordx4 v[134:135], v[58:61], off offset:64 nt
.LBB0_351:
	v_cvt_pk_bf16_f32 v138, v54, v55
	v_cvt_pk_bf16_f32 v139, v56, v57
	s_mov_b64 s[4:5], -1
	s_and_b64 vcc, exec, s[68:69]
	global_store_dwordx2 v[136:137], v[138:139], off offset:64 sc1
	s_cbranch_vccz .LBB0_353
	v_cvt_pk_bf16_f32 v138, v50, v51
	v_cvt_pk_bf16_f32 v139, v52, v53
	global_store_dwordx2 v[136:137], v[138:139], off offset:96 sc1
	s_mov_b64 s[4:5], 0
.LBB0_353:
	s_andn2_b64 vcc, exec, s[4:5]
	s_cbranch_vccnz .LBB0_355
	v_cvt_pk_bf16_f32 v138, v50, v51
	v_cvt_pk_bf16_f32 v139, v52, v53
	global_store_dwordx4 v[134:135], v[54:57], off offset:128 nt
	global_store_dwordx2 v[136:137], v[138:139], off offset:96 sc1
	global_store_dwordx4 v[134:135], v[50:53], off offset:192 nt
.LBB0_355:
	v_add_u32_e32 v136, 0x80, v186
	v_ashrrev_i32_e32 v137, 31, v136
	v_lshlrev_b64 v[134:135], 8, v[136:137]
	v_lshl_add_u64 v[134:135], v[130:131], 0, v[134:135]
	v_cvt_pk_bf16_f32 v138, v74, v75
	v_cvt_pk_bf16_f32 v139, v76, v77
	s_mov_b64 s[4:5], -1
	s_and_b64 vcc, exec, s[68:69]
	global_store_dwordx2 v[134:135], v[138:139], off sc1
	s_cbranch_vccz .LBB0_357
	v_cvt_pk_bf16_f32 v138, v70, v71
	v_cvt_pk_bf16_f32 v139, v72, v73
	global_store_dwordx2 v[134:135], v[138:139], off offset:32 sc1
	s_mov_b64 s[4:5], 0
.LBB0_357:
	v_ashrrev_i32_e32 v137, 7, v136
	v_and_or_b32 v138, v137, -2, v179
	v_ashrrev_i32_e32 v139, 31, v138
	v_lshlrev_b64 v[138:139], 17, v[138:139]
	v_lshlrev_b32_e32 v136, 9, v136
	v_lshl_add_u64 v[132:133], v[132:133], 0, v[138:139]
	v_and_b32_e32 v136, 0x19e00, v136
	v_mov_b32_e32 v137, v0
	s_andn2_b64 vcc, exec, s[4:5]
	v_lshl_add_u64 v[136:137], v[132:133], 0, v[136:137]
	s_cbranch_vccnz .LBB0_359
	v_cvt_pk_bf16_f32 v138, v70, v71
	v_cvt_pk_bf16_f32 v139, v72, v73
	global_store_dwordx4 v[136:137], v[74:77], off nt
	global_store_dwordx2 v[134:135], v[138:139], off offset:32 sc1
	global_store_dwordx4 v[136:137], v[70:73], off offset:64 nt
.LBB0_359:
	v_cvt_pk_bf16_f32 v138, v78, v79
	v_cvt_pk_bf16_f32 v139, v80, v81
	s_mov_b64 s[4:5], -1
	s_and_b64 vcc, exec, s[68:69]
	global_store_dwordx2 v[134:135], v[138:139], off offset:64 sc1
	s_cbranch_vccz .LBB0_361
	v_cvt_pk_bf16_f32 v138, v66, v67
	v_cvt_pk_bf16_f32 v139, v68, v69
	global_store_dwordx2 v[134:135], v[138:139], off offset:96 sc1
	s_mov_b64 s[4:5], 0
.LBB0_361:
	s_andn2_b64 vcc, exec, s[4:5]
	s_cbranch_vccnz .LBB0_363
	v_cvt_pk_bf16_f32 v138, v66, v67
	v_cvt_pk_bf16_f32 v139, v68, v69
	global_store_dwordx4 v[136:137], v[78:81], off offset:128 nt
	global_store_dwordx2 v[134:135], v[138:139], off offset:96 sc1
	global_store_dwordx4 v[136:137], v[66:69], off offset:192 nt
.LBB0_363:
	v_add_u32_e32 v136, 0x90, v186
	v_ashrrev_i32_e32 v137, 31, v136
	v_lshlrev_b64 v[134:135], 8, v[136:137]
	v_lshl_add_u64 v[134:135], v[130:131], 0, v[134:135]
	v_cvt_pk_bf16_f32 v138, v94, v95
	v_cvt_pk_bf16_f32 v139, v96, v97
	s_mov_b64 s[4:5], -1
	s_and_b64 vcc, exec, s[68:69]
	global_store_dwordx2 v[134:135], v[138:139], off sc1
	s_cbranch_vccz .LBB0_365
	v_cvt_pk_bf16_f32 v138, v90, v91
	v_cvt_pk_bf16_f32 v139, v92, v93
	global_store_dwordx2 v[134:135], v[138:139], off offset:32 sc1
	s_mov_b64 s[4:5], 0
.LBB0_365:
	v_lshlrev_b32_e32 v136, 9, v136
	v_and_b32_e32 v136, 0x1be00, v136
	v_mov_b32_e32 v137, v0
	s_andn2_b64 vcc, exec, s[4:5]
	v_lshl_add_u64 v[136:137], v[132:133], 0, v[136:137]
	s_cbranch_vccnz .LBB0_367
	v_cvt_pk_bf16_f32 v138, v90, v91
	v_cvt_pk_bf16_f32 v139, v92, v93
	global_store_dwordx4 v[136:137], v[94:97], off nt
	global_store_dwordx2 v[134:135], v[138:139], off offset:32 sc1
	global_store_dwordx4 v[136:137], v[90:93], off offset:64 nt
.LBB0_367:
	v_cvt_pk_bf16_f32 v138, v86, v87
	v_cvt_pk_bf16_f32 v139, v88, v89
	s_mov_b64 s[4:5], -1
	s_and_b64 vcc, exec, s[68:69]
	global_store_dwordx2 v[134:135], v[138:139], off offset:64 sc1
	s_cbranch_vccz .LBB0_369
	v_cvt_pk_bf16_f32 v138, v82, v83
	v_cvt_pk_bf16_f32 v139, v84, v85
	global_store_dwordx2 v[134:135], v[138:139], off offset:96 sc1
	s_mov_b64 s[4:5], 0
.LBB0_369:
	s_andn2_b64 vcc, exec, s[4:5]
	s_cbranch_vccnz .LBB0_371
	v_cvt_pk_bf16_f32 v138, v82, v83
	v_cvt_pk_bf16_f32 v139, v84, v85
	global_store_dwordx4 v[136:137], v[86:89], off offset:128 nt
	global_store_dwordx2 v[134:135], v[138:139], off offset:96 sc1
	global_store_dwordx4 v[136:137], v[82:85], off offset:192 nt
.LBB0_371:
	v_add_u32_e32 v136, 0xa0, v186
	v_ashrrev_i32_e32 v137, 31, v136
	v_lshlrev_b64 v[134:135], 8, v[136:137]
	v_lshl_add_u64 v[134:135], v[130:131], 0, v[134:135]
	v_cvt_pk_bf16_f32 v138, v106, v107
	v_cvt_pk_bf16_f32 v139, v108, v109
	s_mov_b64 s[4:5], -1
	s_and_b64 vcc, exec, s[68:69]
	global_store_dwordx2 v[134:135], v[138:139], off sc1
	s_cbranch_vccz .LBB0_373
	v_cvt_pk_bf16_f32 v138, v102, v103
	v_cvt_pk_bf16_f32 v139, v104, v105
	global_store_dwordx2 v[134:135], v[138:139], off offset:32 sc1
	s_mov_b64 s[4:5], 0
.LBB0_373:
	v_lshlrev_b32_e32 v136, 9, v136
	v_and_b32_e32 v136, 0x1de00, v136
	v_mov_b32_e32 v137, v0
	s_andn2_b64 vcc, exec, s[4:5]
	v_lshl_add_u64 v[136:137], v[132:133], 0, v[136:137]
	s_cbranch_vccnz .LBB0_375
	v_cvt_pk_bf16_f32 v138, v102, v103
	v_cvt_pk_bf16_f32 v139, v104, v105
	global_store_dwordx4 v[136:137], v[106:109], off nt
	global_store_dwordx2 v[134:135], v[138:139], off offset:32 sc1
	global_store_dwordx4 v[136:137], v[102:105], off offset:64 nt
.LBB0_375:
	v_cvt_pk_bf16_f32 v138, v110, v111
	v_cvt_pk_bf16_f32 v139, v112, v113
	s_mov_b64 s[4:5], -1
	s_and_b64 vcc, exec, s[68:69]
	global_store_dwordx2 v[134:135], v[138:139], off offset:64 sc1
	s_cbranch_vccz .LBB0_377
	v_cvt_pk_bf16_f32 v138, v98, v99
	v_cvt_pk_bf16_f32 v139, v100, v101
	global_store_dwordx2 v[134:135], v[138:139], off offset:96 sc1
	s_mov_b64 s[4:5], 0
.LBB0_377:
	s_andn2_b64 vcc, exec, s[4:5]
	s_cbranch_vccnz .LBB0_379
	v_cvt_pk_bf16_f32 v138, v98, v99
	v_cvt_pk_bf16_f32 v139, v100, v101
	global_store_dwordx4 v[136:137], v[110:113], off offset:128 nt
	global_store_dwordx2 v[134:135], v[138:139], off offset:96 sc1
	global_store_dwordx4 v[136:137], v[98:101], off offset:192 nt
.LBB0_379:
	v_add_u32_e32 v134, 0xb0, v186
	v_ashrrev_i32_e32 v135, 31, v134
	v_lshlrev_b64 v[136:137], 8, v[134:135]
	v_lshl_add_u64 v[130:131], v[130:131], 0, v[136:137]
	v_cvt_pk_bf16_f32 v136, v118, v119
	v_cvt_pk_bf16_f32 v137, v120, v121
	s_mov_b64 s[4:5], -1
	s_and_b64 vcc, exec, s[68:69]
	global_store_dwordx2 v[130:131], v[136:137], off sc1
	s_cbranch_vccz .LBB0_381
	v_cvt_pk_bf16_f32 v136, v114, v115
	v_cvt_pk_bf16_f32 v137, v116, v117
	global_store_dwordx2 v[130:131], v[136:137], off offset:32 sc1
	s_mov_b64 s[4:5], 0
.LBB0_381:
	v_lshlrev_b32_e32 v134, 9, v134
	v_and_b32_e32 v134, 0x1fe00, v134
	v_mov_b32_e32 v135, v0
	s_andn2_b64 vcc, exec, s[4:5]
	v_lshl_add_u64 v[132:133], v[132:133], 0, v[134:135]
	s_cbranch_vccnz .LBB0_383
	v_cvt_pk_bf16_f32 v134, v114, v115
	v_cvt_pk_bf16_f32 v135, v116, v117
	global_store_dwordx4 v[132:133], v[118:121], off nt
	global_store_dwordx2 v[130:131], v[134:135], off offset:32 sc1
	global_store_dwordx4 v[132:133], v[114:117], off offset:64 nt
.LBB0_383:
	v_cvt_pk_bf16_f32 v134, v122, v123
	v_cvt_pk_bf16_f32 v135, v124, v125
	s_mov_b64 s[4:5], -1
	s_and_b64 vcc, exec, s[68:69]
	global_store_dwordx2 v[130:131], v[134:135], off offset:64 sc1
	s_cbranch_vccz .LBB0_385
	v_cvt_pk_bf16_f32 v134, v126, v127
	v_cvt_pk_bf16_f32 v135, v128, v129
	global_store_dwordx2 v[130:131], v[134:135], off offset:96 sc1
	s_mov_b64 s[4:5], 0
.LBB0_385:
	s_andn2_b64 vcc, exec, s[4:5]
	s_cbranch_vccnz .LBB0_387
	v_cvt_pk_bf16_f32 v134, v126, v127
	v_cvt_pk_bf16_f32 v135, v128, v129
	global_store_dwordx4 v[132:133], v[122:125], off offset:128 nt
	global_store_dwordx2 v[130:131], v[134:135], off offset:96 sc1
	global_store_dwordx4 v[132:133], v[126:129], off offset:192 nt

.LBB0_388:
	s_andn2_b64 vcc, exec, s[4:5]
	s_cbranch_vccnz .LBB0_390
	v_mul_f32_e32 v134, 0xbfb8aa3b, v14
	v_mul_f32_e32 v135, 0xbfb8aa3b, v15
	v_mul_f32_e32 v136, 0xbfb8aa3b, v16
	v_mul_f32_e32 v137, 0xbfb8aa3b, v17
	s_lshl_b32 s1, s1, 7
	v_exp_f32_e32 v134, v134
	v_exp_f32_e32 v135, v135
	v_exp_f32_e32 v136, v136
	v_exp_f32_e32 v137, v137
	s_add_i32 s4, s1, 0xffffff80
	s_ashr_i32 s5, s4, 31
	s_lshl_b64 s[4:5], s[4:5], 1
	s_add_u32 s1, s21, s4
	v_add_f32_e32 v134, 1.0, v134
	v_add_f32_e32 v135, 1.0, v135
	v_add_f32_e32 v136, 1.0, v136
	v_add_f32_e32 v137, 1.0, v137
	s_addc_u32 s3, s20, s5
	s_lshl_b32 s4, s44, 1
	v_rcp_f32_e32 v134, v134
	v_rcp_f32_e32 v135, v135
	v_rcp_f32_e32 v136, v136
	v_rcp_f32_e32 v137, v137
	s_add_u32 s4, s1, s4
	s_addc_u32 s5, s3, 0
	v_lshlrev_b32_e32 v130, 1, v178
	v_mov_b32_e32 v131, v0
	v_lshl_add_u64 v[130:131], s[4:5], 0, v[130:131]
	s_mov_b64 s[0:1], 0x8c00000
	v_ashrrev_i32_e32 v187, 31, v186
	v_lshl_add_u64 v[132:133], v[130:131], 0, s[0:1]
	v_lshlrev_b64 v[130:131], 9, v[186:187]
	v_pk_mul_f32 v[134:135], v[2:3], v[134:135]
	v_pk_mul_f32 v[136:137], v[4:5], v[136:137]
	v_lshl_add_u64 v[130:131], v[132:133], 0, v[130:131]
	v_cvt_pk_bf16_f32 v134, v134, v135
	v_cvt_pk_bf16_f32 v135, v136, v137
	global_store_dwordx2 v[130:131], v[134:135], off sc1
	v_mul_f32_e32 v134, 0xbfb8aa3b, v10
	v_mul_f32_e32 v135, 0xbfb8aa3b, v11
	v_mul_f32_e32 v136, 0xbfb8aa3b, v12
	v_mul_f32_e32 v137, 0xbfb8aa3b, v13
	v_exp_f32_e32 v134, v134
	v_exp_f32_e32 v135, v135
	v_exp_f32_e32 v136, v136
	v_exp_f32_e32 v137, v137
	v_add_f32_e32 v134, 1.0, v134
	v_add_f32_e32 v135, 1.0, v135
	v_add_f32_e32 v136, 1.0, v136
	v_add_f32_e32 v137, 1.0, v137
	v_rcp_f32_e32 v134, v134
	v_rcp_f32_e32 v135, v135
	v_rcp_f32_e32 v136, v136
	v_rcp_f32_e32 v137, v137
	v_mul_f32_e32 v138, 0xbfb8aa3b, v24
	v_pk_mul_f32 v[134:135], v[6:7], v[134:135]
	v_mul_f32_e32 v139, 0xbfb8aa3b, v25
	v_pk_mul_f32 v[136:137], v[8:9], v[136:137]
	v_cvt_pk_bf16_f32 v134, v134, v135
	v_cvt_pk_bf16_f32 v135, v136, v137
	v_mul_f32_e32 v136, 0xbfb8aa3b, v22
	v_mul_f32_e32 v137, 0xbfb8aa3b, v23
	v_exp_f32_e32 v136, v136
	v_exp_f32_e32 v137, v137
	v_exp_f32_e32 v138, v138
	v_exp_f32_e32 v139, v139
	v_add_f32_e32 v136, 1.0, v136
	v_add_f32_e32 v137, 1.0, v137
	v_add_f32_e32 v138, 1.0, v138
	v_add_f32_e32 v139, 1.0, v139
	v_rcp_f32_e32 v136, v136
	v_rcp_f32_e32 v137, v137
	v_rcp_f32_e32 v138, v138
	v_rcp_f32_e32 v139, v139
	global_store_dwordx2 v[130:131], v[134:135], off offset:32 sc1
	v_or_b32_e32 v134, 16, v186
	v_ashrrev_i32_e32 v135, 31, v134
	v_lshlrev_b64 v[134:135], 9, v[134:135]
	v_pk_mul_f32 v[136:137], v[30:31], v[136:137]
	v_pk_mul_f32 v[138:139], v[32:33], v[138:139]
	v_lshl_add_u64 v[134:135], v[132:133], 0, v[134:135]
	v_cvt_pk_bf16_f32 v136, v136, v137
	v_cvt_pk_bf16_f32 v137, v138, v139
	global_store_dwordx2 v[134:135], v[136:137], off sc1
	v_mul_f32_e32 v136, 0xbfb8aa3b, v18
	v_mul_f32_e32 v137, 0xbfb8aa3b, v19
	v_mul_f32_e32 v138, 0xbfb8aa3b, v20
	v_mul_f32_e32 v139, 0xbfb8aa3b, v21
	v_exp_f32_e32 v136, v136
	v_exp_f32_e32 v137, v137
	v_exp_f32_e32 v138, v138
	v_exp_f32_e32 v139, v139
	v_add_f32_e32 v136, 1.0, v136
	v_add_f32_e32 v137, 1.0, v137
	v_add_f32_e32 v138, 1.0, v138
	v_add_f32_e32 v139, 1.0, v139
	v_rcp_f32_e32 v136, v136
	v_rcp_f32_e32 v137, v137
	v_rcp_f32_e32 v138, v138
	v_rcp_f32_e32 v139, v139
	s_mov_b64 s[0:1], 0x10000
	v_pk_mul_f32 v[136:137], v[26:27], v[136:137]
	v_pk_mul_f32 v[138:139], v[28:29], v[138:139]
	v_cvt_pk_bf16_f32 v136, v136, v137
	v_cvt_pk_bf16_f32 v137, v138, v139
	global_store_dwordx2 v[134:135], v[136:137], off offset:32 sc1
	v_mul_f32_e32 v136, 0xbfb8aa3b, v46
	v_mul_f32_e32 v137, 0xbfb8aa3b, v47
	v_mul_f32_e32 v138, 0xbfb8aa3b, v48
	v_mul_f32_e32 v139, 0xbfb8aa3b, v49
	v_exp_f32_e32 v136, v136
	v_exp_f32_e32 v137, v137
	v_exp_f32_e32 v138, v138
	v_exp_f32_e32 v139, v139
	v_add_f32_e32 v136, 1.0, v136
	v_add_f32_e32 v137, 1.0, v137
	v_add_f32_e32 v138, 1.0, v138
	v_add_f32_e32 v139, 1.0, v139
	v_rcp_f32_e32 v136, v136
	v_rcp_f32_e32 v137, v137
	v_rcp_f32_e32 v138, v138
	v_rcp_f32_e32 v139, v139
	v_or_b32_e32 v134, 32, v186
	v_ashrrev_i32_e32 v135, 31, v134
	v_lshlrev_b64 v[134:135], 9, v[134:135]
	v_pk_mul_f32 v[136:137], v[34:35], v[136:137]
	v_pk_mul_f32 v[138:139], v[36:37], v[138:139]
	v_lshl_add_u64 v[134:135], v[132:133], 0, v[134:135]
	v_cvt_pk_bf16_f32 v136, v136, v137
	v_cvt_pk_bf16_f32 v137, v138, v139
	global_store_dwordx2 v[134:135], v[136:137], off sc1
	v_mul_f32_e32 v136, 0xbfb8aa3b, v38
	v_mul_f32_e32 v137, 0xbfb8aa3b, v39
	v_mul_f32_e32 v138, 0xbfb8aa3b, v40
	v_mul_f32_e32 v139, 0xbfb8aa3b, v41
	v_exp_f32_e32 v136, v136
	v_exp_f32_e32 v137, v137
	v_exp_f32_e32 v138, v138
	v_exp_f32_e32 v139, v139
	v_add_f32_e32 v136, 1.0, v136
	v_add_f32_e32 v137, 1.0, v137
	v_add_f32_e32 v138, 1.0, v138
	v_add_f32_e32 v139, 1.0, v139
	v_rcp_f32_e32 v136, v136
	v_rcp_f32_e32 v137, v137
	v_rcp_f32_e32 v138, v138
	v_rcp_f32_e32 v139, v139
	v_pk_mul_f32 v[136:137], v[42:43], v[136:137]
	s_nop 0
	v_cvt_pk_bf16_f32 v136, v136, v137
	v_pk_mul_f32 v[138:139], v[44:45], v[138:139]
	s_nop 0
	v_cvt_pk_bf16_f32 v137, v138, v139
	global_store_dwordx2 v[134:135], v[136:137], off offset:32 sc1
	v_or_b32_e32 v134, 48, v186
	v_ashrrev_i32_e32 v135, 31, v134
	v_lshlrev_b64 v[134:135], 9, v[134:135]
	v_lshl_add_u64 v[132:133], v[132:133], 0, v[134:135]
	v_mul_f32_e32 v134, 0xbfb8aa3b, v54
	v_mul_f32_e32 v135, 0xbfb8aa3b, v55
	v_mul_f32_e32 v136, 0xbfb8aa3b, v56
	v_mul_f32_e32 v137, 0xbfb8aa3b, v57
	v_exp_f32_e32 v134, v134
	v_exp_f32_e32 v135, v135
	v_exp_f32_e32 v136, v136
	v_exp_f32_e32 v137, v137
	v_add_f32_e32 v134, 1.0, v134
	v_add_f32_e32 v135, 1.0, v135
	v_add_f32_e32 v136, 1.0, v136
	v_add_f32_e32 v137, 1.0, v137
	v_rcp_f32_e32 v134, v134
	v_rcp_f32_e32 v135, v135
	v_rcp_f32_e32 v136, v136
	v_rcp_f32_e32 v137, v137
	v_pk_mul_f32 v[134:135], v[62:63], v[134:135]
	s_nop 0
	v_cvt_pk_bf16_f32 v134, v134, v135
	v_pk_mul_f32 v[136:137], v[64:65], v[136:137]
	s_nop 0
	v_cvt_pk_bf16_f32 v135, v136, v137
	global_store_dwordx2 v[132:133], v[134:135], off sc1
	v_mul_f32_e32 v134, 0xbfb8aa3b, v50
	v_mul_f32_e32 v135, 0xbfb8aa3b, v51
	v_mul_f32_e32 v136, 0xbfb8aa3b, v52
	v_mul_f32_e32 v137, 0xbfb8aa3b, v53
	v_exp_f32_e32 v134, v134
	v_exp_f32_e32 v135, v135
	v_exp_f32_e32 v136, v136
	v_exp_f32_e32 v137, v137
	v_add_f32_e32 v134, 1.0, v134
	v_add_f32_e32 v135, 1.0, v135
	v_add_f32_e32 v136, 1.0, v136
	v_add_f32_e32 v137, 1.0, v137
	v_rcp_f32_e32 v134, v134
	v_rcp_f32_e32 v135, v135
	v_rcp_f32_e32 v136, v136
	v_rcp_f32_e32 v137, v137
	v_pk_mul_f32 v[134:135], v[58:59], v[134:135]
	s_nop 0
	v_cvt_pk_bf16_f32 v134, v134, v135
	v_pk_mul_f32 v[136:137], v[60:61], v[136:137]
	s_nop 0
	v_cvt_pk_bf16_f32 v135, v136, v137
	global_store_dwordx2 v[132:133], v[134:135], off offset:32 sc1
	v_mul_f32_e32 v134, 0xbfb8aa3b, v78
	v_mul_f32_e32 v135, 0xbfb8aa3b, v79
	v_mul_f32_e32 v136, 0xbfb8aa3b, v80
	v_mul_f32_e32 v137, 0xbfb8aa3b, v81
	v_exp_f32_e32 v134, v134
	v_exp_f32_e32 v135, v135
	v_exp_f32_e32 v136, v136
	v_exp_f32_e32 v137, v137
	v_add_f32_e32 v134, 1.0, v134
	v_add_f32_e32 v135, 1.0, v135
	v_add_f32_e32 v136, 1.0, v136
	v_add_f32_e32 v137, 1.0, v137
	v_rcp_f32_e32 v134, v134
	v_rcp_f32_e32 v135, v135
	v_rcp_f32_e32 v136, v136
	v_rcp_f32_e32 v137, v137
	v_lshl_add_u64 v[132:133], v[130:131], 0, s[0:1]
	v_pk_mul_f32 v[134:135], v[74:75], v[134:135]
	s_mov_b32 s0, 0x10000
	v_pk_mul_f32 v[136:137], v[76:77], v[136:137]
	v_cvt_pk_bf16_f32 v134, v134, v135
	v_cvt_pk_bf16_f32 v135, v136, v137
	v_add_co_u32_e32 v136, vcc, s0, v130
	s_mov_b64 s[0:1], 0x12000
	s_nop 0
	v_addc_co_u32_e32 v137, vcc, 0, v131, vcc
	global_store_dwordx2 v[136:137], v[134:135], off sc1
	v_mul_f32_e32 v134, 0xbfb8aa3b, v66
	v_mul_f32_e32 v135, 0xbfb8aa3b, v67
	v_mul_f32_e32 v136, 0xbfb8aa3b, v68
	v_mul_f32_e32 v137, 0xbfb8aa3b, v69
	v_exp_f32_e32 v134, v134
	v_exp_f32_e32 v135, v135
	v_exp_f32_e32 v136, v136
	v_exp_f32_e32 v137, v137
	v_add_f32_e32 v134, 1.0, v134
	v_add_f32_e32 v135, 1.0, v135
	v_add_f32_e32 v136, 1.0, v136
	v_add_f32_e32 v137, 1.0, v137
	v_rcp_f32_e32 v134, v134
	v_rcp_f32_e32 v135, v135
	v_rcp_f32_e32 v136, v136
	v_rcp_f32_e32 v137, v137
	v_pk_mul_f32 v[134:135], v[70:71], v[134:135]
	s_nop 0
	v_cvt_pk_bf16_f32 v134, v134, v135
	v_pk_mul_f32 v[136:137], v[72:73], v[136:137]
	s_nop 0
	v_cvt_pk_bf16_f32 v135, v136, v137
	global_store_dwordx2 v[132:133], v[134:135], off offset:32 sc1
	v_mul_f32_e32 v134, 0xbfb8aa3b, v86
	v_mul_f32_e32 v135, 0xbfb8aa3b, v87
	v_mul_f32_e32 v136, 0xbfb8aa3b, v88
	v_mul_f32_e32 v137, 0xbfb8aa3b, v89
	v_exp_f32_e32 v134, v134
	v_exp_f32_e32 v135, v135
	v_exp_f32_e32 v136, v136
	v_exp_f32_e32 v137, v137
	v_add_f32_e32 v134, 1.0, v134
	v_add_f32_e32 v135, 1.0, v135
	v_add_f32_e32 v136, 1.0, v136
	v_add_f32_e32 v137, 1.0, v137
	v_rcp_f32_e32 v134, v134
	v_rcp_f32_e32 v135, v135
	v_rcp_f32_e32 v136, v136
	v_rcp_f32_e32 v137, v137
	v_lshl_add_u64 v[132:133], v[130:131], 0, s[0:1]
	v_pk_mul_f32 v[134:135], v[94:95], v[134:135]
	s_mov_b32 s0, 0x12000
	v_pk_mul_f32 v[136:137], v[96:97], v[136:137]
	v_cvt_pk_bf16_f32 v134, v134, v135
	v_cvt_pk_bf16_f32 v135, v136, v137
	v_add_co_u32_e32 v136, vcc, s0, v130
	s_mov_b64 s[0:1], 0x14000
	s_nop 0
	v_addc_co_u32_e32 v137, vcc, 0, v131, vcc
	global_store_dwordx2 v[136:137], v[134:135], off sc1
	v_mul_f32_e32 v134, 0xbfb8aa3b, v82
	v_mul_f32_e32 v135, 0xbfb8aa3b, v83
	v_mul_f32_e32 v136, 0xbfb8aa3b, v84
	v_mul_f32_e32 v137, 0xbfb8aa3b, v85
	v_exp_f32_e32 v134, v134
	v_exp_f32_e32 v135, v135
	v_exp_f32_e32 v136, v136
	v_exp_f32_e32 v137, v137
	v_add_f32_e32 v134, 1.0, v134
	v_add_f32_e32 v135, 1.0, v135
	v_add_f32_e32 v136, 1.0, v136
	v_add_f32_e32 v137, 1.0, v137
	v_rcp_f32_e32 v134, v134
	v_rcp_f32_e32 v135, v135
	v_rcp_f32_e32 v136, v136
	v_rcp_f32_e32 v137, v137
	v_pk_mul_f32 v[134:135], v[90:91], v[134:135]
	s_nop 0
	v_cvt_pk_bf16_f32 v134, v134, v135
	v_pk_mul_f32 v[136:137], v[92:93], v[136:137]
	s_nop 0
	v_cvt_pk_bf16_f32 v135, v136, v137
	global_store_dwordx2 v[132:133], v[134:135], off offset:32 sc1
	v_mul_f32_e32 v134, 0xbfb8aa3b, v110
	v_mul_f32_e32 v135, 0xbfb8aa3b, v111
	v_mul_f32_e32 v136, 0xbfb8aa3b, v112
	v_mul_f32_e32 v137, 0xbfb8aa3b, v113
	v_exp_f32_e32 v134, v134
	v_exp_f32_e32 v135, v135
	v_exp_f32_e32 v136, v136
	v_exp_f32_e32 v137, v137
	v_add_f32_e32 v134, 1.0, v134
	v_add_f32_e32 v135, 1.0, v135
	v_add_f32_e32 v136, 1.0, v136
	v_add_f32_e32 v137, 1.0, v137
	v_rcp_f32_e32 v134, v134
	v_rcp_f32_e32 v135, v135
	v_rcp_f32_e32 v136, v136
	v_rcp_f32_e32 v137, v137
	v_lshl_add_u64 v[132:133], v[130:131], 0, s[0:1]
	v_pk_mul_f32 v[134:135], v[106:107], v[134:135]
	s_mov_b32 s0, 0x14000
	v_pk_mul_f32 v[136:137], v[108:109], v[136:137]
	v_cvt_pk_bf16_f32 v134, v134, v135
	v_cvt_pk_bf16_f32 v135, v136, v137
	v_add_co_u32_e32 v136, vcc, s0, v130
	s_mov_b64 s[0:1], 0x16000
	s_nop 0
	v_addc_co_u32_e32 v137, vcc, 0, v131, vcc
	global_store_dwordx2 v[136:137], v[134:135], off sc1
	v_mul_f32_e32 v134, 0xbfb8aa3b, v98
	v_mul_f32_e32 v135, 0xbfb8aa3b, v99
	v_mul_f32_e32 v136, 0xbfb8aa3b, v100
	v_mul_f32_e32 v137, 0xbfb8aa3b, v101
	v_exp_f32_e32 v134, v134
	v_exp_f32_e32 v135, v135
	v_exp_f32_e32 v136, v136
	v_exp_f32_e32 v137, v137
	v_add_f32_e32 v134, 1.0, v134
	v_add_f32_e32 v135, 1.0, v135
	v_add_f32_e32 v136, 1.0, v136
	v_add_f32_e32 v137, 1.0, v137
	v_rcp_f32_e32 v134, v134
	v_rcp_f32_e32 v135, v135
	v_rcp_f32_e32 v136, v136
	v_rcp_f32_e32 v137, v137
	v_pk_mul_f32 v[134:135], v[102:103], v[134:135]
	s_nop 0
	v_cvt_pk_bf16_f32 v134, v134, v135
	v_pk_mul_f32 v[136:137], v[104:105], v[136:137]
	s_nop 0
	v_cvt_pk_bf16_f32 v135, v136, v137
	global_store_dwordx2 v[132:133], v[134:135], off offset:32 sc1
	v_mul_f32_e32 v134, 0xbfb8aa3b, v122
	v_mul_f32_e32 v135, 0xbfb8aa3b, v123
	v_mul_f32_e32 v136, 0xbfb8aa3b, v124
	v_mul_f32_e32 v137, 0xbfb8aa3b, v125
	v_exp_f32_e32 v134, v134
	v_exp_f32_e32 v135, v135
	v_exp_f32_e32 v136, v136
	v_exp_f32_e32 v137, v137
	v_add_f32_e32 v134, 1.0, v134
	v_add_f32_e32 v135, 1.0, v135
	v_add_f32_e32 v136, 1.0, v136
	v_add_f32_e32 v137, 1.0, v137
	v_rcp_f32_e32 v134, v134
	v_rcp_f32_e32 v135, v135
	v_rcp_f32_e32 v136, v136
	v_rcp_f32_e32 v137, v137
	v_lshl_add_u64 v[132:133], v[130:131], 0, s[0:1]
	s_mov_b32 s0, 0x16000
	v_pk_mul_f32 v[134:135], v[118:119], v[134:135]
	v_pk_mul_f32 v[136:137], v[120:121], v[136:137]
	v_add_co_u32_e32 v130, vcc, s0, v130
	v_cvt_pk_bf16_f32 v134, v134, v135
	v_cvt_pk_bf16_f32 v135, v136, v137
	v_addc_co_u32_e32 v131, vcc, 0, v131, vcc
	global_store_dwordx2 v[130:131], v[134:135], off sc1
	v_mul_f32_e32 v130, 0xbfb8aa3b, v126
	v_mul_f32_e32 v131, 0xbfb8aa3b, v127
	v_mul_f32_e32 v134, 0xbfb8aa3b, v128
	v_mul_f32_e32 v135, 0xbfb8aa3b, v129
	v_exp_f32_e32 v130, v130
	v_exp_f32_e32 v131, v131
	v_exp_f32_e32 v134, v134
	v_exp_f32_e32 v135, v135
	v_add_f32_e32 v130, 1.0, v130
	v_add_f32_e32 v131, 1.0, v131
	v_add_f32_e32 v134, 1.0, v134
	v_add_f32_e32 v135, 1.0, v135
	v_rcp_f32_e32 v130, v130
	v_rcp_f32_e32 v131, v131
	v_rcp_f32_e32 v134, v134
	v_rcp_f32_e32 v135, v135
	v_pk_mul_f32 v[130:131], v[114:115], v[130:131]
	s_nop 0
	v_cvt_pk_bf16_f32 v130, v130, v131
	v_pk_mul_f32 v[134:135], v[116:117], v[134:135]
	s_nop 0
	v_cvt_pk_bf16_f32 v131, v134, v135
	global_store_dwordx2 v[132:133], v[130:131], off offset:32 sc1

.LBB0_391:
	s_lshl_b32 s1, s44, 1
	s_add_u32 s4, s21, s1
	s_addc_u32 s5, s20, 0
	v_lshlrev_b32_e32 v130, 1, v178
	v_mov_b32_e32 v131, v0
	v_lshl_add_u64 v[130:131], s[4:5], 0, v[130:131]
	v_ashrrev_i32_e32 v187, 31, v186
	v_lshl_add_u64 v[130:131], v[130:131], 0, s[78:79]
	v_lshlrev_b64 v[132:133], 9, v[186:187]
	v_lshl_add_u64 v[132:133], v[130:131], 0, v[132:133]
	v_cvt_pk_bf16_f32 v2, v2, v3
	v_cvt_pk_bf16_f32 v3, v4, v5
	global_store_dwordx2 v[132:133], v[2:3], off sc1
	v_cvt_pk_bf16_f32 v2, v6, v7
	v_cvt_pk_bf16_f32 v3, v8, v9
	global_store_dwordx2 v[132:133], v[2:3], off offset:32 sc1
	v_cvt_pk_bf16_f32 v2, v14, v15
	v_cvt_pk_bf16_f32 v3, v16, v17
	global_store_dwordx2 v[132:133], v[2:3], off offset:256 sc1
	v_cvt_pk_bf16_f32 v2, v10, v11
	v_cvt_pk_bf16_f32 v3, v12, v13
	global_store_dwordx2 v[132:133], v[2:3], off offset:288 sc1
	v_or_b32_e32 v2, 16, v186
	v_ashrrev_i32_e32 v3, 31, v2
	v_lshlrev_b64 v[2:3], 9, v[2:3]
	v_lshl_add_u64 v[2:3], v[130:131], 0, v[2:3]
	v_cvt_pk_bf16_f32 v4, v30, v31
	v_cvt_pk_bf16_f32 v5, v32, v33
	global_store_dwordx2 v[2:3], v[4:5], off sc1
	v_cvt_pk_bf16_f32 v4, v26, v27
	v_cvt_pk_bf16_f32 v5, v28, v29
	global_store_dwordx2 v[2:3], v[4:5], off offset:32 sc1
	v_cvt_pk_bf16_f32 v4, v22, v23
	v_cvt_pk_bf16_f32 v5, v24, v25
	global_store_dwordx2 v[2:3], v[4:5], off offset:256 sc1
	v_cvt_pk_bf16_f32 v4, v18, v19
	v_cvt_pk_bf16_f32 v5, v20, v21
	global_store_dwordx2 v[2:3], v[4:5], off offset:288 sc1
	v_or_b32_e32 v2, 32, v186
	v_ashrrev_i32_e32 v3, 31, v2
	v_lshlrev_b64 v[2:3], 9, v[2:3]
	v_lshl_add_u64 v[2:3], v[130:131], 0, v[2:3]
	v_cvt_pk_bf16_f32 v4, v34, v35
	v_cvt_pk_bf16_f32 v5, v36, v37
	global_store_dwordx2 v[2:3], v[4:5], off sc1
	v_cvt_pk_bf16_f32 v4, v42, v43
	v_cvt_pk_bf16_f32 v5, v44, v45
	global_store_dwordx2 v[2:3], v[4:5], off offset:32 sc1
	v_cvt_pk_bf16_f32 v4, v46, v47
	v_cvt_pk_bf16_f32 v5, v48, v49
	global_store_dwordx2 v[2:3], v[4:5], off offset:256 sc1
	v_cvt_pk_bf16_f32 v4, v38, v39
	v_cvt_pk_bf16_f32 v5, v40, v41
	global_store_dwordx2 v[2:3], v[4:5], off offset:288 sc1
	v_or_b32_e32 v2, 48, v186
	v_ashrrev_i32_e32 v3, 31, v2
	v_lshlrev_b64 v[2:3], 9, v[2:3]
	v_lshl_add_u64 v[2:3], v[130:131], 0, v[2:3]
	v_cvt_pk_bf16_f32 v4, v62, v63
	v_cvt_pk_bf16_f32 v5, v64, v65
	global_store_dwordx2 v[2:3], v[4:5], off sc1
	v_cvt_pk_bf16_f32 v4, v58, v59
	v_cvt_pk_bf16_f32 v5, v60, v61
	global_store_dwordx2 v[2:3], v[4:5], off offset:32 sc1
	v_cvt_pk_bf16_f32 v4, v54, v55
	v_cvt_pk_bf16_f32 v5, v56, v57
	global_store_dwordx2 v[2:3], v[4:5], off offset:256 sc1
	v_cvt_pk_bf16_f32 v4, v50, v51
	v_cvt_pk_bf16_f32 v5, v52, v53
	s_mov_b64 s[0:1], 0x10000
	global_store_dwordx2 v[2:3], v[4:5], off offset:288 sc1
	v_lshl_add_u64 v[2:3], v[132:133], 0, s[0:1]
	s_mov_b32 s0, 0x10000
	v_add_co_u32_e32 v6, vcc, s0, v132
	v_cvt_pk_bf16_f32 v4, v74, v75
	v_cvt_pk_bf16_f32 v5, v76, v77
	v_addc_co_u32_e32 v7, vcc, 0, v133, vcc
	global_store_dwordx2 v[6:7], v[4:5], off sc1
	v_cvt_pk_bf16_f32 v4, v70, v71
	v_cvt_pk_bf16_f32 v5, v72, v73
	global_store_dwordx2 v[2:3], v[4:5], off offset:32 sc1
	v_cvt_pk_bf16_f32 v4, v78, v79
	v_cvt_pk_bf16_f32 v5, v80, v81
	global_store_dwordx2 v[2:3], v[4:5], off offset:256 sc1
	v_cvt_pk_bf16_f32 v4, v66, v67
	v_cvt_pk_bf16_f32 v5, v68, v69
	s_mov_b64 s[0:1], 0x12000
	global_store_dwordx2 v[2:3], v[4:5], off offset:288 sc1
	v_lshl_add_u64 v[2:3], v[132:133], 0, s[0:1]
	s_mov_b32 s0, 0x12000
	v_add_co_u32_e32 v6, vcc, s0, v132
	v_cvt_pk_bf16_f32 v4, v94, v95
	v_cvt_pk_bf16_f32 v5, v96, v97
	v_addc_co_u32_e32 v7, vcc, 0, v133, vcc
	global_store_dwordx2 v[6:7], v[4:5], off sc1
	v_cvt_pk_bf16_f32 v4, v90, v91
	v_cvt_pk_bf16_f32 v5, v92, v93
	global_store_dwordx2 v[2:3], v[4:5], off offset:32 sc1
	v_cvt_pk_bf16_f32 v4, v86, v87
	v_cvt_pk_bf16_f32 v5, v88, v89
	global_store_dwordx2 v[2:3], v[4:5], off offset:256 sc1
	v_cvt_pk_bf16_f32 v4, v82, v83
	v_cvt_pk_bf16_f32 v5, v84, v85
	s_mov_b64 s[0:1], 0x14000
	global_store_dwordx2 v[2:3], v[4:5], off offset:288 sc1
	v_lshl_add_u64 v[2:3], v[132:133], 0, s[0:1]
	s_mov_b32 s0, 0x14000
	v_add_co_u32_e32 v6, vcc, s0, v132
	v_cvt_pk_bf16_f32 v4, v106, v107
	v_cvt_pk_bf16_f32 v5, v108, v109
	v_addc_co_u32_e32 v7, vcc, 0, v133, vcc
	global_store_dwordx2 v[6:7], v[4:5], off sc1
	v_cvt_pk_bf16_f32 v4, v102, v103
	v_cvt_pk_bf16_f32 v5, v104, v105
	global_store_dwordx2 v[2:3], v[4:5], off offset:32 sc1
	v_cvt_pk_bf16_f32 v4, v110, v111
	v_cvt_pk_bf16_f32 v5, v112, v113
	global_store_dwordx2 v[2:3], v[4:5], off offset:256 sc1
	v_cvt_pk_bf16_f32 v4, v98, v99
	v_cvt_pk_bf16_f32 v5, v100, v101
	s_mov_b64 s[0:1], 0x16000
	global_store_dwordx2 v[2:3], v[4:5], off offset:288 sc1
	v_lshl_add_u64 v[2:3], v[132:133], 0, s[0:1]
	s_mov_b32 s0, 0x16000
	v_add_co_u32_e32 v6, vcc, s0, v132
	v_cvt_pk_bf16_f32 v4, v118, v119
	v_cvt_pk_bf16_f32 v5, v120, v121
	v_addc_co_u32_e32 v7, vcc, 0, v133, vcc
	global_store_dwordx2 v[6:7], v[4:5], off sc1
	v_cvt_pk_bf16_f32 v4, v114, v115
	v_cvt_pk_bf16_f32 v5, v116, v117
	global_store_dwordx2 v[2:3], v[4:5], off offset:32 sc1
	v_cvt_pk_bf16_f32 v4, v122, v123
	v_cvt_pk_bf16_f32 v5, v124, v125
	global_store_dwordx2 v[2:3], v[4:5], off offset:256 sc1
	v_cvt_pk_bf16_f32 v4, v126, v127
	v_cvt_pk_bf16_f32 v5, v128, v129
	global_store_dwordx2 v[2:3], v[4:5], off offset:288 sc1

.LBB0_453:
	v_cmp_lt_i32_e32 vcc, v228, v222
	s_waitcnt vmcnt(0)
	v_sub_f32_e32 v3, v195, v197
	v_exp_f32_e32 v3, v3
	v_cndmask_b32_e32 v1, v221, v228, vcc
	v_lshlrev_b32_e32 v1, 2, v1
	ds_bpermute_b32 v2, v1, v241
	v_mov_b32_e32 v197, v0
	s_mov_b64 s[10:11], 0xbc00400
	s_mov_b32 s0, 0xbc00000
	ds_bpermute_b32 v1, v1, v238
	s_waitcnt lgkmcnt(1)
	v_add_f32_e32 v2, v241, v2
	v_add_f32_e32 v2, v3, v2
	v_div_scale_f32 v3, s[4:5], v2, v2, 1.0
	v_rcp_f32_e32 v4, v3
	v_div_scale_f32 v5, vcc, 1.0, v2, 1.0
	s_waitcnt lgkmcnt(0)
	v_add_f32_e32 v1, v238, v1
	v_fma_f32 v6, -v3, v4, 1.0
	v_fmac_f32_e32 v4, v6, v4
	v_mul_f32_e32 v6, v5, v4
	v_fma_f32 v7, -v3, v6, v5
	v_fmac_f32_e32 v6, v7, v4
	v_fma_f32 v3, -v3, v6, v5
	v_div_fmas_f32 v3, v3, v4, v6
	v_lshlrev_b64 v[4:5], 11, v[200:201]
	v_lshl_add_u64 v[4:5], s[6:7], 0, v[4:5]
	v_lshl_add_u64 v[4:5], v[4:5], 0, s[8:9]
	v_div_fixup_f32 v2, v3, v2, 1.0
	v_lshl_add_u64 v[4:5], v[4:5], 0, v[196:197]
	v_lshl_add_u64 v[6:7], v[4:5], 0, s[10:11]
	v_pk_mul_f32 v[8:9], v[64:65], v[2:3] op_sel_hi:[1,0]
	v_pk_mul_f32 v[10:11], v[66:67], v[2:3] op_sel_hi:[1,0]
	v_add_co_u32_e32 v4, vcc, s0, v4
	v_cvt_pk_bf16_f32 v8, v8, v9
	v_cvt_pk_bf16_f32 v9, v10, v11
	v_addc_co_u32_e32 v5, vcc, 0, v5, vcc
	global_store_dwordx2 v[4:5], v[8:9], off offset:1024 sc1
	v_pk_mul_f32 v[4:5], v[68:69], v[2:3] op_sel_hi:[1,0]
	v_pk_mul_f32 v[8:9], v[70:71], v[2:3] op_sel_hi:[1,0]
	v_cvt_pk_bf16_f32 v4, v4, v5
	v_cvt_pk_bf16_f32 v5, v8, v9
	global_store_dwordx2 v[6:7], v[4:5], off offset:16 sc1
	v_pk_mul_f32 v[4:5], v[72:73], v[2:3] op_sel_hi:[1,0]
	v_pk_mul_f32 v[8:9], v[74:75], v[2:3] op_sel_hi:[1,0]
	v_cvt_pk_bf16_f32 v4, v4, v5
	v_cvt_pk_bf16_f32 v5, v8, v9
	global_store_dwordx2 v[6:7], v[4:5], off offset:32 sc1
	v_pk_mul_f32 v[4:5], v[76:77], v[2:3] op_sel_hi:[1,0]
	v_pk_mul_f32 v[8:9], v[78:79], v[2:3] op_sel_hi:[1,0]
	v_cvt_pk_bf16_f32 v4, v4, v5
	v_cvt_pk_bf16_f32 v5, v8, v9
	global_store_dwordx2 v[6:7], v[4:5], off offset:48 sc1
	v_pk_mul_f32 v[4:5], v[48:49], v[2:3] op_sel_hi:[1,0]
	v_pk_mul_f32 v[8:9], v[50:51], v[2:3] op_sel_hi:[1,0]
	v_cvt_pk_bf16_f32 v4, v4, v5
	v_cvt_pk_bf16_f32 v5, v8, v9
	global_store_dwordx2 v[6:7], v[4:5], off offset:64 sc1
	v_pk_mul_f32 v[4:5], v[52:53], v[2:3] op_sel_hi:[1,0]
	v_pk_mul_f32 v[8:9], v[54:55], v[2:3] op_sel_hi:[1,0]
	v_cvt_pk_bf16_f32 v4, v4, v5
	v_cvt_pk_bf16_f32 v5, v8, v9
	global_store_dwordx2 v[6:7], v[4:5], off offset:80 sc1
	v_pk_mul_f32 v[4:5], v[56:57], v[2:3] op_sel_hi:[1,0]
	v_pk_mul_f32 v[8:9], v[58:59], v[2:3] op_sel_hi:[1,0]
	v_sub_f32_e32 v3, v195, v239
	v_exp_f32_e32 v3, v3
	v_cvt_pk_bf16_f32 v4, v4, v5
	v_cvt_pk_bf16_f32 v5, v8, v9
	global_store_dwordx2 v[6:7], v[4:5], off offset:96 sc1
	v_add_f32_e32 v1, v3, v1
	v_div_scale_f32 v8, s[4:5], v1, v1, 1.0
	v_rcp_f32_e32 v9, v8
	v_pk_mul_f32 v[4:5], v[60:61], v[2:3] op_sel_hi:[1,0]
	v_pk_mul_f32 v[2:3], v[62:63], v[2:3] op_sel_hi:[1,0]
	v_cvt_pk_bf16_f32 v4, v4, v5
	v_cvt_pk_bf16_f32 v5, v2, v3
	v_fma_f32 v2, -v8, v9, 1.0
	v_fmac_f32_e32 v9, v2, v9
	v_div_scale_f32 v2, vcc, 1.0, v1, 1.0
	v_mul_f32_e32 v3, v2, v9
	global_store_dwordx2 v[6:7], v[4:5], off offset:112 sc1
	v_fma_f32 v4, -v8, v3, v2
	v_fmac_f32_e32 v3, v4, v9
	v_lshlrev_b64 v[4:5], 11, v[198:199]
	v_fma_f32 v2, -v8, v3, v2
	v_lshl_add_u64 v[4:5], s[6:7], 0, v[4:5]
	v_div_fmas_f32 v2, v2, v9, v3
	v_lshl_add_u64 v[4:5], v[4:5], 0, s[8:9]
	v_div_fixup_f32 v2, v2, v1, 1.0
	v_lshl_add_u64 v[4:5], v[4:5], 0, v[196:197]
	v_lshl_add_u64 v[6:7], v[4:5], 0, s[10:11]
	v_pk_mul_f32 v[8:9], v[32:33], v[2:3] op_sel_hi:[1,0]
	v_pk_mul_f32 v[10:11], v[34:35], v[2:3] op_sel_hi:[1,0]
	v_add_co_u32_e32 v4, vcc, s0, v4
	v_cvt_pk_bf16_f32 v8, v8, v9
	v_cvt_pk_bf16_f32 v9, v10, v11
	v_addc_co_u32_e32 v5, vcc, 0, v5, vcc
	global_store_dwordx2 v[4:5], v[8:9], off offset:1024 sc1
	v_pk_mul_f32 v[4:5], v[36:37], v[2:3] op_sel_hi:[1,0]
	v_pk_mul_f32 v[8:9], v[38:39], v[2:3] op_sel_hi:[1,0]
	v_cvt_pk_bf16_f32 v4, v4, v5
	v_cvt_pk_bf16_f32 v5, v8, v9
	global_store_dwordx2 v[6:7], v[4:5], off offset:16 sc1
	v_pk_mul_f32 v[4:5], v[40:41], v[2:3] op_sel_hi:[1,0]
	v_pk_mul_f32 v[8:9], v[42:43], v[2:3] op_sel_hi:[1,0]
	v_cvt_pk_bf16_f32 v4, v4, v5
	v_cvt_pk_bf16_f32 v5, v8, v9
	global_store_dwordx2 v[6:7], v[4:5], off offset:32 sc1
	v_pk_mul_f32 v[4:5], v[44:45], v[2:3] op_sel_hi:[1,0]
	v_pk_mul_f32 v[8:9], v[46:47], v[2:3] op_sel_hi:[1,0]
	v_cvt_pk_bf16_f32 v4, v4, v5
	v_cvt_pk_bf16_f32 v5, v8, v9
	global_store_dwordx2 v[6:7], v[4:5], off offset:48 sc1
	v_pk_mul_f32 v[4:5], v[16:17], v[2:3] op_sel_hi:[1,0]
	v_pk_mul_f32 v[8:9], v[18:19], v[2:3] op_sel_hi:[1,0]
	v_cvt_pk_bf16_f32 v4, v4, v5
	v_cvt_pk_bf16_f32 v5, v8, v9
	global_store_dwordx2 v[6:7], v[4:5], off offset:64 sc1
	v_pk_mul_f32 v[4:5], v[20:21], v[2:3] op_sel_hi:[1,0]
	v_pk_mul_f32 v[8:9], v[22:23], v[2:3] op_sel_hi:[1,0]
	v_cvt_pk_bf16_f32 v4, v4, v5
	v_cvt_pk_bf16_f32 v5, v8, v9
	global_store_dwordx2 v[6:7], v[4:5], off offset:80 sc1
	v_pk_mul_f32 v[4:5], v[24:25], v[2:3] op_sel_hi:[1,0]
	v_pk_mul_f32 v[8:9], v[26:27], v[2:3] op_sel_hi:[1,0]
	v_cvt_pk_bf16_f32 v4, v4, v5
	v_cvt_pk_bf16_f32 v5, v8, v9
	global_store_dwordx2 v[6:7], v[4:5], off offset:96 sc1
	v_pk_mul_f32 v[4:5], v[28:29], v[2:3] op_sel_hi:[1,0]
	v_pk_mul_f32 v[2:3], v[30:31], v[2:3] op_sel_hi:[1,0]
	s_add_i32 s31, s31, s16
	v_cvt_pk_bf16_f32 v4, v4, v5
	v_cvt_pk_bf16_f32 v5, v2, v3
	s_cmpk_gt_i32 s31, 0x17f
	global_store_dwordx2 v[6:7], v[4:5], off offset:112 sc1
	s_cbranch_scc1 .LBB0_505

.LBB0_508:
	s_or_b64 exec, exec, s[10:11]
	v_cvt_f32_i32_e32 v11, v12
	v_sub_f32_e32 v8, v82, v41
	v_cmp_lt_i32_e64 s[10:11], v223, v222
	v_lshlrev_b32_e32 v16, 1, v38
	v_rcp_iflag_f32_e32 v11, v11
	s_nop 0
	v_fma_f32 v8, v9, v11, -v8
	v_ashrrev_i32_e32 v11, 31, v10
	v_cvt_pk_bf16_f32 v12, v8, s0
	v_lshlrev_b64 v[8:9], 11, v[10:11]
	v_lshl_add_u64 v[6:7], v[6:7], 0, v[8:9]
	global_store_short v[6:7], v12, off sc1
	v_cndmask_b32_e64 v6, v221, v223, s[10:11]
	v_cmp_lt_i32_e64 s[10:11], v224, v222
	v_lshlrev_b32_e32 v22, 2, v6
	s_waitcnt lgkmcnt(0)
	s_barrier
	v_cndmask_b32_e64 v6, v221, v224, s[10:11]
	v_cmp_lt_i32_e64 s[10:11], v225, v222
	v_lshlrev_b32_e32 v21, 2, v6
	s_nop 0
	v_cndmask_b32_e64 v6, v221, v225, s[10:11]
	v_cmp_lt_i32_e64 s[10:11], v226, v222
	v_lshlrev_b32_e32 v20, 2, v6
	s_nop 0
	v_cndmask_b32_e64 v6, v221, v226, s[10:11]
	v_cmp_lt_i32_e64 s[10:11], v227, v222
	v_lshlrev_b32_e32 v19, 2, v6
	s_nop 0
	v_cndmask_b32_e64 v6, v221, v227, s[10:11]
	v_cmp_lt_i32_e64 s[10:11], v228, v222
	v_lshlrev_b32_e32 v18, 2, v6
	s_nop 0
	v_cndmask_b32_e64 v6, v221, v228, s[10:11]
	v_lshlrev_b32_e32 v17, 2, v6
	v_add_u32_e32 v6, s44, v56
	ds_read_b128 v[10:13], v6 offset:56320
	s_add_i32 s10, s66, s41
	s_ashr_i32 s11, s10, 31
	s_lshl_b64 s[10:11], s[10:11], 11
	s_add_u32 s50, s42, s10
	s_waitcnt lgkmcnt(0)
	v_pk_mul_f32 v[6:7], v[12:13], v[12:13]
	v_pk_mul_f32 v[8:9], v[10:11], v[10:11]
	s_addc_u32 s51, s43, s11
	v_pk_mov_b32 v[14:15], v[8:9], v[6:7] op_sel:[1,0]
	v_mov_b32_e32 v9, v7
	v_add_u32_e32 v6, s46, v56
	v_pk_add_f32 v[14:15], v[14:15], v[8:9]
	ds_read_b128 v[6:9], v6 offset:56320
	s_waitcnt lgkmcnt(0)
	v_pk_mul_f32 v[24:25], v[8:9], v[8:9]
	v_pk_mul_f32 v[26:27], v[6:7], v[6:7]
	s_nop 0
	v_pk_mov_b32 v[28:29], v[26:27], v[24:25] op_sel:[1,0]
	v_mov_b32_e32 v27, v25
	v_pk_add_f32 v[24:25], v[28:29], v[26:27]
	v_mov_b32_e32 v27, v14
	v_mov_b32_e32 v26, v24
	v_mov_b32_e32 v14, v25
	v_pk_add_f32 v[14:15], v[26:27], v[14:15]
	ds_bpermute_b32 v25, v22, v15
	ds_bpermute_b32 v24, v22, v14
	s_waitcnt lgkmcnt(0)
	v_pk_add_f32 v[14:15], v[14:15], v[24:25]
	ds_bpermute_b32 v25, v21, v15
	ds_bpermute_b32 v24, v21, v14
	s_waitcnt lgkmcnt(0)
	v_pk_add_f32 v[14:15], v[14:15], v[24:25]
	ds_bpermute_b32 v25, v20, v15
	ds_bpermute_b32 v24, v20, v14
	s_waitcnt lgkmcnt(0)
	v_pk_add_f32 v[14:15], v[14:15], v[24:25]
	ds_bpermute_b32 v25, v19, v15
	ds_bpermute_b32 v24, v19, v14
	s_waitcnt lgkmcnt(0)
	v_pk_add_f32 v[14:15], v[14:15], v[24:25]
	ds_bpermute_b32 v25, v18, v15
	ds_bpermute_b32 v24, v18, v14
	s_waitcnt lgkmcnt(0)
	v_pk_add_f32 v[14:15], v[14:15], v[24:25]
	ds_bpermute_b32 v25, v17, v15
	ds_bpermute_b32 v24, v17, v14
	s_waitcnt lgkmcnt(0)
	v_pk_add_f32 v[24:25], v[14:15], v[24:25]
	v_mov_b64_e32 v[14:15], s[34:35]
	v_pk_fma_f32 v[24:25], v[24:25], s[80:81], v[14:15] op_sel_hi:[1,0,0]
	s_nop 0
	v_mul_f32_e32 v23, 0x4b800000, v25
	v_cmp_gt_f32_e64 s[14:15], s92, v25
	v_cmp_gt_f32_e64 s[10:11], s92, v24
	s_nop 0
	v_cndmask_b32_e64 v23, v25, v23, s[14:15]
	v_rsq_f32_e32 v23, v23
	s_nop 0
	v_mul_f32_e32 v25, 0x45800000, v23
	v_cndmask_b32_e64 v26, v23, v25, s[14:15]
	v_pk_mul_f32 v[10:11], v[10:11], v[26:27] op_sel_hi:[1,0]
	v_pk_mul_f32 v[12:13], v[12:13], v[26:27] op_sel_hi:[1,0]
	v_pk_mul_f32 v[10:11], v[2:3], v[10:11]
	v_pk_mul_f32 v[12:13], v[4:5], v[12:13]
	v_mul_f32_e32 v23, 0xbfb8aa3b, v10
	v_exp_f32_e32 v23, v23
	s_nop 0
	v_add_f32_e32 v23, 1.0, v23
	v_rcp_f32_e32 v26, v23
	v_mul_f32_e32 v23, 0xbfb8aa3b, v11
	v_exp_f32_e32 v23, v23
	s_nop 0
	v_add_f32_e32 v23, 1.0, v23
	v_rcp_f32_e32 v27, v23
	v_mul_f32_e32 v23, 0xbfb8aa3b, v12
	v_exp_f32_e32 v23, v23
	v_pk_mul_f32 v[10:11], v[10:11], v[26:27]
	s_nop 0
	v_cvt_pk_bf16_f32 v10, v10, v11
	v_add_f32_e32 v23, 1.0, v23
	v_rcp_f32_e32 v26, v23
	v_mul_f32_e32 v23, 0xbfb8aa3b, v13
	v_exp_f32_e32 v23, v23
	s_nop 0
	v_add_f32_e32 v23, 1.0, v23
	v_rcp_f32_e32 v27, v23
	s_nop 0
	v_pk_mul_f32 v[12:13], v[12:13], v[26:27]
	s_nop 0
	v_cvt_pk_bf16_f32 v11, v12, v13
	global_store_dwordx2 v16, v[10:11], s[50:51] offset:512 sc1
	v_mul_f32_e32 v10, 0x4b800000, v24
	v_cndmask_b32_e64 v10, v24, v10, s[10:11]
	v_rsq_f32_e32 v10, v10
	s_nop 0
	v_mul_f32_e32 v11, 0x45800000, v10
	v_cndmask_b32_e64 v10, v10, v11, s[10:11]
	v_pk_mul_f32 v[6:7], v[6:7], v[10:11] op_sel_hi:[1,0]
	v_pk_mul_f32 v[8:9], v[8:9], v[10:11] op_sel_hi:[1,0]
	v_pk_mul_f32 v[6:7], v[2:3], v[6:7]
	v_pk_mul_f32 v[8:9], v[4:5], v[8:9]
	v_mul_f32_e32 v10, 0xbfb8aa3b, v6
	v_mul_f32_e32 v11, 0xbfb8aa3b, v7
	v_exp_f32_e32 v10, v10
	v_exp_f32_e32 v11, v11
	s_add_i32 s10, s66, s45
	s_ashr_i32 s11, s10, 31
	v_add_f32_e32 v10, 1.0, v10
	v_add_f32_e32 v11, 1.0, v11
	v_rcp_f32_e32 v10, v10
	v_rcp_f32_e32 v11, v11
	s_lshl_b64 s[10:11], s[10:11], 11
	s_add_u32 s10, s42, s10
	s_addc_u32 s11, s43, s11
	v_pk_mul_f32 v[6:7], v[6:7], v[10:11]
	v_mul_f32_e32 v10, 0xbfb8aa3b, v8
	v_mul_f32_e32 v11, 0xbfb8aa3b, v9
	v_exp_f32_e32 v10, v10
	v_exp_f32_e32 v11, v11
	v_cvt_pk_bf16_f32 v6, v6, v7
	v_add_f32_e32 v10, 1.0, v10
	v_add_f32_e32 v11, 1.0, v11
	v_rcp_f32_e32 v10, v10
	v_rcp_f32_e32 v11, v11
	s_nop 0
	v_pk_mul_f32 v[8:9], v[8:9], v[10:11]
	s_nop 0
	v_cvt_pk_bf16_f32 v7, v8, v9
	global_store_dwordx2 v16, v[6:7], s[10:11] offset:512 sc1
	v_add_u32_e32 v6, s59, v56
	ds_read_b128 v[10:13], v6 offset:56320
	s_add_i32 s10, s66, s58
	s_ashr_i32 s11, s10, 31
	s_lshl_b64 s[10:11], s[10:11], 11
	s_add_u32 s50, s42, s10
	s_waitcnt lgkmcnt(0)
	v_pk_mul_f32 v[6:7], v[12:13], v[12:13]
	v_pk_mul_f32 v[8:9], v[10:11], v[10:11]
	s_addc_u32 s51, s43, s11
	v_pk_mov_b32 v[24:25], v[8:9], v[6:7] op_sel:[1,0]
	v_mov_b32_e32 v9, v7
	v_add_u32_e32 v6, s61, v56
	v_pk_add_f32 v[24:25], v[24:25], v[8:9]
	ds_read_b128 v[6:9], v6 offset:56320
	s_waitcnt lgkmcnt(0)
	v_pk_mul_f32 v[26:27], v[8:9], v[8:9]
	v_pk_mul_f32 v[28:29], v[6:7], v[6:7]
	s_nop 0
	v_pk_mov_b32 v[30:31], v[28:29], v[26:27] op_sel:[1,0]
	v_mov_b32_e32 v29, v27
	v_pk_add_f32 v[26:27], v[30:31], v[28:29]
	v_mov_b32_e32 v29, v24
	v_mov_b32_e32 v28, v26
	v_mov_b32_e32 v24, v27
	v_pk_add_f32 v[24:25], v[28:29], v[24:25]
	ds_bpermute_b32 v23, v22, v25
	ds_bpermute_b32 v22, v22, v24
	s_waitcnt lgkmcnt(0)
	v_pk_add_f32 v[22:23], v[24:25], v[22:23]
	ds_bpermute_b32 v25, v21, v23
	ds_bpermute_b32 v24, v21, v22
	s_waitcnt lgkmcnt(0)
	v_pk_add_f32 v[22:23], v[22:23], v[24:25]
	ds_bpermute_b32 v21, v20, v23
	ds_bpermute_b32 v20, v20, v22
	s_waitcnt lgkmcnt(0)
	v_pk_add_f32 v[20:21], v[22:23], v[20:21]
	ds_bpermute_b32 v23, v19, v21
	ds_bpermute_b32 v22, v19, v20
	s_waitcnt lgkmcnt(0)
	v_pk_add_f32 v[20:21], v[20:21], v[22:23]
	ds_bpermute_b32 v19, v18, v21
	ds_bpermute_b32 v18, v18, v20
	s_waitcnt lgkmcnt(0)
	v_pk_add_f32 v[18:19], v[20:21], v[18:19]
	ds_bpermute_b32 v21, v17, v19
	ds_bpermute_b32 v20, v17, v18
	s_waitcnt lgkmcnt(0)
	v_pk_add_f32 v[18:19], v[18:19], v[20:21]
	s_nop 0
	v_pk_fma_f32 v[14:15], v[18:19], s[80:81], v[14:15] op_sel_hi:[1,0,0]
	s_nop 0
	v_mul_f32_e32 v17, 0x4b800000, v15
	v_cmp_gt_f32_e64 s[14:15], s92, v15
	v_cmp_gt_f32_e64 s[10:11], s92, v14
	s_nop 0
	v_cndmask_b32_e64 v15, v15, v17, s[14:15]
	v_rsq_f32_e32 v15, v15
	s_nop 0
	v_mul_f32_e32 v17, 0x45800000, v15
	v_cndmask_b32_e64 v18, v15, v17, s[14:15]
	v_pk_mul_f32 v[10:11], v[10:11], v[18:19] op_sel_hi:[1,0]
	v_pk_mul_f32 v[12:13], v[12:13], v[18:19] op_sel_hi:[1,0]
	v_pk_mul_f32 v[10:11], v[2:3], v[10:11]
	v_pk_mul_f32 v[12:13], v[4:5], v[12:13]
	v_mul_f32_e32 v15, 0xbfb8aa3b, v10
	v_exp_f32_e32 v15, v15
	s_nop 0
	v_add_f32_e32 v15, 1.0, v15
	v_rcp_f32_e32 v18, v15
	v_mul_f32_e32 v15, 0xbfb8aa3b, v11
	v_exp_f32_e32 v15, v15
	s_nop 0
	v_add_f32_e32 v15, 1.0, v15
	v_rcp_f32_e32 v19, v15
	v_mul_f32_e32 v15, 0xbfb8aa3b, v12
	v_exp_f32_e32 v15, v15
	v_pk_mul_f32 v[10:11], v[10:11], v[18:19]
	s_nop 0
	v_cvt_pk_bf16_f32 v10, v10, v11
	v_add_f32_e32 v15, 1.0, v15
	v_rcp_f32_e32 v18, v15
	v_mul_f32_e32 v15, 0xbfb8aa3b, v13
	v_exp_f32_e32 v15, v15
	s_nop 0
	v_add_f32_e32 v15, 1.0, v15
	v_rcp_f32_e32 v19, v15
	s_nop 0
	v_pk_mul_f32 v[12:13], v[12:13], v[18:19]
	s_nop 0
	v_cvt_pk_bf16_f32 v11, v12, v13
	global_store_dwordx2 v16, v[10:11], s[50:51] offset:512 sc1
	v_mul_f32_e32 v10, 0x4b800000, v14
	v_cndmask_b32_e64 v10, v14, v10, s[10:11]
	v_rsq_f32_e32 v10, v10
	s_nop 0
	v_mul_f32_e32 v11, 0x45800000, v10
	v_cndmask_b32_e64 v10, v10, v11, s[10:11]
	v_pk_mul_f32 v[6:7], v[6:7], v[10:11] op_sel_hi:[1,0]
	v_pk_mul_f32 v[8:9], v[8:9], v[10:11] op_sel_hi:[1,0]
	v_pk_mul_f32 v[2:3], v[2:3], v[6:7]
	v_pk_mul_f32 v[4:5], v[4:5], v[8:9]
	v_mul_f32_e32 v6, 0xbfb8aa3b, v2
	v_mul_f32_e32 v7, 0xbfb8aa3b, v3
	v_exp_f32_e32 v6, v6
	v_exp_f32_e32 v7, v7
	s_add_i32 s10, s66, s60
	s_ashr_i32 s11, s10, 31
	v_add_f32_e32 v6, 1.0, v6
	v_add_f32_e32 v7, 1.0, v7
	v_rcp_f32_e32 v6, v6
	v_rcp_f32_e32 v7, v7
	s_lshl_b64 s[10:11], s[10:11], 11
	s_add_u32 s10, s42, s10
	s_addc_u32 s11, s43, s11
	v_pk_mul_f32 v[2:3], v[2:3], v[6:7]
	v_mul_f32_e32 v6, 0xbfb8aa3b, v4
	v_mul_f32_e32 v7, 0xbfb8aa3b, v5
	v_exp_f32_e32 v6, v6
	v_exp_f32_e32 v7, v7
	s_add_i32 s65, s65, s16
	v_cvt_pk_bf16_f32 v2, v2, v3
	v_add_f32_e32 v6, 1.0, v6
	v_add_f32_e32 v7, 1.0, v7
	v_rcp_f32_e32 v6, v6
	v_rcp_f32_e32 v7, v7
	s_cmpk_gt_i32 s65, 0x2ff
	v_pk_mul_f32 v[4:5], v[4:5], v[6:7]
	s_nop 0
	v_cvt_pk_bf16_f32 v3, v4, v5
	global_store_dwordx2 v16, v[2:3], s[10:11] offset:512 sc1
	s_cbranch_scc1 .LBB0_545

.LBB0_531:
	s_or_b64 exec, exec, s[10:11]
	s_add_u32 s42, s42, 0xbc00000
	s_addc_u32 s43, s43, 0
	s_add_u32 s10, s3, s40
	s_waitcnt vmcnt(2)
	ds_write_b128 v61, v[26:29] offset:31744
	ds_write_b128 v61, v[22:25] offset:39936
	ds_write_b128 v61, v[30:33] offset:48128
	s_addc_u32 s11, s1, 0
	s_waitcnt lgkmcnt(0)
	s_barrier
	global_load_dword v46, v40, s[10:11]
	global_load_dword v45, v40, s[10:11] offset:1024
	v_mov_b32_e32 v41, v0
	v_lshl_add_u64 v[8:9], s[10:11], 0, v[40:41]
	s_movk_i32 s0, 0x1000
	global_load_dword v44, v40, s[10:11] offset:2048
	global_load_dword v41, v40, s[10:11] offset:3072
	v_add_co_u32_e64 v10, s[10:11], s0, v8
	s_movk_i32 s0, 0x2000
	s_nop 0
	v_addc_co_u32_e64 v11, s[10:11], 0, v9, s[10:11]
	v_add_co_u32_e64 v12, s[10:11], s0, v8
	s_movk_i32 s0, 0x3000
	s_nop 0
	v_addc_co_u32_e64 v13, s[10:11], 0, v9, s[10:11]
	global_load_dword v43, v[12:13], off offset:-4096
	global_load_dword v33, v[10:11], off offset:1024
	global_load_dword v32, v[10:11], off offset:2048
	global_load_dword v31, v[10:11], off offset:3072
	v_add_co_u32_e64 v10, s[10:11], s0, v8
	s_movk_i32 s0, 0x4000
	s_nop 0
	v_addc_co_u32_e64 v11, s[10:11], 0, v9, s[10:11]
	v_add_co_u32_e64 v18, s[10:11], s0, v8
	s_movk_i32 s0, 0x5000
	s_nop 0
	v_addc_co_u32_e64 v19, s[10:11], 0, v9, s[10:11]
	global_load_dword v30, v[12:13], off
	global_load_dword v29, v[12:13], off offset:1024
	global_load_dword v28, v[12:13], off offset:2048
	global_load_dword v27, v[12:13], off offset:3072
	global_load_dword v26, v[18:19], off offset:-4096
	global_load_dword v22, v[18:19], off
	global_load_dword v20, v[18:19], off offset:1024
	v_add_co_u32_e64 v70, s[10:11], s0, v8
	s_movk_i32 s0, 0x6000
	s_nop 0
	v_addc_co_u32_e64 v71, s[10:11], 0, v9, s[10:11]
	v_add_co_u32_e64 v72, s[10:11], s0, v8
	s_movk_i32 s0, 0x7000
	s_nop 0
	v_addc_co_u32_e64 v73, s[10:11], 0, v9, s[10:11]
	global_load_dword v25, v[10:11], off offset:1024
	global_load_dword v24, v[10:11], off offset:2048
	global_load_dword v23, v[10:11], off offset:3072
	global_load_dword v17, v[70:71], off offset:1024
	global_load_dword v15, v[70:71], off offset:2048
	global_load_dword v21, v[18:19], off offset:2048
	s_nop 0
	global_load_dword v19, v[18:19], off offset:3072
	s_nop 0
	global_load_dword v18, v[72:73], off offset:-4096
	global_load_dword v14, v[72:73], off
	global_load_dword v13, v[72:73], off offset:1024
	global_load_dword v12, v[72:73], off offset:2048
	global_load_dword v10, v[72:73], off offset:3072
	v_add_co_u32_e64 v72, s[10:11], s0, v8
	v_lshlrev_b32_e32 v6, 1, v34
	s_nop 0
	v_addc_co_u32_e64 v73, s[10:11], 0, v9, s[10:11]
	global_load_dword v16, v[70:71], off offset:3072
	global_load_dword v11, v[72:73], off
	global_load_dword v9, v[72:73], off offset:1024
	global_load_dword v8, v[72:73], off offset:2048
	ds_read_u16 v47, v53
	ds_read_u16 v70, v53 offset:512
	ds_read_u16 v71, v53 offset:40960
	ds_read_u16 v72, v53 offset:41472
	ds_read_u16 v88, v53 offset:41984
	ds_read_u16 v89, v53 offset:42496
	ds_read_u16 v90, v53 offset:43008
	ds_read_u16 v82, v53 offset:43520
	s_waitcnt lgkmcnt(7)
	v_lshlrev_b32_e32 v47, 16, v47
	s_waitcnt lgkmcnt(6)
	v_lshlrev_b32_e32 v70, 16, v70
	ds_read_u16 v73, v53 offset:1024
	ds_read_u16 v74, v53 offset:1536
	ds_read_u16 v75, v53 offset:2048
	ds_read_u16 v76, v53 offset:2560
	ds_read_u16 v77, v53 offset:3072
	ds_read_u16 v78, v53 offset:3584
	ds_read_u16 v79, v53 offset:4096
	ds_read_u16 v80, v53 offset:4608
	s_waitcnt lgkmcnt(7)
	v_lshlrev_b32_e32 v73, 16, v73
	s_waitcnt lgkmcnt(6)
	v_lshlrev_b32_e32 v74, 16, v74
	s_waitcnt lgkmcnt(5)
	v_lshlrev_b32_e32 v75, 16, v75
	s_waitcnt lgkmcnt(4)
	v_lshlrev_b32_e32 v76, 16, v76
	s_waitcnt lgkmcnt(3)
	v_lshlrev_b32_e32 v77, 16, v77
	s_waitcnt lgkmcnt(2)
	v_lshlrev_b32_e32 v78, 16, v78
	s_waitcnt lgkmcnt(1)
	v_lshlrev_b32_e32 v79, 16, v79
	s_waitcnt lgkmcnt(0)
	v_lshlrev_b32_e32 v80, 16, v80
	ds_read_u16 v81, v53 offset:5120
	ds_read_u16 v83, v53 offset:5632
	ds_read_u16 v84, v53 offset:6144
	ds_read_u16 v85, v53 offset:6656
	ds_read_u16 v86, v53 offset:7168
	ds_read_u16 v87, v53 offset:7680
	ds_read_u16 v91, v53 offset:8192
	ds_read_u16 v92, v53 offset:8704
	s_waitcnt lgkmcnt(7)
	v_lshlrev_b32_e32 v81, 16, v81
	s_waitcnt lgkmcnt(6)
	v_lshlrev_b32_e32 v83, 16, v83
	s_waitcnt lgkmcnt(5)
	v_lshlrev_b32_e32 v84, 16, v84
	s_waitcnt lgkmcnt(4)
	v_lshlrev_b32_e32 v85, 16, v85
	s_waitcnt lgkmcnt(3)
	v_lshlrev_b32_e32 v86, 16, v86
	s_waitcnt lgkmcnt(2)
	v_lshlrev_b32_e32 v87, 16, v87
	v_mov_b32_e32 v7, v0
	v_lshl_add_u64 v[6:7], s[42:43], 0, v[6:7]
	s_waitcnt vmcnt(30)
	v_fma_f32 v47, v46, v47, v42
	s_waitcnt vmcnt(29)
	v_fmac_f32_e32 v47, v45, v70
	v_fma_f32 v70, v46, v70, v42
	v_fmac_f32_e32 v70, v45, v73
	s_waitcnt vmcnt(28)
	v_fmac_f32_e32 v47, v44, v73
	v_fma_f32 v73, v46, v73, v42
	s_waitcnt vmcnt(27)
	v_fmac_f32_e32 v47, v41, v74
	v_fmac_f32_e32 v70, v44, v74
	v_fmac_f32_e32 v73, v45, v74
	v_fma_f32 v74, v46, v74, v42
	v_fmac_f32_e32 v70, v41, v75
	v_fmac_f32_e32 v73, v44, v75
	v_fmac_f32_e32 v74, v45, v75
	s_waitcnt vmcnt(26)
	v_fmac_f32_e32 v47, v43, v75
	v_fma_f32 v75, v46, v75, v42
	s_waitcnt vmcnt(25)
	v_fmac_f32_e32 v47, v33, v76
	v_fmac_f32_e32 v70, v43, v76
	v_fmac_f32_e32 v73, v41, v76
	v_fmac_f32_e32 v74, v44, v76
	v_fmac_f32_e32 v75, v45, v76
	v_fma_f32 v76, v46, v76, v42
	s_waitcnt vmcnt(24)
	v_fmac_f32_e32 v47, v32, v77
	v_fmac_f32_e32 v70, v33, v77
	v_fmac_f32_e32 v73, v43, v77
	v_fmac_f32_e32 v74, v41, v77
	v_fmac_f32_e32 v75, v44, v77
	v_fmac_f32_e32 v76, v45, v77
	v_fma_f32 v77, v46, v77, v42
	s_waitcnt vmcnt(23)
	v_fmac_f32_e32 v47, v31, v78
	v_fmac_f32_e32 v70, v32, v78
	v_fmac_f32_e32 v73, v33, v78
	v_fmac_f32_e32 v74, v43, v78
	v_fmac_f32_e32 v75, v41, v78
	v_fmac_f32_e32 v76, v44, v78
	v_fmac_f32_e32 v77, v45, v78
	v_fma_f32 v78, v46, v78, v42
	s_waitcnt vmcnt(22)
	v_fmac_f32_e32 v47, v30, v79
	v_fmac_f32_e32 v70, v31, v79
	v_fmac_f32_e32 v73, v32, v79
	v_fmac_f32_e32 v74, v33, v79
	v_fmac_f32_e32 v75, v43, v79
	v_fmac_f32_e32 v76, v41, v79
	v_fmac_f32_e32 v77, v44, v79
	v_fmac_f32_e32 v78, v45, v79
	v_fma_f32 v79, v46, v79, v42
	s_waitcnt vmcnt(21)
	v_fmac_f32_e32 v47, v29, v80
	v_fmac_f32_e32 v70, v30, v80
	v_fmac_f32_e32 v73, v31, v80
	v_fmac_f32_e32 v74, v32, v80
	v_fmac_f32_e32 v75, v33, v80
	v_fmac_f32_e32 v76, v43, v80
	v_fmac_f32_e32 v77, v41, v80
	v_fmac_f32_e32 v78, v44, v80
	v_fmac_f32_e32 v79, v45, v80
	v_fma_f32 v80, v46, v80, v42
	s_waitcnt vmcnt(20)
	v_fmac_f32_e32 v47, v28, v81
	v_fmac_f32_e32 v70, v29, v81
	v_fmac_f32_e32 v73, v30, v81
	v_fmac_f32_e32 v74, v31, v81
	v_fmac_f32_e32 v75, v32, v81
	v_fmac_f32_e32 v76, v33, v81
	v_fmac_f32_e32 v77, v43, v81
	v_fmac_f32_e32 v78, v41, v81
	v_fmac_f32_e32 v79, v44, v81
	v_fmac_f32_e32 v80, v45, v81
	v_fma_f32 v81, v46, v81, v42
	s_waitcnt vmcnt(19)
	v_fmac_f32_e32 v47, v27, v83
	v_fmac_f32_e32 v70, v28, v83
	v_fmac_f32_e32 v73, v29, v83
	v_fmac_f32_e32 v74, v30, v83
	v_fmac_f32_e32 v75, v31, v83
	v_fmac_f32_e32 v76, v32, v83
	v_fmac_f32_e32 v77, v33, v83
	v_fmac_f32_e32 v78, v43, v83
	v_fmac_f32_e32 v79, v41, v83
	v_fmac_f32_e32 v80, v44, v83
	v_fmac_f32_e32 v81, v45, v83
	v_fma_f32 v83, v46, v83, v42
	s_waitcnt vmcnt(18)
	v_fmac_f32_e32 v47, v26, v84
	v_fmac_f32_e32 v70, v27, v84
	v_fmac_f32_e32 v73, v28, v84
	v_fmac_f32_e32 v74, v29, v84
	v_fmac_f32_e32 v75, v30, v84
	v_fmac_f32_e32 v76, v31, v84
	v_fmac_f32_e32 v77, v32, v84
	v_fmac_f32_e32 v78, v33, v84
	v_fmac_f32_e32 v79, v43, v84
	v_fmac_f32_e32 v80, v41, v84
	v_fmac_f32_e32 v81, v44, v84
	v_fmac_f32_e32 v83, v45, v84
	v_fma_f32 v84, v46, v84, v42
	s_waitcnt vmcnt(15)
	v_fmac_f32_e32 v47, v25, v85
	v_fmac_f32_e32 v70, v26, v85
	v_fmac_f32_e32 v73, v27, v85
	v_fmac_f32_e32 v74, v28, v85
	v_fmac_f32_e32 v75, v29, v85
	v_fmac_f32_e32 v76, v30, v85
	v_fmac_f32_e32 v77, v31, v85
	v_fmac_f32_e32 v78, v32, v85
	v_fmac_f32_e32 v79, v33, v85
	v_fmac_f32_e32 v80, v43, v85
	v_fmac_f32_e32 v81, v41, v85
	v_fmac_f32_e32 v83, v44, v85
	v_fmac_f32_e32 v84, v45, v85
	v_fma_f32 v85, v46, v85, v42
	s_waitcnt vmcnt(14)
	v_fmac_f32_e32 v47, v24, v86
	v_fmac_f32_e32 v70, v25, v86
	v_fmac_f32_e32 v73, v26, v86
	v_fmac_f32_e32 v74, v27, v86
	v_fmac_f32_e32 v75, v28, v86
	v_fmac_f32_e32 v76, v29, v86
	v_fmac_f32_e32 v77, v30, v86
	v_fmac_f32_e32 v78, v31, v86
	v_fmac_f32_e32 v79, v32, v86
	v_fmac_f32_e32 v80, v33, v86
	v_fmac_f32_e32 v81, v43, v86
	v_fmac_f32_e32 v83, v41, v86
	v_fmac_f32_e32 v84, v44, v86
	v_fmac_f32_e32 v85, v45, v86
	v_fma_f32 v86, v46, v86, v42
	s_waitcnt vmcnt(13)
	v_fmac_f32_e32 v47, v23, v87
	v_fmac_f32_e32 v70, v24, v87
	v_fmac_f32_e32 v73, v25, v87
	v_fmac_f32_e32 v74, v26, v87
	v_fmac_f32_e32 v75, v27, v87
	v_fmac_f32_e32 v76, v28, v87
	v_fmac_f32_e32 v77, v29, v87
	v_fmac_f32_e32 v78, v30, v87
	v_fmac_f32_e32 v79, v31, v87
	v_fmac_f32_e32 v80, v32, v87
	v_fmac_f32_e32 v81, v33, v87
	v_fmac_f32_e32 v83, v43, v87
	v_fmac_f32_e32 v84, v41, v87
	v_fmac_f32_e32 v85, v44, v87
	v_fmac_f32_e32 v86, v45, v87
	v_fmac_f32_e32 v42, v46, v87
	s_waitcnt lgkmcnt(1)
	v_lshlrev_b32_e32 v46, 16, v91
	v_fmac_f32_e32 v47, v22, v46
	v_fmac_f32_e32 v70, v23, v46
	v_fmac_f32_e32 v73, v24, v46
	v_fmac_f32_e32 v74, v25, v46
	v_fmac_f32_e32 v75, v26, v46
	v_fmac_f32_e32 v76, v27, v46
	v_fmac_f32_e32 v77, v28, v46
	v_fmac_f32_e32 v78, v29, v46
	v_fmac_f32_e32 v79, v30, v46
	v_fmac_f32_e32 v80, v31, v46
	v_fmac_f32_e32 v81, v32, v46
	v_fmac_f32_e32 v83, v33, v46
	v_fmac_f32_e32 v84, v43, v46
	v_fmac_f32_e32 v85, v41, v46
	v_fmac_f32_e32 v86, v44, v46
	v_fmac_f32_e32 v42, v45, v46
	s_waitcnt lgkmcnt(0)
	v_lshlrev_b32_e32 v45, 16, v92
	v_fmac_f32_e32 v47, v20, v45
	v_fmac_f32_e32 v70, v22, v45
	v_fmac_f32_e32 v73, v23, v45
	v_fmac_f32_e32 v74, v24, v45
	v_fmac_f32_e32 v75, v25, v45
	v_fmac_f32_e32 v76, v26, v45
	v_fmac_f32_e32 v77, v27, v45
	v_fmac_f32_e32 v78, v28, v45
	v_fmac_f32_e32 v79, v29, v45
	v_fmac_f32_e32 v80, v30, v45
	v_fmac_f32_e32 v81, v31, v45
	v_fmac_f32_e32 v83, v32, v45
	v_fmac_f32_e32 v84, v33, v45
	v_fmac_f32_e32 v85, v43, v45
	v_fmac_f32_e32 v86, v41, v45
	v_fmac_f32_e32 v42, v44, v45
	ds_read_u16 v44, v53 offset:9216
	ds_read_u16 v45, v53 offset:9728
	ds_read_u16 v46, v53 offset:10240
	ds_read_u16 v87, v53 offset:10752
	ds_read_u16 v91, v53 offset:11264
	ds_read_u16 v92, v53 offset:11776
	ds_read_u16 v93, v53 offset:12288
	ds_read_u16 v94, v53 offset:12800
	s_waitcnt lgkmcnt(7)
	v_lshlrev_b32_e32 v44, 16, v44
	s_waitcnt vmcnt(10)
	v_fmac_f32_e32 v47, v21, v44
	v_fmac_f32_e32 v70, v20, v44
	v_fmac_f32_e32 v73, v22, v44
	v_fmac_f32_e32 v74, v23, v44
	v_fmac_f32_e32 v75, v24, v44
	v_fmac_f32_e32 v76, v25, v44
	v_fmac_f32_e32 v77, v26, v44
	v_fmac_f32_e32 v78, v27, v44
	v_fmac_f32_e32 v79, v28, v44
	v_fmac_f32_e32 v80, v29, v44
	v_fmac_f32_e32 v81, v30, v44
	v_fmac_f32_e32 v83, v31, v44
	v_fmac_f32_e32 v84, v32, v44
	v_fmac_f32_e32 v85, v33, v44
	v_fmac_f32_e32 v86, v43, v44
	v_fmac_f32_e32 v42, v41, v44
	s_waitcnt lgkmcnt(6)
	v_lshlrev_b32_e32 v41, 16, v45
	s_waitcnt vmcnt(9)
	v_fmac_f32_e32 v47, v19, v41
	v_fmac_f32_e32 v70, v21, v41
	v_fmac_f32_e32 v73, v20, v41
	v_fmac_f32_e32 v74, v22, v41
	v_fmac_f32_e32 v75, v23, v41
	v_fmac_f32_e32 v76, v24, v41
	v_fmac_f32_e32 v77, v25, v41
	v_fmac_f32_e32 v78, v26, v41
	v_fmac_f32_e32 v79, v27, v41
	v_fmac_f32_e32 v80, v28, v41
	v_fmac_f32_e32 v81, v29, v41
	v_fmac_f32_e32 v83, v30, v41
	v_fmac_f32_e32 v84, v31, v41
	v_fmac_f32_e32 v85, v32, v41
	v_fmac_f32_e32 v86, v33, v41
	v_fmac_f32_e32 v42, v43, v41
	s_waitcnt lgkmcnt(5)
	v_lshlrev_b32_e32 v41, 16, v46
	s_waitcnt vmcnt(8)
	v_fmac_f32_e32 v47, v18, v41
	v_fmac_f32_e32 v70, v19, v41
	v_fmac_f32_e32 v73, v21, v41
	v_fmac_f32_e32 v74, v20, v41
	v_fmac_f32_e32 v75, v22, v41
	v_fmac_f32_e32 v76, v23, v41
	v_fmac_f32_e32 v77, v24, v41
	v_fmac_f32_e32 v78, v25, v41
	v_fmac_f32_e32 v79, v26, v41
	v_fmac_f32_e32 v80, v27, v41
	v_fmac_f32_e32 v81, v28, v41
	v_fmac_f32_e32 v83, v29, v41
	v_fmac_f32_e32 v84, v30, v41
	v_fmac_f32_e32 v85, v31, v41
	v_fmac_f32_e32 v86, v32, v41
	v_fmac_f32_e32 v42, v33, v41
	s_waitcnt lgkmcnt(4)
	v_lshlrev_b32_e32 v33, 16, v87
	v_fmac_f32_e32 v47, v17, v33
	v_fmac_f32_e32 v70, v18, v33
	v_fmac_f32_e32 v73, v19, v33
	v_fmac_f32_e32 v74, v21, v33
	v_fmac_f32_e32 v75, v20, v33
	v_fmac_f32_e32 v76, v22, v33
	v_fmac_f32_e32 v77, v23, v33
	v_fmac_f32_e32 v78, v24, v33
	v_fmac_f32_e32 v79, v25, v33
	v_fmac_f32_e32 v80, v26, v33
	v_fmac_f32_e32 v81, v27, v33
	v_fmac_f32_e32 v83, v28, v33
	v_fmac_f32_e32 v84, v29, v33
	v_fmac_f32_e32 v85, v30, v33
	v_fmac_f32_e32 v86, v31, v33
	v_fmac_f32_e32 v42, v32, v33
	s_waitcnt lgkmcnt(3)
	v_lshlrev_b32_e32 v32, 16, v91
	v_fmac_f32_e32 v47, v15, v32
	v_fmac_f32_e32 v70, v17, v32
	v_fmac_f32_e32 v73, v18, v32
	v_fmac_f32_e32 v74, v19, v32
	v_fmac_f32_e32 v75, v21, v32
	v_fmac_f32_e32 v76, v20, v32
	v_fmac_f32_e32 v77, v22, v32
	v_fmac_f32_e32 v78, v23, v32
	v_fmac_f32_e32 v79, v24, v32
	v_fmac_f32_e32 v80, v25, v32
	v_fmac_f32_e32 v81, v26, v32
	v_fmac_f32_e32 v83, v27, v32
	v_fmac_f32_e32 v84, v28, v32
	v_fmac_f32_e32 v85, v29, v32
	v_fmac_f32_e32 v86, v30, v32
	v_fmac_f32_e32 v42, v31, v32
	s_waitcnt lgkmcnt(2)
	v_lshlrev_b32_e32 v31, 16, v92
	s_waitcnt vmcnt(3)
	v_fmac_f32_e32 v47, v16, v31
	v_fmac_f32_e32 v70, v15, v31
	v_fmac_f32_e32 v73, v17, v31
	v_fmac_f32_e32 v74, v18, v31
	v_fmac_f32_e32 v75, v19, v31
	v_fmac_f32_e32 v76, v21, v31
	v_fmac_f32_e32 v77, v20, v31
	v_fmac_f32_e32 v78, v22, v31
	v_fmac_f32_e32 v79, v23, v31
	v_fmac_f32_e32 v80, v24, v31
	v_fmac_f32_e32 v81, v25, v31
	v_fmac_f32_e32 v83, v26, v31
	v_fmac_f32_e32 v84, v27, v31
	v_fmac_f32_e32 v85, v28, v31
	v_fmac_f32_e32 v86, v29, v31
	v_fmac_f32_e32 v42, v30, v31
	s_waitcnt lgkmcnt(1)
	v_lshlrev_b32_e32 v30, 16, v93
	v_fmac_f32_e32 v47, v14, v30
	v_fmac_f32_e32 v70, v16, v30
	v_fmac_f32_e32 v73, v15, v30
	v_fmac_f32_e32 v74, v17, v30
	v_fmac_f32_e32 v75, v18, v30
	v_fmac_f32_e32 v76, v19, v30
	v_fmac_f32_e32 v77, v21, v30
	v_fmac_f32_e32 v78, v20, v30
	v_fmac_f32_e32 v79, v22, v30
	v_fmac_f32_e32 v80, v23, v30
	v_fmac_f32_e32 v81, v24, v30
	v_fmac_f32_e32 v83, v25, v30
	v_fmac_f32_e32 v84, v26, v30
	v_fmac_f32_e32 v85, v27, v30
	v_fmac_f32_e32 v86, v28, v30
	v_fmac_f32_e32 v42, v29, v30
	s_waitcnt lgkmcnt(0)
	v_lshlrev_b32_e32 v29, 16, v94
	v_fmac_f32_e32 v47, v13, v29
	v_fmac_f32_e32 v70, v14, v29
	v_fmac_f32_e32 v73, v16, v29
	v_fmac_f32_e32 v74, v15, v29
	v_fmac_f32_e32 v75, v17, v29
	v_fmac_f32_e32 v76, v18, v29
	v_fmac_f32_e32 v77, v19, v29
	v_fmac_f32_e32 v78, v21, v29
	v_fmac_f32_e32 v79, v20, v29
	v_fmac_f32_e32 v80, v22, v29
	v_fmac_f32_e32 v81, v23, v29
	v_fmac_f32_e32 v83, v24, v29
	v_fmac_f32_e32 v84, v25, v29
	v_fmac_f32_e32 v85, v26, v29
	v_fmac_f32_e32 v86, v27, v29
	v_fmac_f32_e32 v42, v28, v29
	ds_read_u16 v28, v53 offset:13312
	ds_read_u16 v29, v53 offset:13824
	ds_read_u16 v30, v53 offset:14336
	ds_read_u16 v31, v53 offset:14848
	ds_read_u16 v32, v53 offset:15360
	ds_read_u16 v33, v53 offset:15872
	ds_read_u16 v41, v53 offset:16384
	ds_read_u16 v43, v53 offset:16896
	s_waitcnt lgkmcnt(7)
	v_lshlrev_b32_e32 v28, 16, v28
	v_fmac_f32_e32 v74, v16, v28
	v_fmac_f32_e32 v75, v15, v28
	v_fmac_f32_e32 v76, v17, v28
	v_fmac_f32_e32 v77, v18, v28
	v_fmac_f32_e32 v78, v19, v28
	v_fmac_f32_e32 v79, v21, v28
	v_fmac_f32_e32 v80, v20, v28
	v_fmac_f32_e32 v81, v22, v28
	v_fmac_f32_e32 v83, v23, v28
	v_fmac_f32_e32 v84, v24, v28
	v_fmac_f32_e32 v85, v25, v28
	v_fmac_f32_e32 v86, v26, v28
	v_fmac_f32_e32 v42, v27, v28
	s_waitcnt lgkmcnt(6)
	v_lshlrev_b32_e32 v27, 16, v29
	v_fmac_f32_e32 v73, v14, v28
	v_fmac_f32_e32 v74, v14, v27
	v_fmac_f32_e32 v75, v16, v27
	v_fmac_f32_e32 v76, v15, v27
	v_fmac_f32_e32 v77, v17, v27
	v_fmac_f32_e32 v78, v18, v27
	v_fmac_f32_e32 v79, v19, v27
	v_fmac_f32_e32 v80, v21, v27
	v_fmac_f32_e32 v81, v20, v27
	v_fmac_f32_e32 v83, v22, v27
	v_fmac_f32_e32 v84, v23, v27
	v_fmac_f32_e32 v85, v24, v27
	v_fmac_f32_e32 v86, v25, v27
	v_fmac_f32_e32 v42, v26, v27
	s_waitcnt lgkmcnt(5)
	v_lshlrev_b32_e32 v26, 16, v30
	v_fmac_f32_e32 v70, v13, v28
	v_fmac_f32_e32 v73, v13, v27
	v_fmac_f32_e32 v74, v13, v26
	v_fmac_f32_e32 v75, v14, v26
	v_fmac_f32_e32 v76, v16, v26
	v_fmac_f32_e32 v77, v15, v26
	v_fmac_f32_e32 v78, v17, v26
	v_fmac_f32_e32 v79, v18, v26
	v_fmac_f32_e32 v80, v19, v26
	v_fmac_f32_e32 v81, v21, v26
	v_fmac_f32_e32 v83, v20, v26
	v_fmac_f32_e32 v84, v22, v26
	v_fmac_f32_e32 v85, v23, v26
	v_fmac_f32_e32 v86, v24, v26
	v_fmac_f32_e32 v42, v25, v26
	s_waitcnt lgkmcnt(4)
	v_lshlrev_b32_e32 v25, 16, v31
	v_fmac_f32_e32 v47, v12, v28
	v_fmac_f32_e32 v70, v12, v27
	v_fmac_f32_e32 v73, v12, v26
	v_fmac_f32_e32 v74, v12, v25
	v_fmac_f32_e32 v75, v13, v25
	v_fmac_f32_e32 v76, v14, v25
	v_fmac_f32_e32 v77, v16, v25
	v_fmac_f32_e32 v78, v15, v25
	v_fmac_f32_e32 v79, v17, v25
	v_fmac_f32_e32 v80, v18, v25
	v_fmac_f32_e32 v81, v19, v25
	v_fmac_f32_e32 v83, v21, v25
	v_fmac_f32_e32 v84, v20, v25
	v_fmac_f32_e32 v85, v22, v25
	v_fmac_f32_e32 v86, v23, v25
	v_fmac_f32_e32 v42, v24, v25
	s_waitcnt lgkmcnt(3)
	v_lshlrev_b32_e32 v24, 16, v32
	v_fmac_f32_e32 v47, v10, v27
	v_fmac_f32_e32 v70, v10, v26
	v_fmac_f32_e32 v73, v10, v25
	v_fmac_f32_e32 v74, v10, v24
	v_fmac_f32_e32 v75, v12, v24
	v_fmac_f32_e32 v76, v13, v24
	v_fmac_f32_e32 v77, v14, v24
	v_fmac_f32_e32 v78, v16, v24
	v_fmac_f32_e32 v79, v15, v24
	v_fmac_f32_e32 v80, v17, v24
	v_fmac_f32_e32 v81, v18, v24
	v_fmac_f32_e32 v83, v19, v24
	v_fmac_f32_e32 v84, v21, v24
	v_fmac_f32_e32 v85, v20, v24
	v_fmac_f32_e32 v86, v22, v24
	v_fmac_f32_e32 v42, v23, v24
	s_waitcnt lgkmcnt(2)
	v_lshlrev_b32_e32 v23, 16, v33
	s_waitcnt vmcnt(2)
	v_fmac_f32_e32 v47, v11, v26
	v_fmac_f32_e32 v70, v11, v25
	v_fmac_f32_e32 v73, v11, v24
	v_fmac_f32_e32 v74, v11, v23
	v_fmac_f32_e32 v75, v10, v23
	v_fmac_f32_e32 v76, v12, v23
	v_fmac_f32_e32 v77, v13, v23
	v_fmac_f32_e32 v78, v14, v23
	v_fmac_f32_e32 v79, v16, v23
	v_fmac_f32_e32 v80, v15, v23
	v_fmac_f32_e32 v81, v17, v23
	v_fmac_f32_e32 v83, v18, v23
	v_fmac_f32_e32 v84, v19, v23
	v_fmac_f32_e32 v85, v21, v23
	v_fmac_f32_e32 v86, v20, v23
	v_fmac_f32_e32 v42, v22, v23
	s_waitcnt lgkmcnt(1)
	v_lshlrev_b32_e32 v22, 16, v41
	s_waitcnt vmcnt(1)
	v_fmac_f32_e32 v47, v9, v25
	v_fmac_f32_e32 v70, v9, v24
	v_fmac_f32_e32 v73, v9, v23
	v_fmac_f32_e32 v74, v9, v22
	v_fmac_f32_e32 v75, v11, v22
	v_fmac_f32_e32 v76, v10, v22
	v_fmac_f32_e32 v77, v12, v22
	v_fmac_f32_e32 v78, v13, v22
	v_fmac_f32_e32 v79, v14, v22
	v_fmac_f32_e32 v80, v16, v22
	v_fmac_f32_e32 v81, v15, v22
	v_fmac_f32_e32 v83, v17, v22
	v_fmac_f32_e32 v84, v18, v22
	v_fmac_f32_e32 v85, v19, v22
	v_fmac_f32_e32 v86, v21, v22
	v_fmac_f32_e32 v42, v20, v22
	s_waitcnt lgkmcnt(0)
	v_lshlrev_b32_e32 v20, 16, v43
	s_waitcnt vmcnt(0)
	v_fmac_f32_e32 v47, v8, v24
	v_fmac_f32_e32 v70, v8, v23
	v_fmac_f32_e32 v73, v8, v22
	v_fmac_f32_e32 v74, v8, v20
	v_fmac_f32_e32 v75, v9, v20
	v_fmac_f32_e32 v76, v11, v20
	v_fmac_f32_e32 v77, v10, v20
	v_fmac_f32_e32 v78, v12, v20
	v_fmac_f32_e32 v79, v13, v20
	v_fmac_f32_e32 v80, v14, v20
	v_fmac_f32_e32 v81, v16, v20
	v_fmac_f32_e32 v83, v15, v20
	v_fmac_f32_e32 v84, v17, v20
	v_fmac_f32_e32 v85, v18, v20
	v_fmac_f32_e32 v86, v19, v20
	v_fmac_f32_e32 v42, v21, v20
	ds_read_u16 v20, v53 offset:17408
	ds_read_u16 v21, v53 offset:17920
	ds_read_u16 v22, v53 offset:18432
	ds_read_u16 v23, v53 offset:18944
	ds_read_u16 v24, v53 offset:19456
	ds_read_u16 v25, v53 offset:19968
	ds_read_u16 v26, v53 offset:20480
	ds_read_u16 v27, v53 offset:20992
	s_waitcnt lgkmcnt(7)
	v_lshlrev_b32_e32 v20, 16, v20
	v_fmac_f32_e32 v79, v12, v20
	v_fmac_f32_e32 v80, v13, v20
	v_fmac_f32_e32 v81, v14, v20
	v_fmac_f32_e32 v83, v16, v20
	v_fmac_f32_e32 v84, v15, v20
	v_fmac_f32_e32 v85, v17, v20
	v_fmac_f32_e32 v86, v18, v20
	v_fmac_f32_e32 v42, v19, v20
	s_waitcnt lgkmcnt(6)
	v_lshlrev_b32_e32 v19, 16, v21
	v_fmac_f32_e32 v79, v10, v19
	v_fmac_f32_e32 v80, v12, v19
	v_fmac_f32_e32 v81, v13, v19
	v_fmac_f32_e32 v83, v14, v19
	v_fmac_f32_e32 v84, v16, v19
	v_fmac_f32_e32 v85, v15, v19
	v_fmac_f32_e32 v86, v17, v19
	v_fmac_f32_e32 v42, v18, v19
	s_waitcnt lgkmcnt(5)
	v_lshlrev_b32_e32 v18, 16, v22
	v_fmac_f32_e32 v79, v11, v18
	v_fmac_f32_e32 v80, v10, v18
	v_fmac_f32_e32 v81, v12, v18
	v_fmac_f32_e32 v83, v13, v18
	v_fmac_f32_e32 v84, v14, v18
	v_fmac_f32_e32 v85, v16, v18
	v_fmac_f32_e32 v86, v15, v18
	v_fmac_f32_e32 v42, v17, v18
	s_waitcnt lgkmcnt(4)
	v_lshlrev_b32_e32 v17, 16, v23
	v_fmac_f32_e32 v79, v9, v17
	v_fmac_f32_e32 v80, v11, v17
	v_fmac_f32_e32 v81, v10, v17
	v_fmac_f32_e32 v83, v12, v17
	v_fmac_f32_e32 v84, v13, v17
	v_fmac_f32_e32 v85, v14, v17
	v_fmac_f32_e32 v86, v16, v17
	v_fmac_f32_e32 v42, v15, v17
	s_waitcnt lgkmcnt(3)
	v_lshlrev_b32_e32 v15, 16, v24
	v_fmac_f32_e32 v78, v10, v20
	v_fmac_f32_e32 v79, v8, v15
	v_fmac_f32_e32 v80, v9, v15
	v_fmac_f32_e32 v81, v11, v15
	v_fmac_f32_e32 v83, v10, v15
	v_fmac_f32_e32 v84, v12, v15
	v_fmac_f32_e32 v85, v13, v15
	v_fmac_f32_e32 v86, v14, v15
	v_fmac_f32_e32 v42, v16, v15
	s_waitcnt lgkmcnt(2)
	v_lshlrev_b32_e32 v15, 16, v25
	v_fmac_f32_e32 v78, v11, v19
	v_fmac_f32_e32 v83, v11, v15
	v_fmac_f32_e32 v84, v10, v15
	v_fmac_f32_e32 v85, v12, v15
	v_fmac_f32_e32 v86, v13, v15
	v_fmac_f32_e32 v42, v14, v15
	s_waitcnt lgkmcnt(1)
	v_lshlrev_b32_e32 v14, 16, v26
	v_fmac_f32_e32 v78, v9, v18
	v_fmac_f32_e32 v81, v9, v15
	v_fmac_f32_e32 v83, v9, v14
	v_fmac_f32_e32 v84, v11, v14
	v_fmac_f32_e32 v85, v10, v14
	v_fmac_f32_e32 v86, v12, v14
	v_fmac_f32_e32 v42, v13, v14
	s_waitcnt lgkmcnt(0)
	v_lshlrev_b32_e32 v13, 16, v27
	v_fmac_f32_e32 v78, v8, v17
	v_fmac_f32_e32 v80, v8, v15
	v_fmac_f32_e32 v81, v8, v14
	v_fmac_f32_e32 v83, v8, v13
	v_fmac_f32_e32 v84, v9, v13
	v_fmac_f32_e32 v85, v11, v13
	v_fmac_f32_e32 v86, v10, v13
	v_fmac_f32_e32 v42, v12, v13
	ds_read_u16 v12, v53 offset:21504
	ds_read_u16 v13, v53 offset:22016
	ds_read_u16 v14, v53 offset:22528
	ds_read_u16 v15, v53 offset:23040
	ds_read_u16 v16, v53 offset:31744
	ds_read_u16 v17, v53 offset:32256
	s_waitcnt lgkmcnt(5)
	v_lshlrev_b32_e32 v12, 16, v12
	v_fmac_f32_e32 v85, v9, v12
	v_fmac_f32_e32 v86, v11, v12
	v_fmac_f32_e32 v42, v10, v12
	s_waitcnt lgkmcnt(4)
	v_lshlrev_b32_e32 v10, 16, v13
	v_fmac_f32_e32 v77, v11, v20
	v_fmac_f32_e32 v85, v8, v10
	v_fmac_f32_e32 v86, v9, v10
	v_fmac_f32_e32 v42, v11, v10
	s_waitcnt lgkmcnt(3)
	v_lshlrev_b32_e32 v10, 16, v14
	v_fmac_f32_e32 v76, v9, v20
	v_fmac_f32_e32 v77, v9, v19
	v_fmac_f32_e32 v42, v9, v10
	s_waitcnt lgkmcnt(2)
	v_lshlrev_b32_e32 v9, 16, v15
	v_fmac_f32_e32 v75, v8, v20
	v_fmac_f32_e32 v76, v8, v19
	v_fmac_f32_e32 v77, v8, v18
	v_fmac_f32_e32 v84, v8, v12
	v_fmac_f32_e32 v86, v8, v10
	v_fmac_f32_e32 v42, v8, v9
	s_waitcnt lgkmcnt(1)
	v_lshlrev_b32_e32 v8, 16, v16
	ds_write2st64_b32 v62, v47, v70 offset0:220 offset1:224
	ds_write2st64_b32 v62, v73, v74 offset0:228 offset1:232
	ds_write2st64_b32 v62, v75, v76 offset0:236 offset1:240
	ds_write2st64_b32 v62, v77, v78 offset0:244 offset1:248
	ds_write_b32 v62, v79 offset:64512
	ds_write_b32 v63, v80
	ds_write_b32 v64, v81
	ds_write_b32 v65, v83
	ds_write_b32 v66, v84
	ds_write_b32 v67, v85
	ds_write_b32 v68, v86
	ds_write_b32 v69, v42
	v_add_f32_e32 v32, 0, v8
	s_waitcnt lgkmcnt(12)
	v_lshlrev_b32_e32 v8, 16, v17
	v_add_f32_e32 v30, v32, v8
	ds_read_u16 v8, v53 offset:32768
	ds_read_u16 v9, v53 offset:33280
	ds_read_u16 v10, v53 offset:33792
	ds_read_u16 v11, v53 offset:34304
	ds_read_u16 v12, v53 offset:34816
	ds_read_u16 v13, v53 offset:35328
	ds_read_u16 v14, v53 offset:35840
	ds_read_u16 v15, v53 offset:36352
	s_waitcnt lgkmcnt(7)
	v_lshlrev_b32_e32 v8, 16, v8
	v_add_f32_e32 v31, v30, v8
	s_waitcnt lgkmcnt(6)
	v_lshlrev_b32_e32 v8, 16, v9
	v_add_f32_e32 v33, v31, v8
	s_waitcnt lgkmcnt(5)
	v_lshlrev_b32_e32 v8, 16, v10
	v_add_f32_e32 v43, v33, v8
	s_waitcnt lgkmcnt(4)
	v_lshlrev_b32_e32 v8, 16, v11
	v_add_f32_e32 v87, v43, v8
	s_waitcnt lgkmcnt(3)
	v_lshlrev_b32_e32 v8, 16, v12
	v_add_f32_e32 v86, v87, v8
	s_waitcnt lgkmcnt(2)
	v_lshlrev_b32_e32 v8, 16, v13
	v_add_f32_e32 v85, v86, v8
	s_waitcnt lgkmcnt(1)
	v_lshlrev_b32_e32 v8, 16, v14
	v_add_f32_e32 v84, v85, v8
	s_waitcnt lgkmcnt(0)
	v_lshlrev_b32_e32 v8, 16, v15
	v_add_f32_e32 v83, v84, v8
	ds_read_u16 v8, v53 offset:36864
	ds_read_u16 v9, v53 offset:37376
	ds_read_u16 v10, v53 offset:37888
	ds_read_u16 v11, v53 offset:38400
	ds_read_u16 v12, v53 offset:38912
	ds_read_u16 v13, v53 offset:39424
	ds_read_u16 v14, v53 offset:39936
	ds_read_u16 v15, v53 offset:40448
	s_waitcnt lgkmcnt(7)
	v_lshlrev_b32_e32 v8, 16, v8
	v_add_f32_e32 v81, v83, v8
	s_waitcnt lgkmcnt(6)
	v_lshlrev_b32_e32 v8, 16, v9
	v_add_f32_e32 v80, v81, v8
	s_waitcnt lgkmcnt(5)
	v_lshlrev_b32_e32 v8, 16, v10
	v_add_f32_e32 v79, v80, v8
	s_waitcnt lgkmcnt(4)
	v_lshlrev_b32_e32 v8, 16, v11
	v_add_f32_e32 v78, v79, v8
	s_waitcnt lgkmcnt(3)
	v_lshlrev_b32_e32 v8, 16, v12
	v_add_f32_e32 v77, v78, v8
	s_waitcnt lgkmcnt(2)
	v_lshlrev_b32_e32 v8, 16, v13
	v_add_f32_e32 v76, v77, v8
	s_waitcnt lgkmcnt(1)
	v_lshlrev_b32_e32 v8, 16, v14
	v_add_f32_e32 v75, v76, v8
	s_waitcnt lgkmcnt(0)
	v_lshlrev_b32_e32 v8, 16, v15
	v_add_f32_e32 v74, v75, v8
	v_lshlrev_b32_e32 v8, 16, v71
	v_add_f32_e32 v73, v74, v8
	v_lshlrev_b32_e32 v8, 16, v72
	v_add_f32_e32 v72, v73, v8
	v_lshlrev_b32_e32 v8, 16, v88
	v_add_f32_e32 v70, v72, v8
	v_lshlrev_b32_e32 v8, 16, v89
	v_add_f32_e32 v71, v70, v8
	v_lshlrev_b32_e32 v8, 16, v90
	v_add_f32_e32 v41, v71, v8
	v_lshlrev_b32_e32 v8, 16, v82
	v_add_f32_e32 v82, v41, v8
	v_add_u32_e32 v8, s66, v55
	s_and_saveexec_b64 s[10:11], s[8:9]
	s_xor_b64 s[14:15], exec, s[10:11]
	s_cbranch_execz .LBB0_543
	ds_read_u16 v45, v53 offset:45568
	ds_read_u16 v42, v53 offset:46080
	ds_read_u16 v9, v53 offset:44032
	ds_read_u16 v44, v53 offset:46592
	ds_read_u16 v10, v53 offset:44544
	ds_read_u16 v46, v53 offset:47104
	ds_read_u16 v11, v53 offset:45056
	s_waitcnt lgkmcnt(4)
	v_lshlrev_b32_e32 v9, 16, v9
	v_add_f32_e32 v88, v82, v9
	s_waitcnt lgkmcnt(2)
	v_lshlrev_b32_e32 v9, 16, v10
	v_add_f32_e32 v92, v88, v9
	s_waitcnt lgkmcnt(0)
	v_lshlrev_b32_e32 v9, 16, v11
	v_sub_f32_e32 v89, v84, v85
	v_add_f32_e32 v91, v92, v9
	v_cmp_lt_i32_e64 s[10:11], 1, v54
	s_mov_b64 s[50:51], 0
	s_mov_b64 s[26:27], 0
	s_and_saveexec_b64 s[20:21], s[10:11]
	s_xor_b64 s[52:53], exec, s[20:21]
	s_cbranch_execz .LBB0_536
	v_cmp_eq_u32_e64 s[10:11], 2, v54
	s_mov_b64 s[20:21], -1
	s_and_saveexec_b64 s[56:57], s[10:11]
	s_cbranch_execz .LBB0_535
	v_add_u32_e32 v9, -4, v8
	v_or_b32_e32 v22, 4, v8
	v_max_i32_e32 v9, s31, v9
	v_min_i32_e32 v10, s30, v22
	v_sub_u32_e32 v9, v10, v9
	v_cvt_f32_i32_e32 v9, v9
	v_sub_f32_e32 v11, v80, v33
	v_or_b32_e32 v20, 1, v8
	v_sub_f32_e32 v13, v79, v43
	v_rcp_iflag_f32_e32 v9, v9
	v_ashrrev_i32_e32 v21, 31, v20
	v_or_b32_e32 v24, 2, v8
	v_sub_f32_e32 v14, v78, v87
	v_fma_f32 v9, v9, v11, -v89
	v_cvt_pk_bf16_f32 v12, v9, s0
	v_ashrrev_i32_e32 v9, 31, v8
	v_lshlrev_b64 v[10:11], 11, v[8:9]
	v_lshl_add_u64 v[10:11], v[6:7], 0, v[10:11]
	global_store_short v[10:11], v12, off sc1
	v_add_u32_e32 v9, -3, v8
	v_or_b32_e32 v10, 5, v8
	v_max_i32_e32 v9, s31, v9
	v_min_i32_e32 v11, s30, v10
	v_sub_u32_e32 v9, v11, v9
	v_cvt_f32_i32_e32 v9, v9
	v_sub_f32_e32 v12, v83, v84
	v_ashrrev_i32_e32 v25, 31, v24
	v_or_b32_e32 v26, 3, v8
	v_rcp_iflag_f32_e32 v9, v9
	v_ashrrev_i32_e32 v27, 31, v26
	v_lshlrev_b64 v[16:17], 11, v[26:27]
	v_lshl_add_u64 v[16:17], v[6:7], 0, v[16:17]
	v_fma_f32 v9, v9, v13, -v12
	v_lshlrev_b64 v[12:13], 11, v[20:21]
	v_cvt_pk_bf16_f32 v9, v9, s0
	v_lshl_add_u64 v[12:13], v[6:7], 0, v[12:13]
	global_store_short v[12:13], v9, off sc1
	v_add_u32_e32 v9, -2, v8
	v_or_b32_e32 v12, 6, v8
	v_max_i32_e32 v9, s31, v9
	v_min_i32_e32 v11, s30, v12
	v_sub_u32_e32 v9, v11, v9
	v_cvt_f32_i32_e32 v9, v9
	v_sub_f32_e32 v13, v81, v83
	v_ashrrev_i32_e32 v23, 31, v22
	v_lshlrev_b64 v[18:19], 11, v[22:23]
	v_rcp_iflag_f32_e32 v9, v9
	v_lshl_add_u64 v[18:19], v[6:7], 0, v[18:19]
	v_or_b32_e32 v28, 13, v8
	v_ashrrev_i32_e32 v29, 31, v28
	v_fma_f32 v9, v9, v14, -v13
	v_lshlrev_b64 v[14:15], 11, v[24:25]
	v_cvt_pk_bf16_f32 v9, v9, s0
	v_lshl_add_u64 v[14:15], v[6:7], 0, v[14:15]
	global_store_short v[14:15], v9, off sc1
	v_add_u32_e32 v9, -1, v8
	v_or_b32_e32 v14, 7, v8
	v_max_i32_e32 v9, s31, v9
	v_min_i32_e32 v11, s30, v14
	v_sub_u32_e32 v9, v11, v9
	v_cvt_f32_i32_e32 v9, v9
	v_sub_f32_e32 v13, v80, v81
	v_sub_f32_e32 v15, v77, v86
	s_xor_b64 s[20:21], exec, -1
	v_rcp_iflag_f32_e32 v9, v9
	s_nop 0
	v_fma_f32 v9, v9, v15, -v13
	v_cvt_pk_bf16_f32 v9, v9, s0
	global_store_short v[16:17], v9, off sc1
	v_or_b32_e32 v16, 8, v8
	v_max_i32_e32 v9, s31, v8
	v_min_i32_e32 v11, s30, v16
	v_sub_u32_e32 v9, v11, v9
	v_cvt_f32_i32_e32 v9, v9
	v_sub_f32_e32 v13, v79, v80
	v_sub_f32_e32 v15, v76, v85
	v_ashrrev_i32_e32 v17, 31, v16
	v_rcp_iflag_f32_e32 v9, v9
	s_nop 0
	v_fma_f32 v9, v9, v15, -v13
	v_cvt_pk_bf16_f32 v9, v9, s0
	global_store_short v[18:19], v9, off sc1
	v_or_b32_e32 v18, 9, v8
	v_max_i32_e32 v9, s31, v20
	v_min_i32_e32 v11, s30, v18
	v_sub_u32_e32 v9, v11, v9
	v_cvt_f32_i32_e32 v9, v9
	v_sub_f32_e32 v13, v78, v79
	v_sub_f32_e32 v15, v75, v84
	v_ashrrev_i32_e32 v11, 31, v10
	v_rcp_iflag_f32_e32 v9, v9
	v_lshlrev_b64 v[20:21], 11, v[10:11]
	v_lshl_add_u64 v[20:21], v[6:7], 0, v[20:21]
	v_ashrrev_i32_e32 v19, 31, v18
	v_fma_f32 v9, v9, v15, -v13
	v_cvt_pk_bf16_f32 v9, v9, s0
	global_store_short v[20:21], v9, off sc1
	v_or_b32_e32 v20, 10, v8
	v_max_i32_e32 v9, s31, v24
	v_min_i32_e32 v11, s30, v20
	v_sub_u32_e32 v9, v11, v9
	v_cvt_f32_i32_e32 v9, v9
	v_sub_f32_e32 v13, v77, v78
	v_sub_f32_e32 v15, v74, v83
	v_ashrrev_i32_e32 v21, 31, v20
	v_rcp_iflag_f32_e32 v9, v9
	s_nop 0
	v_fma_f32 v9, v9, v15, -v13
	v_ashrrev_i32_e32 v13, 31, v12
	v_lshlrev_b64 v[24:25], 11, v[12:13]
	v_cvt_pk_bf16_f32 v9, v9, s0
	v_lshl_add_u64 v[24:25], v[6:7], 0, v[24:25]
	global_store_short v[24:25], v9, off sc1
	v_or_b32_e32 v24, 11, v8
	v_max_i32_e32 v9, s31, v26
	v_min_i32_e32 v11, s30, v24
	v_sub_u32_e32 v9, v11, v9
	v_cvt_f32_i32_e32 v9, v9
	v_sub_f32_e32 v13, v76, v77
	v_sub_f32_e32 v15, v73, v81
	v_ashrrev_i32_e32 v25, 31, v24
	v_rcp_iflag_f32_e32 v9, v9
	s_nop 0
	v_fma_f32 v9, v9, v15, -v13
	v_ashrrev_i32_e32 v15, 31, v14
	v_lshlrev_b64 v[26:27], 11, v[14:15]
	v_cvt_pk_bf16_f32 v9, v9, s0
	v_lshl_add_u64 v[26:27], v[6:7], 0, v[26:27]
	global_store_short v[26:27], v9, off sc1
	v_or_b32_e32 v26, 12, v8
	v_max_i32_e32 v9, s31, v22
	v_min_i32_e32 v11, s30, v26
	v_sub_u32_e32 v9, v11, v9
	v_cvt_f32_i32_e32 v9, v9
	v_sub_f32_e32 v13, v75, v76
	v_sub_f32_e32 v15, v72, v80
	v_lshlrev_b64 v[22:23], 11, v[16:17]
	v_rcp_iflag_f32_e32 v9, v9
	v_lshl_add_u64 v[22:23], v[6:7], 0, v[22:23]
	v_sub_f32_e32 v11, v74, v75
	v_ashrrev_i32_e32 v27, 31, v26
	v_fma_f32 v9, v9, v15, -v13
	v_cvt_pk_bf16_f32 v9, v9, s0
	global_store_short v[22:23], v9, off sc1
	v_max_i32_e32 v9, s31, v10
	v_min_i32_e32 v10, s30, v28
	v_sub_u32_e32 v9, v10, v9
	v_cvt_f32_i32_e32 v9, v9
	v_sub_f32_e32 v13, v70, v79
	v_or_b32_e32 v22, 14, v8
	v_ashrrev_i32_e32 v23, 31, v22
	v_rcp_iflag_f32_e32 v9, v9
	s_nop 0
	v_fma_f32 v9, v9, v13, -v11
	v_lshlrev_b64 v[10:11], 11, v[18:19]
	v_cvt_pk_bf16_f32 v9, v9, s0
	v_lshl_add_u64 v[10:11], v[6:7], 0, v[10:11]
	global_store_short v[10:11], v9, off sc1
	v_max_i32_e32 v9, s31, v12
	v_min_i32_e32 v10, s30, v22
	v_sub_u32_e32 v9, v10, v9
	v_cvt_f32_i32_e32 v9, v9
	v_sub_f32_e32 v11, v73, v74
	v_sub_f32_e32 v12, v71, v78
	v_sub_f32_e32 v13, v41, v77
	v_rcp_iflag_f32_e32 v9, v9
	s_nop 0
	v_fma_f32 v9, v9, v12, -v11
	v_lshlrev_b64 v[10:11], 11, v[20:21]
	v_cvt_pk_bf16_f32 v9, v9, s0
	v_lshl_add_u64 v[10:11], v[6:7], 0, v[10:11]
	global_store_short v[10:11], v9, off sc1
	v_or_b32_e32 v10, 15, v8
	v_max_i32_e32 v9, s31, v14
	v_min_i32_e32 v11, s30, v10
	v_sub_u32_e32 v9, v11, v9
	v_cvt_f32_i32_e32 v9, v9
	v_sub_f32_e32 v12, v72, v73
	v_max_i32_e32 v11, s31, v16
	v_rcp_iflag_f32_e32 v9, v9
	s_nop 0
	v_fma_f32 v9, v9, v13, -v12
	v_lshlrev_b64 v[12:13], 11, v[24:25]
	v_cvt_pk_bf16_f32 v9, v9, s0
	v_lshl_add_u64 v[12:13], v[6:7], 0, v[12:13]
	global_store_short v[12:13], v9, off sc1
	v_add_u32_e32 v9, 16, v8
	v_min_i32_e32 v9, s30, v9
	v_sub_u32_e32 v9, v9, v11
	v_cvt_f32_i32_e32 v9, v9
	v_sub_f32_e32 v12, v70, v72
	v_sub_f32_e32 v13, v82, v76
	v_max_i32_e32 v11, s31, v18
	v_rcp_iflag_f32_e32 v9, v9
	s_nop 0
	v_fma_f32 v9, v9, v13, -v12
	v_lshlrev_b64 v[12:13], 11, v[26:27]
	v_cvt_pk_bf16_f32 v9, v9, s0
	v_lshl_add_u64 v[12:13], v[6:7], 0, v[12:13]
	global_store_short v[12:13], v9, off sc1
	v_add_u32_e32 v9, 17, v8
	v_min_i32_e32 v9, s30, v9
	v_sub_u32_e32 v9, v9, v11
	v_cvt_f32_i32_e32 v9, v9
	v_sub_f32_e32 v12, v71, v70
	v_sub_f32_e32 v13, v88, v75
	v_max_i32_e32 v11, s31, v20
	v_rcp_iflag_f32_e32 v9, v9
	s_nop 0
	v_fma_f32 v9, v9, v13, -v12
	v_lshlrev_b64 v[12:13], 11, v[28:29]
	v_cvt_pk_bf16_f32 v9, v9, s0
	v_lshl_add_u64 v[12:13], v[6:7], 0, v[12:13]
	global_store_short v[12:13], v9, off sc1
	v_add_u32_e32 v9, 18, v8
	v_min_i32_e32 v9, s30, v9
	v_sub_u32_e32 v9, v9, v11
	v_cvt_f32_i32_e32 v9, v9
	v_sub_f32_e32 v12, v41, v71
	v_sub_f32_e32 v13, v92, v74
	v_max_i32_e32 v11, s31, v24
	v_rcp_iflag_f32_e32 v9, v9
	s_nop 0
	v_fma_f32 v9, v9, v13, -v12
	v_lshlrev_b64 v[12:13], 11, v[22:23]
	v_cvt_pk_bf16_f32 v9, v9, s0
	v_lshl_add_u64 v[12:13], v[6:7], 0, v[12:13]
	global_store_short v[12:13], v9, off sc1
	v_add_u32_e32 v9, 19, v8
	v_min_i32_e32 v12, s30, v9
	v_sub_f32_e32 v9, v91, v73
	v_sub_u32_e32 v12, v12, v11

.LBB0_536:
	s_andn2_saveexec_b64 s[20:21], s[52:53]
	v_cmp_ne_u32_e64 s[10:11], 1, v54
	s_andn2_b64 s[26:27], s[26:27], exec
	s_and_b64 s[10:11], s[10:11], exec
	s_or_b64 s[26:27], s[26:27], s[10:11]
	s_mov_b64 s[50:51], exec
	s_or_b64 exec, exec, s[20:21]
	v_add_u32_e32 v11, -2, v8
	v_add_u32_e32 v13, 17, v8
	v_max_i32_e32 v11, s31, v11
	v_min_i32_e32 v90, s30, v13
	s_and_saveexec_b64 s[10:11], s[26:27]
	s_xor_b64 s[10:11], exec, s[10:11]
	s_cbranch_execz .LBB0_540
	v_lshlrev_b32_e32 v9, 16, v45
	v_add_f32_e32 v21, v91, v9
	v_lshlrev_b32_e32 v9, 16, v42
	v_add_f32_e32 v25, v21, v9
	v_lshlrev_b32_e32 v9, 16, v44
	v_add_f32_e32 v23, v25, v9
	v_lshlrev_b32_e32 v9, 16, v46
	v_add_f32_e32 v93, v23, v9
	v_add_u32_e32 v9, -8, v8
	v_or_b32_e32 v18, 8, v8
	v_max_i32_e32 v9, s31, v9
	v_min_i32_e32 v10, s30, v18
	v_sub_u32_e32 v9, v10, v9
	v_cvt_f32_i32_e32 v9, v9
	v_or_b32_e32 v26, 1, v8
	v_sub_f32_e32 v14, v75, v32
	v_ashrrev_i32_e32 v27, 31, v26
	v_rcp_iflag_f32_e32 v9, v9
	v_or_b32_e32 v28, 2, v8
	v_ashrrev_i32_e32 v29, 31, v28
	v_lshlrev_b64 v[16:17], 11, v[28:29]
	v_fma_f32 v9, v9, v76, -v89
	v_cvt_pk_bf16_f32 v10, v9, s0
	v_ashrrev_i32_e32 v9, 31, v8
	v_lshlrev_b64 v[12:13], 11, v[8:9]
	v_lshl_add_u64 v[12:13], v[6:7], 0, v[12:13]
	global_store_short v[12:13], v10, off sc1
	v_add_u32_e32 v9, -7, v8
	v_or_b32_e32 v12, 9, v8
	v_max_i32_e32 v9, s31, v9
	v_min_i32_e32 v10, s30, v12
	v_sub_u32_e32 v9, v10, v9
	v_cvt_f32_i32_e32 v9, v9
	v_sub_f32_e32 v13, v83, v84
	v_lshl_add_u64 v[16:17], v[6:7], 0, v[16:17]
	v_or_b32_e32 v20, 12, v8
	v_rcp_iflag_f32_e32 v9, v9
	v_or_b32_e32 v32, 4, v8
	v_or_b32_e32 v24, 13, v8
	v_or_b32_e32 v42, 5, v8
	v_fma_f32 v9, v9, v14, -v13
	v_lshlrev_b64 v[14:15], 11, v[26:27]
	v_cvt_pk_bf16_f32 v9, v9, s0
	v_lshl_add_u64 v[14:15], v[6:7], 0, v[14:15]
	global_store_short v[14:15], v9, off sc1
	v_add_u32_e32 v9, -6, v8
	v_or_b32_e32 v14, 10, v8
	v_max_i32_e32 v9, s31, v9
	v_min_i32_e32 v10, s30, v14
	v_sub_u32_e32 v9, v10, v9
	v_cvt_f32_i32_e32 v9, v9
	v_sub_f32_e32 v13, v81, v83
	v_sub_f32_e32 v15, v74, v30
	v_or_b32_e32 v30, 3, v8
	v_rcp_iflag_f32_e32 v9, v9
	v_or_b32_e32 v22, 14, v8
	v_ashrrev_i32_e32 v19, 31, v18
	v_lshlrev_b64 v[18:19], 11, v[18:19]
	v_fma_f32 v9, v9, v15, -v13
	v_cvt_pk_bf16_f32 v9, v9, s0
	global_store_short v[16:17], v9, off sc1
	v_add_u32_e32 v9, -5, v8
	v_or_b32_e32 v16, 11, v8
	v_max_i32_e32 v9, s31, v9
	v_min_i32_e32 v10, s30, v16
	v_sub_u32_e32 v9, v10, v9
	v_cvt_f32_i32_e32 v9, v9
	v_sub_f32_e32 v13, v80, v81
	v_sub_f32_e32 v15, v73, v31
	v_ashrrev_i32_e32 v31, 31, v30
	v_rcp_iflag_f32_e32 v9, v9
	v_lshlrev_b64 v[44:45], 11, v[30:31]
	v_lshl_add_u64 v[44:45], v[6:7], 0, v[44:45]
	v_min_i32_e32 v10, s30, v20
	v_fma_f32 v9, v9, v15, -v13
	v_cvt_pk_bf16_f32 v9, v9, s0
	global_store_short v[44:45], v9, off sc1
	v_add_u32_e32 v9, -4, v8
	v_max_i32_e32 v9, s31, v9
	v_sub_u32_e32 v9, v10, v9
	v_cvt_f32_i32_e32 v9, v9
	v_sub_f32_e32 v13, v79, v80
	v_sub_f32_e32 v15, v72, v33
	v_ashrrev_i32_e32 v33, 31, v32
	v_rcp_iflag_f32_e32 v9, v9
	v_lshlrev_b64 v[44:45], 11, v[32:33]
	v_lshl_add_u64 v[44:45], v[6:7], 0, v[44:45]
	v_min_i32_e32 v10, s30, v24
	v_fma_f32 v9, v9, v15, -v13
	v_cvt_pk_bf16_f32 v9, v9, s0
	global_store_short v[44:45], v9, off sc1
	v_add_u32_e32 v9, -3, v8
	v_max_i32_e32 v9, s31, v9
	v_sub_u32_e32 v9, v10, v9
	v_cvt_f32_i32_e32 v9, v9
	v_sub_f32_e32 v13, v78, v79
	v_sub_f32_e32 v15, v70, v43
	v_ashrrev_i32_e32 v43, 31, v42
	v_rcp_iflag_f32_e32 v9, v9
	v_lshlrev_b64 v[44:45], 11, v[42:43]
	v_lshl_add_u64 v[44:45], v[6:7], 0, v[44:45]
	v_sub_f32_e32 v10, v77, v78
	v_fma_f32 v9, v9, v15, -v13
	v_cvt_pk_bf16_f32 v9, v9, s0
	global_store_short v[44:45], v9, off sc1
	v_min_i32_e32 v9, s30, v22
	v_sub_u32_e32 v9, v9, v11
	v_cvt_f32_i32_e32 v9, v9
	v_or_b32_e32 v44, 6, v8
	v_sub_f32_e32 v13, v71, v87
	v_ashrrev_i32_e32 v45, 31, v44
	v_rcp_iflag_f32_e32 v9, v9
	v_lshlrev_b64 v[46:47], 11, v[44:45]
	v_lshl_add_u64 v[46:47], v[6:7], 0, v[46:47]
	v_sub_f32_e32 v15, v76, v77
	v_fma_f32 v9, v9, v13, -v10
	v_cvt_pk_bf16_f32 v9, v9, s0
	global_store_short v[46:47], v9, off sc1
	v_add_u32_e32 v9, -1, v8
	v_or_b32_e32 v10, 15, v8
	v_max_i32_e32 v9, s31, v9
	v_min_i32_e32 v13, s30, v10
	v_sub_u32_e32 v9, v13, v9
	v_cvt_f32_i32_e32 v9, v9
	v_or_b32_e32 v46, 7, v8
	v_sub_f32_e32 v17, v41, v86
	v_ashrrev_i32_e32 v47, 31, v46
	v_rcp_iflag_f32_e32 v9, v9
	v_lshlrev_b64 v[94:95], 11, v[46:47]
	v_lshl_add_u64 v[94:95], v[6:7], 0, v[94:95]
	v_max_i32_e32 v13, s31, v8
	v_fma_f32 v9, v9, v17, -v15
	v_cvt_pk_bf16_f32 v9, v9, s0
	global_store_short v[94:95], v9, off sc1
	v_add_u32_e32 v9, 16, v8
	v_min_i32_e32 v9, s30, v9
	v_sub_u32_e32 v9, v9, v13
	v_cvt_f32_i32_e32 v9, v9
	v_sub_f32_e32 v15, v75, v76
	v_sub_f32_e32 v17, v82, v85
	v_lshl_add_u64 v[18:19], v[6:7], 0, v[18:19]
	v_rcp_iflag_f32_e32 v9, v9
	v_sub_f32_e32 v13, v74, v75
	s_andn2_b64 s[50:51], s[50:51], exec
	v_fma_f32 v9, v9, v17, -v15
	v_cvt_pk_bf16_f32 v9, v9, s0
	global_store_short v[18:19], v9, off sc1
	v_max_i32_e32 v9, s31, v26
	v_sub_u32_e32 v9, v90, v9
	v_cvt_f32_i32_e32 v9, v9
	v_sub_f32_e32 v15, v88, v84
	v_ashrrev_i32_e32 v17, 31, v16
	v_rcp_iflag_f32_e32 v9, v9
	s_nop 0
	v_fma_f32 v9, v9, v15, -v13
	v_ashrrev_i32_e32 v13, 31, v12
	v_lshlrev_b64 v[12:13], 11, v[12:13]
	v_cvt_pk_bf16_f32 v9, v9, s0
	v_lshl_add_u64 v[12:13], v[6:7], 0, v[12:13]
	global_store_short v[12:13], v9, off sc1
	v_add_u32_e32 v9, 18, v8
	v_max_i32_e32 v12, s31, v28
	v_min_i32_e32 v9, s30, v9
	v_sub_u32_e32 v9, v9, v12
	v_cvt_f32_i32_e32 v9, v9
	v_sub_f32_e32 v13, v73, v74
	v_sub_f32_e32 v15, v92, v83
	v_rcp_iflag_f32_e32 v9, v9
	s_nop 0
	v_fma_f32 v9, v9, v15, -v13
	v_ashrrev_i32_e32 v15, 31, v14
	v_lshlrev_b64 v[12:13], 11, v[14:15]
	v_cvt_pk_bf16_f32 v9, v9, s0
	v_lshl_add_u64 v[12:13], v[6:7], 0, v[12:13]
	global_store_short v[12:13], v9, off sc1
	v_add_u32_e32 v9, 19, v8
	v_max_i32_e32 v12, s31, v30
	v_min_i32_e32 v9, s30, v9
	v_sub_u32_e32 v9, v9, v12
	v_cvt_f32_i32_e32 v9, v9
	v_sub_f32_e32 v13, v72, v73
	v_sub_f32_e32 v14, v91, v81
	v_rcp_iflag_f32_e32 v9, v9
	s_nop 0
	v_fma_f32 v9, v9, v14, -v13
	v_lshlrev_b64 v[12:13], 11, v[16:17]
	v_cvt_pk_bf16_f32 v9, v9, s0
	v_lshl_add_u64 v[12:13], v[6:7], 0, v[12:13]
	global_store_short v[12:13], v9, off sc1
	v_add_u32_e32 v9, 20, v8
	v_max_i32_e32 v12, s31, v32
	v_min_i32_e32 v9, s30, v9
	v_sub_u32_e32 v9, v9, v12
	v_cvt_f32_i32_e32 v9, v9
	v_sub_f32_e32 v13, v70, v72
	v_sub_f32_e32 v14, v21, v80
	v_ashrrev_i32_e32 v21, 31, v20
	v_rcp_iflag_f32_e32 v9, v9
	s_nop 0
	v_fma_f32 v9, v9, v14, -v13
	v_lshlrev_b64 v[12:13], 11, v[20:21]
	v_cvt_pk_bf16_f32 v9, v9, s0
	v_lshl_add_u64 v[12:13], v[6:7], 0, v[12:13]
	global_store_short v[12:13], v9, off sc1
	v_add_u32_e32 v9, 21, v8
	v_max_i32_e32 v12, s31, v42
	v_min_i32_e32 v9, s30, v9
	v_sub_u32_e32 v9, v9, v12
	v_cvt_f32_i32_e32 v9, v9
	v_sub_f32_e32 v13, v71, v70
	v_sub_f32_e32 v14, v25, v79
	v_ashrrev_i32_e32 v25, 31, v24
	v_rcp_iflag_f32_e32 v9, v9
	s_nop 0
	v_fma_f32 v9, v9, v14, -v13
	v_lshlrev_b64 v[12:13], 11, v[24:25]
	v_cvt_pk_bf16_f32 v9, v9, s0
	v_lshl_add_u64 v[12:13], v[6:7], 0, v[12:13]
	global_store_short v[12:13], v9, off sc1
	v_add_u32_e32 v9, 22, v8
	v_max_i32_e32 v12, s31, v44
	v_min_i32_e32 v9, s30, v9
	v_sub_u32_e32 v9, v9, v12
	v_cvt_f32_i32_e32 v9, v9
	v_sub_f32_e32 v13, v41, v71
	v_sub_f32_e32 v14, v23, v78
	v_ashrrev_i32_e32 v23, 31, v22
	v_rcp_iflag_f32_e32 v9, v9
	s_nop 0
	v_fma_f32 v9, v9, v14, -v13
	v_lshlrev_b64 v[12:13], 11, v[22:23]
	v_cvt_pk_bf16_f32 v9, v9, s0
	v_lshl_add_u64 v[12:13], v[6:7], 0, v[12:13]
	global_store_short v[12:13], v9, off sc1
	v_add_u32_e32 v9, 23, v8
	v_max_i32_e32 v12, s31, v46
	v_min_i32_e32 v13, s30, v9
	v_sub_f32_e32 v9, v93, v77
	v_sub_u32_e32 v12, v13, v12
.LBB0_540:
	s_or_b64 exec, exec, s[10:11]
	s_and_saveexec_b64 s[10:11], s[50:51]
	s_cbranch_execz .LBB0_542
	v_or_b32_e32 v12, 2, v8
	v_min_i32_e32 v9, s30, v12
	v_sub_u32_e32 v9, v9, v11
	v_cvt_f32_i32_e32 v9, v9
	v_sub_f32_e32 v10, v83, v87
	v_or_b32_e32 v18, 1, v8
	v_sub_f32_e32 v14, v81, v86
	v_rcp_iflag_f32_e32 v9, v9
	v_ashrrev_i32_e32 v19, 31, v18
	v_or_b32_e32 v20, 13, v8
	v_ashrrev_i32_e32 v21, 31, v20
	v_fma_f32 v9, v9, v10, -v89
	v_cvt_pk_bf16_f32 v13, v9, s0
	v_ashrrev_i32_e32 v9, 31, v8
	v_lshlrev_b64 v[10:11], 11, v[8:9]
	v_lshl_add_u64 v[10:11], v[6:7], 0, v[10:11]
	global_store_short v[10:11], v13, off sc1
	v_add_u32_e32 v9, -1, v8
	v_or_b32_e32 v10, 3, v8
	v_max_i32_e32 v9, s31, v9
	v_min_i32_e32 v11, s30, v10
	v_sub_u32_e32 v9, v11, v9
	v_cvt_f32_i32_e32 v9, v9
	v_sub_f32_e32 v13, v83, v84
	v_rcp_iflag_f32_e32 v9, v9
	s_nop 0
	v_fma_f32 v9, v9, v14, -v13
	v_lshlrev_b64 v[14:15], 11, v[18:19]
	v_cvt_pk_bf16_f32 v9, v9, s0
	v_lshl_add_u64 v[14:15], v[6:7], 0, v[14:15]
	global_store_short v[14:15], v9, off sc1
	v_or_b32_e32 v14, 4, v8
	v_max_i32_e32 v9, s31, v8
	v_min_i32_e32 v11, s30, v14
	v_sub_u32_e32 v9, v11, v9
	v_cvt_f32_i32_e32 v9, v9
	v_sub_f32_e32 v13, v81, v83
	v_sub_f32_e32 v15, v80, v85
	v_rcp_iflag_f32_e32 v9, v9
	s_nop 0
	v_fma_f32 v9, v9, v15, -v13
	v_ashrrev_i32_e32 v13, 31, v12
	v_lshlrev_b64 v[16:17], 11, v[12:13]
	v_cvt_pk_bf16_f32 v9, v9, s0
	v_lshl_add_u64 v[16:17], v[6:7], 0, v[16:17]
	global_store_short v[16:17], v9, off sc1
	v_or_b32_e32 v16, 5, v8
	v_max_i32_e32 v9, s31, v18
	v_min_i32_e32 v11, s30, v16
	v_sub_u32_e32 v9, v11, v9
	v_cvt_f32_i32_e32 v9, v9
	v_sub_f32_e32 v13, v80, v81
	v_sub_f32_e32 v15, v79, v84
	v_ashrrev_i32_e32 v11, 31, v10
	v_rcp_iflag_f32_e32 v9, v9
	v_lshlrev_b64 v[18:19], 11, v[10:11]
	v_lshl_add_u64 v[18:19], v[6:7], 0, v[18:19]
	v_ashrrev_i32_e32 v17, 31, v16
	v_fma_f32 v9, v9, v15, -v13
	v_cvt_pk_bf16_f32 v9, v9, s0
	global_store_short v[18:19], v9, off sc1
	v_or_b32_e32 v18, 6, v8
	v_max_i32_e32 v9, s31, v12
	v_min_i32_e32 v11, s30, v18
	v_sub_u32_e32 v9, v11, v9
	v_cvt_f32_i32_e32 v9, v9
	v_sub_f32_e32 v12, v79, v80
	v_sub_f32_e32 v13, v78, v83
	v_ashrrev_i32_e32 v15, 31, v14
	v_rcp_iflag_f32_e32 v9, v9
	v_sub_f32_e32 v11, v78, v79
	v_ashrrev_i32_e32 v19, 31, v18
	v_fma_f32 v9, v9, v13, -v12
	v_lshlrev_b64 v[12:13], 11, v[14:15]
	v_cvt_pk_bf16_f32 v9, v9, s0
	v_lshl_add_u64 v[12:13], v[6:7], 0, v[12:13]
	global_store_short v[12:13], v9, off sc1
	v_or_b32_e32 v12, 7, v8
	v_max_i32_e32 v9, s31, v10
	v_min_i32_e32 v10, s30, v12
	v_sub_u32_e32 v9, v10, v9
	v_cvt_f32_i32_e32 v9, v9
	v_sub_f32_e32 v13, v77, v81
	v_rcp_iflag_f32_e32 v9, v9
	s_nop 0
	v_fma_f32 v9, v9, v13, -v11
	v_lshlrev_b64 v[10:11], 11, v[16:17]
	v_cvt_pk_bf16_f32 v9, v9, s0
	v_lshl_add_u64 v[10:11], v[6:7], 0, v[10:11]
	global_store_short v[10:11], v9, off sc1
	v_or_b32_e32 v10, 8, v8
	v_max_i32_e32 v9, s31, v14
	v_min_i32_e32 v11, s30, v10
	v_sub_u32_e32 v9, v11, v9
	v_cvt_f32_i32_e32 v9, v9
	v_sub_f32_e32 v13, v77, v78
	v_sub_f32_e32 v14, v76, v80
	v_rcp_iflag_f32_e32 v9, v9
	s_nop 0
	v_fma_f32 v9, v9, v14, -v13
	v_lshlrev_b64 v[14:15], 11, v[18:19]
	v_cvt_pk_bf16_f32 v9, v9, s0
	v_lshl_add_u64 v[14:15], v[6:7], 0, v[14:15]
	global_store_short v[14:15], v9, off sc1
	v_or_b32_e32 v14, 9, v8
	v_max_i32_e32 v9, s31, v16
	v_min_i32_e32 v11, s30, v14
	v_sub_u32_e32 v9, v11, v9
	v_cvt_f32_i32_e32 v9, v9
	v_sub_f32_e32 v13, v76, v77
	v_sub_f32_e32 v15, v75, v79
	v_rcp_iflag_f32_e32 v9, v9
	s_nop 0
	v_fma_f32 v9, v9, v15, -v13
	v_ashrrev_i32_e32 v13, 31, v12
	v_lshlrev_b64 v[16:17], 11, v[12:13]
	v_cvt_pk_bf16_f32 v9, v9, s0
	v_lshl_add_u64 v[16:17], v[6:7], 0, v[16:17]
	global_store_short v[16:17], v9, off sc1
	v_or_b32_e32 v16, 10, v8
	v_max_i32_e32 v9, s31, v18
	v_min_i32_e32 v11, s30, v16
	v_sub_u32_e32 v9, v11, v9
	v_cvt_f32_i32_e32 v9, v9
	v_sub_f32_e32 v13, v75, v76
	v_sub_f32_e32 v15, v74, v78
	v_ashrrev_i32_e32 v11, 31, v10
	v_rcp_iflag_f32_e32 v9, v9
	v_lshlrev_b64 v[18:19], 11, v[10:11]
	v_lshl_add_u64 v[18:19], v[6:7], 0, v[18:19]
	v_ashrrev_i32_e32 v17, 31, v16
	v_fma_f32 v9, v9, v15, -v13
	v_cvt_pk_bf16_f32 v9, v9, s0
	global_store_short v[18:19], v9, off sc1
	v_or_b32_e32 v18, 11, v8
	v_max_i32_e32 v9, s31, v12
	v_min_i32_e32 v11, s30, v18
	v_sub_u32_e32 v9, v11, v9
	v_cvt_f32_i32_e32 v9, v9
	v_sub_f32_e32 v12, v74, v75
	v_sub_f32_e32 v13, v73, v77
	v_ashrrev_i32_e32 v15, 31, v14
	v_rcp_iflag_f32_e32 v9, v9
	v_sub_f32_e32 v11, v73, v74
	v_ashrrev_i32_e32 v19, 31, v18
	v_fma_f32 v9, v9, v13, -v12
	v_lshlrev_b64 v[12:13], 11, v[14:15]
	v_cvt_pk_bf16_f32 v9, v9, s0
	v_lshl_add_u64 v[12:13], v[6:7], 0, v[12:13]
	global_store_short v[12:13], v9, off sc1
	v_or_b32_e32 v12, 12, v8
	v_max_i32_e32 v9, s31, v10
	v_min_i32_e32 v10, s30, v12
	v_sub_u32_e32 v9, v10, v9
	v_cvt_f32_i32_e32 v9, v9
	v_sub_f32_e32 v13, v72, v76
	v_sub_f32_e32 v15, v41, v73
	v_rcp_iflag_f32_e32 v9, v9
	s_nop 0
	v_fma_f32 v9, v9, v13, -v11
	v_lshlrev_b64 v[10:11], 11, v[16:17]
	v_cvt_pk_bf16_f32 v9, v9, s0
	v_lshl_add_u64 v[10:11], v[6:7], 0, v[10:11]
	global_store_short v[10:11], v9, off sc1
	v_max_i32_e32 v9, s31, v14
	v_min_i32_e32 v10, s30, v20
	v_sub_u32_e32 v9, v10, v9
	v_cvt_f32_i32_e32 v9, v9
	v_sub_f32_e32 v11, v72, v73
	v_sub_f32_e32 v13, v70, v75
	v_or_b32_e32 v14, 14, v8
	v_rcp_iflag_f32_e32 v9, v9
	s_nop 0
	v_fma_f32 v9, v9, v13, -v11
	v_lshlrev_b64 v[10:11], 11, v[18:19]
	v_cvt_pk_bf16_f32 v9, v9, s0
	v_lshl_add_u64 v[10:11], v[6:7], 0, v[10:11]
	global_store_short v[10:11], v9, off sc1
	v_max_i32_e32 v9, s31, v16
	v_min_i32_e32 v10, s30, v14
	v_sub_u32_e32 v9, v10, v9
	v_cvt_f32_i32_e32 v9, v9
	v_sub_f32_e32 v11, v70, v72
	v_sub_f32_e32 v13, v71, v74
	v_lshlrev_b64 v[16:17], 11, v[20:21]
	v_rcp_iflag_f32_e32 v9, v9
	v_lshl_add_u64 v[16:17], v[6:7], 0, v[16:17]
	v_fma_f32 v9, v9, v13, -v11
	v_ashrrev_i32_e32 v13, 31, v12
	v_lshlrev_b64 v[10:11], 11, v[12:13]
	v_cvt_pk_bf16_f32 v9, v9, s0
	v_lshl_add_u64 v[10:11], v[6:7], 0, v[10:11]
	global_store_short v[10:11], v9, off sc1
	v_or_b32_e32 v10, 15, v8
	v_max_i32_e32 v9, s31, v18
	v_min_i32_e32 v11, s30, v10
	v_sub_u32_e32 v9, v11, v9
	v_cvt_f32_i32_e32 v9, v9
	v_sub_f32_e32 v13, v71, v70
	v_add_u32_e32 v8, 16, v8
	v_min_i32_e32 v8, s30, v8
	v_rcp_iflag_f32_e32 v9, v9
	v_sub_f32_e32 v11, v41, v71
	v_fma_f32 v9, v9, v15, -v13
	v_cvt_pk_bf16_f32 v9, v9, s0
	global_store_short v[16:17], v9, off sc1
	v_max_i32_e32 v9, s31, v12
	v_sub_u32_e32 v8, v8, v9
	v_cvt_f32_i32_e32 v8, v8
	v_sub_f32_e32 v12, v82, v72
	v_ashrrev_i32_e32 v15, 31, v14
	v_rcp_iflag_f32_e32 v8, v8
	s_nop 0
	v_fma_f32 v8, v8, v12, -v11
	v_cvt_pk_bf16_f32 v11, v8, s0
	v_lshlrev_b64 v[8:9], 11, v[14:15]
	v_lshl_add_u64 v[8:9], v[6:7], 0, v[8:9]
	global_store_short v[8:9], v11, off sc1
	v_max_i32_e32 v8, s31, v20
	v_sub_f32_e32 v9, v88, v70
	v_sub_u32_e32 v12, v90, v8

.LBB0_543:
	s_andn2_saveexec_b64 s[10:11], s[14:15]
	s_cbranch_execz .LBB0_508
	v_add_u32_e32 v9, -1, v8
	v_or_b32_e32 v10, 1, v8
	v_max_i32_e32 v9, s31, v9
	v_min_i32_e32 v11, s30, v10
	v_sub_u32_e32 v9, v11, v9
	v_cvt_f32_i32_e32 v9, v9
	v_sub_f32_e32 v12, v84, v85
	v_sub_f32_e32 v13, v84, v86
	v_sub_f32_e32 v14, v83, v85
	v_rcp_iflag_f32_e32 v9, v9
	v_or_b32_e32 v16, 13, v8
	v_ashrrev_i32_e32 v17, 31, v16
	v_fma_f32 v9, v9, v13, -v12
	v_cvt_pk_bf16_f32 v11, v9, s0
	v_ashrrev_i32_e32 v9, 31, v8
	v_lshlrev_b64 v[12:13], 11, v[8:9]
	v_lshl_add_u64 v[12:13], v[6:7], 0, v[12:13]
	global_store_short v[12:13], v11, off sc1
	v_or_b32_e32 v12, 2, v8
	v_max_i32_e32 v9, s31, v8
	v_min_i32_e32 v11, s30, v12
	v_sub_u32_e32 v9, v11, v9
	v_cvt_f32_i32_e32 v9, v9
	v_sub_f32_e32 v13, v83, v84
	v_ashrrev_i32_e32 v11, 31, v10
	v_rcp_iflag_f32_e32 v9, v9
	s_nop 0
	v_fma_f32 v9, v9, v14, -v13
	v_lshlrev_b64 v[14:15], 11, v[10:11]
	v_cvt_pk_bf16_f32 v9, v9, s0
	v_lshl_add_u64 v[14:15], v[6:7], 0, v[14:15]
	global_store_short v[14:15], v9, off sc1
	v_or_b32_e32 v14, 3, v8
	v_max_i32_e32 v9, s31, v10
	v_min_i32_e32 v10, s30, v14
	v_sub_u32_e32 v9, v10, v9
	v_cvt_f32_i32_e32 v9, v9
	v_sub_f32_e32 v11, v81, v83
	v_sub_f32_e32 v13, v81, v84
	v_ashrrev_i32_e32 v15, 31, v14
	v_rcp_iflag_f32_e32 v9, v9
	s_nop 0
	v_fma_f32 v9, v9, v13, -v11
	v_ashrrev_i32_e32 v13, 31, v12
	v_lshlrev_b64 v[10:11], 11, v[12:13]
	v_cvt_pk_bf16_f32 v9, v9, s0
	v_lshl_add_u64 v[10:11], v[6:7], 0, v[10:11]
	global_store_short v[10:11], v9, off sc1
	v_or_b32_e32 v10, 4, v8
	v_max_i32_e32 v9, s31, v12
	v_min_i32_e32 v11, s30, v10
	v_sub_u32_e32 v9, v11, v9
	v_cvt_f32_i32_e32 v9, v9
	v_sub_f32_e32 v12, v80, v81
	v_sub_f32_e32 v13, v80, v83
	v_rcp_iflag_f32_e32 v9, v9
	s_nop 0
	v_fma_f32 v9, v9, v13, -v12
	v_lshlrev_b64 v[12:13], 11, v[14:15]
	v_cvt_pk_bf16_f32 v9, v9, s0
	v_lshl_add_u64 v[12:13], v[6:7], 0, v[12:13]
	global_store_short v[12:13], v9, off sc1
	v_or_b32_e32 v12, 5, v8
	v_max_i32_e32 v9, s31, v14
	v_min_i32_e32 v11, s30, v12
	v_sub_u32_e32 v9, v11, v9
	v_cvt_f32_i32_e32 v9, v9
	v_sub_f32_e32 v13, v79, v80
	v_sub_f32_e32 v14, v79, v81
	v_ashrrev_i32_e32 v11, 31, v10
	v_rcp_iflag_f32_e32 v9, v9
	s_nop 0
	v_fma_f32 v9, v9, v14, -v13
	v_lshlrev_b64 v[14:15], 11, v[10:11]
	v_cvt_pk_bf16_f32 v9, v9, s0
	v_lshl_add_u64 v[14:15], v[6:7], 0, v[14:15]
	global_store_short v[14:15], v9, off sc1
	v_or_b32_e32 v14, 6, v8
	v_max_i32_e32 v9, s31, v10
	v_min_i32_e32 v10, s30, v14
	v_sub_u32_e32 v9, v10, v9
	v_cvt_f32_i32_e32 v9, v9
	v_sub_f32_e32 v11, v78, v79
	v_sub_f32_e32 v13, v78, v80
	v_ashrrev_i32_e32 v15, 31, v14
	v_rcp_iflag_f32_e32 v9, v9
	s_nop 0
	v_fma_f32 v9, v9, v13, -v11
	v_ashrrev_i32_e32 v13, 31, v12
	v_lshlrev_b64 v[10:11], 11, v[12:13]
	v_cvt_pk_bf16_f32 v9, v9, s0
	v_lshl_add_u64 v[10:11], v[6:7], 0, v[10:11]
	global_store_short v[10:11], v9, off sc1
	v_or_b32_e32 v10, 7, v8
	v_max_i32_e32 v9, s31, v12
	v_min_i32_e32 v11, s30, v10
	v_sub_u32_e32 v9, v11, v9
	v_cvt_f32_i32_e32 v9, v9
	v_sub_f32_e32 v12, v77, v78
	v_sub_f32_e32 v13, v77, v79
	v_rcp_iflag_f32_e32 v9, v9
	s_nop 0
	v_fma_f32 v9, v9, v13, -v12
	v_lshlrev_b64 v[12:13], 11, v[14:15]
	v_cvt_pk_bf16_f32 v9, v9, s0
	v_lshl_add_u64 v[12:13], v[6:7], 0, v[12:13]
	global_store_short v[12:13], v9, off sc1
	v_or_b32_e32 v12, 8, v8
	v_max_i32_e32 v9, s31, v14
	v_min_i32_e32 v11, s30, v12
	v_sub_u32_e32 v9, v11, v9
	v_cvt_f32_i32_e32 v9, v9
	v_sub_f32_e32 v13, v76, v77
	v_sub_f32_e32 v14, v76, v78
	v_ashrrev_i32_e32 v11, 31, v10
	v_rcp_iflag_f32_e32 v9, v9
	s_nop 0
	v_fma_f32 v9, v9, v14, -v13
	v_lshlrev_b64 v[14:15], 11, v[10:11]
	v_cvt_pk_bf16_f32 v9, v9, s0
	v_lshl_add_u64 v[14:15], v[6:7], 0, v[14:15]
	global_store_short v[14:15], v9, off sc1
	v_or_b32_e32 v14, 9, v8
	v_max_i32_e32 v9, s31, v10
	v_min_i32_e32 v10, s30, v14
	v_sub_u32_e32 v9, v10, v9
	v_cvt_f32_i32_e32 v9, v9
	v_sub_f32_e32 v11, v75, v76
	v_sub_f32_e32 v13, v75, v77
	v_ashrrev_i32_e32 v15, 31, v14
	v_rcp_iflag_f32_e32 v9, v9
	s_nop 0
	v_fma_f32 v9, v9, v13, -v11
	v_ashrrev_i32_e32 v13, 31, v12
	v_lshlrev_b64 v[10:11], 11, v[12:13]
	v_cvt_pk_bf16_f32 v9, v9, s0
	v_lshl_add_u64 v[10:11], v[6:7], 0, v[10:11]
	global_store_short v[10:11], v9, off sc1
	v_or_b32_e32 v10, 10, v8
	v_max_i32_e32 v9, s31, v12
	v_min_i32_e32 v11, s30, v10
	v_sub_u32_e32 v9, v11, v9
	v_cvt_f32_i32_e32 v9, v9
	v_sub_f32_e32 v12, v74, v75
	v_sub_f32_e32 v13, v74, v76
	v_rcp_iflag_f32_e32 v9, v9
	s_nop 0
	v_fma_f32 v9, v9, v13, -v12
	v_lshlrev_b64 v[12:13], 11, v[14:15]
	v_cvt_pk_bf16_f32 v9, v9, s0
	v_lshl_add_u64 v[12:13], v[6:7], 0, v[12:13]
	global_store_short v[12:13], v9, off sc1
	v_or_b32_e32 v12, 11, v8
	v_max_i32_e32 v9, s31, v14
	v_min_i32_e32 v11, s30, v12
	v_sub_u32_e32 v9, v11, v9
	v_cvt_f32_i32_e32 v9, v9
	v_sub_f32_e32 v13, v73, v74
	v_sub_f32_e32 v14, v73, v75
	v_ashrrev_i32_e32 v11, 31, v10
	v_rcp_iflag_f32_e32 v9, v9
	s_nop 0
	v_fma_f32 v9, v9, v14, -v13
	v_lshlrev_b64 v[14:15], 11, v[10:11]
	v_cvt_pk_bf16_f32 v9, v9, s0
	v_lshl_add_u64 v[14:15], v[6:7], 0, v[14:15]
	global_store_short v[14:15], v9, off sc1
	v_or_b32_e32 v14, 12, v8
	v_max_i32_e32 v9, s31, v10
	v_min_i32_e32 v10, s30, v14
	v_sub_u32_e32 v9, v10, v9
	v_cvt_f32_i32_e32 v9, v9
	v_sub_f32_e32 v11, v72, v73
	v_sub_f32_e32 v13, v72, v74
	v_ashrrev_i32_e32 v15, 31, v14
	v_rcp_iflag_f32_e32 v9, v9
	s_nop 0
	v_fma_f32 v9, v9, v13, -v11
	v_ashrrev_i32_e32 v13, 31, v12
	v_lshlrev_b64 v[10:11], 11, v[12:13]
	v_cvt_pk_bf16_f32 v9, v9, s0
	v_lshl_add_u64 v[10:11], v[6:7], 0, v[10:11]
	global_store_short v[10:11], v9, off sc1
	v_max_i32_e32 v9, s31, v12
	v_min_i32_e32 v10, s30, v16
	v_sub_u32_e32 v9, v10, v9
	v_cvt_f32_i32_e32 v9, v9
	v_sub_f32_e32 v11, v70, v72
	v_sub_f32_e32 v12, v70, v73
	v_sub_f32_e32 v13, v71, v72
	v_rcp_iflag_f32_e32 v9, v9
	s_nop 0
	v_fma_f32 v9, v9, v12, -v11
	v_lshlrev_b64 v[10:11], 11, v[14:15]
	v_cvt_pk_bf16_f32 v9, v9, s0
	v_lshl_add_u64 v[10:11], v[6:7], 0, v[10:11]
	v_or_b32_e32 v12, 14, v8
	global_store_short v[10:11], v9, off sc1
	v_max_i32_e32 v9, s31, v14
	v_min_i32_e32 v10, s30, v12
	v_sub_u32_e32 v9, v10, v9
	v_cvt_f32_i32_e32 v9, v9
	v_sub_f32_e32 v11, v71, v70
	v_sub_f32_e32 v14, v41, v70
	v_rcp_iflag_f32_e32 v9, v9
	s_nop 0
	v_fma_f32 v9, v9, v13, -v11
	v_lshlrev_b64 v[10:11], 11, v[16:17]
	v_cvt_pk_bf16_f32 v9, v9, s0
	v_lshl_add_u64 v[10:11], v[6:7], 0, v[10:11]
	global_store_short v[10:11], v9, off sc1
	v_or_b32_e32 v10, 15, v8
	v_max_i32_e32 v9, s31, v16
	v_min_i32_e32 v11, s30, v10
	v_sub_u32_e32 v9, v11, v9
	v_cvt_f32_i32_e32 v9, v9
	v_sub_f32_e32 v13, v41, v71
	v_add_u32_e32 v8, 16, v8
	v_max_i32_e32 v11, s31, v12
	v_rcp_iflag_f32_e32 v9, v9
	v_min_i32_e32 v8, s30, v8
	v_fma_f32 v9, v9, v14, -v13
	v_ashrrev_i32_e32 v13, 31, v12
	v_lshlrev_b64 v[14:15], 11, v[12:13]
	v_cvt_pk_bf16_f32 v9, v9, s0
	v_lshl_add_u64 v[14:15], v[6:7], 0, v[14:15]
	global_store_short v[14:15], v9, off sc1
	v_sub_f32_e32 v9, v82, v71
	v_sub_u32_e32 v12, v8, v11
	s_branch .LBB0_508

.LBB0_562:
	s_or_b64 exec, exec, s[12:13]
	v_cvt_f32_i32_e32 v2, v38
	v_sub_f32_e32 v1, v170, v165
	v_ashrrev_i32_e32 v37, 31, v36
	v_cmp_lt_i32_e32 vcc, v223, v222
	v_rcp_iflag_f32_e32 v2, v2
	s_add_i32 s12, s59, s41
	s_ashr_i32 s13, s12, 31
	s_lshl_b64 s[12:13], s[12:13], 11
	v_fma_f32 v1, v3, v2, -v1
	v_lshlrev_b64 v[2:3], 11, v[36:37]
	v_cvt_pk_bf16_f32 v1, v1, s0
	v_lshl_add_u64 v[2:3], v[44:45], 0, v[2:3]
	global_store_short v[2:3], v1, off sc1
	s_waitcnt lgkmcnt(0)
	s_barrier
	v_add_u32_e32 v2, s35, v140
	ds_read_b128 v[112:115], v2 offset:56320
	v_cndmask_b32_e32 v1, v221, v223, vcc
	v_lshlrev_b32_e32 v110, 2, v1
	v_cmp_lt_i32_e32 vcc, v224, v222
	v_lshl_add_u64 v[104:105], v[102:103], 0, s[12:13]
	s_waitcnt lgkmcnt(0)
	v_pk_mul_f32 v[2:3], v[114:115], v[114:115]
	v_pk_mul_f32 v[36:37], v[112:113], v[112:113]
	v_cndmask_b32_e32 v1, v221, v224, vcc
	v_pk_mov_b32 v[38:39], v[36:37], v[2:3] op_sel:[1,0]
	v_mov_b32_e32 v37, v3
	v_pk_add_f32 v[2:3], v[38:39], v[36:37]
	v_add_u32_e32 v36, s45, v140
	ds_read_b128 v[36:39], v36 offset:56320
	v_lshlrev_b32_e32 v109, 2, v1
	v_cmp_lt_i32_e32 vcc, v225, v222
	s_waitcnt lgkmcnt(0)
	v_pk_mul_f32 v[116:117], v[38:39], v[38:39]
	v_pk_mul_f32 v[118:119], v[36:37], v[36:37]
	v_cndmask_b32_e32 v1, v221, v225, vcc
	v_pk_mov_b32 v[120:121], v[118:119], v[116:117] op_sel:[1,0]
	v_mov_b32_e32 v119, v117
	v_pk_add_f32 v[116:117], v[120:121], v[118:119]
	v_mov_b32_e32 v119, v2
	v_mov_b32_e32 v118, v116
	v_mov_b32_e32 v2, v117
	v_pk_add_f32 v[2:3], v[118:119], v[2:3]
	ds_bpermute_b32 v117, v110, v3
	ds_bpermute_b32 v116, v110, v2
	v_lshlrev_b32_e32 v108, 2, v1
	v_cmp_lt_i32_e32 vcc, v226, v222
	s_waitcnt lgkmcnt(0)
	v_pk_add_f32 v[2:3], v[2:3], v[116:117]
	ds_bpermute_b32 v117, v109, v3
	ds_bpermute_b32 v116, v109, v2
	v_cndmask_b32_e32 v1, v221, v226, vcc
	v_lshlrev_b32_e32 v107, 2, v1
	v_cmp_lt_i32_e32 vcc, v227, v222
	s_waitcnt lgkmcnt(0)
	v_pk_add_f32 v[2:3], v[2:3], v[116:117]
	ds_bpermute_b32 v117, v108, v3
	ds_bpermute_b32 v116, v108, v2
	v_cndmask_b32_e32 v1, v221, v227, vcc
	v_lshlrev_b32_e32 v106, 2, v1
	v_cmp_lt_i32_e32 vcc, v228, v222
	s_waitcnt lgkmcnt(0)
	v_pk_add_f32 v[2:3], v[2:3], v[116:117]
	ds_bpermute_b32 v117, v107, v3
	ds_bpermute_b32 v116, v107, v2
	v_cndmask_b32_e32 v1, v221, v228, vcc
	v_lshlrev_b32_e32 v1, 2, v1
	s_waitcnt lgkmcnt(0)
	v_pk_add_f32 v[2:3], v[2:3], v[116:117]
	ds_bpermute_b32 v117, v106, v3
	ds_bpermute_b32 v116, v106, v2
	s_waitcnt lgkmcnt(0)
	v_pk_add_f32 v[2:3], v[2:3], v[116:117]
	ds_bpermute_b32 v117, v1, v3
	ds_bpermute_b32 v116, v1, v2
	s_waitcnt lgkmcnt(0)
	v_pk_add_f32 v[116:117], v[2:3], v[116:117]
	v_mov_b64_e32 v[2:3], s[64:65]
	v_pk_fma_f32 v[116:117], v[116:117], s[80:81], v[2:3] op_sel_hi:[1,0,0]
	s_nop 0
	v_mul_f32_e32 v111, 0x4b800000, v117
	v_cmp_gt_f32_e64 s[12:13], s92, v117
	v_cmp_gt_f32_e32 vcc, s92, v116
	s_nop 0
	v_cndmask_b32_e64 v111, v117, v111, s[12:13]
	v_rsq_f32_e32 v111, v111
	s_nop 0
	v_mul_f32_e32 v117, 0x45800000, v111
	v_cndmask_b32_e64 v118, v111, v117, s[12:13]
	v_pk_mul_f32 v[112:113], v[112:113], v[118:119] op_sel_hi:[1,0]
	v_pk_mul_f32 v[114:115], v[114:115], v[118:119] op_sel_hi:[1,0]
	v_pk_mul_f32 v[112:113], v[20:21], v[112:113]
	v_pk_mul_f32 v[114:115], v[22:23], v[114:115]
	v_mul_f32_e32 v111, 0xbfb8aa3b, v112
	v_exp_f32_e32 v111, v111
	s_add_i32 s12, s59, s44
	s_ashr_i32 s13, s12, 31
	s_lshl_b64 s[12:13], s[12:13], 11
	v_add_f32_e32 v111, 1.0, v111
	v_rcp_f32_e32 v118, v111
	v_mul_f32_e32 v111, 0xbfb8aa3b, v113
	v_exp_f32_e32 v111, v111
	s_nop 0
	v_add_f32_e32 v111, 1.0, v111
	v_rcp_f32_e32 v119, v111
	v_mul_f32_e32 v111, 0xbfb8aa3b, v114
	v_exp_f32_e32 v111, v111
	v_pk_mul_f32 v[112:113], v[112:113], v[118:119]
	s_nop 0
	v_cvt_pk_bf16_f32 v112, v112, v113
	v_add_f32_e32 v111, 1.0, v111
	v_rcp_f32_e32 v118, v111
	v_mul_f32_e32 v111, 0xbfb8aa3b, v115
	v_exp_f32_e32 v111, v111
	s_nop 0
	v_add_f32_e32 v111, 1.0, v111
	v_rcp_f32_e32 v119, v111
	s_nop 0
	v_pk_mul_f32 v[114:115], v[114:115], v[118:119]
	s_nop 0
	v_cvt_pk_bf16_f32 v113, v114, v115
	global_store_dwordx2 v[104:105], v[112:113], off offset:512 sc1
	v_mul_f32_e32 v104, 0x4b800000, v116
	v_cndmask_b32_e32 v104, v116, v104, vcc
	v_rsq_f32_e32 v104, v104
	s_nop 0
	v_mul_f32_e32 v105, 0x45800000, v104
	v_cndmask_b32_e32 v104, v104, v105, vcc
	v_pk_mul_f32 v[36:37], v[36:37], v[104:105] op_sel_hi:[1,0]
	v_pk_mul_f32 v[38:39], v[38:39], v[104:105] op_sel_hi:[1,0]
	v_pk_mul_f32 v[36:37], v[20:21], v[36:37]
	v_pk_mul_f32 v[38:39], v[22:23], v[38:39]
	v_mul_f32_e32 v104, 0xbfb8aa3b, v36
	v_mul_f32_e32 v105, 0xbfb8aa3b, v37
	v_exp_f32_e32 v104, v104
	v_exp_f32_e32 v105, v105
	v_add_f32_e32 v104, 1.0, v104
	v_add_f32_e32 v105, 1.0, v105
	v_rcp_f32_e32 v104, v104
	v_rcp_f32_e32 v105, v105
	s_nop 0
	v_pk_mul_f32 v[36:37], v[36:37], v[104:105]
	v_mul_f32_e32 v104, 0xbfb8aa3b, v38
	v_mul_f32_e32 v105, 0xbfb8aa3b, v39
	v_exp_f32_e32 v104, v104
	v_exp_f32_e32 v105, v105
	v_cvt_pk_bf16_f32 v36, v36, v37
	v_add_f32_e32 v104, 1.0, v104
	v_add_f32_e32 v105, 1.0, v105
	v_rcp_f32_e32 v104, v104
	v_rcp_f32_e32 v105, v105
	s_nop 0
	v_pk_mul_f32 v[38:39], v[38:39], v[104:105]
	s_nop 0
	v_cvt_pk_bf16_f32 v37, v38, v39
	v_lshl_add_u64 v[38:39], v[102:103], 0, s[12:13]
	global_store_dwordx2 v[38:39], v[36:37], off offset:512 sc1
	v_add_u32_e32 v36, s56, v140
	ds_read_b128 v[112:115], v36 offset:56320
	s_add_i32 s12, s59, s46
	s_ashr_i32 s13, s12, 31
	s_lshl_b64 s[12:13], s[12:13], 11
	s_waitcnt lgkmcnt(0)
	v_pk_mul_f32 v[36:37], v[114:115], v[114:115]
	v_pk_mul_f32 v[38:39], v[112:113], v[112:113]
	s_nop 0
	v_pk_mov_b32 v[104:105], v[38:39], v[36:37] op_sel:[1,0]
	v_mov_b32_e32 v39, v37
	v_add_u32_e32 v36, s58, v140
	v_pk_add_f32 v[116:117], v[104:105], v[38:39]
	ds_read_b128 v[36:39], v36 offset:56320
	v_lshl_add_u64 v[104:105], v[102:103], 0, s[12:13]
	s_waitcnt lgkmcnt(0)
	v_pk_mul_f32 v[118:119], v[38:39], v[38:39]
	v_pk_mul_f32 v[120:121], v[36:37], v[36:37]
	s_nop 0
	v_pk_mov_b32 v[122:123], v[120:121], v[118:119] op_sel:[1,0]
	v_mov_b32_e32 v121, v119
	v_pk_add_f32 v[118:119], v[122:123], v[120:121]
	v_mov_b32_e32 v121, v116
	v_mov_b32_e32 v120, v118
	v_mov_b32_e32 v116, v119
	v_pk_add_f32 v[116:117], v[120:121], v[116:117]
	ds_bpermute_b32 v111, v110, v117
	ds_bpermute_b32 v110, v110, v116
	s_waitcnt lgkmcnt(0)
	v_pk_add_f32 v[110:111], v[116:117], v[110:111]
	ds_bpermute_b32 v117, v109, v111
	ds_bpermute_b32 v116, v109, v110
	s_waitcnt lgkmcnt(0)
	v_pk_add_f32 v[110:111], v[110:111], v[116:117]
	ds_bpermute_b32 v109, v108, v111
	ds_bpermute_b32 v108, v108, v110
	s_waitcnt lgkmcnt(0)
	v_pk_add_f32 v[108:109], v[110:111], v[108:109]
	ds_bpermute_b32 v111, v107, v109
	ds_bpermute_b32 v110, v107, v108
	s_waitcnt lgkmcnt(0)
	v_pk_add_f32 v[108:109], v[108:109], v[110:111]
	ds_bpermute_b32 v107, v106, v109
	ds_bpermute_b32 v106, v106, v108
	s_waitcnt lgkmcnt(0)
	v_pk_add_f32 v[106:107], v[108:109], v[106:107]
	ds_bpermute_b32 v109, v1, v107
	ds_bpermute_b32 v108, v1, v106
	s_waitcnt lgkmcnt(0)
	v_pk_add_f32 v[106:107], v[106:107], v[108:109]
	s_nop 0
	v_pk_fma_f32 v[2:3], v[106:107], s[80:81], v[2:3] op_sel_hi:[1,0,0]
	s_nop 0
	v_mul_f32_e32 v1, 0x4b800000, v3
	v_cmp_gt_f32_e64 s[12:13], s92, v3
	v_cmp_gt_f32_e32 vcc, s92, v2
	s_nop 0
	v_cndmask_b32_e64 v1, v3, v1, s[12:13]
	v_rsq_f32_e32 v1, v1
	s_nop 0
	v_mul_f32_e32 v3, 0x45800000, v1
	v_cndmask_b32_e64 v106, v1, v3, s[12:13]
	v_pk_mul_f32 v[108:109], v[112:113], v[106:107] op_sel_hi:[1,0]
	v_pk_mul_f32 v[106:107], v[114:115], v[106:107] op_sel_hi:[1,0]
	v_pk_mul_f32 v[108:109], v[20:21], v[108:109]
	v_pk_mul_f32 v[106:107], v[22:23], v[106:107]
	v_mul_f32_e32 v1, 0xbfb8aa3b, v108
	v_exp_f32_e32 v1, v1
	s_add_i32 s12, s59, s57
	s_ashr_i32 s13, s12, 31
	s_lshl_b64 s[12:13], s[12:13], 11
	v_add_f32_e32 v1, 1.0, v1
	v_rcp_f32_e32 v110, v1
	v_mul_f32_e32 v1, 0xbfb8aa3b, v109
	v_exp_f32_e32 v1, v1
	s_cmp_eq_u32 s40, s81
	v_add_f32_e32 v1, 1.0, v1
	v_rcp_f32_e32 v111, v1
	v_mul_f32_e32 v1, 0xbfb8aa3b, v106
	v_exp_f32_e32 v1, v1
	v_pk_mul_f32 v[108:109], v[108:109], v[110:111]
	s_nop 0
	v_cvt_pk_bf16_f32 v108, v108, v109
	v_add_f32_e32 v1, 1.0, v1
	v_rcp_f32_e32 v110, v1
	v_mul_f32_e32 v1, 0xbfb8aa3b, v107
	v_exp_f32_e32 v1, v1
	s_nop 0
	v_add_f32_e32 v1, 1.0, v1
	v_rcp_f32_e32 v111, v1
	v_mul_f32_e32 v1, 0x4b800000, v2
	v_cndmask_b32_e32 v1, v2, v1, vcc
	v_rsq_f32_e32 v1, v1
	v_pk_mul_f32 v[106:107], v[106:107], v[110:111]
	v_mul_f32_e32 v2, 0x45800000, v1
	v_cndmask_b32_e32 v2, v1, v2, vcc
	v_pk_mul_f32 v[36:37], v[36:37], v[2:3] op_sel_hi:[1,0]
	v_pk_mul_f32 v[2:3], v[38:39], v[2:3] op_sel_hi:[1,0]
	v_pk_mul_f32 v[36:37], v[20:21], v[36:37]
	v_pk_mul_f32 v[2:3], v[22:23], v[2:3]
	v_mul_f32_e32 v1, 0xbfb8aa3b, v36
	v_exp_f32_e32 v1, v1
	v_cvt_pk_bf16_f32 v109, v106, v107
	global_store_dwordx2 v[104:105], v[108:109], off offset:512 sc1
	v_add_f32_e32 v1, 1.0, v1
	v_rcp_f32_e32 v38, v1
	v_mul_f32_e32 v1, 0xbfb8aa3b, v37
	v_exp_f32_e32 v1, v1
	s_nop 0
	v_add_f32_e32 v1, 1.0, v1
	v_rcp_f32_e32 v39, v1
	v_mul_f32_e32 v1, 0xbfb8aa3b, v2
	v_exp_f32_e32 v1, v1
	v_pk_mul_f32 v[36:37], v[36:37], v[38:39]
	s_nop 0
	v_cvt_pk_bf16_f32 v36, v36, v37
	v_add_f32_e32 v1, 1.0, v1
	v_rcp_f32_e32 v38, v1
	v_mul_f32_e32 v1, 0xbfb8aa3b, v3
	v_exp_f32_e32 v1, v1
	s_nop 0
	v_add_f32_e32 v1, 1.0, v1
	v_rcp_f32_e32 v39, v1
	s_nop 0
	v_pk_mul_f32 v[2:3], v[2:3], v[38:39]
	s_nop 0
	v_cvt_pk_bf16_f32 v37, v2, v3
	v_lshl_add_u64 v[2:3], v[102:103], 0, s[12:13]
	global_store_dwordx2 v[2:3], v[36:37], off offset:512 sc1
	s_cbranch_scc1 .LBB0_605

.LBB0_591:
	global_load_dword v160, v[46:47], off
	global_load_dword v158, v[46:47], off offset:1024
	global_load_dword v157, v[46:47], off offset:2048
	global_load_dword v156, v[46:47], off offset:3072
	global_load_dword v155, v[48:49], off
	global_load_dword v154, v[50:51], off
	global_load_dword v153, v[52:53], off
	global_load_dword v129, v[54:55], off
	global_load_dword v127, v[56:57], off
	global_load_dword v126, v[58:59], off
	global_load_dword v125, v[60:61], off
	global_load_dword v123, v[62:63], off
	global_load_dword v122, v[64:65], off
	global_load_dword v121, v[66:67], off
	global_load_dword v119, v[68:69], off
	global_load_dword v118, v[70:71], off
	global_load_dword v116, v[72:73], off
	global_load_dword v115, v[74:75], off
	global_load_dword v113, v[76:77], off
	global_load_dword v112, v[78:79], off
	global_load_dword v111, v[80:81], off
	global_load_dword v109, v[82:83], off
	global_load_dword v108, v[84:85], off
	global_load_dword v106, v[86:87], off
	global_load_dword v105, v[88:89], off
	global_load_dword v104, v[90:91], off
	global_load_dword v39, v[92:93], off
	global_load_dword v38, v[94:95], off
	global_load_dword v36, v[96:97], off
	global_load_dword v2, v[98:99], off
	global_load_dword v1, v[100:101], off
	ds_read_u16 v3, v137
	ds_read_u16 v37, v137 offset:512
	ds_read_u16 v107, v137 offset:1024
	ds_read_u16 v110, v137 offset:1536
	ds_read_u16 v114, v137 offset:2048
	ds_read_u16 v117, v137 offset:2560
	ds_read_u16 v120, v137 offset:3072
	ds_read_u16 v124, v137 offset:3584
	s_waitcnt lgkmcnt(7)
	v_lshlrev_b32_e32 v3, 16, v3
	s_waitcnt lgkmcnt(6)
	v_lshlrev_b32_e32 v37, 16, v37
	s_waitcnt lgkmcnt(5)
	v_lshlrev_b32_e32 v107, 16, v107
	s_waitcnt lgkmcnt(4)
	v_lshlrev_b32_e32 v110, 16, v110
	ds_read_u16 v128, v137 offset:4096
	ds_read_u16 v159, v137 offset:4608
	ds_read_u16 v161, v137 offset:5120
	ds_read_u16 v162, v137 offset:5632
	ds_read_u16 v163, v137 offset:6144
	ds_read_u16 v164, v137 offset:6656
	ds_read_u16 v165, v137 offset:7168
	ds_read_u16 v166, v137 offset:7680
	s_waitcnt lgkmcnt(11)
	v_lshlrev_b32_e32 v114, 16, v114
	s_waitcnt lgkmcnt(10)
	v_lshlrev_b32_e32 v117, 16, v117
	s_waitcnt lgkmcnt(9)
	v_lshlrev_b32_e32 v120, 16, v120
	s_waitcnt lgkmcnt(8)
	v_lshlrev_b32_e32 v124, 16, v124
	s_waitcnt lgkmcnt(7)
	v_lshlrev_b32_e32 v128, 16, v128
	s_waitcnt lgkmcnt(6)
	v_lshlrev_b32_e32 v159, 16, v159
	s_waitcnt lgkmcnt(5)
	v_lshlrev_b32_e32 v161, 16, v161
	s_waitcnt lgkmcnt(4)
	v_lshlrev_b32_e32 v162, 16, v162
	s_waitcnt lgkmcnt(3)
	v_lshlrev_b32_e32 v163, 16, v163
	s_waitcnt lgkmcnt(2)
	v_lshlrev_b32_e32 v164, 16, v164
	s_waitcnt lgkmcnt(1)
	v_lshlrev_b32_e32 v165, 16, v165
	s_waitcnt lgkmcnt(0)
	v_lshlrev_b32_e32 v166, 16, v166
	s_and_b32 s0, s59, 0xffffff00
	s_and_b32 s3, s59, 0x7ffff000
	s_add_i32 s12, s0, 0x100
	s_add_i32 s13, s3, 0x1000
	s_cmpk_lt_i32 s1, 0x100
	s_cselect_b32 s30, s0, s3
	s_cselect_b32 s31, s12, s13
	s_waitcnt vmcnt(30)
	v_fma_f32 v3, v160, v3, v134
	s_waitcnt vmcnt(29)
	v_fmac_f32_e32 v3, v158, v37
	v_fma_f32 v37, v160, v37, v134
	s_waitcnt vmcnt(28)
	v_fmac_f32_e32 v3, v157, v107
	v_fmac_f32_e32 v37, v158, v107
	v_fma_f32 v107, v160, v107, v134
	s_waitcnt vmcnt(27)
	v_fmac_f32_e32 v3, v156, v110
	v_fmac_f32_e32 v37, v157, v110
	v_fmac_f32_e32 v107, v158, v110
	v_fma_f32 v110, v160, v110, v134
	s_waitcnt vmcnt(26)
	v_fmac_f32_e32 v3, v155, v114
	v_fmac_f32_e32 v37, v156, v114
	v_fmac_f32_e32 v107, v157, v114
	v_fmac_f32_e32 v110, v158, v114
	v_fma_f32 v114, v160, v114, v134
	s_waitcnt vmcnt(25)
	v_fmac_f32_e32 v3, v154, v117
	v_fmac_f32_e32 v37, v155, v117
	v_fmac_f32_e32 v107, v156, v117
	v_fmac_f32_e32 v110, v157, v117
	v_fmac_f32_e32 v114, v158, v117
	v_fma_f32 v117, v160, v117, v134
	s_waitcnt vmcnt(24)
	v_fmac_f32_e32 v3, v153, v120
	v_fmac_f32_e32 v37, v154, v120
	v_fmac_f32_e32 v107, v155, v120
	v_fmac_f32_e32 v110, v156, v120
	v_fmac_f32_e32 v114, v157, v120
	v_fmac_f32_e32 v117, v158, v120
	v_fma_f32 v120, v160, v120, v134
	s_waitcnt vmcnt(23)
	v_fmac_f32_e32 v3, v129, v124
	v_fmac_f32_e32 v37, v153, v124
	v_fmac_f32_e32 v107, v154, v124
	v_fmac_f32_e32 v110, v155, v124
	v_fmac_f32_e32 v114, v156, v124
	v_fmac_f32_e32 v117, v157, v124
	v_fmac_f32_e32 v120, v158, v124
	v_fma_f32 v124, v160, v124, v134
	s_waitcnt vmcnt(22)
	v_fmac_f32_e32 v3, v127, v128
	v_fmac_f32_e32 v37, v129, v128
	v_fmac_f32_e32 v107, v153, v128
	v_fmac_f32_e32 v110, v154, v128
	v_fmac_f32_e32 v114, v155, v128
	v_fmac_f32_e32 v117, v156, v128
	v_fmac_f32_e32 v120, v157, v128
	v_fmac_f32_e32 v124, v158, v128
	v_fma_f32 v128, v160, v128, v134
	s_waitcnt vmcnt(21)
	v_fmac_f32_e32 v3, v126, v159
	v_fmac_f32_e32 v37, v127, v159
	v_fmac_f32_e32 v107, v129, v159
	v_fmac_f32_e32 v110, v153, v159
	v_fmac_f32_e32 v114, v154, v159
	v_fmac_f32_e32 v117, v155, v159
	v_fmac_f32_e32 v120, v156, v159
	v_fmac_f32_e32 v124, v157, v159
	v_fmac_f32_e32 v128, v158, v159
	v_fma_f32 v159, v160, v159, v134
	s_waitcnt vmcnt(20)
	v_fmac_f32_e32 v3, v125, v161
	v_fmac_f32_e32 v37, v126, v161
	v_fmac_f32_e32 v107, v127, v161
	v_fmac_f32_e32 v110, v129, v161
	v_fmac_f32_e32 v114, v153, v161
	v_fmac_f32_e32 v117, v154, v161
	v_fmac_f32_e32 v120, v155, v161
	v_fmac_f32_e32 v124, v156, v161
	v_fmac_f32_e32 v128, v157, v161
	v_fmac_f32_e32 v159, v158, v161
	v_fma_f32 v161, v160, v161, v134
	s_waitcnt vmcnt(19)
	v_fmac_f32_e32 v3, v123, v162
	v_fmac_f32_e32 v37, v125, v162
	v_fmac_f32_e32 v107, v126, v162
	v_fmac_f32_e32 v110, v127, v162
	v_fmac_f32_e32 v114, v129, v162
	v_fmac_f32_e32 v117, v153, v162
	v_fmac_f32_e32 v120, v154, v162
	v_fmac_f32_e32 v124, v155, v162
	v_fmac_f32_e32 v128, v156, v162
	v_fmac_f32_e32 v159, v157, v162
	v_fmac_f32_e32 v161, v158, v162
	v_fma_f32 v162, v160, v162, v134
	s_waitcnt vmcnt(18)
	v_fmac_f32_e32 v3, v122, v163
	v_fmac_f32_e32 v37, v123, v163
	v_fmac_f32_e32 v107, v125, v163
	v_fmac_f32_e32 v110, v126, v163
	v_fmac_f32_e32 v114, v127, v163
	v_fmac_f32_e32 v117, v129, v163
	v_fmac_f32_e32 v120, v153, v163
	v_fmac_f32_e32 v124, v154, v163
	v_fmac_f32_e32 v128, v155, v163
	v_fmac_f32_e32 v159, v156, v163
	v_fmac_f32_e32 v161, v157, v163
	v_fmac_f32_e32 v162, v158, v163
	v_fma_f32 v163, v160, v163, v134
	s_waitcnt vmcnt(17)
	v_fmac_f32_e32 v3, v121, v164
	v_fmac_f32_e32 v37, v122, v164
	v_fmac_f32_e32 v107, v123, v164
	v_fmac_f32_e32 v110, v125, v164
	v_fmac_f32_e32 v114, v126, v164
	v_fmac_f32_e32 v117, v127, v164
	v_fmac_f32_e32 v120, v129, v164
	v_fmac_f32_e32 v124, v153, v164
	v_fmac_f32_e32 v128, v154, v164
	v_fmac_f32_e32 v159, v155, v164
	v_fmac_f32_e32 v161, v156, v164
	v_fmac_f32_e32 v162, v157, v164
	v_fmac_f32_e32 v163, v158, v164
	v_fma_f32 v164, v160, v164, v134
	s_waitcnt vmcnt(16)
	v_fmac_f32_e32 v3, v119, v165
	v_fmac_f32_e32 v37, v121, v165
	v_fmac_f32_e32 v107, v122, v165
	v_fmac_f32_e32 v110, v123, v165
	v_fmac_f32_e32 v114, v125, v165
	v_fmac_f32_e32 v117, v126, v165
	v_fmac_f32_e32 v120, v127, v165
	v_fmac_f32_e32 v124, v129, v165
	v_fmac_f32_e32 v128, v153, v165
	v_fmac_f32_e32 v159, v154, v165
	v_fmac_f32_e32 v161, v155, v165
	v_fmac_f32_e32 v162, v156, v165
	v_fmac_f32_e32 v163, v157, v165
	v_fmac_f32_e32 v164, v158, v165
	v_fma_f32 v165, v160, v165, v134
	s_waitcnt vmcnt(15)
	v_fmac_f32_e32 v3, v118, v166
	v_fmac_f32_e32 v37, v119, v166
	v_fmac_f32_e32 v107, v121, v166
	v_fmac_f32_e32 v110, v122, v166
	v_fmac_f32_e32 v114, v123, v166
	v_fmac_f32_e32 v117, v125, v166
	v_fmac_f32_e32 v120, v126, v166
	v_fmac_f32_e32 v124, v127, v166
	v_fmac_f32_e32 v128, v129, v166
	v_fmac_f32_e32 v159, v153, v166
	v_fmac_f32_e32 v161, v154, v166
	v_fmac_f32_e32 v162, v155, v166
	v_fmac_f32_e32 v163, v156, v166
	v_fmac_f32_e32 v164, v157, v166
	v_fmac_f32_e32 v165, v158, v166
	v_fma_f32 v160, v160, v166, v134
	ds_read_u16 v166, v137 offset:8192
	s_waitcnt lgkmcnt(0)
	v_lshlrev_b32_e32 v166, 16, v166
	v_fmac_f32_e32 v160, v158, v166
	ds_read_u16 v158, v137 offset:8704
	v_fmac_f32_e32 v165, v157, v166
	v_fmac_f32_e32 v164, v156, v166
	v_fmac_f32_e32 v163, v155, v166
	v_fmac_f32_e32 v162, v154, v166
	s_waitcnt lgkmcnt(0)
	v_lshlrev_b32_e32 v158, 16, v158
	v_fmac_f32_e32 v160, v157, v158
	ds_read_u16 v157, v137 offset:9216
	v_fmac_f32_e32 v165, v156, v158
	v_fmac_f32_e32 v164, v155, v158
	v_fmac_f32_e32 v163, v154, v158
	v_fmac_f32_e32 v161, v153, v166
	s_waitcnt lgkmcnt(0)
	v_lshlrev_b32_e32 v157, 16, v157
	v_fmac_f32_e32 v160, v156, v157
	ds_read_u16 v156, v137 offset:9728
	v_fmac_f32_e32 v165, v155, v157
	v_fmac_f32_e32 v164, v154, v157
	v_fmac_f32_e32 v162, v153, v158
	v_fmac_f32_e32 v163, v153, v157
	s_waitcnt lgkmcnt(0)
	v_lshlrev_b32_e32 v156, 16, v156
	v_fmac_f32_e32 v160, v155, v156
	ds_read_u16 v155, v137 offset:10240
	v_fmac_f32_e32 v165, v154, v156
	v_fmac_f32_e32 v164, v153, v156
	v_fmac_f32_e32 v159, v129, v166
	v_fmac_f32_e32 v161, v129, v158
	s_waitcnt lgkmcnt(0)
	v_lshlrev_b32_e32 v155, 16, v155
	v_fmac_f32_e32 v160, v154, v155
	ds_read_u16 v154, v137 offset:10752
	v_fmac_f32_e32 v165, v153, v155
	v_fmac_f32_e32 v162, v129, v157
	v_fmac_f32_e32 v163, v129, v156
	v_fmac_f32_e32 v164, v129, v155
	s_waitcnt lgkmcnt(0)
	v_lshlrev_b32_e32 v154, 16, v154
	v_fmac_f32_e32 v160, v153, v154
	ds_read_u16 v153, v137 offset:11264
	v_fmac_f32_e32 v165, v129, v154
	v_fmac_f32_e32 v128, v127, v166
	v_fmac_f32_e32 v159, v127, v158
	v_fmac_f32_e32 v161, v127, v157
	s_waitcnt lgkmcnt(0)
	v_lshlrev_b32_e32 v153, 16, v153
	v_fmac_f32_e32 v160, v129, v153
	ds_read_u16 v129, v137 offset:11776
	v_fmac_f32_e32 v162, v127, v156
	v_fmac_f32_e32 v163, v127, v155
	v_fmac_f32_e32 v164, v127, v154
	v_fmac_f32_e32 v165, v127, v153
	s_waitcnt lgkmcnt(0)
	v_lshlrev_b32_e32 v129, 16, v129
	v_fmac_f32_e32 v160, v127, v129
	ds_read_u16 v127, v137 offset:12288
	v_fmac_f32_e32 v124, v126, v166
	v_fmac_f32_e32 v128, v126, v158
	v_fmac_f32_e32 v159, v126, v157
	v_fmac_f32_e32 v161, v126, v156
	s_waitcnt lgkmcnt(0)
	v_lshlrev_b32_e32 v127, 16, v127
	v_fmac_f32_e32 v162, v126, v155
	v_fmac_f32_e32 v163, v126, v154
	v_fmac_f32_e32 v164, v126, v153
	v_fmac_f32_e32 v165, v126, v129
	v_fmac_f32_e32 v160, v126, v127
	ds_read_u16 v126, v137 offset:12800
	v_fmac_f32_e32 v120, v125, v166
	v_fmac_f32_e32 v124, v125, v158
	v_fmac_f32_e32 v128, v125, v157
	v_fmac_f32_e32 v159, v125, v156
	s_waitcnt lgkmcnt(0)
	v_lshlrev_b32_e32 v126, 16, v126
	v_fmac_f32_e32 v161, v125, v155
	v_fmac_f32_e32 v162, v125, v154
	v_fmac_f32_e32 v163, v125, v153
	v_fmac_f32_e32 v164, v125, v129
	v_fmac_f32_e32 v165, v125, v127
	v_fmac_f32_e32 v160, v125, v126
	ds_read_u16 v125, v137 offset:13312
	v_fmac_f32_e32 v117, v123, v166
	v_fmac_f32_e32 v120, v123, v158
	v_fmac_f32_e32 v124, v123, v157
	v_fmac_f32_e32 v128, v123, v156
	s_waitcnt lgkmcnt(0)
	v_lshlrev_b32_e32 v125, 16, v125
	v_fmac_f32_e32 v159, v123, v155
	v_fmac_f32_e32 v161, v123, v154
	v_fmac_f32_e32 v162, v123, v153
	v_fmac_f32_e32 v163, v123, v129
	v_fmac_f32_e32 v164, v123, v127
	v_fmac_f32_e32 v165, v123, v126
	v_fmac_f32_e32 v160, v123, v125
	ds_read_u16 v123, v137 offset:13824
	v_fmac_f32_e32 v114, v122, v166
	v_fmac_f32_e32 v117, v122, v158
	v_fmac_f32_e32 v120, v122, v157
	v_fmac_f32_e32 v124, v122, v156
	s_waitcnt lgkmcnt(0)
	v_lshlrev_b32_e32 v123, 16, v123
	v_fmac_f32_e32 v128, v122, v155
	v_fmac_f32_e32 v159, v122, v154
	v_fmac_f32_e32 v161, v122, v153
	v_fmac_f32_e32 v162, v122, v129
	v_fmac_f32_e32 v163, v122, v127
	v_fmac_f32_e32 v164, v122, v126
	v_fmac_f32_e32 v165, v122, v125
	v_fmac_f32_e32 v160, v122, v123
	ds_read_u16 v122, v137 offset:14336
	v_fmac_f32_e32 v110, v121, v166
	v_fmac_f32_e32 v114, v121, v158
	v_fmac_f32_e32 v117, v121, v157
	v_fmac_f32_e32 v120, v121, v156
	s_waitcnt lgkmcnt(0)
	v_lshlrev_b32_e32 v122, 16, v122
	v_fmac_f32_e32 v124, v121, v155
	v_fmac_f32_e32 v128, v121, v154
	v_fmac_f32_e32 v159, v121, v153
	v_fmac_f32_e32 v161, v121, v129
	v_fmac_f32_e32 v162, v121, v127
	v_fmac_f32_e32 v163, v121, v126
	v_fmac_f32_e32 v164, v121, v125
	v_fmac_f32_e32 v165, v121, v123
	v_fmac_f32_e32 v160, v121, v122
	ds_read_u16 v121, v137 offset:14848
	v_fmac_f32_e32 v107, v119, v166
	v_fmac_f32_e32 v110, v119, v158
	v_fmac_f32_e32 v114, v119, v157
	v_fmac_f32_e32 v117, v119, v156
	s_waitcnt lgkmcnt(0)
	v_lshlrev_b32_e32 v121, 16, v121
	v_fmac_f32_e32 v120, v119, v155
	v_fmac_f32_e32 v124, v119, v154
	v_fmac_f32_e32 v128, v119, v153
	v_fmac_f32_e32 v159, v119, v129
	v_fmac_f32_e32 v161, v119, v127
	v_fmac_f32_e32 v162, v119, v126
	v_fmac_f32_e32 v163, v119, v125
	v_fmac_f32_e32 v164, v119, v123
	v_fmac_f32_e32 v165, v119, v122
	v_fmac_f32_e32 v160, v119, v121
	ds_read_u16 v119, v137 offset:15360
	v_fmac_f32_e32 v37, v118, v166
	v_fmac_f32_e32 v107, v118, v158
	v_fmac_f32_e32 v110, v118, v157
	v_fmac_f32_e32 v114, v118, v156
	s_waitcnt lgkmcnt(0)
	v_lshlrev_b32_e32 v119, 16, v119
	v_fmac_f32_e32 v117, v118, v155
	v_fmac_f32_e32 v120, v118, v154
	v_fmac_f32_e32 v124, v118, v153
	v_fmac_f32_e32 v128, v118, v129
	v_fmac_f32_e32 v159, v118, v127
	v_fmac_f32_e32 v161, v118, v126
	v_fmac_f32_e32 v162, v118, v125
	v_fmac_f32_e32 v163, v118, v123
	v_fmac_f32_e32 v164, v118, v122
	v_fmac_f32_e32 v165, v118, v121
	v_fmac_f32_e32 v160, v118, v119
	ds_read_u16 v118, v137 offset:15872
	s_waitcnt vmcnt(14)
	v_fmac_f32_e32 v3, v116, v166
	v_fmac_f32_e32 v37, v116, v158
	v_fmac_f32_e32 v107, v116, v157
	v_fmac_f32_e32 v110, v116, v156
	s_waitcnt lgkmcnt(0)
	v_lshlrev_b32_e32 v118, 16, v118
	v_fmac_f32_e32 v114, v116, v155
	v_fmac_f32_e32 v117, v116, v154
	v_fmac_f32_e32 v120, v116, v153
	v_fmac_f32_e32 v124, v116, v129
	v_fmac_f32_e32 v128, v116, v127
	v_fmac_f32_e32 v159, v116, v126
	v_fmac_f32_e32 v161, v116, v125
	v_fmac_f32_e32 v162, v116, v123
	v_fmac_f32_e32 v163, v116, v122
	v_fmac_f32_e32 v164, v116, v121
	v_fmac_f32_e32 v165, v116, v119
	v_fmac_f32_e32 v160, v116, v118
	ds_read_u16 v116, v137 offset:16384
	s_waitcnt vmcnt(13)
	v_fmac_f32_e32 v3, v115, v158
	v_fmac_f32_e32 v37, v115, v157
	v_fmac_f32_e32 v107, v115, v156
	v_fmac_f32_e32 v110, v115, v155
	s_waitcnt lgkmcnt(0)
	v_lshlrev_b32_e32 v116, 16, v116
	v_fmac_f32_e32 v114, v115, v154
	v_fmac_f32_e32 v117, v115, v153
	v_fmac_f32_e32 v120, v115, v129
	v_fmac_f32_e32 v124, v115, v127
	v_fmac_f32_e32 v128, v115, v126
	v_fmac_f32_e32 v159, v115, v125
	v_fmac_f32_e32 v161, v115, v123
	v_fmac_f32_e32 v162, v115, v122
	v_fmac_f32_e32 v163, v115, v121
	v_fmac_f32_e32 v164, v115, v119
	v_fmac_f32_e32 v165, v115, v118
	v_fmac_f32_e32 v160, v115, v116
	ds_read_u16 v115, v137 offset:16896
	s_waitcnt vmcnt(12)
	v_fmac_f32_e32 v3, v113, v157
	v_fmac_f32_e32 v37, v113, v156
	v_fmac_f32_e32 v107, v113, v155
	v_fmac_f32_e32 v110, v113, v154
	s_waitcnt lgkmcnt(0)
	v_lshlrev_b32_e32 v115, 16, v115
	v_fmac_f32_e32 v114, v113, v153
	v_fmac_f32_e32 v117, v113, v129
	v_fmac_f32_e32 v120, v113, v127
	v_fmac_f32_e32 v124, v113, v126
	v_fmac_f32_e32 v128, v113, v125
	v_fmac_f32_e32 v159, v113, v123
	v_fmac_f32_e32 v161, v113, v122
	v_fmac_f32_e32 v162, v113, v121
	v_fmac_f32_e32 v163, v113, v119
	v_fmac_f32_e32 v164, v113, v118
	v_fmac_f32_e32 v165, v113, v116
	v_fmac_f32_e32 v160, v113, v115
	ds_read_u16 v113, v137 offset:17408
	s_waitcnt vmcnt(11)
	v_fmac_f32_e32 v3, v112, v156
	v_fmac_f32_e32 v37, v112, v155
	v_fmac_f32_e32 v107, v112, v154
	v_fmac_f32_e32 v110, v112, v153
	s_waitcnt lgkmcnt(0)
	v_lshlrev_b32_e32 v113, 16, v113
	v_fmac_f32_e32 v114, v112, v129
	v_fmac_f32_e32 v117, v112, v127
	v_fmac_f32_e32 v120, v112, v126
	v_fmac_f32_e32 v124, v112, v125
	v_fmac_f32_e32 v128, v112, v123
	v_fmac_f32_e32 v159, v112, v122
	v_fmac_f32_e32 v161, v112, v121
	v_fmac_f32_e32 v162, v112, v119
	v_fmac_f32_e32 v163, v112, v118
	v_fmac_f32_e32 v164, v112, v116
	v_fmac_f32_e32 v165, v112, v115
	v_fmac_f32_e32 v160, v112, v113
	ds_read_u16 v112, v137 offset:17920
	s_waitcnt vmcnt(10)
	v_fmac_f32_e32 v3, v111, v155
	v_fmac_f32_e32 v37, v111, v154
	v_fmac_f32_e32 v107, v111, v153
	v_fmac_f32_e32 v110, v111, v129
	s_waitcnt lgkmcnt(0)
	v_lshlrev_b32_e32 v112, 16, v112
	v_fmac_f32_e32 v114, v111, v127
	v_fmac_f32_e32 v117, v111, v126
	v_fmac_f32_e32 v120, v111, v125
	v_fmac_f32_e32 v124, v111, v123
	v_fmac_f32_e32 v128, v111, v122
	v_fmac_f32_e32 v159, v111, v121
	v_fmac_f32_e32 v161, v111, v119
	v_fmac_f32_e32 v162, v111, v118
	v_fmac_f32_e32 v163, v111, v116
	v_fmac_f32_e32 v164, v111, v115
	v_fmac_f32_e32 v165, v111, v113
	v_fmac_f32_e32 v160, v111, v112
	ds_read_u16 v111, v137 offset:18432
	s_waitcnt vmcnt(9)
	v_fmac_f32_e32 v3, v109, v154
	v_fmac_f32_e32 v37, v109, v153
	v_fmac_f32_e32 v107, v109, v129
	v_fmac_f32_e32 v110, v109, v127
	s_waitcnt lgkmcnt(0)
	v_lshlrev_b32_e32 v111, 16, v111
	v_fmac_f32_e32 v114, v109, v126
	v_fmac_f32_e32 v117, v109, v125
	v_fmac_f32_e32 v120, v109, v123
	v_fmac_f32_e32 v124, v109, v122
	v_fmac_f32_e32 v128, v109, v121
	v_fmac_f32_e32 v159, v109, v119
	v_fmac_f32_e32 v161, v109, v118
	v_fmac_f32_e32 v162, v109, v116
	v_fmac_f32_e32 v163, v109, v115
	v_fmac_f32_e32 v164, v109, v113
	v_fmac_f32_e32 v165, v109, v112
	v_fmac_f32_e32 v160, v109, v111
	ds_read_u16 v109, v137 offset:18944
	s_waitcnt vmcnt(8)
	v_fmac_f32_e32 v3, v108, v153
	v_fmac_f32_e32 v37, v108, v129
	v_fmac_f32_e32 v107, v108, v127
	v_fmac_f32_e32 v110, v108, v126
	s_waitcnt lgkmcnt(0)
	v_lshlrev_b32_e32 v109, 16, v109
	v_fmac_f32_e32 v114, v108, v125
	v_fmac_f32_e32 v117, v108, v123
	v_fmac_f32_e32 v120, v108, v122
	v_fmac_f32_e32 v124, v108, v121
	v_fmac_f32_e32 v128, v108, v119
	v_fmac_f32_e32 v159, v108, v118
	v_fmac_f32_e32 v161, v108, v116
	v_fmac_f32_e32 v162, v108, v115
	v_fmac_f32_e32 v163, v108, v113
	v_fmac_f32_e32 v164, v108, v112
	v_fmac_f32_e32 v165, v108, v111
	v_fmac_f32_e32 v160, v108, v109
	ds_read_u16 v108, v137 offset:19456
	s_waitcnt vmcnt(7)
	v_fmac_f32_e32 v3, v106, v129
	v_fmac_f32_e32 v37, v106, v127
	v_fmac_f32_e32 v107, v106, v126
	v_fmac_f32_e32 v110, v106, v125
	s_waitcnt lgkmcnt(0)
	v_lshlrev_b32_e32 v108, 16, v108
	v_fmac_f32_e32 v114, v106, v123
	v_fmac_f32_e32 v117, v106, v122
	v_fmac_f32_e32 v120, v106, v121
	v_fmac_f32_e32 v124, v106, v119
	v_fmac_f32_e32 v128, v106, v118
	v_fmac_f32_e32 v159, v106, v116
	v_fmac_f32_e32 v161, v106, v115
	v_fmac_f32_e32 v162, v106, v113
	v_fmac_f32_e32 v163, v106, v112
	v_fmac_f32_e32 v164, v106, v111
	v_fmac_f32_e32 v165, v106, v109
	v_fmac_f32_e32 v160, v106, v108
	ds_read_u16 v106, v137 offset:19968
	s_waitcnt vmcnt(6)
	v_fmac_f32_e32 v3, v105, v127
	v_fmac_f32_e32 v37, v105, v126
	v_fmac_f32_e32 v107, v105, v125
	v_fmac_f32_e32 v110, v105, v123
	s_waitcnt lgkmcnt(0)
	v_lshlrev_b32_e32 v106, 16, v106
	v_fmac_f32_e32 v114, v105, v122
	v_fmac_f32_e32 v117, v105, v121
	v_fmac_f32_e32 v120, v105, v119
	v_fmac_f32_e32 v124, v105, v118
	v_fmac_f32_e32 v128, v105, v116
	v_fmac_f32_e32 v159, v105, v115
	v_fmac_f32_e32 v161, v105, v113
	v_fmac_f32_e32 v162, v105, v112
	v_fmac_f32_e32 v163, v105, v111
	v_fmac_f32_e32 v164, v105, v109
	v_fmac_f32_e32 v165, v105, v108
	v_fmac_f32_e32 v160, v105, v106
	ds_read_u16 v105, v137 offset:20480
	s_waitcnt vmcnt(5)
	v_fmac_f32_e32 v3, v104, v126
	v_fmac_f32_e32 v37, v104, v125
	v_fmac_f32_e32 v107, v104, v123
	v_fmac_f32_e32 v110, v104, v122
	s_waitcnt lgkmcnt(0)
	v_lshlrev_b32_e32 v105, 16, v105
	v_fmac_f32_e32 v114, v104, v121
	v_fmac_f32_e32 v117, v104, v119
	v_fmac_f32_e32 v120, v104, v118
	v_fmac_f32_e32 v124, v104, v116
	v_fmac_f32_e32 v128, v104, v115
	v_fmac_f32_e32 v159, v104, v113
	v_fmac_f32_e32 v161, v104, v112
	v_fmac_f32_e32 v162, v104, v111
	v_fmac_f32_e32 v163, v104, v109
	v_fmac_f32_e32 v164, v104, v108
	v_fmac_f32_e32 v165, v104, v106
	v_fmac_f32_e32 v160, v104, v105
	ds_read_u16 v104, v137 offset:20992
	s_waitcnt vmcnt(4)
	v_fmac_f32_e32 v3, v39, v125
	v_fmac_f32_e32 v37, v39, v123
	v_fmac_f32_e32 v107, v39, v122
	v_fmac_f32_e32 v110, v39, v121
	s_waitcnt lgkmcnt(0)
	v_lshlrev_b32_e32 v104, 16, v104
	v_fmac_f32_e32 v114, v39, v119
	v_fmac_f32_e32 v117, v39, v118
	v_fmac_f32_e32 v120, v39, v116
	v_fmac_f32_e32 v124, v39, v115
	v_fmac_f32_e32 v128, v39, v113
	v_fmac_f32_e32 v159, v39, v112
	v_fmac_f32_e32 v161, v39, v111
	v_fmac_f32_e32 v162, v39, v109
	v_fmac_f32_e32 v163, v39, v108
	v_fmac_f32_e32 v164, v39, v106
	v_fmac_f32_e32 v165, v39, v105
	v_fmac_f32_e32 v160, v39, v104
	ds_read_u16 v39, v137 offset:21504
	s_waitcnt vmcnt(3)
	v_fmac_f32_e32 v3, v38, v123
	v_fmac_f32_e32 v37, v38, v122
	v_fmac_f32_e32 v107, v38, v121
	v_fmac_f32_e32 v110, v38, v119
	s_waitcnt lgkmcnt(0)
	v_lshlrev_b32_e32 v39, 16, v39
	v_fmac_f32_e32 v114, v38, v118
	v_fmac_f32_e32 v117, v38, v116
	v_fmac_f32_e32 v120, v38, v115
	v_fmac_f32_e32 v124, v38, v113
	v_fmac_f32_e32 v128, v38, v112
	v_fmac_f32_e32 v159, v38, v111
	v_fmac_f32_e32 v161, v38, v109
	v_fmac_f32_e32 v162, v38, v108
	v_fmac_f32_e32 v163, v38, v106
	v_fmac_f32_e32 v164, v38, v105
	v_fmac_f32_e32 v165, v38, v104
	v_fmac_f32_e32 v160, v38, v39
	ds_read_u16 v38, v137 offset:22016
	s_waitcnt vmcnt(2)
	v_fmac_f32_e32 v3, v36, v122
	v_fmac_f32_e32 v37, v36, v121
	v_fmac_f32_e32 v107, v36, v119
	v_fmac_f32_e32 v110, v36, v118
	s_waitcnt lgkmcnt(0)
	v_lshlrev_b32_e32 v38, 16, v38
	v_fmac_f32_e32 v114, v36, v116
	v_fmac_f32_e32 v117, v36, v115
	v_fmac_f32_e32 v120, v36, v113
	v_fmac_f32_e32 v124, v36, v112
	v_fmac_f32_e32 v128, v36, v111
	v_fmac_f32_e32 v159, v36, v109
	v_fmac_f32_e32 v161, v36, v108
	v_fmac_f32_e32 v162, v36, v106
	v_fmac_f32_e32 v163, v36, v105
	v_fmac_f32_e32 v164, v36, v104
	v_fmac_f32_e32 v165, v36, v39
	v_fmac_f32_e32 v160, v36, v38
	ds_read_u16 v36, v137 offset:22528
	s_waitcnt vmcnt(1)
	v_fmac_f32_e32 v3, v2, v121
	v_fmac_f32_e32 v37, v2, v119
	v_fmac_f32_e32 v107, v2, v118
	v_fmac_f32_e32 v110, v2, v116
	s_waitcnt lgkmcnt(0)
	v_lshlrev_b32_e32 v36, 16, v36
	v_fmac_f32_e32 v114, v2, v115
	v_fmac_f32_e32 v117, v2, v113
	v_fmac_f32_e32 v120, v2, v112
	v_fmac_f32_e32 v124, v2, v111
	v_fmac_f32_e32 v128, v2, v109
	v_fmac_f32_e32 v159, v2, v108
	v_fmac_f32_e32 v161, v2, v106
	v_fmac_f32_e32 v162, v2, v105
	v_fmac_f32_e32 v163, v2, v104
	v_fmac_f32_e32 v164, v2, v39
	v_fmac_f32_e32 v165, v2, v38
	v_fmac_f32_e32 v160, v2, v36
	ds_read_u16 v2, v137 offset:23040
	s_waitcnt vmcnt(0)
	v_fmac_f32_e32 v3, v1, v119
	v_fmac_f32_e32 v37, v1, v118
	v_fmac_f32_e32 v107, v1, v116
	v_fmac_f32_e32 v110, v1, v115
	s_waitcnt lgkmcnt(0)
	v_lshlrev_b32_e32 v2, 16, v2
	v_fmac_f32_e32 v114, v1, v113
	v_fmac_f32_e32 v117, v1, v112
	v_fmac_f32_e32 v120, v1, v111
	v_fmac_f32_e32 v124, v1, v109
	v_fmac_f32_e32 v128, v1, v108
	v_fmac_f32_e32 v159, v1, v106
	v_fmac_f32_e32 v161, v1, v105
	v_fmac_f32_e32 v162, v1, v104
	v_fmac_f32_e32 v163, v1, v39
	v_fmac_f32_e32 v164, v1, v38
	v_fmac_f32_e32 v165, v1, v36
	v_fmac_f32_e32 v160, v1, v2
	ds_write2st64_b32 v145, v3, v37 offset0:220 offset1:224
	ds_write2st64_b32 v145, v107, v110 offset0:228 offset1:232
	ds_write2st64_b32 v145, v114, v117 offset0:236 offset1:240
	ds_write2st64_b32 v145, v120, v124 offset0:244 offset1:248
	ds_write_b32 v145, v128 offset:64512
	ds_write_b32 v146, v159
	ds_write_b32 v147, v161
	ds_write_b32 v148, v162
	ds_write_b32 v149, v163
	ds_write_b32 v150, v164
	ds_write_b32 v151, v165
	ds_write_b32 v152, v160
	ds_read_u16 v1, v137 offset:31744
	ds_read_u16 v2, v137 offset:40960
	s_waitcnt lgkmcnt(1)
	v_lshlrev_b32_e32 v1, 16, v1
	v_add_f32_e32 v122, 0, v1
	ds_read_u16 v1, v137 offset:32256
	s_waitcnt lgkmcnt(1)
	v_lshlrev_b32_e32 v2, 16, v2
	s_waitcnt lgkmcnt(0)
	v_lshlrev_b32_e32 v1, 16, v1
	v_add_f32_e32 v120, v122, v1
	ds_read_u16 v1, v137 offset:32768
	s_waitcnt lgkmcnt(0)
	v_lshlrev_b32_e32 v1, 16, v1
	v_add_f32_e32 v121, v120, v1
	ds_read_u16 v1, v137 offset:33280
	s_waitcnt lgkmcnt(0)
	v_lshlrev_b32_e32 v1, 16, v1
	v_add_f32_e32 v123, v121, v1
	ds_read_u16 v1, v137 offset:33792
	s_waitcnt lgkmcnt(0)
	v_lshlrev_b32_e32 v1, 16, v1
	v_add_f32_e32 v125, v123, v1
	ds_read_u16 v1, v137 offset:34304
	s_waitcnt lgkmcnt(0)
	v_lshlrev_b32_e32 v1, 16, v1
	v_add_f32_e32 v164, v125, v1
	ds_read_u16 v1, v137 offset:34816
	s_waitcnt lgkmcnt(0)
	v_lshlrev_b32_e32 v1, 16, v1
	v_add_f32_e32 v163, v164, v1
	ds_read_u16 v1, v137 offset:35328
	s_waitcnt lgkmcnt(0)
	v_lshlrev_b32_e32 v1, 16, v1
	v_add_f32_e32 v162, v163, v1
	ds_read_u16 v1, v137 offset:35840
	s_waitcnt lgkmcnt(0)
	v_lshlrev_b32_e32 v1, 16, v1
	v_add_f32_e32 v161, v162, v1
	ds_read_u16 v1, v137 offset:36352
	s_waitcnt lgkmcnt(0)
	v_lshlrev_b32_e32 v1, 16, v1
	v_add_f32_e32 v160, v161, v1
	ds_read_u16 v1, v137 offset:36864
	s_waitcnt lgkmcnt(0)
	v_lshlrev_b32_e32 v1, 16, v1
	v_add_f32_e32 v159, v160, v1
	ds_read_u16 v1, v137 offset:37376
	s_waitcnt lgkmcnt(0)
	v_lshlrev_b32_e32 v1, 16, v1
	v_add_f32_e32 v158, v159, v1
	ds_read_u16 v1, v137 offset:37888
	s_waitcnt lgkmcnt(0)
	v_lshlrev_b32_e32 v1, 16, v1
	v_add_f32_e32 v157, v158, v1
	ds_read_u16 v1, v137 offset:38400
	s_waitcnt lgkmcnt(0)
	v_lshlrev_b32_e32 v1, 16, v1
	v_add_f32_e32 v156, v157, v1
	ds_read_u16 v1, v137 offset:38912
	s_waitcnt lgkmcnt(0)
	v_lshlrev_b32_e32 v1, 16, v1
	v_add_f32_e32 v155, v156, v1
	ds_read_u16 v1, v137 offset:39424
	s_waitcnt lgkmcnt(0)
	v_lshlrev_b32_e32 v1, 16, v1
	v_add_f32_e32 v154, v155, v1
	ds_read_u16 v1, v137 offset:39936
	s_waitcnt lgkmcnt(0)
	v_lshlrev_b32_e32 v1, 16, v1
	v_add_f32_e32 v153, v154, v1
	ds_read_u16 v1, v137 offset:40448
	s_waitcnt lgkmcnt(0)
	v_lshlrev_b32_e32 v1, 16, v1
	v_add_f32_e32 v1, v153, v1
	v_add_f32_e32 v169, v1, v2
	ds_read_u16 v2, v137 offset:41472
	s_waitcnt lgkmcnt(0)
	v_lshlrev_b32_e32 v2, 16, v2
	v_add_f32_e32 v168, v169, v2
	ds_read_u16 v2, v137 offset:41984
	s_waitcnt lgkmcnt(0)
	v_lshlrev_b32_e32 v2, 16, v2
	v_add_f32_e32 v166, v168, v2
	ds_read_u16 v2, v137 offset:42496
	s_waitcnt lgkmcnt(0)
	v_lshlrev_b32_e32 v2, 16, v2
	v_add_f32_e32 v167, v166, v2
	ds_read_u16 v2, v137 offset:43008
	s_waitcnt lgkmcnt(0)
	v_lshlrev_b32_e32 v2, 16, v2
	v_add_f32_e32 v165, v167, v2
	ds_read_u16 v2, v137 offset:43520
	s_waitcnt lgkmcnt(0)
	v_lshlrev_b32_e32 v2, 16, v2
	v_add_f32_e32 v170, v165, v2
	v_add_u32_e32 v2, s59, v139
	s_and_saveexec_b64 s[12:13], s[14:15]
	s_xor_b64 s[12:13], exec, s[12:13]
	s_cbranch_execz .LBB0_603
	ds_read_u16 v127, v137 offset:45568
	ds_read_u16 v124, v137 offset:46080
	ds_read_u16 v3, v137 offset:44032
	ds_read_u16 v126, v137 offset:46592
	ds_read_u16 v36, v137 offset:44544
	ds_read_u16 v128, v137 offset:47104
	ds_read_u16 v37, v137 offset:45056
	s_waitcnt lgkmcnt(4)
	v_lshlrev_b32_e32 v3, 16, v3
	v_add_f32_e32 v171, v170, v3
	s_waitcnt lgkmcnt(2)
	v_lshlrev_b32_e32 v3, 16, v36
	v_add_f32_e32 v175, v171, v3
	s_waitcnt lgkmcnt(0)
	v_lshlrev_b32_e32 v3, 16, v37
	v_sub_f32_e32 v172, v161, v162
	v_add_f32_e32 v174, v175, v3
	v_cmp_lt_i32_e32 vcc, 1, v138
	s_mov_b64 s[42:43], 0
	s_mov_b64 s[26:27], 0
	s_and_saveexec_b64 s[20:21], vcc
	s_xor_b64 s[50:51], exec, s[20:21]
	s_cbranch_execz .LBB0_596
	v_cmp_eq_u32_e32 vcc, 2, v138
	s_mov_b64 s[20:21], -1
	s_and_saveexec_b64 s[52:53], vcc
	s_cbranch_execz .LBB0_595
	v_add_u32_e32 v3, -4, v2
	v_or_b32_e32 v112, 4, v2
	v_max_i32_e32 v3, s30, v3
	v_min_i32_e32 v36, s31, v112
	v_sub_u32_e32 v3, v36, v3
	v_cvt_f32_i32_e32 v3, v3
	v_sub_f32_e32 v37, v158, v123
	v_or_b32_e32 v110, 1, v2
	v_sub_f32_e32 v39, v157, v125
	v_rcp_iflag_f32_e32 v3, v3
	v_ashrrev_i32_e32 v111, 31, v110
	v_or_b32_e32 v114, 2, v2
	v_sub_f32_e32 v104, v156, v164
	v_fma_f32 v3, v3, v37, -v172
	v_cvt_pk_bf16_f32 v38, v3, s0
	v_ashrrev_i32_e32 v3, 31, v2
	v_lshlrev_b64 v[36:37], 11, v[2:3]
	v_lshl_add_u64 v[36:37], v[44:45], 0, v[36:37]
	global_store_short v[36:37], v38, off sc1
	v_add_u32_e32 v3, -3, v2
	v_or_b32_e32 v36, 5, v2
	v_max_i32_e32 v3, s30, v3
	v_min_i32_e32 v37, s31, v36
	v_sub_u32_e32 v3, v37, v3
	v_cvt_f32_i32_e32 v3, v3
	v_sub_f32_e32 v38, v160, v161
	v_ashrrev_i32_e32 v115, 31, v114
	v_or_b32_e32 v116, 3, v2
	v_rcp_iflag_f32_e32 v3, v3
	v_ashrrev_i32_e32 v117, 31, v116
	v_lshlrev_b64 v[106:107], 11, v[116:117]
	v_lshl_add_u64 v[106:107], v[44:45], 0, v[106:107]
	v_fma_f32 v3, v3, v39, -v38
	v_lshlrev_b64 v[38:39], 11, v[110:111]
	v_cvt_pk_bf16_f32 v3, v3, s0
	v_lshl_add_u64 v[38:39], v[44:45], 0, v[38:39]
	global_store_short v[38:39], v3, off sc1
	v_add_u32_e32 v3, -2, v2
	v_or_b32_e32 v38, 6, v2
	v_max_i32_e32 v3, s30, v3
	v_min_i32_e32 v37, s31, v38
	v_sub_u32_e32 v3, v37, v3
	v_cvt_f32_i32_e32 v3, v3
	v_sub_f32_e32 v39, v159, v160
	v_ashrrev_i32_e32 v113, 31, v112
	v_lshlrev_b64 v[108:109], 11, v[112:113]
	v_rcp_iflag_f32_e32 v3, v3
	v_lshl_add_u64 v[108:109], v[44:45], 0, v[108:109]
	v_or_b32_e32 v118, 13, v2
	v_ashrrev_i32_e32 v119, 31, v118
	v_fma_f32 v3, v3, v104, -v39
	v_lshlrev_b64 v[104:105], 11, v[114:115]
	v_cvt_pk_bf16_f32 v3, v3, s0
	v_lshl_add_u64 v[104:105], v[44:45], 0, v[104:105]
	global_store_short v[104:105], v3, off sc1
	v_add_u32_e32 v3, -1, v2
	v_or_b32_e32 v104, 7, v2
	v_max_i32_e32 v3, s30, v3
	v_min_i32_e32 v37, s31, v104
	v_sub_u32_e32 v3, v37, v3
	v_cvt_f32_i32_e32 v3, v3
	v_sub_f32_e32 v39, v158, v159
	v_sub_f32_e32 v105, v155, v163
	s_xor_b64 s[20:21], exec, -1
	v_rcp_iflag_f32_e32 v3, v3
	s_nop 0
	v_fma_f32 v3, v3, v105, -v39
	v_cvt_pk_bf16_f32 v3, v3, s0
	global_store_short v[106:107], v3, off sc1
	v_or_b32_e32 v106, 8, v2
	v_max_i32_e32 v3, s30, v2
	v_min_i32_e32 v37, s31, v106
	v_sub_u32_e32 v3, v37, v3
	v_cvt_f32_i32_e32 v3, v3
	v_sub_f32_e32 v39, v157, v158
	v_sub_f32_e32 v105, v154, v162
	v_ashrrev_i32_e32 v107, 31, v106
	v_rcp_iflag_f32_e32 v3, v3
	s_nop 0
	v_fma_f32 v3, v3, v105, -v39
	v_cvt_pk_bf16_f32 v3, v3, s0
	global_store_short v[108:109], v3, off sc1
	v_or_b32_e32 v108, 9, v2
	v_max_i32_e32 v3, s30, v110
	v_min_i32_e32 v37, s31, v108
	v_sub_u32_e32 v3, v37, v3
	v_cvt_f32_i32_e32 v3, v3
	v_sub_f32_e32 v39, v156, v157
	v_sub_f32_e32 v105, v153, v161
	v_ashrrev_i32_e32 v37, 31, v36
	v_rcp_iflag_f32_e32 v3, v3
	v_lshlrev_b64 v[110:111], 11, v[36:37]
	v_lshl_add_u64 v[110:111], v[44:45], 0, v[110:111]
	v_ashrrev_i32_e32 v109, 31, v108
	v_fma_f32 v3, v3, v105, -v39
	v_cvt_pk_bf16_f32 v3, v3, s0
	global_store_short v[110:111], v3, off sc1
	v_or_b32_e32 v110, 10, v2
	v_max_i32_e32 v3, s30, v114
	v_min_i32_e32 v37, s31, v110
	v_sub_u32_e32 v3, v37, v3
	v_cvt_f32_i32_e32 v3, v3
	v_sub_f32_e32 v39, v155, v156
	v_sub_f32_e32 v105, v1, v160
	v_ashrrev_i32_e32 v111, 31, v110
	v_rcp_iflag_f32_e32 v3, v3
	s_nop 0
	v_fma_f32 v3, v3, v105, -v39
	v_ashrrev_i32_e32 v39, 31, v38
	v_lshlrev_b64 v[114:115], 11, v[38:39]
	v_cvt_pk_bf16_f32 v3, v3, s0
	v_lshl_add_u64 v[114:115], v[44:45], 0, v[114:115]
	global_store_short v[114:115], v3, off sc1
	v_or_b32_e32 v114, 11, v2
	v_max_i32_e32 v3, s30, v116
	v_min_i32_e32 v37, s31, v114
	v_sub_u32_e32 v3, v37, v3
	v_cvt_f32_i32_e32 v3, v3
	v_sub_f32_e32 v39, v154, v155
	v_sub_f32_e32 v105, v169, v159
	v_ashrrev_i32_e32 v115, 31, v114
	v_rcp_iflag_f32_e32 v3, v3
	s_nop 0
	v_fma_f32 v3, v3, v105, -v39
	v_ashrrev_i32_e32 v105, 31, v104
	v_lshlrev_b64 v[116:117], 11, v[104:105]
	v_cvt_pk_bf16_f32 v3, v3, s0
	v_lshl_add_u64 v[116:117], v[44:45], 0, v[116:117]
	global_store_short v[116:117], v3, off sc1
	v_or_b32_e32 v116, 12, v2
	v_max_i32_e32 v3, s30, v112
	v_min_i32_e32 v37, s31, v116
	v_sub_u32_e32 v3, v37, v3
	v_cvt_f32_i32_e32 v3, v3
	v_sub_f32_e32 v39, v153, v154
	v_sub_f32_e32 v105, v168, v158
	v_lshlrev_b64 v[112:113], 11, v[106:107]
	v_rcp_iflag_f32_e32 v3, v3
	v_lshl_add_u64 v[112:113], v[44:45], 0, v[112:113]
	v_sub_f32_e32 v37, v1, v153
	v_ashrrev_i32_e32 v117, 31, v116
	v_fma_f32 v3, v3, v105, -v39
	v_cvt_pk_bf16_f32 v3, v3, s0
	global_store_short v[112:113], v3, off sc1
	v_max_i32_e32 v3, s30, v36
	v_min_i32_e32 v36, s31, v118
	v_sub_u32_e32 v3, v36, v3
	v_cvt_f32_i32_e32 v3, v3
	v_sub_f32_e32 v39, v166, v157
	v_or_b32_e32 v112, 14, v2
	v_ashrrev_i32_e32 v113, 31, v112
	v_rcp_iflag_f32_e32 v3, v3
	s_nop 0
	v_fma_f32 v3, v3, v39, -v37
	v_lshlrev_b64 v[36:37], 11, v[108:109]
	v_cvt_pk_bf16_f32 v3, v3, s0
	v_lshl_add_u64 v[36:37], v[44:45], 0, v[36:37]
	global_store_short v[36:37], v3, off sc1
	v_max_i32_e32 v3, s30, v38
	v_min_i32_e32 v36, s31, v112
	v_sub_u32_e32 v3, v36, v3
	v_cvt_f32_i32_e32 v3, v3
	v_sub_f32_e32 v37, v169, v1
	v_sub_f32_e32 v38, v167, v156
	v_sub_f32_e32 v39, v165, v155
	v_rcp_iflag_f32_e32 v3, v3
	s_nop 0
	v_fma_f32 v3, v3, v38, -v37
	v_lshlrev_b64 v[36:37], 11, v[110:111]
	v_cvt_pk_bf16_f32 v3, v3, s0
	v_lshl_add_u64 v[36:37], v[44:45], 0, v[36:37]
	global_store_short v[36:37], v3, off sc1
	v_or_b32_e32 v36, 15, v2
	v_max_i32_e32 v3, s30, v104
	v_min_i32_e32 v37, s31, v36
	v_sub_u32_e32 v3, v37, v3
	v_cvt_f32_i32_e32 v3, v3
	v_sub_f32_e32 v38, v168, v169
	v_max_i32_e32 v37, s30, v106
	v_rcp_iflag_f32_e32 v3, v3
	s_nop 0
	v_fma_f32 v3, v3, v39, -v38
	v_lshlrev_b64 v[38:39], 11, v[114:115]
	v_cvt_pk_bf16_f32 v3, v3, s0
	v_lshl_add_u64 v[38:39], v[44:45], 0, v[38:39]
	global_store_short v[38:39], v3, off sc1
	v_add_u32_e32 v3, 16, v2
	v_min_i32_e32 v3, s31, v3
	v_sub_u32_e32 v3, v3, v37
	v_cvt_f32_i32_e32 v3, v3
	v_sub_f32_e32 v38, v166, v168
	v_sub_f32_e32 v39, v170, v154
	v_max_i32_e32 v37, s30, v108
	v_rcp_iflag_f32_e32 v3, v3
	s_nop 0
	v_fma_f32 v3, v3, v39, -v38
	v_lshlrev_b64 v[38:39], 11, v[116:117]
	v_cvt_pk_bf16_f32 v3, v3, s0
	v_lshl_add_u64 v[38:39], v[44:45], 0, v[38:39]
	global_store_short v[38:39], v3, off sc1
	v_add_u32_e32 v3, 17, v2
	v_min_i32_e32 v3, s31, v3
	v_sub_u32_e32 v3, v3, v37
	v_cvt_f32_i32_e32 v3, v3
	v_sub_f32_e32 v38, v167, v166
	v_sub_f32_e32 v39, v171, v153
	v_max_i32_e32 v37, s30, v110
	v_rcp_iflag_f32_e32 v3, v3
	s_nop 0
	v_fma_f32 v3, v3, v39, -v38
	v_lshlrev_b64 v[38:39], 11, v[118:119]
	v_cvt_pk_bf16_f32 v3, v3, s0
	v_lshl_add_u64 v[38:39], v[44:45], 0, v[38:39]
	global_store_short v[38:39], v3, off sc1
	v_add_u32_e32 v3, 18, v2
	v_min_i32_e32 v3, s31, v3
	v_sub_u32_e32 v3, v3, v37
	v_cvt_f32_i32_e32 v3, v3
	v_sub_f32_e32 v38, v165, v167
	v_sub_f32_e32 v39, v175, v1
	v_max_i32_e32 v37, s30, v114
	v_rcp_iflag_f32_e32 v3, v3
	s_nop 0
	v_fma_f32 v3, v3, v39, -v38
	v_lshlrev_b64 v[38:39], 11, v[112:113]
	v_cvt_pk_bf16_f32 v3, v3, s0
	v_lshl_add_u64 v[38:39], v[44:45], 0, v[38:39]
	global_store_short v[38:39], v3, off sc1
	v_add_u32_e32 v3, 19, v2
	v_min_i32_e32 v38, s31, v3
	v_sub_f32_e32 v3, v174, v169
	v_sub_u32_e32 v38, v38, v37

.LBB0_596:
	s_andn2_saveexec_b64 s[20:21], s[50:51]
	v_cmp_ne_u32_e32 vcc, 1, v138
	s_andn2_b64 s[26:27], s[26:27], exec
	s_and_b64 s[36:37], vcc, exec
	s_or_b64 s[26:27], s[26:27], s[36:37]
	s_mov_b64 s[42:43], exec
	s_or_b64 exec, exec, s[20:21]
	v_add_u32_e32 v37, -2, v2
	v_add_u32_e32 v39, 17, v2
	v_max_i32_e32 v37, s30, v37
	v_min_i32_e32 v173, s31, v39
	s_and_saveexec_b64 s[20:21], s[26:27]
	s_xor_b64 s[50:51], exec, s[20:21]
	s_cbranch_execz .LBB0_600
	v_lshlrev_b32_e32 v3, 16, v127
	v_add_f32_e32 v111, v174, v3
	v_lshlrev_b32_e32 v3, 16, v124
	v_add_f32_e32 v115, v111, v3
	v_lshlrev_b32_e32 v3, 16, v126
	v_add_f32_e32 v113, v115, v3
	v_lshlrev_b32_e32 v3, 16, v128
	v_add_f32_e32 v176, v113, v3
	v_add_u32_e32 v3, -8, v2
	v_or_b32_e32 v108, 8, v2
	v_max_i32_e32 v3, s30, v3
	v_min_i32_e32 v36, s31, v108
	v_sub_u32_e32 v3, v36, v3
	v_cvt_f32_i32_e32 v3, v3
	v_or_b32_e32 v116, 1, v2
	v_sub_f32_e32 v104, v153, v122
	v_ashrrev_i32_e32 v117, 31, v116
	v_rcp_iflag_f32_e32 v3, v3
	v_or_b32_e32 v118, 2, v2
	v_ashrrev_i32_e32 v119, 31, v118
	v_lshlrev_b64 v[106:107], 11, v[118:119]
	v_fma_f32 v3, v3, v154, -v172
	v_cvt_pk_bf16_f32 v36, v3, s0
	v_ashrrev_i32_e32 v3, 31, v2
	v_lshlrev_b64 v[38:39], 11, v[2:3]
	v_lshl_add_u64 v[38:39], v[44:45], 0, v[38:39]
	global_store_short v[38:39], v36, off sc1
	v_add_u32_e32 v3, -7, v2
	v_or_b32_e32 v38, 9, v2
	v_max_i32_e32 v3, s30, v3
	v_min_i32_e32 v36, s31, v38
	v_sub_u32_e32 v3, v36, v3
	v_cvt_f32_i32_e32 v3, v3
	v_sub_f32_e32 v39, v160, v161
	v_lshl_add_u64 v[106:107], v[44:45], 0, v[106:107]
	v_or_b32_e32 v110, 12, v2
	v_rcp_iflag_f32_e32 v3, v3
	v_or_b32_e32 v122, 4, v2
	v_or_b32_e32 v114, 13, v2
	v_or_b32_e32 v124, 5, v2
	v_fma_f32 v3, v3, v104, -v39
	v_lshlrev_b64 v[104:105], 11, v[116:117]
	v_cvt_pk_bf16_f32 v3, v3, s0
	v_lshl_add_u64 v[104:105], v[44:45], 0, v[104:105]
	global_store_short v[104:105], v3, off sc1
	v_add_u32_e32 v3, -6, v2
	v_or_b32_e32 v104, 10, v2
	v_max_i32_e32 v3, s30, v3
	v_min_i32_e32 v36, s31, v104
	v_sub_u32_e32 v3, v36, v3
	v_cvt_f32_i32_e32 v3, v3
	v_sub_f32_e32 v39, v159, v160
	v_sub_f32_e32 v105, v1, v120
	v_or_b32_e32 v120, 3, v2
	v_rcp_iflag_f32_e32 v3, v3
	v_or_b32_e32 v112, 14, v2
	v_ashrrev_i32_e32 v109, 31, v108
	v_lshlrev_b64 v[108:109], 11, v[108:109]
	v_fma_f32 v3, v3, v105, -v39
	v_cvt_pk_bf16_f32 v3, v3, s0
	global_store_short v[106:107], v3, off sc1
	v_add_u32_e32 v3, -5, v2
	v_or_b32_e32 v106, 11, v2
	v_max_i32_e32 v3, s30, v3
	v_min_i32_e32 v36, s31, v106
	v_sub_u32_e32 v3, v36, v3
	v_cvt_f32_i32_e32 v3, v3
	v_sub_f32_e32 v39, v158, v159
	v_sub_f32_e32 v105, v169, v121
	v_ashrrev_i32_e32 v121, 31, v120
	v_rcp_iflag_f32_e32 v3, v3
	v_lshlrev_b64 v[126:127], 11, v[120:121]
	v_lshl_add_u64 v[126:127], v[44:45], 0, v[126:127]
	v_min_i32_e32 v36, s31, v110
	v_fma_f32 v3, v3, v105, -v39
	v_cvt_pk_bf16_f32 v3, v3, s0
	global_store_short v[126:127], v3, off sc1
	v_add_u32_e32 v3, -4, v2
	v_max_i32_e32 v3, s30, v3
	v_sub_u32_e32 v3, v36, v3
	v_cvt_f32_i32_e32 v3, v3
	v_sub_f32_e32 v39, v157, v158
	v_sub_f32_e32 v105, v168, v123
	v_ashrrev_i32_e32 v123, 31, v122
	v_rcp_iflag_f32_e32 v3, v3
	v_lshlrev_b64 v[126:127], 11, v[122:123]
	v_lshl_add_u64 v[126:127], v[44:45], 0, v[126:127]
	v_min_i32_e32 v36, s31, v114
	v_fma_f32 v3, v3, v105, -v39
	v_cvt_pk_bf16_f32 v3, v3, s0
	global_store_short v[126:127], v3, off sc1
	v_add_u32_e32 v3, -3, v2
	v_max_i32_e32 v3, s30, v3
	v_sub_u32_e32 v3, v36, v3
	v_cvt_f32_i32_e32 v3, v3
	v_sub_f32_e32 v39, v156, v157
	v_sub_f32_e32 v105, v166, v125
	v_ashrrev_i32_e32 v125, 31, v124
	v_rcp_iflag_f32_e32 v3, v3
	v_lshlrev_b64 v[126:127], 11, v[124:125]
	v_lshl_add_u64 v[126:127], v[44:45], 0, v[126:127]
	v_sub_f32_e32 v36, v155, v156
	v_fma_f32 v3, v3, v105, -v39
	v_cvt_pk_bf16_f32 v3, v3, s0
	global_store_short v[126:127], v3, off sc1
	v_min_i32_e32 v3, s31, v112
	v_sub_u32_e32 v3, v3, v37
	v_cvt_f32_i32_e32 v3, v3
	v_or_b32_e32 v126, 6, v2
	v_sub_f32_e32 v39, v167, v164
	v_ashrrev_i32_e32 v127, 31, v126
	v_rcp_iflag_f32_e32 v3, v3
	v_lshlrev_b64 v[128:129], 11, v[126:127]
	v_lshl_add_u64 v[128:129], v[44:45], 0, v[128:129]
	v_sub_f32_e32 v105, v154, v155
	v_fma_f32 v3, v3, v39, -v36
	v_cvt_pk_bf16_f32 v3, v3, s0
	global_store_short v[128:129], v3, off sc1
	v_add_u32_e32 v3, -1, v2
	v_or_b32_e32 v36, 15, v2
	v_max_i32_e32 v3, s30, v3
	v_min_i32_e32 v39, s31, v36
	v_sub_u32_e32 v3, v39, v3
	v_cvt_f32_i32_e32 v3, v3
	v_or_b32_e32 v128, 7, v2
	v_sub_f32_e32 v107, v165, v163
	v_ashrrev_i32_e32 v129, 31, v128
	v_rcp_iflag_f32_e32 v3, v3
	v_lshlrev_b64 v[178:179], 11, v[128:129]
	v_lshl_add_u64 v[178:179], v[44:45], 0, v[178:179]
	v_max_i32_e32 v39, s30, v2
	v_fma_f32 v3, v3, v107, -v105
	v_cvt_pk_bf16_f32 v3, v3, s0
	global_store_short v[178:179], v3, off sc1
	v_add_u32_e32 v3, 16, v2
	v_min_i32_e32 v3, s31, v3
	v_sub_u32_e32 v3, v3, v39
	v_cvt_f32_i32_e32 v3, v3
	v_sub_f32_e32 v105, v153, v154
	v_sub_f32_e32 v107, v170, v162
	v_lshl_add_u64 v[108:109], v[44:45], 0, v[108:109]
	v_rcp_iflag_f32_e32 v3, v3
	v_sub_f32_e32 v39, v1, v153
	s_andn2_b64 s[42:43], s[42:43], exec
	v_fma_f32 v3, v3, v107, -v105
	v_cvt_pk_bf16_f32 v3, v3, s0
	global_store_short v[108:109], v3, off sc1
	v_max_i32_e32 v3, s30, v116
	v_sub_u32_e32 v3, v173, v3
	v_cvt_f32_i32_e32 v3, v3
	v_sub_f32_e32 v105, v171, v161
	v_ashrrev_i32_e32 v107, 31, v106
	v_rcp_iflag_f32_e32 v3, v3
	s_nop 0
	v_fma_f32 v3, v3, v105, -v39
	v_ashrrev_i32_e32 v39, 31, v38
	v_lshlrev_b64 v[38:39], 11, v[38:39]
	v_cvt_pk_bf16_f32 v3, v3, s0
	v_lshl_add_u64 v[38:39], v[44:45], 0, v[38:39]
	global_store_short v[38:39], v3, off sc1
	v_add_u32_e32 v3, 18, v2
	v_max_i32_e32 v38, s30, v118
	v_min_i32_e32 v3, s31, v3
	v_sub_u32_e32 v3, v3, v38
	v_cvt_f32_i32_e32 v3, v3
	v_sub_f32_e32 v39, v169, v1
	v_sub_f32_e32 v105, v175, v160
	v_rcp_iflag_f32_e32 v3, v3
	s_nop 0
	v_fma_f32 v3, v3, v105, -v39
	v_ashrrev_i32_e32 v105, 31, v104
	v_lshlrev_b64 v[38:39], 11, v[104:105]
	v_cvt_pk_bf16_f32 v3, v3, s0
	v_lshl_add_u64 v[38:39], v[44:45], 0, v[38:39]
	global_store_short v[38:39], v3, off sc1
	v_add_u32_e32 v3, 19, v2
	v_max_i32_e32 v38, s30, v120
	v_min_i32_e32 v3, s31, v3
	v_sub_u32_e32 v3, v3, v38
	v_cvt_f32_i32_e32 v3, v3
	v_sub_f32_e32 v39, v168, v169
	v_sub_f32_e32 v104, v174, v159
	v_rcp_iflag_f32_e32 v3, v3
	s_nop 0
	v_fma_f32 v3, v3, v104, -v39
	v_lshlrev_b64 v[38:39], 11, v[106:107]
	v_cvt_pk_bf16_f32 v3, v3, s0
	v_lshl_add_u64 v[38:39], v[44:45], 0, v[38:39]
	global_store_short v[38:39], v3, off sc1
	v_add_u32_e32 v3, 20, v2
	v_max_i32_e32 v38, s30, v122
	v_min_i32_e32 v3, s31, v3
	v_sub_u32_e32 v3, v3, v38
	v_cvt_f32_i32_e32 v3, v3
	v_sub_f32_e32 v39, v166, v168
	v_sub_f32_e32 v104, v111, v158
	v_ashrrev_i32_e32 v111, 31, v110
	v_rcp_iflag_f32_e32 v3, v3
	s_nop 0
	v_fma_f32 v3, v3, v104, -v39
	v_lshlrev_b64 v[38:39], 11, v[110:111]
	v_cvt_pk_bf16_f32 v3, v3, s0
	v_lshl_add_u64 v[38:39], v[44:45], 0, v[38:39]
	global_store_short v[38:39], v3, off sc1
	v_add_u32_e32 v3, 21, v2
	v_max_i32_e32 v38, s30, v124
	v_min_i32_e32 v3, s31, v3
	v_sub_u32_e32 v3, v3, v38
	v_cvt_f32_i32_e32 v3, v3
	v_sub_f32_e32 v39, v167, v166
	v_sub_f32_e32 v104, v115, v157
	v_ashrrev_i32_e32 v115, 31, v114
	v_rcp_iflag_f32_e32 v3, v3
	s_nop 0
	v_fma_f32 v3, v3, v104, -v39
	v_lshlrev_b64 v[38:39], 11, v[114:115]
	v_cvt_pk_bf16_f32 v3, v3, s0
	v_lshl_add_u64 v[38:39], v[44:45], 0, v[38:39]
	global_store_short v[38:39], v3, off sc1
	v_add_u32_e32 v3, 22, v2
	v_max_i32_e32 v38, s30, v126
	v_min_i32_e32 v3, s31, v3
	v_sub_u32_e32 v3, v3, v38
	v_cvt_f32_i32_e32 v3, v3
	v_sub_f32_e32 v39, v165, v167
	v_sub_f32_e32 v104, v113, v156
	v_ashrrev_i32_e32 v113, 31, v112
	v_rcp_iflag_f32_e32 v3, v3
	s_nop 0
	v_fma_f32 v3, v3, v104, -v39
	v_lshlrev_b64 v[38:39], 11, v[112:113]
	v_cvt_pk_bf16_f32 v3, v3, s0
	v_lshl_add_u64 v[38:39], v[44:45], 0, v[38:39]
	global_store_short v[38:39], v3, off sc1
	v_add_u32_e32 v3, 23, v2
	v_max_i32_e32 v38, s30, v128
	v_min_i32_e32 v39, s31, v3
	v_sub_f32_e32 v3, v176, v155
	v_sub_u32_e32 v38, v39, v38
.LBB0_600:
	s_or_b64 exec, exec, s[50:51]
	s_and_saveexec_b64 s[50:51], s[42:43]
	s_cbranch_execz .LBB0_602
	v_or_b32_e32 v38, 2, v2
	v_min_i32_e32 v3, s31, v38
	v_sub_u32_e32 v3, v3, v37
	v_cvt_f32_i32_e32 v3, v3
	v_sub_f32_e32 v36, v160, v164
	v_or_b32_e32 v108, 1, v2
	v_sub_f32_e32 v104, v159, v163
	v_rcp_iflag_f32_e32 v3, v3
	v_ashrrev_i32_e32 v109, 31, v108
	v_or_b32_e32 v110, 13, v2
	v_ashrrev_i32_e32 v111, 31, v110
	v_fma_f32 v3, v3, v36, -v172
	v_cvt_pk_bf16_f32 v39, v3, s0
	v_ashrrev_i32_e32 v3, 31, v2
	v_lshlrev_b64 v[36:37], 11, v[2:3]
	v_lshl_add_u64 v[36:37], v[44:45], 0, v[36:37]
	global_store_short v[36:37], v39, off sc1
	v_add_u32_e32 v3, -1, v2
	v_or_b32_e32 v36, 3, v2
	v_max_i32_e32 v3, s30, v3
	v_min_i32_e32 v37, s31, v36
	v_sub_u32_e32 v3, v37, v3
	v_cvt_f32_i32_e32 v3, v3
	v_sub_f32_e32 v39, v160, v161
	v_rcp_iflag_f32_e32 v3, v3
	s_nop 0
	v_fma_f32 v3, v3, v104, -v39
	v_lshlrev_b64 v[104:105], 11, v[108:109]
	v_cvt_pk_bf16_f32 v3, v3, s0
	v_lshl_add_u64 v[104:105], v[44:45], 0, v[104:105]
	global_store_short v[104:105], v3, off sc1
	v_or_b32_e32 v104, 4, v2
	v_max_i32_e32 v3, s30, v2
	v_min_i32_e32 v37, s31, v104
	v_sub_u32_e32 v3, v37, v3
	v_cvt_f32_i32_e32 v3, v3
	v_sub_f32_e32 v39, v159, v160
	v_sub_f32_e32 v105, v158, v162
	v_rcp_iflag_f32_e32 v3, v3
	s_nop 0
	v_fma_f32 v3, v3, v105, -v39
	v_ashrrev_i32_e32 v39, 31, v38
	v_lshlrev_b64 v[106:107], 11, v[38:39]
	v_cvt_pk_bf16_f32 v3, v3, s0
	v_lshl_add_u64 v[106:107], v[44:45], 0, v[106:107]
	global_store_short v[106:107], v3, off sc1
	v_or_b32_e32 v106, 5, v2
	v_max_i32_e32 v3, s30, v108
	v_min_i32_e32 v37, s31, v106
	v_sub_u32_e32 v3, v37, v3
	v_cvt_f32_i32_e32 v3, v3
	v_sub_f32_e32 v39, v158, v159
	v_sub_f32_e32 v105, v157, v161
	v_ashrrev_i32_e32 v37, 31, v36
	v_rcp_iflag_f32_e32 v3, v3
	v_lshlrev_b64 v[108:109], 11, v[36:37]
	v_lshl_add_u64 v[108:109], v[44:45], 0, v[108:109]
	v_ashrrev_i32_e32 v107, 31, v106
	v_fma_f32 v3, v3, v105, -v39
	v_cvt_pk_bf16_f32 v3, v3, s0
	global_store_short v[108:109], v3, off sc1
	v_or_b32_e32 v108, 6, v2
	v_max_i32_e32 v3, s30, v38
	v_min_i32_e32 v37, s31, v108
	v_sub_u32_e32 v3, v37, v3
	v_cvt_f32_i32_e32 v3, v3
	v_sub_f32_e32 v38, v157, v158
	v_sub_f32_e32 v39, v156, v160
	v_ashrrev_i32_e32 v105, 31, v104
	v_rcp_iflag_f32_e32 v3, v3
	v_sub_f32_e32 v37, v156, v157
	v_ashrrev_i32_e32 v109, 31, v108
	v_fma_f32 v3, v3, v39, -v38
	v_lshlrev_b64 v[38:39], 11, v[104:105]
	v_cvt_pk_bf16_f32 v3, v3, s0
	v_lshl_add_u64 v[38:39], v[44:45], 0, v[38:39]
	global_store_short v[38:39], v3, off sc1
	v_or_b32_e32 v38, 7, v2
	v_max_i32_e32 v3, s30, v36
	v_min_i32_e32 v36, s31, v38
	v_sub_u32_e32 v3, v36, v3
	v_cvt_f32_i32_e32 v3, v3
	v_sub_f32_e32 v39, v155, v159
	v_rcp_iflag_f32_e32 v3, v3
	s_nop 0
	v_fma_f32 v3, v3, v39, -v37
	v_lshlrev_b64 v[36:37], 11, v[106:107]
	v_cvt_pk_bf16_f32 v3, v3, s0
	v_lshl_add_u64 v[36:37], v[44:45], 0, v[36:37]
	global_store_short v[36:37], v3, off sc1
	v_or_b32_e32 v36, 8, v2
	v_max_i32_e32 v3, s30, v104
	v_min_i32_e32 v37, s31, v36
	v_sub_u32_e32 v3, v37, v3
	v_cvt_f32_i32_e32 v3, v3
	v_sub_f32_e32 v39, v155, v156
	v_sub_f32_e32 v104, v154, v158
	v_rcp_iflag_f32_e32 v3, v3
	s_nop 0
	v_fma_f32 v3, v3, v104, -v39
	v_lshlrev_b64 v[104:105], 11, v[108:109]
	v_cvt_pk_bf16_f32 v3, v3, s0
	v_lshl_add_u64 v[104:105], v[44:45], 0, v[104:105]
	global_store_short v[104:105], v3, off sc1
	v_or_b32_e32 v104, 9, v2
	v_max_i32_e32 v3, s30, v106
	v_min_i32_e32 v37, s31, v104
	v_sub_u32_e32 v3, v37, v3
	v_cvt_f32_i32_e32 v3, v3
	v_sub_f32_e32 v39, v154, v155
	v_sub_f32_e32 v105, v153, v157
	v_rcp_iflag_f32_e32 v3, v3
	s_nop 0
	v_fma_f32 v3, v3, v105, -v39
	v_ashrrev_i32_e32 v39, 31, v38
	v_lshlrev_b64 v[106:107], 11, v[38:39]
	v_cvt_pk_bf16_f32 v3, v3, s0
	v_lshl_add_u64 v[106:107], v[44:45], 0, v[106:107]
	global_store_short v[106:107], v3, off sc1
	v_or_b32_e32 v106, 10, v2
	v_max_i32_e32 v3, s30, v108
	v_min_i32_e32 v37, s31, v106
	v_sub_u32_e32 v3, v37, v3
	v_cvt_f32_i32_e32 v3, v3
	v_sub_f32_e32 v39, v153, v154
	v_sub_f32_e32 v105, v1, v156
	v_ashrrev_i32_e32 v37, 31, v36
	v_rcp_iflag_f32_e32 v3, v3
	v_lshlrev_b64 v[108:109], 11, v[36:37]
	v_lshl_add_u64 v[108:109], v[44:45], 0, v[108:109]
	v_ashrrev_i32_e32 v107, 31, v106
	v_fma_f32 v3, v3, v105, -v39
	v_cvt_pk_bf16_f32 v3, v3, s0
	global_store_short v[108:109], v3, off sc1
	v_or_b32_e32 v108, 11, v2
	v_max_i32_e32 v3, s30, v38
	v_min_i32_e32 v37, s31, v108
	v_sub_u32_e32 v3, v37, v3
	v_cvt_f32_i32_e32 v3, v3
	v_sub_f32_e32 v38, v1, v153
	v_sub_f32_e32 v39, v169, v155
	v_ashrrev_i32_e32 v105, 31, v104
	v_rcp_iflag_f32_e32 v3, v3
	v_sub_f32_e32 v37, v169, v1
	v_ashrrev_i32_e32 v109, 31, v108
	v_sub_f32_e32 v1, v167, v1
	v_fma_f32 v3, v3, v39, -v38
	v_lshlrev_b64 v[38:39], 11, v[104:105]
	v_cvt_pk_bf16_f32 v3, v3, s0
	v_lshl_add_u64 v[38:39], v[44:45], 0, v[38:39]
	global_store_short v[38:39], v3, off sc1
	v_or_b32_e32 v38, 12, v2
	v_max_i32_e32 v3, s30, v36
	v_min_i32_e32 v36, s31, v38
	v_sub_u32_e32 v3, v36, v3
	v_cvt_f32_i32_e32 v3, v3
	v_sub_f32_e32 v39, v168, v154
	v_rcp_iflag_f32_e32 v3, v3
	s_nop 0
	v_fma_f32 v3, v3, v39, -v37
	v_lshlrev_b64 v[36:37], 11, v[106:107]
	v_cvt_pk_bf16_f32 v3, v3, s0
	v_lshl_add_u64 v[36:37], v[44:45], 0, v[36:37]
	global_store_short v[36:37], v3, off sc1
	v_max_i32_e32 v3, s30, v104
	v_min_i32_e32 v36, s31, v110
	v_sub_u32_e32 v3, v36, v3
	v_cvt_f32_i32_e32 v3, v3
	v_sub_f32_e32 v37, v168, v169
	v_sub_f32_e32 v39, v166, v153
	v_or_b32_e32 v104, 14, v2
	v_rcp_iflag_f32_e32 v3, v3
	v_ashrrev_i32_e32 v105, 31, v104
	v_fma_f32 v3, v3, v39, -v37
	v_lshlrev_b64 v[36:37], 11, v[108:109]
	v_cvt_pk_bf16_f32 v3, v3, s0
	v_lshl_add_u64 v[36:37], v[44:45], 0, v[36:37]
	global_store_short v[36:37], v3, off sc1
	v_max_i32_e32 v3, s30, v106
	v_min_i32_e32 v36, s31, v104
	v_sub_u32_e32 v3, v36, v3
	v_cvt_f32_i32_e32 v3, v3
	v_sub_f32_e32 v37, v166, v168
	v_ashrrev_i32_e32 v39, 31, v38
	v_lshlrev_b64 v[106:107], 11, v[110:111]
	v_rcp_iflag_f32_e32 v3, v3
	v_lshl_add_u64 v[106:107], v[44:45], 0, v[106:107]
	v_fma_f32 v1, v3, v1, -v37
	v_lshlrev_b64 v[36:37], 11, v[38:39]
	v_cvt_pk_bf16_f32 v1, v1, s0
	v_lshl_add_u64 v[36:37], v[44:45], 0, v[36:37]
	global_store_short v[36:37], v1, off sc1
	v_or_b32_e32 v36, 15, v2
	v_max_i32_e32 v1, s30, v108
	v_min_i32_e32 v3, s31, v36
	v_sub_u32_e32 v1, v3, v1
	v_cvt_f32_i32_e32 v1, v1
	v_sub_f32_e32 v37, v167, v166
	v_sub_f32_e32 v39, v165, v169
	v_sub_f32_e32 v3, v165, v167
	v_rcp_iflag_f32_e32 v1, v1
	s_nop 0
	v_fma_f32 v1, v1, v39, -v37
	v_cvt_pk_bf16_f32 v1, v1, s0
	global_store_short v[106:107], v1, off sc1
	v_add_u32_e32 v1, 16, v2
	v_max_i32_e32 v2, s30, v38
	v_min_i32_e32 v1, s31, v1
	v_sub_u32_e32 v1, v1, v2
	v_cvt_f32_i32_e32 v1, v1
	v_sub_f32_e32 v37, v170, v168
	v_rcp_iflag_f32_e32 v1, v1
	s_nop 0
	v_fma_f32 v1, v1, v37, -v3
	v_lshlrev_b64 v[2:3], 11, v[104:105]
	v_cvt_pk_bf16_f32 v1, v1, s0
	v_lshl_add_u64 v[2:3], v[44:45], 0, v[2:3]
	global_store_short v[2:3], v1, off sc1
	v_max_i32_e32 v1, s30, v110
	v_sub_f32_e32 v3, v171, v166
	v_sub_u32_e32 v38, v173, v1

.LBB0_603:
	s_andn2_saveexec_b64 s[12:13], s[12:13]
	s_cbranch_execz .LBB0_562
	v_add_u32_e32 v3, -1, v2
	v_or_b32_e32 v36, 1, v2
	v_max_i32_e32 v3, s30, v3
	v_min_i32_e32 v37, s31, v36
	v_sub_u32_e32 v3, v37, v3
	v_cvt_f32_i32_e32 v3, v3
	v_sub_f32_e32 v38, v161, v162
	v_sub_f32_e32 v39, v161, v163
	v_sub_f32_e32 v104, v160, v162
	v_rcp_iflag_f32_e32 v3, v3
	v_or_b32_e32 v106, 13, v2
	v_ashrrev_i32_e32 v107, 31, v106
	v_fma_f32 v3, v3, v39, -v38
	v_cvt_pk_bf16_f32 v37, v3, s0
	v_ashrrev_i32_e32 v3, 31, v2
	v_lshlrev_b64 v[38:39], 11, v[2:3]
	v_lshl_add_u64 v[38:39], v[44:45], 0, v[38:39]
	global_store_short v[38:39], v37, off sc1
	v_or_b32_e32 v38, 2, v2
	v_max_i32_e32 v3, s30, v2
	v_min_i32_e32 v37, s31, v38
	v_sub_u32_e32 v3, v37, v3
	v_cvt_f32_i32_e32 v3, v3
	v_sub_f32_e32 v39, v160, v161
	v_ashrrev_i32_e32 v37, 31, v36
	v_rcp_iflag_f32_e32 v3, v3
	s_nop 0
	v_fma_f32 v3, v3, v104, -v39
	v_lshlrev_b64 v[104:105], 11, v[36:37]
	v_cvt_pk_bf16_f32 v3, v3, s0
	v_lshl_add_u64 v[104:105], v[44:45], 0, v[104:105]
	global_store_short v[104:105], v3, off sc1
	v_or_b32_e32 v104, 3, v2
	v_max_i32_e32 v3, s30, v36
	v_min_i32_e32 v36, s31, v104
	v_sub_u32_e32 v3, v36, v3
	v_cvt_f32_i32_e32 v3, v3
	v_sub_f32_e32 v37, v159, v160
	v_sub_f32_e32 v39, v159, v161
	v_ashrrev_i32_e32 v105, 31, v104
	v_rcp_iflag_f32_e32 v3, v3
	s_nop 0
	v_fma_f32 v3, v3, v39, -v37
	v_ashrrev_i32_e32 v39, 31, v38
	v_lshlrev_b64 v[36:37], 11, v[38:39]
	v_cvt_pk_bf16_f32 v3, v3, s0
	v_lshl_add_u64 v[36:37], v[44:45], 0, v[36:37]
	global_store_short v[36:37], v3, off sc1
	v_or_b32_e32 v36, 4, v2
	v_max_i32_e32 v3, s30, v38
	v_min_i32_e32 v37, s31, v36
	v_sub_u32_e32 v3, v37, v3
	v_cvt_f32_i32_e32 v3, v3
	v_sub_f32_e32 v38, v158, v159
	v_sub_f32_e32 v39, v158, v160
	v_rcp_iflag_f32_e32 v3, v3
	s_nop 0
	v_fma_f32 v3, v3, v39, -v38
	v_lshlrev_b64 v[38:39], 11, v[104:105]
	v_cvt_pk_bf16_f32 v3, v3, s0
	v_lshl_add_u64 v[38:39], v[44:45], 0, v[38:39]
	global_store_short v[38:39], v3, off sc1
	v_or_b32_e32 v38, 5, v2
	v_max_i32_e32 v3, s30, v104
	v_min_i32_e32 v37, s31, v38
	v_sub_u32_e32 v3, v37, v3
	v_cvt_f32_i32_e32 v3, v3
	v_sub_f32_e32 v39, v157, v158
	v_sub_f32_e32 v104, v157, v159
	v_ashrrev_i32_e32 v37, 31, v36
	v_rcp_iflag_f32_e32 v3, v3
	s_nop 0
	v_fma_f32 v3, v3, v104, -v39
	v_lshlrev_b64 v[104:105], 11, v[36:37]
	v_cvt_pk_bf16_f32 v3, v3, s0
	v_lshl_add_u64 v[104:105], v[44:45], 0, v[104:105]
	global_store_short v[104:105], v3, off sc1
	v_or_b32_e32 v104, 6, v2
	v_max_i32_e32 v3, s30, v36
	v_min_i32_e32 v36, s31, v104
	v_sub_u32_e32 v3, v36, v3
	v_cvt_f32_i32_e32 v3, v3
	v_sub_f32_e32 v37, v156, v157
	v_sub_f32_e32 v39, v156, v158
	v_ashrrev_i32_e32 v105, 31, v104
	v_rcp_iflag_f32_e32 v3, v3
	s_nop 0
	v_fma_f32 v3, v3, v39, -v37
	v_ashrrev_i32_e32 v39, 31, v38
	v_lshlrev_b64 v[36:37], 11, v[38:39]
	v_cvt_pk_bf16_f32 v3, v3, s0
	v_lshl_add_u64 v[36:37], v[44:45], 0, v[36:37]
	global_store_short v[36:37], v3, off sc1
	v_or_b32_e32 v36, 7, v2
	v_max_i32_e32 v3, s30, v38
	v_min_i32_e32 v37, s31, v36
	v_sub_u32_e32 v3, v37, v3
	v_cvt_f32_i32_e32 v3, v3
	v_sub_f32_e32 v38, v155, v156
	v_sub_f32_e32 v39, v155, v157
	v_rcp_iflag_f32_e32 v3, v3
	s_nop 0
	v_fma_f32 v3, v3, v39, -v38
	v_lshlrev_b64 v[38:39], 11, v[104:105]
	v_cvt_pk_bf16_f32 v3, v3, s0
	v_lshl_add_u64 v[38:39], v[44:45], 0, v[38:39]
	global_store_short v[38:39], v3, off sc1
	v_or_b32_e32 v38, 8, v2
	v_max_i32_e32 v3, s30, v104
	v_min_i32_e32 v37, s31, v38
	v_sub_u32_e32 v3, v37, v3
	v_cvt_f32_i32_e32 v3, v3
	v_sub_f32_e32 v39, v154, v155
	v_sub_f32_e32 v104, v154, v156
	v_ashrrev_i32_e32 v37, 31, v36
	v_rcp_iflag_f32_e32 v3, v3
	s_nop 0
	v_fma_f32 v3, v3, v104, -v39
	v_lshlrev_b64 v[104:105], 11, v[36:37]
	v_cvt_pk_bf16_f32 v3, v3, s0
	v_lshl_add_u64 v[104:105], v[44:45], 0, v[104:105]
	global_store_short v[104:105], v3, off sc1
	v_or_b32_e32 v104, 9, v2
	v_max_i32_e32 v3, s30, v36
	v_min_i32_e32 v36, s31, v104
	v_sub_u32_e32 v3, v36, v3
	v_cvt_f32_i32_e32 v3, v3
	v_sub_f32_e32 v37, v153, v154
	v_sub_f32_e32 v39, v153, v155
	v_ashrrev_i32_e32 v105, 31, v104
	v_rcp_iflag_f32_e32 v3, v3
	s_nop 0
	v_fma_f32 v3, v3, v39, -v37
	v_ashrrev_i32_e32 v39, 31, v38
	v_lshlrev_b64 v[36:37], 11, v[38:39]
	v_cvt_pk_bf16_f32 v3, v3, s0
	v_lshl_add_u64 v[36:37], v[44:45], 0, v[36:37]
	global_store_short v[36:37], v3, off sc1
	v_or_b32_e32 v36, 10, v2
	v_max_i32_e32 v3, s30, v38
	v_min_i32_e32 v37, s31, v36
	v_sub_u32_e32 v3, v37, v3
	v_cvt_f32_i32_e32 v3, v3
	v_sub_f32_e32 v38, v1, v153
	v_sub_f32_e32 v39, v1, v154
	v_rcp_iflag_f32_e32 v3, v3
	s_nop 0
	v_fma_f32 v3, v3, v39, -v38
	v_lshlrev_b64 v[38:39], 11, v[104:105]
	v_cvt_pk_bf16_f32 v3, v3, s0
	v_lshl_add_u64 v[38:39], v[44:45], 0, v[38:39]
	global_store_short v[38:39], v3, off sc1
	v_or_b32_e32 v38, 11, v2
	v_max_i32_e32 v3, s30, v104
	v_min_i32_e32 v37, s31, v38
	v_sub_u32_e32 v3, v37, v3
	v_cvt_f32_i32_e32 v3, v3
	v_sub_f32_e32 v39, v169, v1
	v_sub_f32_e32 v104, v169, v153
	v_ashrrev_i32_e32 v37, 31, v36
	v_rcp_iflag_f32_e32 v3, v3
	v_sub_f32_e32 v1, v168, v1
	v_fma_f32 v3, v3, v104, -v39
	v_lshlrev_b64 v[104:105], 11, v[36:37]
	v_cvt_pk_bf16_f32 v3, v3, s0
	v_lshl_add_u64 v[104:105], v[44:45], 0, v[104:105]
	global_store_short v[104:105], v3, off sc1
	v_or_b32_e32 v104, 12, v2
	v_max_i32_e32 v3, s30, v36
	v_min_i32_e32 v36, s31, v104
	v_sub_u32_e32 v3, v36, v3
	v_cvt_f32_i32_e32 v3, v3
	v_sub_f32_e32 v37, v168, v169
	v_ashrrev_i32_e32 v39, 31, v38
	v_ashrrev_i32_e32 v105, 31, v104
	v_rcp_iflag_f32_e32 v3, v3
	s_nop 0
	v_fma_f32 v1, v3, v1, -v37
	v_lshlrev_b64 v[36:37], 11, v[38:39]
	v_cvt_pk_bf16_f32 v1, v1, s0
	v_lshl_add_u64 v[36:37], v[44:45], 0, v[36:37]
	global_store_short v[36:37], v1, off sc1
	v_max_i32_e32 v1, s30, v38
	v_min_i32_e32 v3, s31, v106
	v_sub_u32_e32 v1, v3, v1
	v_cvt_f32_i32_e32 v1, v1
	v_sub_f32_e32 v36, v166, v168
	v_sub_f32_e32 v37, v166, v169
	v_or_b32_e32 v38, 14, v2
	v_rcp_iflag_f32_e32 v1, v1
	v_min_i32_e32 v3, s31, v38
	v_sub_f32_e32 v39, v165, v166
	v_fma_f32 v1, v1, v37, -v36
	v_lshlrev_b64 v[36:37], 11, v[104:105]
	v_cvt_pk_bf16_f32 v1, v1, s0
	v_lshl_add_u64 v[36:37], v[44:45], 0, v[36:37]
	global_store_short v[36:37], v1, off sc1
	v_max_i32_e32 v1, s30, v104
	v_sub_u32_e32 v1, v3, v1
	v_cvt_f32_i32_e32 v1, v1
	v_sub_f32_e32 v36, v167, v166
	v_sub_f32_e32 v37, v167, v168
	v_rcp_iflag_f32_e32 v1, v1
	s_nop 0
	v_fma_f32 v1, v1, v37, -v36
	v_lshlrev_b64 v[36:37], 11, v[106:107]
	v_cvt_pk_bf16_f32 v1, v1, s0
	v_lshl_add_u64 v[36:37], v[44:45], 0, v[36:37]
	global_store_short v[36:37], v1, off sc1
	v_or_b32_e32 v36, 15, v2
	v_max_i32_e32 v1, s30, v106
	v_min_i32_e32 v3, s31, v36
	v_sub_u32_e32 v1, v3, v1
	v_cvt_f32_i32_e32 v1, v1
	v_sub_f32_e32 v37, v165, v167
	v_sub_f32_e32 v3, v170, v167
	v_rcp_iflag_f32_e32 v1, v1
	s_nop 0
	v_fma_f32 v1, v1, v39, -v37
	v_ashrrev_i32_e32 v39, 31, v38
	v_lshlrev_b64 v[104:105], 11, v[38:39]
	v_cvt_pk_bf16_f32 v1, v1, s0
	v_lshl_add_u64 v[104:105], v[44:45], 0, v[104:105]
	global_store_short v[104:105], v1, off sc1
	v_add_u32_e32 v1, 16, v2
	v_max_i32_e32 v2, s30, v38
	v_min_i32_e32 v1, s31, v1
	v_sub_u32_e32 v38, v1, v2
	s_branch .LBB0_562

.LBB0_682:
	v_add_u32_e32 v200, s21, v1
	s_waitcnt vmcnt(0)
	v_pk_mul_f32 v[204:205], v[192:193], v[162:163]
	v_lshl_add_u64 v[162:163], v[198:199], 1, s[58:59]
	v_ashrrev_i32_e32 v201, 31, v200
	v_lshl_add_u64 v[210:211], v[162:163], 0, s[62:63]
	v_lshlrev_b64 v[162:163], 11, v[200:201]
	v_mov_b32_e32 v191, v190
	v_lshl_add_u64 v[216:217], v[210:211], 0, v[162:163]
	v_pk_mul_f32 v[202:203], v[190:191], v[164:165]
	global_load_dwordx4 v[162:165], v[216:217], off
	global_load_dwordx4 v[178:181], v[216:217], off offset:256
	v_or_b32_e32 v214, 16, v200
	v_ashrrev_i32_e32 v215, 31, v214
	v_pk_mul_f32 v[206:207], v[190:191], v[88:89]
	v_pk_mul_f32 v[208:209], v[192:193], v[86:87]
	global_load_dwordx4 v[86:89], v[176:177], off offset:528
	s_mov_b64 s[26:27], -1
	s_and_b64 vcc, exec, s[34:35]
	s_waitcnt vmcnt(2)
	v_lshlrev_b32_e32 v174, 16, v162
	v_and_b32_e32 v175, 0xffff0000, v162
	v_lshlrev_b32_e32 v162, 16, v163
	v_and_b32_e32 v163, 0xffff0000, v163
	v_pk_mul_f32 v[230:231], v[92:93], v[162:163]
	v_lshlrev_b64 v[162:163], 11, v[214:215]
	v_lshlrev_b32_e32 v176, 16, v164
	v_and_b32_e32 v177, 0xffff0000, v164
	v_lshlrev_b32_e32 v164, 16, v165
	v_and_b32_e32 v165, 0xffff0000, v165
	v_lshl_add_u64 v[212:213], v[210:211], 0, v[162:163]
	v_pk_mul_f32 v[218:219], v[90:91], v[174:175]
	v_pk_mul_f32 v[232:233], v[94:95], v[176:177]
	v_pk_mul_f32 v[240:241], v[96:97], v[164:165]
	global_load_dwordx4 v[174:177], v[212:213], off
	global_load_dwordx4 v[162:165], v[212:213], off offset:256
	v_pk_fma_f32 v[160:161], v[160:161], v[206:207], v[230:231]
	v_pk_fma_f32 v[158:159], v[158:159], v[208:209], v[218:219]
	v_pk_fma_f32 v[156:157], v[156:157], v[202:203], v[240:241]
	v_pk_fma_f32 v[154:155], v[154:155], v[204:205], v[232:233]
	s_cbranch_vccz .LBB0_684
	v_mov_b32_e32 v230, v159
	v_mov_b32_e32 v231, v155
	v_mov_b32_e32 v218, v158
	v_mov_b32_e32 v219, v154
	v_pk_mul_f32 v[230:231], v[230:231], v[230:231]
	v_mov_b32_e32 v232, v161
	v_mov_b32_e32 v233, v157
	v_pk_fma_f32 v[218:219], v[218:219], v[218:219], v[230:231]
	v_mov_b32_e32 v230, v160
	v_mov_b32_e32 v231, v156
	v_pk_mul_f32 v[232:233], v[232:233], v[232:233]
	v_pk_mul_f32 v[242:243], v[68:69], v[156:157]
	v_pk_fma_f32 v[230:231], v[230:231], v[230:231], v[232:233]
	v_pk_mul_f32 v[232:233], v[66:67], v[154:155]
	v_pk_add_f32 v[218:219], v[218:219], v[230:231]
	v_pk_mul_f32 v[230:231], v[70:71], v[158:159]
	v_add_f32_e32 v240, v218, v219
	v_pk_mul_f32 v[218:219], v[72:73], v[160:161]
	v_cvt_pk_bf16_f32 v230, v230, v231
	v_cvt_pk_bf16_f32 v231, v218, v219
	v_cvt_pk_bf16_f32 v232, v232, v233
	v_cvt_pk_bf16_f32 v233, v242, v243
	global_store_dwordx4 v[216:217], v[230:233], off sc1
	s_mov_b64 s[26:27], 0

.LBB0_686:
	s_waitcnt vmcnt(3)
	s_nop 0
	v_lshlrev_b32_e32 v154, 16, v178
	v_and_b32_e32 v155, 0xffff0000, v178
	v_lshlrev_b32_e32 v156, 16, v179
	v_and_b32_e32 v157, 0xffff0000, v179
	v_lshlrev_b32_e32 v158, 16, v180
	v_and_b32_e32 v159, 0xffff0000, v180
	v_lshlrev_b32_e32 v160, 16, v181
	v_and_b32_e32 v161, 0xffff0000, v181
	v_mov_b32_e32 v191, v190
	v_pk_mul_f32 v[178:179], v[82:83], v[154:155]
	v_pk_mul_f32 v[180:181], v[84:85], v[156:157]
	s_waitcnt vmcnt(2)
	v_pk_mul_f32 v[230:231], v[86:87], v[158:159]
	v_pk_mul_f32 v[232:233], v[88:89], v[160:161]
	v_pk_mul_f32 v[154:155], v[190:191], v[172:173]
	v_pk_mul_f32 v[156:157], v[192:193], v[170:171]
	v_pk_mul_f32 v[158:159], v[190:191], v[168:169]
	v_pk_mul_f32 v[160:161], v[192:193], v[166:167]
	v_pk_fma_f32 v[152:153], v[152:153], v[158:159], v[180:181]
	v_pk_fma_f32 v[150:151], v[150:151], v[160:161], v[178:179]
	v_pk_fma_f32 v[148:149], v[148:149], v[154:155], v[232:233]
	v_pk_fma_f32 v[146:147], v[146:147], v[156:157], v[230:231]
	s_and_b64 vcc, exec, s[6:7]
	s_mov_b64 s[20:21], -1
	s_cbranch_vccnz .LBB0_688
	v_mov_b32_e32 v168, v151
	v_mov_b32_e32 v169, v147
	v_mov_b32_e32 v166, v150
	v_mov_b32_e32 v167, v146
	v_pk_mul_f32 v[168:169], v[168:169], v[168:169]
	v_mov_b32_e32 v170, v153
	v_mov_b32_e32 v171, v149
	v_pk_fma_f32 v[166:167], v[166:167], v[166:167], v[168:169]
	v_mov_b32_e32 v168, v152
	v_mov_b32_e32 v169, v148
	v_pk_mul_f32 v[170:171], v[170:171], v[170:171]
	v_pk_mul_f32 v[172:173], v[60:61], v[148:149]
	v_pk_fma_f32 v[168:169], v[168:169], v[168:169], v[170:171]
	v_pk_mul_f32 v[170:171], v[64:65], v[152:153]
	v_pk_add_f32 v[166:167], v[166:167], v[168:169]
	v_pk_mul_f32 v[168:169], v[62:63], v[150:151]
	v_add_f32_e32 v166, v166, v167
	v_pk_mul_f32 v[178:179], v[58:59], v[146:147]
	v_add_f32_e32 v166, v166, v240
	v_cvt_pk_bf16_f32 v168, v168, v169
	v_cvt_pk_bf16_f32 v169, v170, v171
	v_cvt_pk_bf16_f32 v170, v178, v179
	v_cvt_pk_bf16_f32 v171, v172, v173
	s_mov_b64 s[20:21], 0
	global_store_dwordx4 v[216:217], v[168:171], off offset:256 sc1

.LBB0_694:
	s_waitcnt vmcnt(1)
	v_lshlrev_b32_e32 v146, 16, v174
	s_waitcnt lgkmcnt(0)
	v_and_b32_e32 v147, 0xffff0000, v174
	v_lshlrev_b32_e32 v148, 16, v175
	v_and_b32_e32 v149, 0xffff0000, v175
	v_lshlrev_b32_e32 v150, 16, v176
	v_and_b32_e32 v151, 0xffff0000, v176
	v_lshlrev_b32_e32 v152, 16, v177
	v_and_b32_e32 v153, 0xffff0000, v177
	v_pk_mul_f32 v[146:147], v[90:91], v[146:147]
	v_pk_mul_f32 v[148:149], v[92:93], v[148:149]
	v_pk_mul_f32 v[150:151], v[94:95], v[150:151]
	v_pk_mul_f32 v[152:153], v[96:97], v[152:153]
	v_pk_fma_f32 v[144:145], v[144:145], v[206:207], v[148:149]
	v_pk_fma_f32 v[142:143], v[142:143], v[208:209], v[146:147]
	v_pk_fma_f32 v[140:141], v[140:141], v[202:203], v[152:153]
	v_pk_fma_f32 v[138:139], v[138:139], v[204:205], v[150:151]
	s_and_b64 vcc, exec, s[6:7]
	s_mov_b64 s[20:21], -1
	s_cbranch_vccnz .LBB0_696
	v_mov_b32_e32 v148, v143
	v_mov_b32_e32 v149, v139
	v_mov_b32_e32 v146, v142
	v_mov_b32_e32 v147, v138
	v_pk_mul_f32 v[148:149], v[148:149], v[148:149]
	v_mov_b32_e32 v150, v145
	v_mov_b32_e32 v151, v141
	v_pk_fma_f32 v[146:147], v[146:147], v[146:147], v[148:149]
	v_mov_b32_e32 v148, v144
	v_mov_b32_e32 v149, v140
	v_pk_mul_f32 v[150:151], v[150:151], v[150:151]
	v_pk_mul_f32 v[166:167], v[68:69], v[140:141]
	v_pk_fma_f32 v[148:149], v[148:149], v[148:149], v[150:151]
	v_pk_mul_f32 v[150:151], v[70:71], v[142:143]
	v_pk_add_f32 v[146:147], v[146:147], v[148:149]
	v_pk_mul_f32 v[152:153], v[66:67], v[138:139]
	v_add_f32_e32 v148, v146, v147
	v_pk_mul_f32 v[146:147], v[72:73], v[144:145]
	v_cvt_pk_bf16_f32 v150, v150, v151
	v_cvt_pk_bf16_f32 v151, v146, v147
	v_cvt_pk_bf16_f32 v152, v152, v153
	v_cvt_pk_bf16_f32 v153, v166, v167
	s_mov_b64 s[20:21], 0
	global_store_dwordx4 v[212:213], v[150:153], off sc1

.LBB0_698:
	s_waitcnt vmcnt(0)
	s_nop 0
	v_lshlrev_b32_e32 v138, 16, v162
	v_and_b32_e32 v139, 0xffff0000, v162
	v_lshlrev_b32_e32 v140, 16, v163
	v_and_b32_e32 v141, 0xffff0000, v163
	v_lshlrev_b32_e32 v142, 16, v164
	v_and_b32_e32 v143, 0xffff0000, v164
	v_lshlrev_b32_e32 v144, 16, v165
	v_and_b32_e32 v145, 0xffff0000, v165
	v_pk_mul_f32 v[138:139], v[82:83], v[138:139]
	v_pk_mul_f32 v[140:141], v[84:85], v[140:141]
	v_pk_mul_f32 v[142:143], v[86:87], v[142:143]
	v_pk_mul_f32 v[144:145], v[88:89], v[144:145]
	v_pk_fma_f32 v[136:137], v[136:137], v[158:159], v[140:141]
	v_pk_fma_f32 v[134:135], v[134:135], v[160:161], v[138:139]
	v_pk_fma_f32 v[132:133], v[132:133], v[154:155], v[144:145]
	v_pk_fma_f32 v[130:131], v[130:131], v[156:157], v[142:143]
	s_and_b64 vcc, exec, s[6:7]
	s_mov_b64 s[20:21], -1
	s_cbranch_vccnz .LBB0_701
	v_mov_b32_e32 v140, v135
	v_mov_b32_e32 v141, v131
	v_mov_b32_e32 v138, v134
	v_mov_b32_e32 v139, v130
	v_pk_mul_f32 v[140:141], v[140:141], v[140:141]
	v_mov_b32_e32 v142, v137
	v_mov_b32_e32 v143, v133
	v_pk_fma_f32 v[138:139], v[138:139], v[138:139], v[140:141]
	v_mov_b32_e32 v140, v136
	v_mov_b32_e32 v141, v132
	v_pk_mul_f32 v[142:143], v[142:143], v[142:143]
	v_pk_mul_f32 v[144:145], v[60:61], v[132:133]
	v_pk_fma_f32 v[140:141], v[140:141], v[140:141], v[142:143]
	v_pk_mul_f32 v[142:143], v[64:65], v[136:137]
	v_pk_add_f32 v[138:139], v[138:139], v[140:141]
	v_pk_mul_f32 v[140:141], v[62:63], v[134:135]
	v_add_f32_e32 v138, v138, v139
	v_pk_mul_f32 v[150:151], v[58:59], v[130:131]
	v_add_f32_e32 v138, v138, v148
	v_cvt_pk_bf16_f32 v140, v140, v141
	v_cvt_pk_bf16_f32 v141, v142, v143
	v_cvt_pk_bf16_f32 v142, v150, v151
	v_cvt_pk_bf16_f32 v143, v144, v145
	global_store_dwordx4 v[212:213], v[140:143], off offset:256 sc1
	s_cbranch_execz .LBB0_702

.LBB0_706:
	v_or_b32_e32 v148, 32, v200
	v_ashrrev_i32_e32 v149, 31, v148
	s_waitcnt lgkmcnt(0)
	v_lshlrev_b64 v[130:131], 11, v[148:149]
	v_lshl_add_u64 v[146:147], v[210:211], 0, v[130:131]
	v_or_b32_e32 v144, 48, v200
	global_load_dwordx4 v[150:153], v[146:147], off
	v_ashrrev_i32_e32 v145, 31, v144
	v_lshlrev_b64 v[130:131], 11, v[144:145]
	v_lshl_add_u64 v[142:143], v[210:211], 0, v[130:131]
	global_load_dwordx4 v[138:141], v[146:147], off offset:256
	global_load_dwordx4 v[134:137], v[142:143], off
	global_load_dwordx4 v[130:133], v[142:143], off offset:256
	s_and_b64 vcc, exec, s[6:7]
	s_mov_b64 s[20:21], -1
	s_waitcnt vmcnt(3)
	v_lshlrev_b32_e32 v162, 16, v150
	v_and_b32_e32 v163, 0xffff0000, v150
	v_lshlrev_b32_e32 v150, 16, v151
	v_and_b32_e32 v151, 0xffff0000, v151
	v_lshlrev_b32_e32 v164, 16, v152
	v_and_b32_e32 v165, 0xffff0000, v152
	v_lshlrev_b32_e32 v152, 16, v153
	v_and_b32_e32 v153, 0xffff0000, v153
	v_pk_mul_f32 v[162:163], v[90:91], v[162:163]
	v_pk_mul_f32 v[150:151], v[92:93], v[150:151]
	v_pk_mul_f32 v[164:165], v[94:95], v[164:165]
	v_pk_mul_f32 v[152:153], v[96:97], v[152:153]
	v_pk_fma_f32 v[128:129], v[128:129], v[206:207], v[150:151]
	v_pk_fma_f32 v[126:127], v[126:127], v[208:209], v[162:163]
	v_pk_fma_f32 v[124:125], v[124:125], v[202:203], v[152:153]
	v_pk_fma_f32 v[122:123], v[122:123], v[204:205], v[164:165]
	s_cbranch_vccnz .LBB0_708
	v_mov_b32_e32 v152, v127
	v_mov_b32_e32 v153, v123
	v_mov_b32_e32 v150, v126
	v_mov_b32_e32 v151, v122
	v_pk_mul_f32 v[152:153], v[152:153], v[152:153]
	v_mov_b32_e32 v162, v129
	v_mov_b32_e32 v163, v125
	v_pk_fma_f32 v[150:151], v[150:151], v[150:151], v[152:153]
	v_mov_b32_e32 v152, v128
	v_mov_b32_e32 v153, v124
	v_pk_mul_f32 v[162:163], v[162:163], v[162:163]
	v_pk_mul_f32 v[166:167], v[68:69], v[124:125]
	v_pk_fma_f32 v[152:153], v[152:153], v[152:153], v[162:163]
	v_pk_mul_f32 v[162:163], v[70:71], v[126:127]
	v_pk_add_f32 v[150:151], v[150:151], v[152:153]
	v_pk_mul_f32 v[152:153], v[72:73], v[128:129]
	v_pk_mul_f32 v[164:165], v[66:67], v[122:123]
	v_add_f32_e32 v150, v150, v151
	v_cvt_pk_bf16_f32 v162, v162, v163
	v_cvt_pk_bf16_f32 v163, v152, v153
	v_cvt_pk_bf16_f32 v164, v164, v165
	v_cvt_pk_bf16_f32 v165, v166, v167
	s_mov_b64 s[20:21], 0
	global_store_dwordx4 v[146:147], v[162:165], off sc1

.LBB0_710:
	s_waitcnt vmcnt(2)
	s_nop 0
	v_lshlrev_b32_e32 v122, 16, v138
	v_and_b32_e32 v123, 0xffff0000, v138
	v_lshlrev_b32_e32 v124, 16, v139
	v_and_b32_e32 v125, 0xffff0000, v139
	v_lshlrev_b32_e32 v126, 16, v140
	v_and_b32_e32 v127, 0xffff0000, v140
	v_lshlrev_b32_e32 v128, 16, v141
	v_and_b32_e32 v129, 0xffff0000, v141
	v_pk_mul_f32 v[122:123], v[82:83], v[122:123]
	v_pk_mul_f32 v[124:125], v[84:85], v[124:125]
	v_pk_mul_f32 v[126:127], v[86:87], v[126:127]
	v_pk_mul_f32 v[128:129], v[88:89], v[128:129]
	v_pk_fma_f32 v[120:121], v[120:121], v[158:159], v[124:125]
	v_pk_fma_f32 v[118:119], v[118:119], v[160:161], v[122:123]
	v_pk_fma_f32 v[116:117], v[116:117], v[154:155], v[128:129]
	v_pk_fma_f32 v[114:115], v[114:115], v[156:157], v[126:127]
	s_and_b64 vcc, exec, s[6:7]
	s_mov_b64 s[20:21], -1
	s_cbranch_vccnz .LBB0_713
	v_mov_b32_e32 v124, v119
	v_mov_b32_e32 v125, v115
	v_mov_b32_e32 v122, v118
	v_mov_b32_e32 v123, v114
	v_pk_mul_f32 v[124:125], v[124:125], v[124:125]
	v_mov_b32_e32 v126, v121
	v_mov_b32_e32 v127, v117
	v_pk_fma_f32 v[122:123], v[122:123], v[122:123], v[124:125]
	v_mov_b32_e32 v124, v120
	v_mov_b32_e32 v125, v116
	v_pk_mul_f32 v[126:127], v[126:127], v[126:127]
	v_pk_mul_f32 v[128:129], v[60:61], v[116:117]
	v_pk_fma_f32 v[124:125], v[124:125], v[124:125], v[126:127]
	v_pk_mul_f32 v[126:127], v[64:65], v[120:121]
	v_pk_add_f32 v[122:123], v[122:123], v[124:125]
	v_pk_mul_f32 v[124:125], v[62:63], v[118:119]
	v_add_f32_e32 v122, v122, v123
	v_pk_mul_f32 v[138:139], v[58:59], v[114:115]
	v_add_f32_e32 v122, v122, v150
	v_cvt_pk_bf16_f32 v124, v124, v125
	v_cvt_pk_bf16_f32 v125, v126, v127
	v_cvt_pk_bf16_f32 v126, v138, v139
	v_cvt_pk_bf16_f32 v127, v128, v129
	global_store_dwordx4 v[146:147], v[124:127], off offset:256 sc1
	s_cbranch_execz .LBB0_714

.LBB0_718:
	s_waitcnt vmcnt(1)
	v_lshlrev_b32_e32 v114, 16, v134
	s_waitcnt lgkmcnt(0)
	v_and_b32_e32 v115, 0xffff0000, v134
	v_lshlrev_b32_e32 v116, 16, v135
	v_and_b32_e32 v117, 0xffff0000, v135
	v_lshlrev_b32_e32 v118, 16, v136
	v_and_b32_e32 v119, 0xffff0000, v136
	v_lshlrev_b32_e32 v120, 16, v137
	v_and_b32_e32 v121, 0xffff0000, v137
	v_pk_mul_f32 v[114:115], v[90:91], v[114:115]
	v_pk_mul_f32 v[116:117], v[92:93], v[116:117]
	v_pk_mul_f32 v[118:119], v[94:95], v[118:119]
	v_pk_mul_f32 v[120:121], v[96:97], v[120:121]
	v_pk_fma_f32 v[112:113], v[112:113], v[206:207], v[116:117]
	v_pk_fma_f32 v[110:111], v[110:111], v[208:209], v[114:115]
	v_pk_fma_f32 v[108:109], v[108:109], v[202:203], v[120:121]
	v_pk_fma_f32 v[106:107], v[106:107], v[204:205], v[118:119]
	s_and_b64 vcc, exec, s[6:7]
	s_mov_b64 s[20:21], -1
	s_cbranch_vccnz .LBB0_720
	v_mov_b32_e32 v116, v111
	v_mov_b32_e32 v117, v107
	v_mov_b32_e32 v114, v110
	v_mov_b32_e32 v115, v106
	v_pk_mul_f32 v[116:117], v[116:117], v[116:117]
	v_mov_b32_e32 v118, v113
	v_mov_b32_e32 v119, v109
	v_pk_fma_f32 v[114:115], v[114:115], v[114:115], v[116:117]
	v_mov_b32_e32 v116, v112
	v_mov_b32_e32 v117, v108
	v_pk_mul_f32 v[118:119], v[118:119], v[118:119]
	v_pk_mul_f32 v[122:123], v[68:69], v[108:109]
	v_pk_fma_f32 v[116:117], v[116:117], v[116:117], v[118:119]
	v_pk_mul_f32 v[118:119], v[70:71], v[110:111]
	v_pk_add_f32 v[114:115], v[114:115], v[116:117]
	v_pk_mul_f32 v[120:121], v[66:67], v[106:107]
	v_add_f32_e32 v116, v114, v115
	v_pk_mul_f32 v[114:115], v[72:73], v[112:113]
	v_cvt_pk_bf16_f32 v118, v118, v119
	v_cvt_pk_bf16_f32 v119, v114, v115
	v_cvt_pk_bf16_f32 v120, v120, v121
	v_cvt_pk_bf16_f32 v121, v122, v123
	s_mov_b64 s[20:21], 0
	global_store_dwordx4 v[142:143], v[118:121], off sc1

.LBB0_722:
	s_waitcnt vmcnt(0)
	s_nop 0
	v_lshlrev_b32_e32 v106, 16, v130
	v_and_b32_e32 v107, 0xffff0000, v130
	v_lshlrev_b32_e32 v108, 16, v131
	v_and_b32_e32 v109, 0xffff0000, v131
	v_lshlrev_b32_e32 v110, 16, v132
	v_and_b32_e32 v111, 0xffff0000, v132
	v_lshlrev_b32_e32 v112, 16, v133
	v_and_b32_e32 v113, 0xffff0000, v133
	v_pk_mul_f32 v[106:107], v[82:83], v[106:107]
	v_pk_mul_f32 v[108:109], v[84:85], v[108:109]
	v_pk_mul_f32 v[110:111], v[86:87], v[110:111]
	v_pk_mul_f32 v[112:113], v[88:89], v[112:113]
	v_pk_fma_f32 v[104:105], v[104:105], v[158:159], v[108:109]
	v_pk_fma_f32 v[102:103], v[102:103], v[160:161], v[106:107]
	v_pk_fma_f32 v[100:101], v[100:101], v[154:155], v[112:113]
	v_pk_fma_f32 v[98:99], v[98:99], v[156:157], v[110:111]
	s_and_b64 vcc, exec, s[6:7]
	s_mov_b64 s[20:21], -1
	s_cbranch_vccnz .LBB0_725
	v_mov_b32_e32 v108, v103
	v_mov_b32_e32 v109, v99
	v_mov_b32_e32 v106, v102
	v_mov_b32_e32 v107, v98
	v_pk_mul_f32 v[108:109], v[108:109], v[108:109]
	v_mov_b32_e32 v110, v105
	v_mov_b32_e32 v111, v101
	v_pk_fma_f32 v[106:107], v[106:107], v[106:107], v[108:109]
	v_mov_b32_e32 v108, v104
	v_mov_b32_e32 v109, v100
	v_pk_mul_f32 v[110:111], v[110:111], v[110:111]
	v_pk_mul_f32 v[112:113], v[60:61], v[100:101]
	v_pk_fma_f32 v[108:109], v[108:109], v[108:109], v[110:111]
	v_pk_mul_f32 v[110:111], v[64:65], v[104:105]
	v_pk_add_f32 v[106:107], v[106:107], v[108:109]
	v_pk_mul_f32 v[108:109], v[62:63], v[102:103]
	v_add_f32_e32 v106, v106, v107
	v_pk_mul_f32 v[118:119], v[58:59], v[98:99]
	v_add_f32_e32 v106, v106, v116
	v_cvt_pk_bf16_f32 v108, v108, v109
	v_cvt_pk_bf16_f32 v109, v110, v111
	v_cvt_pk_bf16_f32 v110, v118, v119
	v_cvt_pk_bf16_f32 v111, v112, v113
	global_store_dwordx4 v[142:143], v[108:111], off offset:256 sc1
	s_cbranch_execz .LBB0_726

.LBB0_730:
	v_add_u32_e32 v116, 0x80, v200
	v_ashrrev_i32_e32 v117, 31, v116
	s_waitcnt lgkmcnt(0)
	v_lshlrev_b64 v[98:99], 11, v[116:117]
	v_lshl_add_u64 v[114:115], v[210:211], 0, v[98:99]
	v_add_u32_e32 v112, 0x90, v200
	global_load_dwordx4 v[118:121], v[114:115], off
	v_ashrrev_i32_e32 v113, 31, v112
	v_lshlrev_b64 v[98:99], 11, v[112:113]
	v_lshl_add_u64 v[110:111], v[210:211], 0, v[98:99]
	global_load_dwordx4 v[106:109], v[114:115], off offset:256
	global_load_dwordx4 v[102:105], v[110:111], off
	global_load_dwordx4 v[98:101], v[110:111], off offset:256
	s_and_b64 vcc, exec, s[6:7]
	s_mov_b64 s[20:21], -1
	s_waitcnt vmcnt(3)
	v_lshlrev_b32_e32 v122, 16, v118
	v_and_b32_e32 v123, 0xffff0000, v118
	v_lshlrev_b32_e32 v118, 16, v119
	v_and_b32_e32 v119, 0xffff0000, v119
	v_lshlrev_b32_e32 v124, 16, v120
	v_and_b32_e32 v125, 0xffff0000, v120
	v_lshlrev_b32_e32 v120, 16, v121
	v_and_b32_e32 v121, 0xffff0000, v121
	v_pk_mul_f32 v[122:123], v[90:91], v[122:123]
	v_pk_mul_f32 v[118:119], v[92:93], v[118:119]
	v_pk_mul_f32 v[124:125], v[94:95], v[124:125]
	v_pk_mul_f32 v[120:121], v[96:97], v[120:121]
	v_pk_fma_f32 v[80:81], v[80:81], v[206:207], v[118:119]
	v_pk_fma_f32 v[78:79], v[78:79], v[208:209], v[122:123]
	v_pk_fma_f32 v[76:77], v[76:77], v[202:203], v[120:121]
	v_pk_fma_f32 v[74:75], v[74:75], v[204:205], v[124:125]
	s_cbranch_vccnz .LBB0_732
	v_mov_b32_e32 v120, v79
	v_mov_b32_e32 v121, v75
	v_mov_b32_e32 v118, v78
	v_mov_b32_e32 v119, v74
	v_pk_mul_f32 v[120:121], v[120:121], v[120:121]
	v_mov_b32_e32 v122, v81
	v_mov_b32_e32 v123, v77
	v_pk_fma_f32 v[118:119], v[118:119], v[118:119], v[120:121]
	v_mov_b32_e32 v120, v80
	v_mov_b32_e32 v121, v76
	v_pk_mul_f32 v[122:123], v[122:123], v[122:123]
	v_pk_mul_f32 v[124:125], v[68:69], v[76:77]
	v_pk_fma_f32 v[120:121], v[120:121], v[120:121], v[122:123]
	v_pk_mul_f32 v[122:123], v[72:73], v[80:81]
	v_pk_add_f32 v[118:119], v[118:119], v[120:121]
	v_pk_mul_f32 v[120:121], v[70:71], v[78:79]
	v_pk_mul_f32 v[126:127], v[66:67], v[74:75]
	v_add_f32_e32 v118, v118, v119
	v_cvt_pk_bf16_f32 v120, v120, v121
	v_cvt_pk_bf16_f32 v121, v122, v123
	v_cvt_pk_bf16_f32 v122, v126, v127
	v_cvt_pk_bf16_f32 v123, v124, v125
	s_mov_b64 s[20:21], 0
	global_store_dwordx4 v[114:115], v[120:123], off sc1

.LBB0_734:
	s_waitcnt vmcnt(2)
	s_nop 0
	v_lshlrev_b32_e32 v74, 16, v106
	v_and_b32_e32 v75, 0xffff0000, v106
	v_lshlrev_b32_e32 v76, 16, v107
	v_and_b32_e32 v77, 0xffff0000, v107
	v_lshlrev_b32_e32 v78, 16, v108
	v_and_b32_e32 v79, 0xffff0000, v108
	v_lshlrev_b32_e32 v80, 16, v109
	v_and_b32_e32 v81, 0xffff0000, v109
	v_pk_mul_f32 v[74:75], v[82:83], v[74:75]
	v_pk_mul_f32 v[76:77], v[84:85], v[76:77]
	v_pk_mul_f32 v[78:79], v[86:87], v[78:79]
	v_pk_mul_f32 v[80:81], v[88:89], v[80:81]
	v_pk_fma_f32 v[56:57], v[56:57], v[158:159], v[76:77]
	v_pk_fma_f32 v[54:55], v[54:55], v[160:161], v[74:75]
	v_pk_fma_f32 v[52:53], v[52:53], v[154:155], v[80:81]
	v_pk_fma_f32 v[50:51], v[50:51], v[156:157], v[78:79]
	s_and_b64 vcc, exec, s[6:7]
	s_mov_b64 s[20:21], -1
	s_cbranch_vccnz .LBB0_737
	v_mov_b32_e32 v76, v55
	v_mov_b32_e32 v77, v51
	v_mov_b32_e32 v74, v54
	v_mov_b32_e32 v75, v50
	v_pk_mul_f32 v[76:77], v[76:77], v[76:77]
	v_mov_b32_e32 v78, v57
	v_mov_b32_e32 v79, v53
	v_pk_fma_f32 v[74:75], v[74:75], v[74:75], v[76:77]
	v_mov_b32_e32 v76, v56
	v_mov_b32_e32 v77, v52
	v_pk_mul_f32 v[78:79], v[78:79], v[78:79]
	v_pk_mul_f32 v[80:81], v[60:61], v[52:53]
	v_pk_fma_f32 v[76:77], v[76:77], v[76:77], v[78:79]
	v_pk_mul_f32 v[78:79], v[64:65], v[56:57]
	v_pk_add_f32 v[74:75], v[74:75], v[76:77]
	v_pk_mul_f32 v[76:77], v[62:63], v[54:55]
	v_add_f32_e32 v74, v74, v75
	v_pk_mul_f32 v[106:107], v[58:59], v[50:51]
	v_add_f32_e32 v74, v74, v118
	v_cvt_pk_bf16_f32 v76, v76, v77
	v_cvt_pk_bf16_f32 v77, v78, v79
	v_cvt_pk_bf16_f32 v78, v106, v107
	v_cvt_pk_bf16_f32 v79, v80, v81
	global_store_dwordx4 v[114:115], v[76:79], off offset:256 sc1
	s_cbranch_execz .LBB0_738

.LBB0_742:
	s_waitcnt vmcnt(1)
	v_lshlrev_b32_e32 v50, 16, v102
	s_waitcnt lgkmcnt(0)
	v_and_b32_e32 v51, 0xffff0000, v102
	v_lshlrev_b32_e32 v52, 16, v103
	v_and_b32_e32 v53, 0xffff0000, v103
	v_lshlrev_b32_e32 v54, 16, v104
	v_and_b32_e32 v55, 0xffff0000, v104
	v_lshlrev_b32_e32 v56, 16, v105
	v_and_b32_e32 v57, 0xffff0000, v105
	v_pk_mul_f32 v[50:51], v[90:91], v[50:51]
	v_pk_mul_f32 v[52:53], v[92:93], v[52:53]
	v_pk_mul_f32 v[54:55], v[94:95], v[54:55]
	v_pk_mul_f32 v[56:57], v[96:97], v[56:57]
	v_pk_fma_f32 v[48:49], v[48:49], v[206:207], v[52:53]
	v_pk_fma_f32 v[46:47], v[46:47], v[208:209], v[50:51]
	v_pk_fma_f32 v[44:45], v[44:45], v[202:203], v[56:57]
	v_pk_fma_f32 v[42:43], v[42:43], v[204:205], v[54:55]
	s_and_b64 vcc, exec, s[6:7]
	s_mov_b64 s[20:21], -1
	s_cbranch_vccnz .LBB0_744
	v_mov_b32_e32 v52, v47
	v_mov_b32_e32 v53, v43
	v_mov_b32_e32 v50, v46
	v_mov_b32_e32 v51, v42
	v_pk_mul_f32 v[52:53], v[52:53], v[52:53]
	v_mov_b32_e32 v54, v49
	v_mov_b32_e32 v55, v45
	v_pk_fma_f32 v[50:51], v[50:51], v[50:51], v[52:53]
	v_mov_b32_e32 v52, v48
	v_mov_b32_e32 v53, v44
	v_pk_mul_f32 v[54:55], v[54:55], v[54:55]
	v_pk_mul_f32 v[74:75], v[68:69], v[44:45]
	v_pk_fma_f32 v[52:53], v[52:53], v[52:53], v[54:55]
	v_pk_mul_f32 v[54:55], v[70:71], v[46:47]
	v_pk_add_f32 v[50:51], v[50:51], v[52:53]
	v_pk_mul_f32 v[56:57], v[66:67], v[42:43]
	v_add_f32_e32 v52, v50, v51
	v_pk_mul_f32 v[50:51], v[72:73], v[48:49]
	v_cvt_pk_bf16_f32 v54, v54, v55
	v_cvt_pk_bf16_f32 v55, v50, v51
	v_cvt_pk_bf16_f32 v56, v56, v57
	v_cvt_pk_bf16_f32 v57, v74, v75
	s_mov_b64 s[20:21], 0
	global_store_dwordx4 v[110:111], v[54:57], off sc1

.LBB0_746:
	s_waitcnt vmcnt(0)
	s_nop 0
	v_lshlrev_b32_e32 v42, 16, v98
	v_and_b32_e32 v43, 0xffff0000, v98
	v_lshlrev_b32_e32 v44, 16, v99
	v_and_b32_e32 v45, 0xffff0000, v99
	v_lshlrev_b32_e32 v46, 16, v100
	v_and_b32_e32 v47, 0xffff0000, v100
	v_lshlrev_b32_e32 v48, 16, v101
	v_and_b32_e32 v49, 0xffff0000, v101
	v_pk_mul_f32 v[42:43], v[82:83], v[42:43]
	v_pk_mul_f32 v[44:45], v[84:85], v[44:45]
	v_pk_mul_f32 v[46:47], v[86:87], v[46:47]
	v_pk_mul_f32 v[48:49], v[88:89], v[48:49]
	v_pk_fma_f32 v[40:41], v[40:41], v[158:159], v[44:45]
	v_pk_fma_f32 v[38:39], v[38:39], v[160:161], v[42:43]
	v_pk_fma_f32 v[36:37], v[36:37], v[154:155], v[48:49]
	v_pk_fma_f32 v[34:35], v[34:35], v[156:157], v[46:47]
	s_and_b64 vcc, exec, s[6:7]
	s_mov_b64 s[20:21], -1
	s_cbranch_vccnz .LBB0_749
	v_mov_b32_e32 v44, v39
	v_mov_b32_e32 v45, v35
	v_mov_b32_e32 v42, v38
	v_mov_b32_e32 v43, v34
	v_pk_mul_f32 v[44:45], v[44:45], v[44:45]
	v_mov_b32_e32 v46, v41
	v_mov_b32_e32 v47, v37
	v_pk_fma_f32 v[42:43], v[42:43], v[42:43], v[44:45]
	v_mov_b32_e32 v44, v40
	v_mov_b32_e32 v45, v36
	v_pk_mul_f32 v[46:47], v[46:47], v[46:47]
	v_pk_mul_f32 v[48:49], v[60:61], v[36:37]
	v_pk_fma_f32 v[44:45], v[44:45], v[44:45], v[46:47]
	v_pk_mul_f32 v[46:47], v[64:65], v[40:41]
	v_pk_add_f32 v[42:43], v[42:43], v[44:45]
	v_pk_mul_f32 v[44:45], v[62:63], v[38:39]
	v_add_f32_e32 v42, v42, v43
	v_pk_mul_f32 v[54:55], v[58:59], v[34:35]
	v_add_f32_e32 v42, v42, v52
	v_cvt_pk_bf16_f32 v44, v44, v45
	v_cvt_pk_bf16_f32 v45, v46, v47
	v_cvt_pk_bf16_f32 v46, v54, v55
	v_cvt_pk_bf16_f32 v47, v48, v49
	global_store_dwordx4 v[110:111], v[44:47], off offset:256 sc1
	s_cbranch_execz .LBB0_750

.LBB0_754:
	v_add_u32_e32 v52, 0xa0, v200
	v_ashrrev_i32_e32 v53, 31, v52
	s_waitcnt lgkmcnt(0)
	v_lshlrev_b64 v[34:35], 11, v[52:53]
	v_lshl_add_u64 v[50:51], v[210:211], 0, v[34:35]
	v_add_u32_e32 v48, 0xb0, v200
	global_load_dwordx4 v[54:57], v[50:51], off
	v_ashrrev_i32_e32 v49, 31, v48
	v_lshlrev_b64 v[34:35], 11, v[48:49]
	v_lshl_add_u64 v[46:47], v[210:211], 0, v[34:35]
	global_load_dwordx4 v[42:45], v[50:51], off offset:256
	global_load_dwordx4 v[38:41], v[46:47], off
	global_load_dwordx4 v[34:37], v[46:47], off offset:256
	s_and_b64 vcc, exec, s[6:7]
	s_mov_b64 s[20:21], -1
	s_waitcnt vmcnt(3)
	v_lshlrev_b32_e32 v74, 16, v54
	v_and_b32_e32 v75, 0xffff0000, v54
	v_lshlrev_b32_e32 v54, 16, v55
	v_and_b32_e32 v55, 0xffff0000, v55
	v_lshlrev_b32_e32 v76, 16, v56
	v_and_b32_e32 v77, 0xffff0000, v56
	v_lshlrev_b32_e32 v56, 16, v57
	v_and_b32_e32 v57, 0xffff0000, v57
	v_pk_mul_f32 v[74:75], v[90:91], v[74:75]
	v_pk_mul_f32 v[54:55], v[92:93], v[54:55]
	v_pk_mul_f32 v[76:77], v[94:95], v[76:77]
	v_pk_mul_f32 v[56:57], v[96:97], v[56:57]
	v_pk_fma_f32 v[32:33], v[32:33], v[206:207], v[54:55]
	v_pk_fma_f32 v[30:31], v[30:31], v[208:209], v[74:75]
	v_pk_fma_f32 v[28:29], v[28:29], v[202:203], v[56:57]
	v_pk_fma_f32 v[26:27], v[26:27], v[204:205], v[76:77]
	s_cbranch_vccnz .LBB0_756
	v_mov_b32_e32 v56, v31
	v_mov_b32_e32 v57, v27
	v_mov_b32_e32 v54, v30
	v_mov_b32_e32 v55, v26
	v_pk_mul_f32 v[56:57], v[56:57], v[56:57]
	v_mov_b32_e32 v74, v33
	v_mov_b32_e32 v75, v29
	v_pk_fma_f32 v[54:55], v[54:55], v[54:55], v[56:57]
	v_mov_b32_e32 v56, v32
	v_mov_b32_e32 v57, v28
	v_pk_mul_f32 v[74:75], v[74:75], v[74:75]
	v_pk_mul_f32 v[78:79], v[68:69], v[28:29]
	v_pk_fma_f32 v[56:57], v[56:57], v[56:57], v[74:75]
	v_pk_mul_f32 v[74:75], v[70:71], v[30:31]
	v_pk_add_f32 v[54:55], v[54:55], v[56:57]
	v_pk_mul_f32 v[56:57], v[72:73], v[32:33]
	v_pk_mul_f32 v[76:77], v[66:67], v[26:27]
	v_add_f32_e32 v54, v54, v55
	v_cvt_pk_bf16_f32 v74, v74, v75
	v_cvt_pk_bf16_f32 v75, v56, v57
	v_cvt_pk_bf16_f32 v76, v76, v77
	v_cvt_pk_bf16_f32 v77, v78, v79
	s_mov_b64 s[20:21], 0
	global_store_dwordx4 v[50:51], v[74:77], off sc1

.LBB0_758:
	s_waitcnt vmcnt(2)
	s_nop 0
	v_lshlrev_b32_e32 v26, 16, v42
	v_and_b32_e32 v27, 0xffff0000, v42
	v_lshlrev_b32_e32 v28, 16, v43
	v_and_b32_e32 v29, 0xffff0000, v43
	v_lshlrev_b32_e32 v30, 16, v44
	v_and_b32_e32 v31, 0xffff0000, v44
	v_lshlrev_b32_e32 v32, 16, v45
	v_and_b32_e32 v33, 0xffff0000, v45
	v_pk_mul_f32 v[26:27], v[82:83], v[26:27]
	v_pk_mul_f32 v[28:29], v[84:85], v[28:29]
	v_pk_mul_f32 v[30:31], v[86:87], v[30:31]
	v_pk_mul_f32 v[32:33], v[88:89], v[32:33]
	v_pk_fma_f32 v[24:25], v[24:25], v[158:159], v[28:29]
	v_pk_fma_f32 v[22:23], v[22:23], v[160:161], v[26:27]
	v_pk_fma_f32 v[20:21], v[20:21], v[154:155], v[32:33]
	v_pk_fma_f32 v[18:19], v[18:19], v[156:157], v[30:31]
	s_and_b64 vcc, exec, s[6:7]
	s_mov_b64 s[20:21], -1
	s_cbranch_vccnz .LBB0_761
	v_mov_b32_e32 v28, v23
	v_mov_b32_e32 v29, v19
	v_mov_b32_e32 v26, v22
	v_mov_b32_e32 v27, v18
	v_pk_mul_f32 v[28:29], v[28:29], v[28:29]
	v_mov_b32_e32 v30, v25
	v_mov_b32_e32 v31, v21
	v_pk_fma_f32 v[26:27], v[26:27], v[26:27], v[28:29]
	v_mov_b32_e32 v28, v24
	v_mov_b32_e32 v29, v20
	v_pk_mul_f32 v[30:31], v[30:31], v[30:31]
	v_pk_mul_f32 v[32:33], v[60:61], v[20:21]
	v_pk_fma_f32 v[28:29], v[28:29], v[28:29], v[30:31]
	v_pk_mul_f32 v[30:31], v[64:65], v[24:25]
	v_pk_add_f32 v[26:27], v[26:27], v[28:29]
	v_pk_mul_f32 v[28:29], v[62:63], v[22:23]
	v_add_f32_e32 v26, v26, v27
	v_pk_mul_f32 v[42:43], v[58:59], v[18:19]
	v_add_f32_e32 v26, v26, v54
	v_cvt_pk_bf16_f32 v28, v28, v29
	v_cvt_pk_bf16_f32 v29, v30, v31
	v_cvt_pk_bf16_f32 v30, v42, v43
	v_cvt_pk_bf16_f32 v31, v32, v33
	global_store_dwordx4 v[50:51], v[28:31], off offset:256 sc1
	s_cbranch_execz .LBB0_762

.LBB0_766:
	s_waitcnt vmcnt(1)
	v_lshlrev_b32_e32 v18, 16, v38
	s_waitcnt lgkmcnt(0)
	v_and_b32_e32 v19, 0xffff0000, v38
	v_lshlrev_b32_e32 v20, 16, v39
	v_and_b32_e32 v21, 0xffff0000, v39
	v_lshlrev_b32_e32 v22, 16, v40
	v_and_b32_e32 v23, 0xffff0000, v40
	v_lshlrev_b32_e32 v24, 16, v41
	v_and_b32_e32 v25, 0xffff0000, v41
	v_pk_mul_f32 v[18:19], v[90:91], v[18:19]
	v_pk_mul_f32 v[20:21], v[92:93], v[20:21]
	v_pk_mul_f32 v[22:23], v[94:95], v[22:23]
	v_pk_mul_f32 v[24:25], v[96:97], v[24:25]
	v_pk_fma_f32 v[16:17], v[16:17], v[206:207], v[20:21]
	v_pk_fma_f32 v[14:15], v[14:15], v[208:209], v[18:19]
	v_pk_fma_f32 v[12:13], v[12:13], v[202:203], v[24:25]
	v_pk_fma_f32 v[10:11], v[10:11], v[204:205], v[22:23]
	s_and_b64 vcc, exec, s[6:7]
	s_mov_b64 s[20:21], -1
	s_cbranch_vccnz .LBB0_768
	v_mov_b32_e32 v20, v15
	v_mov_b32_e32 v21, v11
	v_mov_b32_e32 v18, v14
	v_mov_b32_e32 v19, v10
	v_pk_mul_f32 v[20:21], v[20:21], v[20:21]
	v_mov_b32_e32 v22, v17
	v_mov_b32_e32 v23, v13
	v_pk_fma_f32 v[18:19], v[18:19], v[18:19], v[20:21]
	v_mov_b32_e32 v20, v16
	v_mov_b32_e32 v21, v12
	v_pk_mul_f32 v[22:23], v[22:23], v[22:23]
	v_pk_mul_f32 v[26:27], v[68:69], v[12:13]
	v_pk_fma_f32 v[20:21], v[20:21], v[20:21], v[22:23]
	v_pk_mul_f32 v[22:23], v[70:71], v[14:15]
	v_pk_add_f32 v[18:19], v[18:19], v[20:21]
	v_pk_mul_f32 v[24:25], v[66:67], v[10:11]
	v_add_f32_e32 v20, v18, v19
	v_pk_mul_f32 v[18:19], v[72:73], v[16:17]
	v_cvt_pk_bf16_f32 v22, v22, v23
	v_cvt_pk_bf16_f32 v23, v18, v19
	v_cvt_pk_bf16_f32 v24, v24, v25
	v_cvt_pk_bf16_f32 v25, v26, v27
	s_mov_b64 s[20:21], 0
	global_store_dwordx4 v[46:47], v[22:25], off sc1

.LBB0_770:
	s_waitcnt vmcnt(0)
	s_nop 0
	v_lshlrev_b32_e32 v10, 16, v34
	v_and_b32_e32 v11, 0xffff0000, v34
	v_lshlrev_b32_e32 v12, 16, v35
	v_and_b32_e32 v13, 0xffff0000, v35
	v_lshlrev_b32_e32 v14, 16, v36
	v_and_b32_e32 v15, 0xffff0000, v36
	v_lshlrev_b32_e32 v16, 16, v37
	v_and_b32_e32 v17, 0xffff0000, v37
	v_pk_mul_f32 v[10:11], v[82:83], v[10:11]
	v_pk_mul_f32 v[12:13], v[84:85], v[12:13]
	v_pk_mul_f32 v[14:15], v[86:87], v[14:15]
	v_pk_mul_f32 v[16:17], v[88:89], v[16:17]
	v_pk_fma_f32 v[8:9], v[8:9], v[158:159], v[12:13]
	v_pk_fma_f32 v[6:7], v[6:7], v[160:161], v[10:11]
	v_pk_fma_f32 v[4:5], v[4:5], v[154:155], v[16:17]
	v_pk_fma_f32 v[2:3], v[2:3], v[156:157], v[14:15]
	s_and_b64 vcc, exec, s[6:7]
	s_mov_b64 s[20:21], -1
	s_cbranch_vccnz .LBB0_776
	v_mov_b32_e32 v12, v7
	v_mov_b32_e32 v13, v3
	v_mov_b32_e32 v10, v6
	v_mov_b32_e32 v11, v2
	v_pk_mul_f32 v[12:13], v[12:13], v[12:13]
	v_mov_b32_e32 v14, v9
	v_mov_b32_e32 v15, v5
	v_pk_fma_f32 v[10:11], v[10:11], v[10:11], v[12:13]
	v_mov_b32_e32 v12, v8
	v_mov_b32_e32 v13, v4
	v_pk_mul_f32 v[14:15], v[14:15], v[14:15]
	v_pk_mul_f32 v[16:17], v[60:61], v[4:5]
	v_pk_fma_f32 v[12:13], v[12:13], v[12:13], v[14:15]
	v_pk_mul_f32 v[14:15], v[64:65], v[8:9]
	v_pk_add_f32 v[10:11], v[10:11], v[12:13]
	v_pk_mul_f32 v[12:13], v[62:63], v[6:7]
	v_add_f32_e32 v10, v10, v11
	v_pk_mul_f32 v[22:23], v[58:59], v[2:3]
	v_add_f32_e32 v10, v10, v20
	v_cvt_pk_bf16_f32 v12, v12, v13
	v_cvt_pk_bf16_f32 v13, v14, v15
	v_cvt_pk_bf16_f32 v14, v22, v23
	v_cvt_pk_bf16_f32 v15, v16, v17
	global_store_dwordx4 v[46:47], v[12:15], off offset:256 sc1
	s_cbranch_execz .LBB0_777

.LBB0_798:
	s_cmp_eq_u32 s3, 1
	s_cselect_b64 s[12:13], -1, 0
	v_readlane_b32 s0, v254, 30
	v_cndmask_b32_e64 v138, 0.5, 1.0, s[12:13]
	s_waitcnt vmcnt(0)
	v_pk_mul_f32 v[124:125], v[138:139], v[98:99] op_sel_hi:[0,1]
	v_add_u32_e32 v120, s0, v114
	v_lshl_add_u64 v[98:99], v[118:119], 1, s[4:5]
	v_ashrrev_i32_e32 v121, 31, v120
	v_lshl_add_u64 v[130:131], v[98:99], 0, s[62:63]
	v_lshlrev_b64 v[98:99], 11, v[120:121]
	v_lshl_add_u64 v[136:137], v[130:131], 0, v[98:99]
	v_pk_mul_f32 v[122:123], v[138:139], v[100:101] op_sel_hi:[0,1]
	global_load_dwordx4 v[98:101], v[136:137], off
	global_load_dwordx4 v[114:117], v[136:137], off offset:256
	v_or_b32_e32 v134, 16, v120
	v_ashrrev_i32_e32 v135, 31, v134
	v_pk_mul_f32 v[126:127], v[138:139], v[64:65] op_sel_hi:[0,1]
	v_pk_mul_f32 v[128:129], v[138:139], v[62:63] op_sel_hi:[0,1]
	global_load_dwordx4 v[62:65], v[112:113], off offset:528
	s_mov_b64 s[12:13], -1
	s_and_b64 vcc, exec, s[10:11]
	s_waitcnt vmcnt(2)
	v_lshlrev_b32_e32 v110, 16, v98
	v_and_b32_e32 v111, 0xffff0000, v98
	v_lshlrev_b32_e32 v98, 16, v99
	v_and_b32_e32 v99, 0xffff0000, v99
	v_pk_mul_f32 v[142:143], v[68:69], v[98:99]
	v_lshlrev_b64 v[98:99], 11, v[134:135]
	v_lshlrev_b32_e32 v112, 16, v100
	v_and_b32_e32 v113, 0xffff0000, v100
	v_lshlrev_b32_e32 v100, 16, v101
	v_and_b32_e32 v101, 0xffff0000, v101
	v_lshl_add_u64 v[132:133], v[130:131], 0, v[98:99]
	v_pk_mul_f32 v[140:141], v[66:67], v[110:111]
	v_pk_mul_f32 v[144:145], v[74:75], v[112:113]
	v_pk_mul_f32 v[146:147], v[76:77], v[100:101]
	global_load_dwordx4 v[110:113], v[132:133], off
	global_load_dwordx4 v[98:101], v[132:133], off offset:256
	v_pk_fma_f32 v[96:97], v[96:97], v[126:127], v[142:143]
	v_pk_fma_f32 v[94:95], v[94:95], v[128:129], v[140:141]
	v_pk_fma_f32 v[92:93], v[92:93], v[122:123], v[146:147]
	v_pk_fma_f32 v[90:91], v[90:91], v[124:125], v[144:145]
	s_cbranch_vccz .LBB0_800
	v_mov_b32_e32 v142, v95
	v_mov_b32_e32 v143, v91
	v_mov_b32_e32 v140, v94
	v_mov_b32_e32 v141, v90
	v_pk_mul_f32 v[142:143], v[142:143], v[142:143]
	v_mov_b32_e32 v144, v97
	v_mov_b32_e32 v145, v93
	v_pk_fma_f32 v[140:141], v[140:141], v[140:141], v[142:143]
	v_mov_b32_e32 v142, v96
	v_mov_b32_e32 v143, v92
	v_pk_mul_f32 v[144:145], v[144:145], v[144:145]
	v_pk_mul_f32 v[148:149], v[52:53], v[92:93]
	v_pk_fma_f32 v[142:143], v[142:143], v[142:143], v[144:145]
	v_pk_mul_f32 v[144:145], v[54:55], v[94:95]
	v_pk_add_f32 v[140:141], v[140:141], v[142:143]
	v_pk_mul_f32 v[146:147], v[50:51], v[90:91]
	v_add_f32_e32 v142, v140, v141
	v_pk_mul_f32 v[140:141], v[56:57], v[96:97]
	v_cvt_pk_bf16_f32 v144, v144, v145
	v_cvt_pk_bf16_f32 v145, v140, v141
	v_cvt_pk_bf16_f32 v146, v146, v147
	v_cvt_pk_bf16_f32 v147, v148, v149
	global_store_dwordx4 v[136:137], v[144:147], off sc1
	s_mov_b64 s[12:13], 0

.LBB0_802:
	s_waitcnt vmcnt(3)
	v_lshlrev_b32_e32 v94, 16, v116
	v_and_b32_e32 v95, 0xffff0000, v116
	v_mov_b32_e32 v139, v138
	v_lshlrev_b32_e32 v90, 16, v114
	v_and_b32_e32 v91, 0xffff0000, v114
	v_lshlrev_b32_e32 v92, 16, v115
	v_and_b32_e32 v93, 0xffff0000, v115
	v_lshlrev_b32_e32 v96, 16, v117
	v_and_b32_e32 v97, 0xffff0000, v117
	s_waitcnt vmcnt(2)
	v_pk_mul_f32 v[144:145], v[62:63], v[94:95]
	v_mov_b32_e32 v94, v138
	v_mov_b32_e32 v95, v138
	v_pk_mul_f32 v[114:115], v[58:59], v[90:91]
	v_pk_mul_f32 v[116:117], v[60:61], v[92:93]
	v_pk_mul_f32 v[146:147], v[64:65], v[96:97]
	v_pk_mul_f32 v[90:91], v[94:95], v[108:109]
	v_pk_mul_f32 v[92:93], v[138:139], v[106:107]
	v_pk_mul_f32 v[94:95], v[94:95], v[104:105]
	v_pk_mul_f32 v[96:97], v[138:139], v[102:103]
	v_pk_fma_f32 v[88:89], v[88:89], v[94:95], v[116:117]
	v_pk_fma_f32 v[86:87], v[86:87], v[96:97], v[114:115]
	v_pk_fma_f32 v[84:85], v[84:85], v[90:91], v[146:147]
	v_pk_fma_f32 v[82:83], v[82:83], v[92:93], v[144:145]
	s_and_b64 vcc, exec, s[6:7]
	s_mov_b64 s[10:11], -1
	s_cbranch_vccnz .LBB0_804
	v_mov_b32_e32 v104, v87
	v_mov_b32_e32 v105, v83
	v_mov_b32_e32 v102, v86
	v_mov_b32_e32 v103, v82
	v_pk_mul_f32 v[104:105], v[104:105], v[104:105]
	v_mov_b32_e32 v106, v89
	v_mov_b32_e32 v107, v85
	v_pk_fma_f32 v[102:103], v[102:103], v[102:103], v[104:105]
	v_mov_b32_e32 v104, v88
	v_mov_b32_e32 v105, v84
	v_pk_mul_f32 v[106:107], v[106:107], v[106:107]
	v_pk_mul_f32 v[108:109], v[36:37], v[84:85]
	v_pk_fma_f32 v[104:105], v[104:105], v[104:105], v[106:107]
	v_pk_mul_f32 v[106:107], v[40:41], v[88:89]
	v_pk_add_f32 v[102:103], v[102:103], v[104:105]
	v_pk_mul_f32 v[104:105], v[38:39], v[86:87]
	v_add_f32_e32 v102, v102, v103
	v_pk_mul_f32 v[114:115], v[34:35], v[82:83]
	v_add_f32_e32 v102, v102, v142
	v_cvt_pk_bf16_f32 v104, v104, v105
	v_cvt_pk_bf16_f32 v105, v106, v107
	v_cvt_pk_bf16_f32 v106, v114, v115
	v_cvt_pk_bf16_f32 v107, v108, v109
	s_mov_b64 s[10:11], 0
	global_store_dwordx4 v[136:137], v[104:107], off offset:256 sc1

.LBB0_810:
	s_waitcnt vmcnt(1) lgkmcnt(0)
	v_lshlrev_b32_e32 v82, 16, v110
	v_and_b32_e32 v83, 0xffff0000, v110
	v_lshlrev_b32_e32 v84, 16, v111
	v_and_b32_e32 v85, 0xffff0000, v111
	v_lshlrev_b32_e32 v86, 16, v112
	v_and_b32_e32 v87, 0xffff0000, v112
	v_lshlrev_b32_e32 v88, 16, v113
	v_and_b32_e32 v89, 0xffff0000, v113
	v_pk_mul_f32 v[82:83], v[66:67], v[82:83]
	v_pk_mul_f32 v[84:85], v[68:69], v[84:85]
	v_pk_mul_f32 v[86:87], v[74:75], v[86:87]
	v_pk_mul_f32 v[88:89], v[76:77], v[88:89]
	v_pk_fma_f32 v[80:81], v[80:81], v[126:127], v[84:85]
	v_pk_fma_f32 v[78:79], v[78:79], v[128:129], v[82:83]
	v_pk_fma_f32 v[72:73], v[72:73], v[122:123], v[88:89]
	v_pk_fma_f32 v[70:71], v[70:71], v[124:125], v[86:87]
	s_and_b64 vcc, exec, s[6:7]
	s_mov_b64 s[12:13], -1
	s_cbranch_vccnz .LBB0_812
	v_mov_b32_e32 v84, v79
	v_mov_b32_e32 v85, v71
	v_mov_b32_e32 v82, v78
	v_mov_b32_e32 v83, v70
	v_pk_mul_f32 v[84:85], v[84:85], v[84:85]
	v_mov_b32_e32 v86, v81
	v_mov_b32_e32 v87, v73
	v_pk_fma_f32 v[82:83], v[82:83], v[82:83], v[84:85]
	v_mov_b32_e32 v84, v80
	v_mov_b32_e32 v85, v72
	v_pk_mul_f32 v[86:87], v[86:87], v[86:87]
	v_pk_mul_f32 v[88:89], v[50:51], v[70:71]
	v_pk_fma_f32 v[84:85], v[84:85], v[84:85], v[86:87]
	v_pk_mul_f32 v[86:87], v[52:53], v[72:73]
	v_pk_add_f32 v[82:83], v[82:83], v[84:85]
	v_pk_mul_f32 v[84:85], v[56:57], v[80:81]
	v_add_f32_e32 v1, v82, v83
	v_pk_mul_f32 v[82:83], v[54:55], v[78:79]
	s_mov_b64 s[12:13], 0
	v_cvt_pk_bf16_f32 v82, v82, v83
	v_cvt_pk_bf16_f32 v83, v84, v85
	v_cvt_pk_bf16_f32 v84, v88, v89
	v_cvt_pk_bf16_f32 v85, v86, v87
	global_store_dwordx4 v[132:133], v[82:85], off sc1

.LBB0_814:
	s_waitcnt vmcnt(0)
	s_nop 0
	v_lshlrev_b32_e32 v70, 16, v98
	v_and_b32_e32 v71, 0xffff0000, v98
	v_lshlrev_b32_e32 v72, 16, v99
	v_and_b32_e32 v73, 0xffff0000, v99
	v_lshlrev_b32_e32 v78, 16, v100
	v_and_b32_e32 v79, 0xffff0000, v100
	v_lshlrev_b32_e32 v80, 16, v101
	v_and_b32_e32 v81, 0xffff0000, v101
	v_pk_mul_f32 v[70:71], v[58:59], v[70:71]
	v_pk_mul_f32 v[72:73], v[60:61], v[72:73]
	v_pk_mul_f32 v[78:79], v[62:63], v[78:79]
	v_pk_mul_f32 v[80:81], v[64:65], v[80:81]
	v_pk_fma_f32 v[48:49], v[48:49], v[94:95], v[72:73]
	v_pk_fma_f32 v[46:47], v[46:47], v[96:97], v[70:71]
	v_pk_fma_f32 v[44:45], v[44:45], v[90:91], v[80:81]
	v_pk_fma_f32 v[42:43], v[42:43], v[92:93], v[78:79]
	s_and_b64 vcc, exec, s[6:7]
	s_mov_b64 s[12:13], -1
	s_cbranch_vccnz .LBB0_817
	v_mov_b32_e32 v72, v47
	v_mov_b32_e32 v73, v43
	v_mov_b32_e32 v70, v46
	v_mov_b32_e32 v71, v42
	v_pk_mul_f32 v[72:73], v[72:73], v[72:73]
	v_mov_b32_e32 v78, v49
	v_mov_b32_e32 v79, v45
	v_pk_fma_f32 v[70:71], v[70:71], v[70:71], v[72:73]
	v_mov_b32_e32 v72, v48
	v_mov_b32_e32 v73, v44
	v_pk_mul_f32 v[78:79], v[78:79], v[78:79]
	v_pk_mul_f32 v[84:85], v[36:37], v[44:45]
	v_pk_fma_f32 v[72:73], v[72:73], v[72:73], v[78:79]
	v_pk_mul_f32 v[78:79], v[38:39], v[46:47]
	v_pk_add_f32 v[70:71], v[70:71], v[72:73]
	v_pk_mul_f32 v[72:73], v[40:41], v[48:49]
	v_add_f32_e32 v70, v70, v71
	v_pk_mul_f32 v[80:81], v[34:35], v[42:43]
	v_add_f32_e32 v70, v70, v1
	v_cvt_pk_bf16_f32 v78, v78, v79
	v_cvt_pk_bf16_f32 v79, v72, v73
	v_cvt_pk_bf16_f32 v80, v80, v81
	v_cvt_pk_bf16_f32 v81, v84, v85
	global_store_dwordx4 v[132:133], v[78:81], off offset:256 sc1
	s_cbranch_execz .LBB0_818

.LBB0_822:
	v_or_b32_e32 v84, 32, v120
	v_ashrrev_i32_e32 v85, 31, v84
	s_waitcnt lgkmcnt(0)
	v_lshlrev_b64 v[42:43], 11, v[84:85]
	v_lshl_add_u64 v[82:83], v[130:131], 0, v[42:43]
	v_or_b32_e32 v80, 48, v120
	global_load_dwordx4 v[86:89], v[82:83], off
	v_ashrrev_i32_e32 v81, 31, v80
	v_lshlrev_b64 v[42:43], 11, v[80:81]
	v_lshl_add_u64 v[78:79], v[130:131], 0, v[42:43]
	global_load_dwordx4 v[70:73], v[82:83], off offset:256
	global_load_dwordx4 v[46:49], v[78:79], off
	global_load_dwordx4 v[42:45], v[78:79], off offset:256
	s_and_b64 vcc, exec, s[6:7]
	s_mov_b64 s[12:13], -1
	s_waitcnt vmcnt(3)
	v_lshlrev_b32_e32 v98, 16, v86
	v_and_b32_e32 v99, 0xffff0000, v86
	v_lshlrev_b32_e32 v86, 16, v87
	v_and_b32_e32 v87, 0xffff0000, v87
	v_lshlrev_b32_e32 v100, 16, v88
	v_and_b32_e32 v101, 0xffff0000, v88
	v_lshlrev_b32_e32 v88, 16, v89
	v_and_b32_e32 v89, 0xffff0000, v89
	v_pk_mul_f32 v[98:99], v[66:67], v[98:99]
	v_pk_mul_f32 v[86:87], v[68:69], v[86:87]
	v_pk_mul_f32 v[100:101], v[74:75], v[100:101]
	v_pk_mul_f32 v[88:89], v[76:77], v[88:89]
	v_pk_fma_f32 v[32:33], v[32:33], v[126:127], v[86:87]
	v_pk_fma_f32 v[30:31], v[30:31], v[128:129], v[98:99]
	v_pk_fma_f32 v[28:29], v[28:29], v[122:123], v[88:89]
	v_pk_fma_f32 v[26:27], v[26:27], v[124:125], v[100:101]
	s_cbranch_vccnz .LBB0_824
	v_mov_b32_e32 v88, v31
	v_mov_b32_e32 v89, v27
	v_mov_b32_e32 v86, v30
	v_mov_b32_e32 v87, v26
	v_pk_mul_f32 v[88:89], v[88:89], v[88:89]
	v_mov_b32_e32 v98, v33
	v_mov_b32_e32 v99, v29
	v_pk_fma_f32 v[86:87], v[86:87], v[86:87], v[88:89]
	v_mov_b32_e32 v88, v32
	v_mov_b32_e32 v89, v28
	v_pk_mul_f32 v[98:99], v[98:99], v[98:99]
	v_pk_mul_f32 v[100:101], v[50:51], v[26:27]
	v_pk_fma_f32 v[88:89], v[88:89], v[88:89], v[98:99]
	v_pk_mul_f32 v[98:99], v[52:53], v[28:29]
	v_pk_add_f32 v[86:87], v[86:87], v[88:89]
	v_pk_mul_f32 v[88:89], v[56:57], v[32:33]
	v_add_f32_e32 v1, v86, v87
	v_pk_mul_f32 v[86:87], v[54:55], v[30:31]
	s_mov_b64 s[12:13], 0
	v_cvt_pk_bf16_f32 v86, v86, v87
	v_cvt_pk_bf16_f32 v87, v88, v89
	v_cvt_pk_bf16_f32 v88, v100, v101
	v_cvt_pk_bf16_f32 v89, v98, v99
	global_store_dwordx4 v[82:83], v[86:89], off sc1

.LBB0_826:
	s_waitcnt vmcnt(2)
	s_nop 0
	v_lshlrev_b32_e32 v26, 16, v70
	v_and_b32_e32 v27, 0xffff0000, v70
	v_lshlrev_b32_e32 v28, 16, v71
	v_and_b32_e32 v29, 0xffff0000, v71
	v_lshlrev_b32_e32 v30, 16, v72
	v_and_b32_e32 v31, 0xffff0000, v72
	v_lshlrev_b32_e32 v32, 16, v73
	v_and_b32_e32 v33, 0xffff0000, v73
	v_pk_mul_f32 v[26:27], v[58:59], v[26:27]
	v_pk_mul_f32 v[28:29], v[60:61], v[28:29]
	v_pk_mul_f32 v[30:31], v[62:63], v[30:31]
	v_pk_mul_f32 v[32:33], v[64:65], v[32:33]
	v_pk_fma_f32 v[24:25], v[24:25], v[94:95], v[28:29]
	v_pk_fma_f32 v[22:23], v[22:23], v[96:97], v[26:27]
	v_pk_fma_f32 v[20:21], v[20:21], v[90:91], v[32:33]
	v_pk_fma_f32 v[18:19], v[18:19], v[92:93], v[30:31]
	s_and_b64 vcc, exec, s[6:7]
	s_mov_b64 s[12:13], -1
	s_cbranch_vccnz .LBB0_829
	v_mov_b32_e32 v28, v23
	v_mov_b32_e32 v29, v19
	v_mov_b32_e32 v26, v22
	v_mov_b32_e32 v27, v18
	v_pk_mul_f32 v[28:29], v[28:29], v[28:29]
	v_mov_b32_e32 v30, v25
	v_mov_b32_e32 v31, v21
	v_pk_fma_f32 v[26:27], v[26:27], v[26:27], v[28:29]
	v_mov_b32_e32 v28, v24
	v_mov_b32_e32 v29, v20
	v_pk_mul_f32 v[30:31], v[30:31], v[30:31]
	v_pk_mul_f32 v[32:33], v[36:37], v[20:21]
	v_pk_fma_f32 v[28:29], v[28:29], v[28:29], v[30:31]
	v_pk_mul_f32 v[30:31], v[40:41], v[24:25]
	v_pk_add_f32 v[26:27], v[26:27], v[28:29]
	v_pk_mul_f32 v[28:29], v[38:39], v[22:23]
	v_add_f32_e32 v26, v26, v27
	v_pk_mul_f32 v[70:71], v[34:35], v[18:19]
	v_add_f32_e32 v26, v26, v1
	v_cvt_pk_bf16_f32 v28, v28, v29
	v_cvt_pk_bf16_f32 v29, v30, v31
	v_cvt_pk_bf16_f32 v30, v70, v71
	v_cvt_pk_bf16_f32 v31, v32, v33
	global_store_dwordx4 v[82:83], v[28:31], off offset:256 sc1
	s_cbranch_execz .LBB0_830

.LBB0_834:
	s_waitcnt vmcnt(1) lgkmcnt(0)
	v_lshlrev_b32_e32 v18, 16, v46
	v_and_b32_e32 v19, 0xffff0000, v46
	v_lshlrev_b32_e32 v20, 16, v47
	v_and_b32_e32 v21, 0xffff0000, v47
	v_lshlrev_b32_e32 v22, 16, v48
	v_and_b32_e32 v23, 0xffff0000, v48
	v_lshlrev_b32_e32 v24, 16, v49
	v_and_b32_e32 v25, 0xffff0000, v49
	v_pk_mul_f32 v[18:19], v[66:67], v[18:19]
	v_pk_mul_f32 v[20:21], v[68:69], v[20:21]
	v_pk_mul_f32 v[22:23], v[74:75], v[22:23]
	v_pk_mul_f32 v[24:25], v[76:77], v[24:25]
	v_pk_fma_f32 v[16:17], v[16:17], v[126:127], v[20:21]
	v_pk_fma_f32 v[14:15], v[14:15], v[128:129], v[18:19]
	v_pk_fma_f32 v[12:13], v[12:13], v[122:123], v[24:25]
	v_pk_fma_f32 v[10:11], v[10:11], v[124:125], v[22:23]
	s_and_b64 vcc, exec, s[6:7]
	s_mov_b64 s[12:13], -1
	s_cbranch_vccnz .LBB0_836
	v_mov_b32_e32 v20, v15
	v_mov_b32_e32 v21, v11
	v_mov_b32_e32 v18, v14
	v_mov_b32_e32 v19, v10
	v_pk_mul_f32 v[20:21], v[20:21], v[20:21]
	v_mov_b32_e32 v22, v17
	v_mov_b32_e32 v23, v13
	v_pk_fma_f32 v[18:19], v[18:19], v[18:19], v[20:21]
	v_mov_b32_e32 v20, v16
	v_mov_b32_e32 v21, v12
	v_pk_mul_f32 v[22:23], v[22:23], v[22:23]
	v_pk_mul_f32 v[24:25], v[50:51], v[10:11]
	v_pk_fma_f32 v[20:21], v[20:21], v[20:21], v[22:23]
	v_pk_mul_f32 v[22:23], v[52:53], v[12:13]
	v_pk_add_f32 v[18:19], v[18:19], v[20:21]
	v_pk_mul_f32 v[20:21], v[56:57], v[16:17]
	v_add_f32_e32 v1, v18, v19
	v_pk_mul_f32 v[18:19], v[54:55], v[14:15]
	s_mov_b64 s[12:13], 0
	v_cvt_pk_bf16_f32 v18, v18, v19
	v_cvt_pk_bf16_f32 v19, v20, v21
	v_cvt_pk_bf16_f32 v20, v24, v25
	v_cvt_pk_bf16_f32 v21, v22, v23
	global_store_dwordx4 v[78:79], v[18:21], off sc1

.LBB0_838:
	s_waitcnt vmcnt(0)
	s_nop 0
	v_lshlrev_b32_e32 v10, 16, v42
	v_and_b32_e32 v11, 0xffff0000, v42
	v_lshlrev_b32_e32 v12, 16, v43
	v_and_b32_e32 v13, 0xffff0000, v43
	v_lshlrev_b32_e32 v14, 16, v44
	v_and_b32_e32 v15, 0xffff0000, v44
	v_lshlrev_b32_e32 v16, 16, v45
	v_and_b32_e32 v17, 0xffff0000, v45
	v_pk_mul_f32 v[10:11], v[58:59], v[10:11]
	v_pk_mul_f32 v[12:13], v[60:61], v[12:13]
	v_pk_mul_f32 v[14:15], v[62:63], v[14:15]
	v_pk_mul_f32 v[16:17], v[64:65], v[16:17]
	v_pk_fma_f32 v[8:9], v[8:9], v[94:95], v[12:13]
	v_pk_fma_f32 v[6:7], v[6:7], v[96:97], v[10:11]
	v_pk_fma_f32 v[4:5], v[4:5], v[90:91], v[16:17]
	v_pk_fma_f32 v[2:3], v[2:3], v[92:93], v[14:15]
	s_and_b64 vcc, exec, s[6:7]
	s_mov_b64 s[8:9], -1
	s_cbranch_vccnz .LBB0_841
	v_mov_b32_e32 v12, v7
	v_mov_b32_e32 v13, v3
	v_mov_b32_e32 v10, v6
	v_mov_b32_e32 v11, v2
	v_pk_mul_f32 v[12:13], v[12:13], v[12:13]
	v_mov_b32_e32 v14, v9
	v_mov_b32_e32 v15, v5
	v_pk_fma_f32 v[10:11], v[10:11], v[10:11], v[12:13]
	v_mov_b32_e32 v12, v8
	v_mov_b32_e32 v13, v4
	v_pk_mul_f32 v[14:15], v[14:15], v[14:15]
	v_pk_mul_f32 v[16:17], v[36:37], v[4:5]
	v_pk_fma_f32 v[12:13], v[12:13], v[12:13], v[14:15]
	v_pk_mul_f32 v[14:15], v[40:41], v[8:9]
	v_pk_add_f32 v[10:11], v[10:11], v[12:13]
	v_pk_mul_f32 v[12:13], v[38:39], v[6:7]
	v_add_f32_e32 v10, v10, v11
	v_pk_mul_f32 v[20:21], v[34:35], v[2:3]
	v_add_f32_e32 v10, v10, v1
	v_cvt_pk_bf16_f32 v12, v12, v13
	v_cvt_pk_bf16_f32 v13, v14, v15
	v_cvt_pk_bf16_f32 v14, v20, v21
	v_cvt_pk_bf16_f32 v15, v16, v17
	global_store_dwordx4 v[78:79], v[12:15], off offset:256 sc1
	s_cbranch_execz .LBB0_842
